# conv-weight prefetch moved ahead of the rstd math in the fused epilogue; removed redundant NaN-canonicalising v_max ops in attention pass 1 (MFMA->VALU distances re-padded)
# speedup vs baseline: 1.0574x; 1.0050x over previous
.LBB0_588:
	v_lshl_add_u64 v[0:1], v[220:221], 0, s[56:57]
	s_barrier
	s_waitcnt vmcnt(3)
	ds_write_b128 v237, v[32:35]
	s_waitcnt vmcnt(2)
	ds_write_b128 v238, v[36:39]
	s_waitcnt vmcnt(1)
	ds_write_b128 v239, v[40:43]
	s_waitcnt vmcnt(0)
	ds_write_b128 v240, v[44:47]
	s_waitcnt lgkmcnt(0)
	s_barrier
	global_load_dwordx4 v[32:35], v[0:1], off
	v_lshl_add_u64 v[0:1], v[218:219], 0, s[56:57]
	global_load_dwordx4 v[36:39], v[0:1], off
	v_lshl_add_u64 v[0:1], v[216:217], 0, s[56:57]
	global_load_dwordx4 v[40:43], v[0:1], off
	v_lshl_add_u64 v[0:1], v[214:215], 0, s[56:57]
	global_load_dwordx4 v[44:47], v[0:1], off
	ds_read_b128 v[0:3], v166 offset:8704
	ds_read_b128 v[4:7], v166
	ds_read_b128 v[70:73], v166 offset:32
	ds_read_b128 v[74:77], v166 offset:8736
	s_waitcnt lgkmcnt(2)
	v_mfma_f32_32x32x16_bf16 v[16:31], v[4:7], v[140:143], 0
	v_mov_b32_e32 v66, v168
	v_mov_b32_e32 v68, v167
	s_add_u32 s56, s56, 0x8000
	s_addc_u32 s57, s57, 0
	s_cmp_eq_u32 s53, s56
	v_mfma_f32_32x32x16_bf16 v[0:15], v[0:3], v[140:143], 0
	s_waitcnt lgkmcnt(1)
	v_mfma_f32_32x32x16_bf16 v[16:31], v[70:73], v[136:139], v[16:31]
	s_waitcnt lgkmcnt(0)
	v_mfma_f32_32x32x16_bf16 v[0:15], v[74:77], v[136:139], v[0:15]
	ds_read_b128 v[70:73], v166 offset:64
	ds_read_b128 v[74:77], v166 offset:8768
	s_waitcnt lgkmcnt(1)
	v_mfma_f32_32x32x16_bf16 v[16:31], v[70:73], v[132:135], v[16:31]
	s_waitcnt lgkmcnt(0)
	v_mfma_f32_32x32x16_bf16 v[0:15], v[74:77], v[132:135], v[0:15]
	ds_read_b128 v[70:73], v166 offset:96
	ds_read_b128 v[74:77], v166 offset:8800
	s_waitcnt lgkmcnt(1)
	v_mfma_f32_32x32x16_bf16 v[16:31], v[70:73], v[128:131], v[16:31]
	s_waitcnt lgkmcnt(0)
	v_mfma_f32_32x32x16_bf16 v[0:15], v[74:77], v[128:131], v[0:15]
	s_nop 11
	v_max_f32_e32 v67, v17, v1
	v_max_f32_e32 v69, v18, v2
	v_max3_f32 v67, v16, v0, v67
	v_max_f32_e32 v70, v19, v3
	v_max3_f32 v67, v67, v69, v70
	v_max_f32_e32 v69, v20, v4
	v_max_f32_e32 v70, v21, v5
	v_max3_f32 v67, v67, v69, v70
	v_max_f32_e32 v69, v22, v6
	v_max_f32_e32 v70, v23, v7
	v_max3_f32 v67, v67, v69, v70
	v_max_f32_e32 v69, v24, v8
	v_max_f32_e32 v70, v25, v9
	v_max3_f32 v67, v67, v69, v70
	v_max_f32_e32 v69, v26, v10
	v_max_f32_e32 v70, v27, v11
	v_max3_f32 v67, v67, v69, v70
	v_max_f32_e32 v69, v28, v12
	v_max_f32_e32 v70, v29, v13
	v_max3_f32 v67, v67, v69, v70
	v_max_f32_e32 v69, v30, v14
	v_max_f32_e32 v70, v31, v15
	v_max3_f32 v67, v67, v69, v70
	ds_bpermute_b32 v69, v232, v67
	s_waitcnt lgkmcnt(0)
	v_max3_f32 v168, v66, v67, v69
	v_sub_f32_e32 v0, v0, v168
	v_exp_f32_e32 v163, v0
	v_sub_f32_e32 v0, v17, v168
	v_exp_f32_e32 v125, v0
	v_sub_f32_e32 v0, v1, v168
	v_exp_f32_e32 v127, v0
	v_sub_f32_e32 v0, v18, v168
	v_exp_f32_e32 v121, v0
	v_sub_f32_e32 v0, v2, v168
	v_exp_f32_e32 v123, v0
	v_sub_f32_e32 v0, v19, v168
	v_exp_f32_e32 v115, v0
	v_sub_f32_e32 v0, v3, v168
	v_exp_f32_e32 v119, v0
	v_sub_f32_e32 v0, v20, v168
	v_exp_f32_e32 v109, v0
	v_sub_f32_e32 v0, v4, v168
	v_exp_f32_e32 v113, v0
	v_sub_f32_e32 v0, v21, v168
	v_exp_f32_e32 v111, v0
	v_sub_f32_e32 v0, v5, v168
	v_exp_f32_e32 v117, v0
	v_sub_f32_e32 v0, v22, v168
	v_exp_f32_e32 v105, v0
	v_sub_f32_e32 v0, v6, v168
	v_exp_f32_e32 v107, v0
	v_sub_f32_e32 v0, v23, v168
	v_exp_f32_e32 v101, v0
	v_sub_f32_e32 v0, v7, v168
	v_exp_f32_e32 v103, v0
	v_sub_f32_e32 v0, v24, v168
	v_exp_f32_e32 v97, v0
	v_sub_f32_e32 v0, v8, v168
	v_exp_f32_e32 v99, v0
	v_sub_f32_e32 v0, v25, v168
	v_exp_f32_e32 v93, v0
	v_sub_f32_e32 v0, v9, v168
	v_exp_f32_e32 v95, v0
	v_sub_f32_e32 v0, v26, v168
	v_exp_f32_e32 v89, v0
	v_sub_f32_e32 v0, v10, v168
	v_exp_f32_e32 v91, v0
	v_sub_f32_e32 v0, v27, v168
	v_exp_f32_e32 v85, v0
	v_sub_f32_e32 v0, v11, v168
	v_exp_f32_e32 v87, v0
	v_sub_f32_e32 v0, v28, v168
	v_exp_f32_e32 v81, v0
	v_sub_f32_e32 v0, v12, v168
	v_exp_f32_e32 v83, v0
	v_sub_f32_e32 v0, v29, v168
	v_exp_f32_e32 v77, v0
	v_sub_f32_e32 v0, v13, v168
	v_exp_f32_e32 v79, v0
	v_sub_f32_e32 v0, v30, v168
	v_exp_f32_e32 v73, v0
	v_sub_f32_e32 v0, v14, v168
	v_exp_f32_e32 v75, v0
	v_sub_f32_e32 v0, v31, v168
	v_exp_f32_e32 v67, v0
	v_sub_f32_e32 v0, v15, v168
	v_exp_f32_e32 v71, v0
	v_sub_f32_e32 v0, v66, v168
	v_exp_f32_e32 v69, v0
	ds_read_b128 v[0:3], v166 offset:128
	ds_read_b128 v[4:7], v166 offset:8832
	v_sub_f32_e32 v16, v16, v168
	v_exp_f32_e32 v161, v16
	s_waitcnt lgkmcnt(1)
	v_mfma_f32_32x32x16_bf16 v[16:31], v[0:3], v[156:159], 0
	ds_read_b128 v[170:173], v166 offset:160
	ds_read_b128 v[178:181], v166 offset:8864
	s_waitcnt lgkmcnt(2)
	v_mfma_f32_32x32x16_bf16 v[0:15], v[4:7], v[156:159], 0
	s_waitcnt lgkmcnt(1)
	v_mfma_f32_32x32x16_bf16 v[16:31], v[170:173], v[152:155], v[16:31]
	s_waitcnt lgkmcnt(0)
	v_mfma_f32_32x32x16_bf16 v[0:15], v[178:181], v[152:155], v[0:15]
	ds_read_b128 v[170:173], v166 offset:192
	ds_read_b128 v[178:181], v166 offset:8896
	s_waitcnt lgkmcnt(1)
	v_mfma_f32_32x32x16_bf16 v[16:31], v[170:173], v[148:151], v[16:31]
	s_waitcnt lgkmcnt(0)
	v_mfma_f32_32x32x16_bf16 v[0:15], v[178:181], v[148:151], v[0:15]
	ds_read_b128 v[170:173], v166 offset:224
	ds_read_b128 v[178:181], v166 offset:8928
	s_waitcnt lgkmcnt(1)
	v_mfma_f32_32x32x16_bf16 v[16:31], v[170:173], v[144:147], v[16:31]
	s_waitcnt lgkmcnt(0)
	v_mfma_f32_32x32x16_bf16 v[0:15], v[178:181], v[144:147], v[0:15]
	s_nop 11
	v_max_f32_e32 v66, v17, v1
	v_max_f32_e32 v70, v18, v2
	v_max3_f32 v66, v16, v0, v66
	v_max_f32_e32 v72, v19, v3
	v_max3_f32 v66, v66, v70, v72
	v_max_f32_e32 v70, v20, v4
	v_max_f32_e32 v72, v21, v5
	v_max3_f32 v66, v66, v70, v72
	v_max_f32_e32 v70, v22, v6
	v_max_f32_e32 v72, v23, v7
	v_max3_f32 v66, v66, v70, v72
	v_max_f32_e32 v70, v24, v8
	v_max_f32_e32 v72, v25, v9
	v_max3_f32 v66, v66, v70, v72
	v_max_f32_e32 v70, v26, v10
	v_max_f32_e32 v72, v27, v11
	v_max3_f32 v66, v66, v70, v72
	v_max_f32_e32 v70, v28, v12
	v_max_f32_e32 v72, v29, v13
	v_max3_f32 v66, v66, v70, v72
	v_max_f32_e32 v70, v30, v14
	v_max_f32_e32 v72, v31, v15
	v_max3_f32 v66, v66, v70, v72
	ds_bpermute_b32 v70, v232, v66
	s_waitcnt lgkmcnt(0)
	v_max3_f32 v167, v68, v66, v70
	v_sub_f32_e32 v0, v0, v167
	v_exp_f32_e32 v162, v0
	v_sub_f32_e32 v0, v17, v167
	v_exp_f32_e32 v124, v0
	v_sub_f32_e32 v0, v1, v167
	v_exp_f32_e32 v126, v0
	v_sub_f32_e32 v0, v18, v167
	v_exp_f32_e32 v120, v0
	v_sub_f32_e32 v0, v2, v167
	v_exp_f32_e32 v122, v0
	v_sub_f32_e32 v0, v19, v167
	v_sub_f32_e32 v16, v16, v167
	v_exp_f32_e32 v114, v0
	v_sub_f32_e32 v0, v3, v167
	v_exp_f32_e32 v160, v16
	v_exp_f32_e32 v118, v0
	v_sub_f32_e32 v0, v20, v167
	v_exp_f32_e32 v108, v0
	v_sub_f32_e32 v0, v4, v167
	v_exp_f32_e32 v112, v0
	v_sub_f32_e32 v0, v21, v167
	v_exp_f32_e32 v110, v0
	v_sub_f32_e32 v0, v5, v167
	v_sub_f32_e32 v4, v23, v167
	v_exp_f32_e32 v116, v0
	v_pk_add_f32 v[0:1], v[160:161], v[162:163]
	v_exp_f32_e32 v100, v4
	v_sub_f32_e32 v4, v7, v167
	v_pk_add_f32 v[0:1], v[0:1], 0 op_sel_hi:[1,0]
	v_pk_add_f32 v[2:3], v[124:125], v[126:127]
	v_exp_f32_e32 v102, v4
	v_sub_f32_e32 v4, v24, v167
	v_pk_add_f32 v[0:1], v[2:3], v[0:1]
	v_pk_add_f32 v[2:3], v[120:121], v[122:123]
	v_exp_f32_e32 v96, v4
	v_sub_f32_e32 v4, v8, v167
	v_pk_add_f32 v[0:1], v[2:3], v[0:1]
	v_pk_add_f32 v[2:3], v[114:115], v[118:119]
	v_exp_f32_e32 v98, v4
	v_sub_f32_e32 v4, v25, v167
	v_pk_add_f32 v[0:1], v[2:3], v[0:1]
	v_pk_add_f32 v[2:3], v[108:109], v[112:113]
	v_exp_f32_e32 v92, v4
	v_sub_f32_e32 v4, v9, v167
	v_pk_add_f32 v[0:1], v[2:3], v[0:1]
	v_pk_add_f32 v[2:3], v[110:111], v[116:117]
	v_exp_f32_e32 v94, v4
	v_sub_f32_e32 v4, v26, v167
	v_pk_add_f32 v[0:1], v[2:3], v[0:1]
	v_sub_f32_e32 v2, v22, v167
	v_exp_f32_e32 v88, v4
	v_sub_f32_e32 v4, v10, v167
	v_exp_f32_e32 v104, v2
	v_sub_f32_e32 v2, v6, v167
	v_exp_f32_e32 v90, v4
	v_sub_f32_e32 v4, v27, v167
	v_exp_f32_e32 v106, v2
	v_exp_f32_e32 v84, v4
	v_sub_f32_e32 v4, v11, v167
	v_exp_f32_e32 v86, v4
	v_sub_f32_e32 v4, v28, v167
	v_exp_f32_e32 v80, v4
	v_sub_f32_e32 v4, v12, v167
	v_exp_f32_e32 v82, v4
	v_sub_f32_e32 v4, v29, v167
	v_pk_add_f32 v[2:3], v[104:105], v[106:107]
	v_exp_f32_e32 v76, v4
	v_sub_f32_e32 v4, v13, v167
	v_exp_f32_e32 v78, v4
	v_sub_f32_e32 v4, v30, v167
	v_pk_add_f32 v[0:1], v[2:3], v[0:1]
	v_pk_add_f32 v[2:3], v[100:101], v[102:103]
	v_exp_f32_e32 v72, v4
	v_sub_f32_e32 v4, v14, v167
	v_pk_add_f32 v[0:1], v[2:3], v[0:1]
	v_pk_add_f32 v[2:3], v[96:97], v[98:99]
	v_exp_f32_e32 v74, v4
	v_sub_f32_e32 v4, v31, v167
	v_pk_add_f32 v[0:1], v[2:3], v[0:1]
	v_pk_add_f32 v[2:3], v[92:93], v[94:95]
	v_exp_f32_e32 v66, v4
	v_sub_f32_e32 v4, v15, v167
	v_pk_add_f32 v[0:1], v[2:3], v[0:1]
	v_pk_add_f32 v[2:3], v[88:89], v[90:91]
	v_exp_f32_e32 v70, v4
	v_pk_add_f32 v[0:1], v[2:3], v[0:1]
	v_pk_add_f32 v[2:3], v[84:85], v[86:87]
	v_sub_f32_e32 v4, v68, v167
	v_pk_add_f32 v[0:1], v[2:3], v[0:1]
	v_pk_add_f32 v[2:3], v[80:81], v[82:83]
	v_exp_f32_e32 v68, v4
	v_pk_add_f32 v[0:1], v[2:3], v[0:1]
	v_pk_add_f32 v[2:3], v[76:77], v[78:79]
	s_nop 0
	v_pk_add_f32 v[0:1], v[2:3], v[0:1]
	v_pk_add_f32 v[2:3], v[72:73], v[74:75]
	s_nop 0
	v_pk_add_f32 v[0:1], v[2:3], v[0:1]
	v_pk_add_f32 v[2:3], v[66:67], v[70:71]
	s_nop 0
	v_pk_add_f32 v[0:1], v[2:3], v[0:1]
	s_nop 0
	v_pk_fma_f32 v[64:65], v[64:65], v[68:69], v[0:1]
	s_cbranch_scc0 .LBB0_588
	s_barrier
	s_waitcnt vmcnt(3)
	ds_write_b128 v237, v[32:35]
	s_waitcnt vmcnt(2)
	ds_write_b128 v238, v[36:39]
	s_waitcnt vmcnt(1)
	ds_write_b128 v239, v[40:43]
	s_waitcnt vmcnt(0)
	ds_write_b128 v240, v[44:47]
	s_waitcnt lgkmcnt(0)
	s_barrier
	ds_read_b128 v[0:3], v166 offset:8704
	ds_read_b128 v[4:7], v166
	ds_read_b128 v[32:35], v166 offset:32
	ds_read_b128 v[36:39], v166 offset:8736
	s_waitcnt lgkmcnt(2)
	v_mfma_f32_32x32x16_bf16 v[16:31], v[4:7], v[140:143], 0
	v_cmp_ne_u32_e32 vcc, 0, v165
	v_mfma_f32_32x32x16_bf16 v[0:15], v[0:3], v[140:143], 0
	s_waitcnt lgkmcnt(1)
	v_mfma_f32_32x32x16_bf16 v[16:31], v[32:35], v[136:139], v[16:31]
	s_waitcnt lgkmcnt(0)
	v_mfma_f32_32x32x16_bf16 v[0:15], v[36:39], v[136:139], v[0:15]
	ds_read_b128 v[32:35], v166 offset:64
	ds_read_b128 v[36:39], v166 offset:8768
	s_waitcnt lgkmcnt(1)
	v_mfma_f32_32x32x16_bf16 v[16:31], v[32:35], v[132:135], v[16:31]
	s_waitcnt lgkmcnt(0)
	v_mfma_f32_32x32x16_bf16 v[0:15], v[36:39], v[132:135], v[0:15]
	ds_read_b128 v[32:35], v166 offset:96
	ds_read_b128 v[36:39], v166 offset:8800
	s_waitcnt lgkmcnt(1)
	v_mfma_f32_32x32x16_bf16 v[16:31], v[32:35], v[128:131], v[16:31]
	s_waitcnt lgkmcnt(0)
	v_mfma_f32_32x32x16_bf16 v[0:15], v[36:39], v[128:131], v[0:15]
	s_nop 11
	v_max_f32_e32 v32, v17, v1
	v_max_f32_e32 v33, v18, v2
	v_max3_f32 v32, v16, v0, v32
	v_max_f32_e32 v34, v19, v3
	v_max3_f32 v32, v32, v33, v34
	v_max_f32_e32 v33, v20, v4
	v_max_f32_e32 v34, v21, v5
	v_max3_f32 v32, v32, v33, v34
	v_max_f32_e32 v33, v22, v6
	v_max_f32_e32 v34, v23, v7
	v_max3_f32 v32, v32, v33, v34
	v_max_f32_e32 v33, v24, v8
	v_max_f32_e32 v34, v25, v9
	v_max3_f32 v32, v32, v33, v34
	v_max_f32_e32 v33, v26, v10
	v_max_f32_e32 v34, v27, v11
	v_max3_f32 v32, v32, v33, v34
	v_max_f32_e32 v33, v28, v12
	v_max_f32_e32 v34, v29, v13
	v_max3_f32 v32, v32, v33, v34
	v_max_f32_e32 v33, v30, v14
	v_max_f32_e32 v35, v31, v31
	v_max_f32_e32 v34, v35, v15
	v_max3_f32 v32, v32, v33, v34
	ds_bpermute_b32 v33, v232, v32
	s_waitcnt lgkmcnt(0)
	v_max3_f32 v32, v168, v32, v33
	v_sub_f32_e32 v16, v16, v32
	v_sub_f32_e32 v0, v0, v32
	v_exp_f32_e32 v16, v16
	v_exp_f32_e32 v0, v0
	v_sub_f32_e32 v1, v1, v32
	v_exp_f32_e32 v1, v1
	v_sub_f32_e32 v2, v2, v32
	v_add_f32_e32 v0, v16, v0
	v_sub_f32_e32 v16, v17, v32
	v_exp_f32_e32 v16, v16
	v_add_f32_e32 v0, 0, v0
	v_exp_f32_e32 v2, v2
	v_add_f32_e32 v1, v16, v1
	v_add_f32_e32 v0, v1, v0
	v_sub_f32_e32 v1, v18, v32
	v_exp_f32_e32 v1, v1
	s_nop 0
	v_add_f32_e32 v1, v1, v2
	v_add_f32_e32 v0, v1, v0
	v_sub_f32_e32 v1, v19, v32
	v_sub_f32_e32 v2, v3, v32
	v_exp_f32_e32 v1, v1
	v_exp_f32_e32 v2, v2
	s_nop 0
	v_add_f32_e32 v1, v1, v2
	v_add_f32_e32 v0, v1, v0
	v_sub_f32_e32 v1, v20, v32
	v_sub_f32_e32 v2, v4, v32
	v_exp_f32_e32 v1, v1
	v_exp_f32_e32 v2, v2
	s_nop 0
	v_add_f32_e32 v1, v1, v2
	v_add_f32_e32 v0, v1, v0
	v_sub_f32_e32 v1, v21, v32
	v_sub_f32_e32 v2, v5, v32
	v_exp_f32_e32 v1, v1
	v_exp_f32_e32 v2, v2
	s_nop 0
	v_add_f32_e32 v1, v1, v2
	v_add_f32_e32 v0, v1, v0
	v_sub_f32_e32 v1, v22, v32
	v_sub_f32_e32 v2, v6, v32
	v_exp_f32_e32 v1, v1
	v_exp_f32_e32 v2, v2
	s_nop 0
	v_add_f32_e32 v1, v1, v2
	v_add_f32_e32 v0, v1, v0
	v_sub_f32_e32 v1, v23, v32
	v_sub_f32_e32 v2, v7, v32
	v_exp_f32_e32 v1, v1
	v_exp_f32_e32 v2, v2
	s_nop 0
	v_add_f32_e32 v1, v1, v2
	v_add_f32_e32 v0, v1, v0
	v_sub_f32_e32 v1, v24, v32
	v_sub_f32_e32 v2, v8, v32
	v_exp_f32_e32 v1, v1
	v_exp_f32_e32 v2, v2
	s_nop 0
	v_add_f32_e32 v1, v1, v2
	v_add_f32_e32 v0, v1, v0
	v_sub_f32_e32 v1, v25, v32
	v_sub_f32_e32 v2, v9, v32
	v_exp_f32_e32 v1, v1
	v_exp_f32_e32 v2, v2
	s_nop 0
	v_add_f32_e32 v1, v1, v2
	v_add_f32_e32 v0, v1, v0
	v_sub_f32_e32 v1, v26, v32
	v_sub_f32_e32 v2, v10, v32
	v_exp_f32_e32 v1, v1
	v_exp_f32_e32 v2, v2
	s_nop 0
	v_add_f32_e32 v1, v1, v2
	v_add_f32_e32 v0, v1, v0
	v_sub_f32_e32 v1, v27, v32
	v_sub_f32_e32 v2, v11, v32
	v_exp_f32_e32 v1, v1
	v_exp_f32_e32 v2, v2
	s_nop 0
	v_add_f32_e32 v1, v1, v2
	v_add_f32_e32 v0, v1, v0
	v_sub_f32_e32 v1, v28, v32
	v_sub_f32_e32 v2, v12, v32
	v_exp_f32_e32 v1, v1
	v_exp_f32_e32 v2, v2
	s_nop 0
	v_add_f32_e32 v1, v1, v2
	v_add_f32_e32 v0, v1, v0
	v_sub_f32_e32 v1, v29, v32
	v_sub_f32_e32 v2, v13, v32
	v_exp_f32_e32 v1, v1
	v_exp_f32_e32 v2, v2
	s_nop 0
	v_add_f32_e32 v1, v1, v2
	v_add_f32_e32 v0, v1, v0
	v_sub_f32_e32 v1, v30, v32
	v_sub_f32_e32 v2, v14, v32
	v_exp_f32_e32 v1, v1
	v_exp_f32_e32 v2, v2
	s_nop 0
	v_add_f32_e32 v1, v1, v2
	v_add_f32_e32 v0, v1, v0
	v_sub_f32_e32 v1, v31, v32
	v_sub_f32_e32 v2, v15, v32
	v_exp_f32_e32 v1, v1
	v_exp_f32_e32 v2, v2
	s_nop 0
	v_add_f32_e32 v1, v1, v2
	v_add_f32_e32 v33, v1, v0
	v_sub_f32_e32 v0, v168, v32
	v_exp_f32_e32 v0, v0
	s_nop 0
	v_fmac_f32_e32 v33, v65, v0
	ds_read_b128 v[0:3], v166 offset:128
	ds_read_b128 v[4:7], v166 offset:8832
	s_waitcnt lgkmcnt(1)
	v_mfma_f32_32x32x16_bf16 v[16:31], v[0:3], v[156:159], 0
	ds_read_b128 v[34:37], v166 offset:160
	ds_read_b128 v[38:41], v166 offset:8864
	s_waitcnt lgkmcnt(2)
	v_mfma_f32_32x32x16_bf16 v[0:15], v[4:7], v[156:159], 0
	s_waitcnt lgkmcnt(1)
	v_mfma_f32_32x32x16_bf16 v[16:31], v[34:37], v[152:155], v[16:31]
	s_waitcnt lgkmcnt(0)
	v_mfma_f32_32x32x16_bf16 v[0:15], v[38:41], v[152:155], v[0:15]
	ds_read_b128 v[34:37], v166 offset:192
	ds_read_b128 v[38:41], v166 offset:8896
	s_waitcnt lgkmcnt(1)
	v_mfma_f32_32x32x16_bf16 v[16:31], v[34:37], v[148:151], v[16:31]
	s_waitcnt lgkmcnt(0)
	v_mfma_f32_32x32x16_bf16 v[0:15], v[38:41], v[148:151], v[0:15]
	ds_read_b128 v[34:37], v166 offset:224
	ds_read_b128 v[38:41], v166 offset:8928
	s_waitcnt lgkmcnt(1)
	v_mfma_f32_32x32x16_bf16 v[16:31], v[34:37], v[144:147], v[16:31]
	s_waitcnt lgkmcnt(0)
	v_mfma_f32_32x32x16_bf16 v[0:15], v[38:41], v[144:147], v[0:15]
	s_nop 11
	v_max_f32_e32 v34, v17, v1
	v_max_f32_e32 v35, v18, v2
	v_max3_f32 v34, v16, v0, v34
	v_max_f32_e32 v36, v19, v3
	v_max3_f32 v34, v34, v35, v36
	v_max_f32_e32 v35, v20, v4
	v_max_f32_e32 v36, v21, v5
	v_max3_f32 v34, v34, v35, v36
	v_max_f32_e32 v35, v22, v6
	v_max_f32_e32 v36, v23, v7
	v_max3_f32 v34, v34, v35, v36
	v_max_f32_e32 v35, v24, v8
	v_max_f32_e32 v36, v25, v9
	v_max3_f32 v34, v34, v35, v36
	v_max_f32_e32 v35, v26, v10
	v_max_f32_e32 v36, v27, v11
	v_max3_f32 v34, v34, v35, v36
	v_max_f32_e32 v35, v28, v12
	v_max_f32_e32 v36, v29, v13
	v_max3_f32 v34, v34, v35, v36
	v_max_f32_e32 v35, v30, v14
	v_max_f32_e32 v37, v31, v31
	v_max_f32_e32 v36, v37, v15
	v_max3_f32 v34, v34, v35, v36
	ds_bpermute_b32 v35, v232, v34
	s_waitcnt lgkmcnt(0)
	v_max3_f32 v34, v167, v34, v35
	v_sub_f32_e32 v16, v16, v34
	v_sub_f32_e32 v0, v0, v34
	v_exp_f32_e32 v16, v16
	v_exp_f32_e32 v0, v0
	v_sub_f32_e32 v1, v1, v34
	v_exp_f32_e32 v1, v1
	v_sub_f32_e32 v2, v2, v34
	v_add_f32_e32 v0, v16, v0
	v_sub_f32_e32 v16, v17, v34
	v_exp_f32_e32 v16, v16
	v_add_f32_e32 v0, 0, v0
	v_exp_f32_e32 v2, v2
	v_add_f32_e32 v1, v16, v1
	v_add_f32_e32 v0, v1, v0
	v_sub_f32_e32 v1, v18, v34
	v_exp_f32_e32 v1, v1
	s_nop 0
	v_add_f32_e32 v1, v1, v2
	v_add_f32_e32 v0, v1, v0
	v_sub_f32_e32 v1, v19, v34
	v_sub_f32_e32 v2, v3, v34
	v_exp_f32_e32 v1, v1
	v_exp_f32_e32 v2, v2
	v_lshlrev_b32_e32 v3, 3, v192
	v_add_f32_e32 v1, v1, v2
	v_add_f32_e32 v0, v1, v0
	v_sub_f32_e32 v1, v20, v34
	v_sub_f32_e32 v2, v4, v34
	v_exp_f32_e32 v1, v1
	v_exp_f32_e32 v2, v2
	v_lshlrev_b32_e32 v4, 3, v236
	v_add_f32_e32 v1, v1, v2
	v_add_f32_e32 v0, v1, v0
	v_sub_f32_e32 v1, v21, v34
	v_sub_f32_e32 v2, v5, v34
	v_exp_f32_e32 v1, v1
	v_exp_f32_e32 v2, v2
	s_nop 0
	v_add_f32_e32 v1, v1, v2
	v_add_f32_e32 v0, v1, v0
	v_sub_f32_e32 v1, v22, v34
	v_sub_f32_e32 v2, v6, v34
	v_exp_f32_e32 v1, v1
	v_exp_f32_e32 v2, v2
	s_nop 0
	v_add_f32_e32 v1, v1, v2
	v_add_f32_e32 v0, v1, v0
	v_sub_f32_e32 v1, v23, v34
	v_sub_f32_e32 v2, v7, v34
	v_exp_f32_e32 v1, v1
	v_exp_f32_e32 v2, v2
	s_nop 0
	v_add_f32_e32 v1, v1, v2
	v_add_f32_e32 v0, v1, v0
	v_sub_f32_e32 v1, v24, v34
	v_sub_f32_e32 v2, v8, v34
	v_exp_f32_e32 v1, v1
	v_exp_f32_e32 v2, v2
	s_nop 0
	v_add_f32_e32 v1, v1, v2
	v_add_f32_e32 v0, v1, v0
	v_sub_f32_e32 v1, v25, v34
	v_sub_f32_e32 v2, v9, v34
	v_exp_f32_e32 v1, v1
	v_exp_f32_e32 v2, v2
	s_nop 0
	v_add_f32_e32 v1, v1, v2
	v_add_f32_e32 v0, v1, v0
	v_sub_f32_e32 v1, v26, v34
	v_sub_f32_e32 v2, v10, v34
	v_exp_f32_e32 v1, v1
	v_exp_f32_e32 v2, v2
	s_nop 0
	v_add_f32_e32 v1, v1, v2
	v_add_f32_e32 v0, v1, v0
	v_sub_f32_e32 v1, v27, v34
	v_sub_f32_e32 v2, v11, v34
	v_exp_f32_e32 v1, v1
	v_exp_f32_e32 v2, v2
	s_nop 0
	v_add_f32_e32 v1, v1, v2
	v_add_f32_e32 v0, v1, v0
	v_sub_f32_e32 v1, v28, v34
	v_sub_f32_e32 v2, v12, v34
	v_exp_f32_e32 v1, v1
	v_exp_f32_e32 v2, v2
	s_nop 0
	v_add_f32_e32 v1, v1, v2
	v_add_f32_e32 v0, v1, v0
	v_sub_f32_e32 v1, v29, v34
	v_sub_f32_e32 v2, v13, v34
	v_exp_f32_e32 v1, v1
	v_exp_f32_e32 v2, v2
	s_nop 0
	v_add_f32_e32 v1, v1, v2
	v_add_f32_e32 v0, v1, v0
	v_sub_f32_e32 v1, v30, v34
	v_sub_f32_e32 v2, v14, v34
	v_exp_f32_e32 v1, v1
	v_exp_f32_e32 v2, v2
	s_nop 0
	v_add_f32_e32 v1, v1, v2
	v_add_f32_e32 v0, v1, v0
	v_sub_f32_e32 v1, v31, v34
	v_sub_f32_e32 v2, v15, v34
	v_exp_f32_e32 v1, v1
	v_exp_f32_e32 v2, v2
	s_nop 0
	v_add_f32_e32 v1, v1, v2
	v_add_f32_e32 v0, v1, v0
	v_sub_f32_e32 v1, v167, v34
	v_exp_f32_e32 v1, v1
	ds_bpermute_b32 v2, v232, v33
	v_fmac_f32_e32 v0, v64, v1
	ds_bpermute_b32 v5, v232, v0
	v_lshlrev_b32_e32 v1, 1, v164
	s_and_saveexec_b64 s[56:57], vcc
	s_xor_b64 s[56:57], exec, s[56:57]
	v_lshlrev_b32_e32 v1, 1, v164
	v_lshlrev_b32_e32 v4, 3, v236
	v_lshlrev_b32_e32 v3, 3, v192
	s_or_saveexec_b64 s[56:57], s[56:57]
	s_waitcnt lgkmcnt(1)
	v_add_f32_e32 v2, v33, v2
	s_waitcnt lgkmcnt(0)
	v_add_f32_e32 v0, v0, v5
	s_xor_b64 exec, exec, s[56:57]
	s_cbranch_execz .LBB0_593
	v_or_b32_e32 v5, v1, v4
	v_lshlrev_b32_e32 v5, 8, v5
	v_add3_u32 v5, s76, v3, v5
	v_mov_b32_e32 v33, v2
	v_mov_b32_e32 v35, v0
	ds_write2_b64 v5, v[32:33], v[34:35] offset1:32
.LBB0_593:
	s_or_b64 exec, exec, s[56:57]
	s_add_u32 s53, s70, s34
	s_addc_u32 s55, s71, s35
	v_bfe_u32 v26, v213, 3, 7
	s_add_u32 s56, s53, s30
	v_and_b32_e32 v5, 56, v177
	v_mul_u32_u24_e32 v6, s54, v26
	v_and_b32_e32 v10, 0xffffffc0, v54
	v_bfe_u32 v27, v176, 3, 7
	s_addc_u32 s57, s55, s31
	v_lshlrev_b32_e32 v8, 1, v6
	v_mov_b32_e32 v9, v209
	v_ashrrev_i32_e32 v11, 31, v10
	v_lshlrev_b32_e32 v14, 1, v5
	v_mul_u32_u24_e32 v5, s54, v27
	v_and_b32_e32 v20, 0xffffffc0, v50
	v_lshl_add_u64 v[6:7], s[56:57], 0, v[8:9]
	v_lshlrev_b64 v[10:11], 1, v[10:11]
	v_lshlrev_b32_e32 v16, 1, v5
	v_mov_b32_e32 v17, v209
	v_ashrrev_i32_e32 v21, 31, v20
	v_lshl_add_u64 v[12:13], v[6:7], 0, v[10:11]
	v_mov_b32_e32 v15, v209
	v_lshl_add_u64 v[18:19], s[56:57], 0, v[16:17]
	v_lshlrev_b64 v[20:21], 1, v[20:21]
	v_lshl_add_u64 v[12:13], v[12:13], 0, v[14:15]
	v_lshl_add_u64 v[18:19], v[18:19], 0, v[20:21]
	global_load_dwordx4 v[168:171], v[56:57], off
	global_load_dwordx4 v[164:167], v[58:59], off
	global_load_dwordx4 v[160:163], v[60:61], off
	global_load_dwordx4 v[172:175], v[62:63], off
	v_lshl_add_u64 v[18:19], v[18:19], 0, v[14:15]
	global_load_dwordx4 v[176:179], v[12:13], off
	global_load_dwordx4 v[180:183], v[18:19], off
	v_and_b32_e32 v12, 0xffffffc0, v52
	v_bfe_u32 v28, v184, 3, 7
	v_ashrrev_i32_e32 v13, 31, v12
	v_mul_u32_u24_e32 v5, s54, v28
	v_and_b32_e32 v24, 0xffffffc0, v48
	v_lshlrev_b64 v[12:13], 1, v[12:13]
	v_lshlrev_b32_e32 v18, 1, v5
	v_mov_b32_e32 v19, v209
	v_ashrrev_i32_e32 v25, 31, v24
	v_lshl_add_u64 v[6:7], v[6:7], 0, v[12:13]
	v_lshl_add_u64 v[22:23], s[56:57], 0, v[18:19]
	v_lshlrev_b64 v[24:25], 1, v[24:25]
	v_lshl_add_u64 v[6:7], v[6:7], 0, v[14:15]
	v_lshl_add_u64 v[22:23], v[22:23], 0, v[24:25]
	v_lshl_add_u64 v[14:15], v[22:23], 0, v[14:15]
	global_load_dwordx4 v[184:187], v[6:7], off
	global_load_dwordx4 v[188:191], v[14:15], off
	v_sub_u32_e32 v1, v1, v4
	v_lshlrev_b32_e32 v1, 8, v1
	v_add3_u32 v1, s76, v3, v1
	v_add_u32_e32 v1, 0x800, v1
	s_waitcnt lgkmcnt(0)
	s_barrier
	ds_read2_b64 v[4:7], v1 offset1:32
	s_lshl_b32 s52, s52, 8
	s_add_u32 s52, s52, 0x100
	s_add_u32 s30, s30, s34
	s_waitcnt lgkmcnt(0)
	v_max_f32_e32 v22, v32, v4
	v_sub_f32_e32 v1, v32, v22
	v_exp_f32_e32 v14, v1
	v_sub_f32_e32 v1, v4, v22
	v_exp_f32_e32 v15, v1
	v_mov_b32_e32 v3, v5
	v_pk_mul_f32 v[2:3], v[2:3], v[14:15]
	v_max_f32_e32 v14, v34, v6
	v_sub_f32_e32 v1, v34, v14
	v_exp_f32_e32 v4, v1
	v_sub_f32_e32 v1, v6, v14
	v_exp_f32_e32 v5, v1
	v_add_f32_e32 v1, v2, v3
	v_log_f32_e32 v2, v1
	v_mov_b32_e32 v1, v7
	v_pk_mul_f32 v[0:1], v[0:1], v[4:5]
	s_addc_u32 s31, s31, s35
	v_add_f32_e32 v0, v0, v1
	v_log_f32_e32 v0, v0
	v_mul_i32_i24_e32 v1, 0x4800, v236
	v_add_f32_e32 v2, v22, v2
	v_xor_b32_e32 v64, 0x80000000, v2
	v_add_f32_e32 v0, v14, v0
	v_sub_f32_e32 v80, v233, v0
	v_add3_u32 v14, 0, v1, v212
	v_mul_i32_i24_e32 v0, 0x4800, v51
	v_mul_u32_u24_e32 v1, 0x90, v26
	v_add3_u32 v22, 0, v0, v1
	v_mul_i32_i24_e32 v0, 0x4800, v53
	v_mul_u32_u24_e32 v2, 0x90, v27
	v_add3_u32 v23, 0, v0, v2
	v_mul_i32_i24_e32 v0, 0x4800, v55
	v_add3_u32 v26, 0, v0, v1
	v_mul_i32_i24_e32 v0, 0x4800, v194
	v_mul_u32_u24_e32 v1, 0x90, v28
	v_add3_u32 v27, 0, v0, v1
	v_or_b32_e32 v0, 32, v192
	v_mul_u32_u24_e32 v28, 0x90, v0
	v_mul_u32_u24_e32 v29, 0x110, v0
	v_and_b32_e32 v0, 7, v213
	v_lshlrev_b32_e32 v0, 4, v0
	v_mov_b32_e32 v1, v209
	v_lshl_add_u64 v[0:1], s[30:31], 0, v[0:1]
	v_lshl_add_u64 v[2:3], v[0:1], 0, v[8:9]
	v_lshl_add_u64 v[4:5], v[2:3], 0, v[10:11]
	v_lshl_add_u64 v[2:3], v[2:3], 0, v[12:13]
	v_lshl_add_u64 v[224:225], s[14:15], 0, v[2:3]
	v_lshl_add_u64 v[2:3], v[0:1], 0, v[16:17]
	v_lshl_add_u64 v[0:1], v[0:1], 0, v[18:19]
	v_lshl_add_u64 v[0:1], v[0:1], 0, v[24:25]
	v_and_b32_e32 v6, 0x70, v193
	v_add_u32_e32 v7, v195, v208
	v_mul_u32_u24_e32 v15, 0x90, v192
	v_lshl_add_u64 v[2:3], v[2:3], 0, v[20:21]
	v_lshl_add_u64 v[228:229], s[14:15], 0, v[0:1]
	v_mov_b32_e32 v0, 0
	v_mov_b32_e32 v65, v64
	v_mov_b32_e32 v66, v64
	v_mov_b32_e32 v67, v64
	v_mov_b32_e32 v68, v64
	v_mov_b32_e32 v69, v64
	v_mov_b32_e32 v70, v64
	v_mov_b32_e32 v71, v64
	v_mov_b32_e32 v72, v64
	v_mov_b32_e32 v73, v64
	v_mov_b32_e32 v74, v64
	v_mov_b32_e32 v75, v64
	v_mov_b32_e32 v76, v64
	v_mov_b32_e32 v77, v64
	v_mov_b32_e32 v78, v64
	v_mov_b32_e32 v79, v64
	v_mov_b32_e32 v81, v80
	v_mov_b32_e32 v82, v80
	v_mov_b32_e32 v83, v80
	v_mov_b32_e32 v84, v80
	v_mov_b32_e32 v85, v80
	v_mov_b32_e32 v86, v80
	v_mov_b32_e32 v87, v80
	v_mov_b32_e32 v88, v80
	v_mov_b32_e32 v89, v80
	v_mov_b32_e32 v90, v80
	v_mov_b32_e32 v91, v80
	v_mov_b32_e32 v92, v80
	v_mov_b32_e32 v93, v80
	v_mov_b32_e32 v94, v80
	v_mov_b32_e32 v95, v80
	v_lshl_add_u64 v[222:223], s[14:15], 0, v[4:5]
	v_lshl_add_u64 v[226:227], s[14:15], 0, v[2:3]
	s_mov_b64 s[30:31], 0
	v_add_u32_e32 v243, v22, v6
	v_add_u32_e32 v244, v23, v6
	v_add_u32_e32 v245, v26, v6
	v_add_u32_e32 v246, v27, v6
	v_add_u32_e32 v242, v7, v49
	v_add_u32_e32 v247, v14, v15
	v_add_u32_e32 v248, v14, v28
	v_add_u32_e32 v241, v7, v29
	v_mov_b32_e32 v1, v0
	v_mov_b32_e32 v2, v0
	v_mov_b32_e32 v3, v0
	v_mov_b32_e32 v4, v0
	v_mov_b32_e32 v5, v0
	v_mov_b32_e32 v6, v0
	v_mov_b32_e32 v7, v0
	v_mov_b32_e32 v8, v0
	v_mov_b32_e32 v9, v0
	v_mov_b32_e32 v10, v0
	v_mov_b32_e32 v11, v0
	v_mov_b32_e32 v12, v0
	v_mov_b32_e32 v13, v0
	v_mov_b32_e32 v14, v0
	v_mov_b32_e32 v15, v0
	v_mov_b32_e32 v16, v0
	v_mov_b32_e32 v17, v0
	v_mov_b32_e32 v18, v0
	v_mov_b32_e32 v19, v0
	v_mov_b32_e32 v20, v0
	v_mov_b32_e32 v21, v0
	v_mov_b32_e32 v22, v0
	v_mov_b32_e32 v23, v0
	v_mov_b32_e32 v24, v0
	v_mov_b32_e32 v25, v0
	v_mov_b32_e32 v26, v0
	v_mov_b32_e32 v27, v0
	v_mov_b32_e32 v28, v0
	v_mov_b32_e32 v29, v0
	v_mov_b32_e32 v30, v0
	v_mov_b32_e32 v31, v0
	v_mov_b32_e32 v32, v0
	v_mov_b32_e32 v33, v0
	v_mov_b32_e32 v34, v0
	v_mov_b32_e32 v35, v0
	v_mov_b32_e32 v36, v0
	v_mov_b32_e32 v37, v0
	v_mov_b32_e32 v38, v0
	v_mov_b32_e32 v39, v0
	v_mov_b32_e32 v40, v0
	v_mov_b32_e32 v41, v0
	v_mov_b32_e32 v42, v0
	v_mov_b32_e32 v43, v0
	v_mov_b32_e32 v44, v0
	v_mov_b32_e32 v45, v0
	v_mov_b32_e32 v46, v0
	v_mov_b32_e32 v47, v0
	v_mov_b32_e32 v48, v0
	v_mov_b32_e32 v49, v0
	v_mov_b32_e32 v50, v0
	v_mov_b32_e32 v51, v0
	v_mov_b32_e32 v52, v0
	v_mov_b32_e32 v53, v0
	v_mov_b32_e32 v54, v0
	v_mov_b32_e32 v55, v0
	v_mov_b32_e32 v56, v0
	v_mov_b32_e32 v57, v0
	v_mov_b32_e32 v58, v0
	v_mov_b32_e32 v59, v0
	v_mov_b32_e32 v60, v0
	v_mov_b32_e32 v61, v0
	v_mov_b32_e32 v62, v0
	v_mov_b32_e32 v63, v0

.LBB0_831:
	s_and_b32 s32, s12, 1
	v_readlane_b32 s92, v254, 49
	v_readlane_b32 s93, v254, 50
	s_nop 0
	s_add_i32 s4, s88, -32
	s_ashr_i32 s4, s4, 2
	s_add_i32 s4, s4, 1
	s_cmp_gt_i32 s88, 31
	s_cselect_b32 s4, s4, 0
	s_mul_hi_i32 s5, s4, 0x5800
	s_mulk_i32 s4, 0x5800
	s_add_u32 s4, s92, s4
	s_addc_u32 s5, s93, s5
	v_lshl_add_u32 v236, s88, 8, v170
	v_lshlrev_b32_e32 v236, 2, v236
	v_lshl_or_b32 v177, s66, 7, v172
	v_lshlrev_b32_e32 v177, 2, v177
	global_load_dword v210, v236, s[10:11] offset:0
	global_load_dword v211, v236, s[10:11] offset:64
	global_load_dword v212, v236, s[10:11] offset:128
	global_load_dword v213, v236, s[10:11] offset:192
	global_load_dword v214, v236, s[10:11] offset:512
	global_load_dword v215, v236, s[10:11] offset:576
	global_load_dword v216, v236, s[10:11] offset:640
	global_load_dword v217, v236, s[10:11] offset:704
	global_load_dwordx4 v[202:205], v177, s[4:5]
	global_load_dwordx4 v[206:209], v177, s[4:5] offset:16
	v_add_u32_e32 v226, 0x2c00, v177
	global_load_dwordx4 v[218:221], v226, s[4:5]
	global_load_dwordx4 v[222:225], v226, s[4:5] offset:16
	v_readlane_b32 s2, v254, 5
	v_readlane_b32 s3, v254, 6
	v_readlane_b32 s28, v254, 7
	v_readlane_b32 s29, v254, 8
	s_mul_i32 s76, s88, 0x160000
	s_lshl_b32 s67, s66, 8
	s_add_i32 s76, s76, s67
	s_add_i32 s76, s76, 0x9300000
	s_add_u32 s76, s76, s70
	s_addc_u32 s77, s71, 0
	v_mul_u32_u24_e32 v168, 0x1600, v170
	v_lshl_add_u32 v168, v172, 1, v168
	s_mov_b32 s57, 0x20800
	v_lshl_add_u32 v169, v172, 2, s57
	v_and_b32_e32 v237, 15, v170
	v_cmp_eq_u32_e64 s[78:79], 0, v237
	v_cmp_eq_u32_e64 s[80:81], 15, v237
	v_and_b32_e32 v231, 8, v237
	v_lshlrev_b32_e32 v231, 9, v231
	s_lshl_b32 s67, s32, 10
	v_add3_u32 v231, v231, v169, s67
	global_load_dwordx4 v[116:119], v177, s[2:3]
	v_add_u32_e32 v229, 0x5800, v177
	global_load_dwordx4 v[124:127], v229, s[2:3]
	v_add_u32_e32 v228, 0xb000, v177
	global_load_dwordx4 v[128:131], v228, s[2:3]
	global_load_dwordx4 v[132:135], v177, s[28:29]
	v_add_u32_e32 v228, 0x2c00, v177
	global_load_dwordx4 v[160:163], v228, s[2:3]
	v_add_u32_e32 v229, 0x8400, v177
	global_load_dwordx4 v[164:167], v229, s[2:3]
	v_add_u32_e32 v228, 0xdc00, v177
	global_load_dwordx4 v[178:181], v228, s[2:3]
	v_add_u32_e32 v229, 0x2c00, v177
	global_load_dwordx4 v[182:185], v229, s[28:29]
	s_waitcnt vmcnt(12)
	v_fmamk_f32 v210, v210, 0x3a800000, v176
	v_fmamk_f32 v211, v211, 0x3a800000, v176
	v_fmamk_f32 v212, v212, 0x3a800000, v176
	v_fmamk_f32 v213, v213, 0x3a800000, v176
	v_fmamk_f32 v214, v214, 0x3a800000, v176
	v_fmamk_f32 v215, v215, 0x3a800000, v176
	v_fmamk_f32 v216, v216, 0x3a800000, v176
	v_fmamk_f32 v217, v217, 0x3a800000, v176
	s_mov_b32 s67, 0x800000
	v_mul_f32_e32 v226, 0x4b800000, v210
	v_mul_f32_e32 v227, 0x4b800000, v211
	v_mul_f32_e32 v228, 0x4b800000, v212
	v_mul_f32_e32 v229, 0x4b800000, v213
	v_mul_f32_e32 v232, 0x4b800000, v214
	v_mul_f32_e32 v233, 0x4b800000, v215
	v_mul_f32_e32 v234, 0x4b800000, v216
	v_mul_f32_e32 v235, 0x4b800000, v217
	v_cmp_gt_f32_e32 vcc, s67, v210
	s_nop 1
	v_cndmask_b32_e32 v210, v210, v226, vcc
	v_rsq_f32_e32 v210, v210
	s_nop 0
	v_mul_f32_e32 v226, 0x45800000, v210
	v_cndmask_b32_e32 v210, v210, v226, vcc
	v_cmp_gt_f32_e32 vcc, s67, v211
	s_nop 1
	v_cndmask_b32_e32 v211, v211, v227, vcc
	v_rsq_f32_e32 v211, v211
	s_nop 0
	v_mul_f32_e32 v227, 0x45800000, v211
	v_cndmask_b32_e32 v211, v211, v227, vcc
	v_cmp_gt_f32_e32 vcc, s67, v212
	s_nop 1
	v_cndmask_b32_e32 v212, v212, v228, vcc
	v_rsq_f32_e32 v212, v212
	s_nop 0
	v_mul_f32_e32 v228, 0x45800000, v212
	v_cndmask_b32_e32 v212, v212, v228, vcc
	v_cmp_gt_f32_e32 vcc, s67, v213
	s_nop 1
	v_cndmask_b32_e32 v213, v213, v229, vcc
	v_rsq_f32_e32 v213, v213
	s_nop 0
	v_mul_f32_e32 v229, 0x45800000, v213
	v_cndmask_b32_e32 v213, v213, v229, vcc
	v_cmp_gt_f32_e32 vcc, s67, v214
	s_nop 1
	v_cndmask_b32_e32 v214, v214, v232, vcc
	v_rsq_f32_e32 v214, v214
	s_nop 0
	v_mul_f32_e32 v232, 0x45800000, v214
	v_cndmask_b32_e32 v214, v214, v232, vcc
	v_cmp_gt_f32_e32 vcc, s67, v215
	s_nop 1
	v_cndmask_b32_e32 v215, v215, v233, vcc
	v_rsq_f32_e32 v215, v215
	s_nop 0
	v_mul_f32_e32 v233, 0x45800000, v215
	v_cndmask_b32_e32 v215, v215, v233, vcc
	v_cmp_gt_f32_e32 vcc, s67, v216
	s_nop 1
	v_cndmask_b32_e32 v216, v216, v234, vcc
	v_rsq_f32_e32 v216, v216
	s_nop 0
	v_mul_f32_e32 v234, 0x45800000, v216
	v_cndmask_b32_e32 v216, v216, v234, vcc
	v_cmp_gt_f32_e32 vcc, s67, v217
	s_nop 1
	v_cndmask_b32_e32 v217, v217, v235, vcc
	v_rsq_f32_e32 v217, v217
	s_nop 0
	v_mul_f32_e32 v235, 0x45800000, v217
	v_cndmask_b32_e32 v217, v217, v235, vcc
	s_waitcnt vmcnt(8)
	v_fma_f32 v140, v140, v210, v202
	v_fma_f32 v141, v141, v210, v203
	v_fma_f32 v142, v142, v210, v204
	v_fma_f32 v143, v143, v210, v205
	v_fma_f32 v136, v136, v210, v206
	v_fma_f32 v137, v137, v210, v207
	v_fma_f32 v138, v138, v210, v208
	v_fma_f32 v139, v139, v210, v209
	v_fma_f32 v120, v120, v210, v218
	v_fma_f32 v121, v121, v210, v219
	v_fma_f32 v122, v122, v210, v220
	v_fma_f32 v123, v123, v210, v221
	v_fma_f32 v112, v112, v210, v222
	v_fma_f32 v113, v113, v210, v223
	v_fma_f32 v114, v114, v210, v224
	v_fma_f32 v115, v115, v210, v225
	v_fma_f32 v108, v108, v211, v202
	v_fma_f32 v109, v109, v211, v203
	v_fma_f32 v110, v110, v211, v204
	v_fma_f32 v111, v111, v211, v205
	v_fma_f32 v104, v104, v211, v206
	v_fma_f32 v105, v105, v211, v207
	v_fma_f32 v106, v106, v211, v208
	v_fma_f32 v107, v107, v211, v209
	v_fma_f32 v100, v100, v211, v218
	v_fma_f32 v101, v101, v211, v219
	v_fma_f32 v102, v102, v211, v220
	v_fma_f32 v103, v103, v211, v221
	v_fma_f32 v96, v96, v211, v222
	v_fma_f32 v97, v97, v211, v223
	v_fma_f32 v98, v98, v211, v224
	v_fma_f32 v99, v99, v211, v225
	v_fma_f32 v92, v92, v212, v202
	v_fma_f32 v93, v93, v212, v203
	v_fma_f32 v94, v94, v212, v204
	v_fma_f32 v95, v95, v212, v205
	v_fma_f32 v88, v88, v212, v206
	v_fma_f32 v89, v89, v212, v207
	v_fma_f32 v90, v90, v212, v208
	v_fma_f32 v91, v91, v212, v209
	v_fma_f32 v84, v84, v212, v218
	v_fma_f32 v85, v85, v212, v219
	v_fma_f32 v86, v86, v212, v220
	v_fma_f32 v87, v87, v212, v221
	v_fma_f32 v80, v80, v212, v222
	v_fma_f32 v81, v81, v212, v223
	v_fma_f32 v82, v82, v212, v224
	v_fma_f32 v83, v83, v212, v225
	v_fma_f32 v76, v76, v213, v202
	v_fma_f32 v77, v77, v213, v203
	v_fma_f32 v78, v78, v213, v204
	v_fma_f32 v79, v79, v213, v205
	v_fma_f32 v72, v72, v213, v206
	v_fma_f32 v73, v73, v213, v207
	v_fma_f32 v74, v74, v213, v208
	v_fma_f32 v75, v75, v213, v209
	v_fma_f32 v68, v68, v213, v218
	v_fma_f32 v69, v69, v213, v219
	v_fma_f32 v70, v70, v213, v220
	v_fma_f32 v71, v71, v213, v221
	v_fma_f32 v64, v64, v213, v222
	v_fma_f32 v65, v65, v213, v223
	v_fma_f32 v66, v66, v213, v224
	v_fma_f32 v67, v67, v213, v225
	v_fma_f32 v60, v60, v214, v202
	v_fma_f32 v61, v61, v214, v203
	v_fma_f32 v62, v62, v214, v204
	v_fma_f32 v63, v63, v214, v205
	v_fma_f32 v56, v56, v214, v206
	v_fma_f32 v57, v57, v214, v207
	v_fma_f32 v58, v58, v214, v208
	v_fma_f32 v59, v59, v214, v209
	v_fma_f32 v52, v52, v214, v218
	v_fma_f32 v53, v53, v214, v219
	v_fma_f32 v54, v54, v214, v220
	v_fma_f32 v55, v55, v214, v221
	v_fma_f32 v48, v48, v214, v222
	v_fma_f32 v49, v49, v214, v223
	v_fma_f32 v50, v50, v214, v224
	v_fma_f32 v51, v51, v214, v225
	v_fma_f32 v44, v44, v215, v202
	v_fma_f32 v45, v45, v215, v203
	v_fma_f32 v46, v46, v215, v204
	v_fma_f32 v47, v47, v215, v205
	v_fma_f32 v40, v40, v215, v206
	v_fma_f32 v41, v41, v215, v207
	v_fma_f32 v42, v42, v215, v208
	v_fma_f32 v43, v43, v215, v209
	v_fma_f32 v36, v36, v215, v218
	v_fma_f32 v37, v37, v215, v219
	v_fma_f32 v38, v38, v215, v220
	v_fma_f32 v39, v39, v215, v221
	v_fma_f32 v32, v32, v215, v222
	v_fma_f32 v33, v33, v215, v223
	v_fma_f32 v34, v34, v215, v224
	v_fma_f32 v35, v35, v215, v225
	v_fma_f32 v28, v28, v216, v202
	v_fma_f32 v29, v29, v216, v203
	v_fma_f32 v30, v30, v216, v204
	v_fma_f32 v31, v31, v216, v205
	v_fma_f32 v24, v24, v216, v206
	v_fma_f32 v25, v25, v216, v207
	v_fma_f32 v26, v26, v216, v208
	v_fma_f32 v27, v27, v216, v209
	v_fma_f32 v20, v20, v216, v218
	v_fma_f32 v21, v21, v216, v219
	v_fma_f32 v22, v22, v216, v220
	v_fma_f32 v23, v23, v216, v221
	v_fma_f32 v16, v16, v216, v222
	v_fma_f32 v17, v17, v216, v223
	v_fma_f32 v18, v18, v216, v224
	v_fma_f32 v19, v19, v216, v225
	v_fma_f32 v12, v12, v217, v202
	v_fma_f32 v13, v13, v217, v203
	v_fma_f32 v14, v14, v217, v204
	v_fma_f32 v15, v15, v217, v205
	v_fma_f32 v8, v8, v217, v206
	v_fma_f32 v9, v9, v217, v207
	v_fma_f32 v10, v10, v217, v208
	v_fma_f32 v11, v11, v217, v209
	v_fma_f32 v4, v4, v217, v218
	v_fma_f32 v5, v5, v217, v219
	v_fma_f32 v6, v6, v217, v220
	v_fma_f32 v7, v7, v217, v221
	v_fma_f32 v0, v0, v217, v222
	v_fma_f32 v1, v1, v217, v223
	v_fma_f32 v2, v2, v217, v224
	v_fma_f32 v3, v3, v217, v225
	v_mov_b32_e32 v214, 0
	v_mov_b32_e32 v215, 0
	v_mov_b32_e32 v216, 0
	v_mov_b32_e32 v217, 0
	s_lshl_b32 s100, s32, 12
	s_sub_i32 s100, 0x2000, s100
	s_mul_i32 s101, s32, 0x1400
	s_add_i32 s101, s101, 0xc00
	s_lshl_b32 s67, s32, 10
	s_add_i32 s98, s67, 5120
	s_add_i32 s99, s67, 1024
	s_mov_b64 s[90:91], exec
	s_mov_b64 exec, s[78:79]
	v_add_u32_e32 v250, s100, v169
	ds_write_b128 v250, v[140:143] offset:0
	ds_write_b128 v250, v[136:139] offset:16
	ds_write_b128 v250, v[120:123] offset:512
	ds_write_b128 v250, v[112:115] offset:528
	v_add_u32_e32 v250, s98, v169
	ds_write_b128 v250, v[60:63] offset:0
	ds_write_b128 v250, v[56:59] offset:16
	ds_write_b128 v250, v[52:55] offset:512
	ds_write_b128 v250, v[48:51] offset:528
	ds_write_b128 v169, v[214:217] offset:0
	ds_write_b128 v169, v[214:217] offset:16
	ds_write_b128 v169, v[214:217] offset:512
	ds_write_b128 v169, v[214:217] offset:528
	s_mov_b64 exec, s[80:81]
	v_add_u32_e32 v251, s99, v169
	ds_write_b128 v251, v[76:79] offset:0
	ds_write_b128 v251, v[72:75] offset:16
	ds_write_b128 v251, v[68:71] offset:512
	ds_write_b128 v251, v[64:67] offset:528
	v_add_u32_e32 v251, s101, v169
	ds_write_b128 v251, v[12:15] offset:0
	ds_write_b128 v251, v[8:11] offset:16
	ds_write_b128 v251, v[4:7] offset:512
	ds_write_b128 v251, v[0:3] offset:528
	ds_write_b128 v169, v[214:217] offset:7168
	ds_write_b128 v169, v[214:217] offset:7184
	ds_write_b128 v169, v[214:217] offset:7680
	ds_write_b128 v169, v[214:217] offset:7696
	s_mov_b64 exec, s[90:91]
	s_waitcnt lgkmcnt(0)
	s_barrier
	ds_read_b128 v[186:189], v231 offset:0
	ds_read_b128 v[190:193], v231 offset:512
	ds_read_b128 v[194:197], v231 offset:2048
	ds_read_b128 v[198:201], v231 offset:2560
	s_waitcnt vmcnt(0)
	v_cndmask_b32_e64 v218, 0, v116, s[78:79]
	v_cndmask_b32_e64 v222, 0, v128, s[80:81]
	v_cndmask_b32_e64 v219, 0, v117, s[78:79]
	v_cndmask_b32_e64 v223, 0, v129, s[80:81]
	v_cndmask_b32_e64 v220, 0, v118, s[78:79]
	v_cndmask_b32_e64 v224, 0, v130, s[80:81]
	v_cndmask_b32_e64 v221, 0, v119, s[78:79]
	v_cndmask_b32_e64 v225, 0, v131, s[80:81]
	v_cndmask_b32_e64 v226, 0, v160, s[78:79]
	v_cndmask_b32_e64 v232, 0, v178, s[80:81]
	v_cndmask_b32_e64 v227, 0, v161, s[78:79]
	v_cndmask_b32_e64 v233, 0, v179, s[80:81]
	v_cndmask_b32_e64 v228, 0, v162, s[78:79]
	v_cndmask_b32_e64 v234, 0, v180, s[80:81]
	v_cndmask_b32_e64 v229, 0, v163, s[78:79]
	v_cndmask_b32_e64 v235, 0, v181, s[80:81]
	s_waitcnt lgkmcnt(0)
	s_nop 1
	v_fma_f32 v202, v124, v140, v132
	v_fma_f32 v203, v125, v141, v133
	v_fma_f32 v204, v126, v142, v134
	v_fma_f32 v205, v127, v143, v135
	v_fmac_f32_dpp v202, v140, v116 row_shr:1 row_mask:0xf bank_mask:0xf
	v_fmac_f32_dpp v203, v141, v117 row_shr:1 row_mask:0xf bank_mask:0xf
	v_fmac_f32_dpp v204, v142, v118 row_shr:1 row_mask:0xf bank_mask:0xf
	v_fmac_f32_dpp v205, v143, v119 row_shr:1 row_mask:0xf bank_mask:0xf
	v_fmac_f32_e32 v202, v186, v218
	v_fmac_f32_e32 v203, v187, v219
	v_fmac_f32_e32 v204, v188, v220
	v_fmac_f32_e32 v205, v189, v221
	v_fmac_f32_dpp v202, v140, v128 row_shl:1 row_mask:0xf bank_mask:0xf
	v_fmac_f32_dpp v203, v141, v129 row_shl:1 row_mask:0xf bank_mask:0xf
	v_fmac_f32_dpp v204, v142, v130 row_shl:1 row_mask:0xf bank_mask:0xf
	v_fmac_f32_dpp v205, v143, v131 row_shl:1 row_mask:0xf bank_mask:0xf
	v_fmac_f32_dpp v202, v108, v222 row_ror:15 row_mask:0xf bank_mask:0xf
	v_fmac_f32_dpp v203, v109, v223 row_ror:15 row_mask:0xf bank_mask:0xf
	v_fmac_f32_dpp v204, v110, v224 row_ror:15 row_mask:0xf bank_mask:0xf
	v_fmac_f32_dpp v205, v111, v225 row_ror:15 row_mask:0xf bank_mask:0xf
	v_fma_f32 v206, v164, v120, v182
	v_fma_f32 v207, v165, v121, v183
	v_fma_f32 v208, v166, v122, v184
	v_fma_f32 v209, v167, v123, v185
	v_fmac_f32_dpp v206, v120, v160 row_shr:1 row_mask:0xf bank_mask:0xf
	v_fmac_f32_dpp v207, v121, v161 row_shr:1 row_mask:0xf bank_mask:0xf
	v_fmac_f32_dpp v208, v122, v162 row_shr:1 row_mask:0xf bank_mask:0xf
	v_fmac_f32_dpp v209, v123, v163 row_shr:1 row_mask:0xf bank_mask:0xf
	v_fmac_f32_e32 v206, v190, v226
	v_fmac_f32_e32 v207, v191, v227
	v_fmac_f32_e32 v208, v192, v228
	v_fmac_f32_e32 v209, v193, v229
	v_fmac_f32_dpp v206, v120, v178 row_shl:1 row_mask:0xf bank_mask:0xf
	v_fmac_f32_dpp v207, v121, v179 row_shl:1 row_mask:0xf bank_mask:0xf
	v_fmac_f32_dpp v208, v122, v180 row_shl:1 row_mask:0xf bank_mask:0xf
	v_fmac_f32_dpp v209, v123, v181 row_shl:1 row_mask:0xf bank_mask:0xf
	v_fmac_f32_dpp v206, v100, v232 row_ror:15 row_mask:0xf bank_mask:0xf
	v_fmac_f32_dpp v207, v101, v233 row_ror:15 row_mask:0xf bank_mask:0xf
	v_fmac_f32_dpp v208, v102, v234 row_ror:15 row_mask:0xf bank_mask:0xf
	v_fmac_f32_dpp v209, v103, v235 row_ror:15 row_mask:0xf bank_mask:0xf
	v_mul_f32_e32 v210, 0xbfb8aa3b, v202
	v_mul_f32_e32 v211, 0xbfb8aa3b, v203
	v_mul_f32_e32 v212, 0xbfb8aa3b, v204
	v_mul_f32_e32 v213, 0xbfb8aa3b, v205
	v_exp_f32_e32 v210, v210
	v_exp_f32_e32 v211, v211
	v_exp_f32_e32 v212, v212
	v_exp_f32_e32 v213, v213
	v_add_f32_e32 v210, 1.0, v210
	v_add_f32_e32 v211, 1.0, v211
	v_add_f32_e32 v212, 1.0, v212
	v_add_f32_e32 v213, 1.0, v213
	v_rcp_f32_e32 v210, v210
	v_rcp_f32_e32 v211, v211
	v_rcp_f32_e32 v212, v212
	v_rcp_f32_e32 v213, v213
	v_mul_f32_e32 v202, v202, v210
	v_mul_f32_e32 v203, v203, v211
	v_mul_f32_e32 v204, v204, v212
	v_mul_f32_e32 v205, v205, v213
	v_mul_f32_e32 v202, v202, v206
	v_mul_f32_e32 v203, v203, v207
	v_mul_f32_e32 v204, v204, v208
	v_mul_f32_e32 v205, v205, v209
	v_cvt_pk_bf16_f32 v236, v202, v203
	v_cvt_pk_bf16_f32 v237, v204, v205
	v_fma_f32 v202, v124, v108, v132
	v_fma_f32 v203, v125, v109, v133
	v_fma_f32 v204, v126, v110, v134
	v_fma_f32 v205, v127, v111, v135
	v_fmac_f32_dpp v202, v108, v116 row_shr:1 row_mask:0xf bank_mask:0xf
	v_fmac_f32_dpp v203, v109, v117 row_shr:1 row_mask:0xf bank_mask:0xf
	v_fmac_f32_dpp v204, v110, v118 row_shr:1 row_mask:0xf bank_mask:0xf
	v_fmac_f32_dpp v205, v111, v119 row_shr:1 row_mask:0xf bank_mask:0xf
	v_fmac_f32_dpp v202, v140, v218 row_ror:1 row_mask:0xf bank_mask:0xf
	v_fmac_f32_dpp v203, v141, v219 row_ror:1 row_mask:0xf bank_mask:0xf
	v_fmac_f32_dpp v204, v142, v220 row_ror:1 row_mask:0xf bank_mask:0xf
	v_fmac_f32_dpp v205, v143, v221 row_ror:1 row_mask:0xf bank_mask:0xf
	v_fmac_f32_dpp v202, v108, v128 row_shl:1 row_mask:0xf bank_mask:0xf
	v_fmac_f32_dpp v203, v109, v129 row_shl:1 row_mask:0xf bank_mask:0xf
	v_fmac_f32_dpp v204, v110, v130 row_shl:1 row_mask:0xf bank_mask:0xf
	v_fmac_f32_dpp v205, v111, v131 row_shl:1 row_mask:0xf bank_mask:0xf
	v_fmac_f32_dpp v202, v92, v222 row_ror:15 row_mask:0xf bank_mask:0xf
	v_fmac_f32_dpp v203, v93, v223 row_ror:15 row_mask:0xf bank_mask:0xf
	v_fmac_f32_dpp v204, v94, v224 row_ror:15 row_mask:0xf bank_mask:0xf
	v_fmac_f32_dpp v205, v95, v225 row_ror:15 row_mask:0xf bank_mask:0xf
	v_fma_f32 v206, v164, v100, v182
	v_fma_f32 v207, v165, v101, v183
	v_fma_f32 v208, v166, v102, v184
	v_fma_f32 v209, v167, v103, v185
	v_fmac_f32_dpp v206, v100, v160 row_shr:1 row_mask:0xf bank_mask:0xf
	v_fmac_f32_dpp v207, v101, v161 row_shr:1 row_mask:0xf bank_mask:0xf
	v_fmac_f32_dpp v208, v102, v162 row_shr:1 row_mask:0xf bank_mask:0xf
	v_fmac_f32_dpp v209, v103, v163 row_shr:1 row_mask:0xf bank_mask:0xf
	v_fmac_f32_dpp v206, v120, v226 row_ror:1 row_mask:0xf bank_mask:0xf
	v_fmac_f32_dpp v207, v121, v227 row_ror:1 row_mask:0xf bank_mask:0xf
	v_fmac_f32_dpp v208, v122, v228 row_ror:1 row_mask:0xf bank_mask:0xf
	v_fmac_f32_dpp v209, v123, v229 row_ror:1 row_mask:0xf bank_mask:0xf
	v_fmac_f32_dpp v206, v100, v178 row_shl:1 row_mask:0xf bank_mask:0xf
	v_fmac_f32_dpp v207, v101, v179 row_shl:1 row_mask:0xf bank_mask:0xf
	v_fmac_f32_dpp v208, v102, v180 row_shl:1 row_mask:0xf bank_mask:0xf
	v_fmac_f32_dpp v209, v103, v181 row_shl:1 row_mask:0xf bank_mask:0xf
	v_fmac_f32_dpp v206, v84, v232 row_ror:15 row_mask:0xf bank_mask:0xf
	v_fmac_f32_dpp v207, v85, v233 row_ror:15 row_mask:0xf bank_mask:0xf
	v_fmac_f32_dpp v208, v86, v234 row_ror:15 row_mask:0xf bank_mask:0xf
	v_fmac_f32_dpp v209, v87, v235 row_ror:15 row_mask:0xf bank_mask:0xf
	v_mul_f32_e32 v210, 0xbfb8aa3b, v202
	v_mul_f32_e32 v211, 0xbfb8aa3b, v203
	v_mul_f32_e32 v212, 0xbfb8aa3b, v204
	v_mul_f32_e32 v213, 0xbfb8aa3b, v205
	v_exp_f32_e32 v210, v210
	v_exp_f32_e32 v211, v211
	v_exp_f32_e32 v212, v212
	v_exp_f32_e32 v213, v213
	v_add_f32_e32 v210, 1.0, v210
	v_add_f32_e32 v211, 1.0, v211
	v_add_f32_e32 v212, 1.0, v212
	v_add_f32_e32 v213, 1.0, v213
	v_rcp_f32_e32 v210, v210
	v_rcp_f32_e32 v211, v211
	v_rcp_f32_e32 v212, v212
	v_rcp_f32_e32 v213, v213
	v_mul_f32_e32 v202, v202, v210
	v_mul_f32_e32 v203, v203, v211
	v_mul_f32_e32 v204, v204, v212
	v_mul_f32_e32 v205, v205, v213
	v_mul_f32_e32 v202, v202, v206
	v_mul_f32_e32 v203, v203, v207
	v_mul_f32_e32 v204, v204, v208
	v_mul_f32_e32 v205, v205, v209
	v_cvt_pk_bf16_f32 v238, v202, v203
	v_cvt_pk_bf16_f32 v239, v204, v205
	v_fma_f32 v202, v124, v92, v132
	v_fma_f32 v203, v125, v93, v133
	v_fma_f32 v204, v126, v94, v134
	v_fma_f32 v205, v127, v95, v135
	v_fmac_f32_dpp v202, v92, v116 row_shr:1 row_mask:0xf bank_mask:0xf
	v_fmac_f32_dpp v203, v93, v117 row_shr:1 row_mask:0xf bank_mask:0xf
	v_fmac_f32_dpp v204, v94, v118 row_shr:1 row_mask:0xf bank_mask:0xf
	v_fmac_f32_dpp v205, v95, v119 row_shr:1 row_mask:0xf bank_mask:0xf
	v_fmac_f32_dpp v202, v108, v218 row_ror:1 row_mask:0xf bank_mask:0xf
	v_fmac_f32_dpp v203, v109, v219 row_ror:1 row_mask:0xf bank_mask:0xf
	v_fmac_f32_dpp v204, v110, v220 row_ror:1 row_mask:0xf bank_mask:0xf
	v_fmac_f32_dpp v205, v111, v221 row_ror:1 row_mask:0xf bank_mask:0xf
	v_fmac_f32_dpp v202, v92, v128 row_shl:1 row_mask:0xf bank_mask:0xf
	v_fmac_f32_dpp v203, v93, v129 row_shl:1 row_mask:0xf bank_mask:0xf
	v_fmac_f32_dpp v204, v94, v130 row_shl:1 row_mask:0xf bank_mask:0xf
	v_fmac_f32_dpp v205, v95, v131 row_shl:1 row_mask:0xf bank_mask:0xf
	v_fmac_f32_dpp v202, v76, v222 row_ror:15 row_mask:0xf bank_mask:0xf
	v_fmac_f32_dpp v203, v77, v223 row_ror:15 row_mask:0xf bank_mask:0xf
	v_fmac_f32_dpp v204, v78, v224 row_ror:15 row_mask:0xf bank_mask:0xf
	v_fmac_f32_dpp v205, v79, v225 row_ror:15 row_mask:0xf bank_mask:0xf
	v_fma_f32 v206, v164, v84, v182
	v_fma_f32 v207, v165, v85, v183
	v_fma_f32 v208, v166, v86, v184
	v_fma_f32 v209, v167, v87, v185
	v_fmac_f32_dpp v206, v84, v160 row_shr:1 row_mask:0xf bank_mask:0xf
	v_fmac_f32_dpp v207, v85, v161 row_shr:1 row_mask:0xf bank_mask:0xf
	v_fmac_f32_dpp v208, v86, v162 row_shr:1 row_mask:0xf bank_mask:0xf
	v_fmac_f32_dpp v209, v87, v163 row_shr:1 row_mask:0xf bank_mask:0xf
	v_fmac_f32_dpp v206, v100, v226 row_ror:1 row_mask:0xf bank_mask:0xf
	v_fmac_f32_dpp v207, v101, v227 row_ror:1 row_mask:0xf bank_mask:0xf
	v_fmac_f32_dpp v208, v102, v228 row_ror:1 row_mask:0xf bank_mask:0xf
	v_fmac_f32_dpp v209, v103, v229 row_ror:1 row_mask:0xf bank_mask:0xf
	v_fmac_f32_dpp v206, v84, v178 row_shl:1 row_mask:0xf bank_mask:0xf
	v_fmac_f32_dpp v207, v85, v179 row_shl:1 row_mask:0xf bank_mask:0xf
	v_fmac_f32_dpp v208, v86, v180 row_shl:1 row_mask:0xf bank_mask:0xf
	v_fmac_f32_dpp v209, v87, v181 row_shl:1 row_mask:0xf bank_mask:0xf
	v_fmac_f32_dpp v206, v68, v232 row_ror:15 row_mask:0xf bank_mask:0xf
	v_fmac_f32_dpp v207, v69, v233 row_ror:15 row_mask:0xf bank_mask:0xf
	v_fmac_f32_dpp v208, v70, v234 row_ror:15 row_mask:0xf bank_mask:0xf
	v_fmac_f32_dpp v209, v71, v235 row_ror:15 row_mask:0xf bank_mask:0xf
	v_mul_f32_e32 v210, 0xbfb8aa3b, v202
	v_mul_f32_e32 v211, 0xbfb8aa3b, v203
	v_mul_f32_e32 v212, 0xbfb8aa3b, v204
	v_mul_f32_e32 v213, 0xbfb8aa3b, v205
	v_exp_f32_e32 v210, v210
	v_exp_f32_e32 v211, v211
	v_exp_f32_e32 v212, v212
	v_exp_f32_e32 v213, v213
	v_add_f32_e32 v210, 1.0, v210
	v_add_f32_e32 v211, 1.0, v211
	v_add_f32_e32 v212, 1.0, v212
	v_add_f32_e32 v213, 1.0, v213
	v_rcp_f32_e32 v210, v210
	v_rcp_f32_e32 v211, v211
	v_rcp_f32_e32 v212, v212
	v_rcp_f32_e32 v213, v213
	v_mul_f32_e32 v202, v202, v210
	v_mul_f32_e32 v203, v203, v211
	v_mul_f32_e32 v204, v204, v212
	v_mul_f32_e32 v205, v205, v213
	v_mul_f32_e32 v202, v202, v206
	v_mul_f32_e32 v203, v203, v207
	v_mul_f32_e32 v204, v204, v208
	v_mul_f32_e32 v205, v205, v209
	v_cvt_pk_bf16_f32 v240, v202, v203
	v_cvt_pk_bf16_f32 v241, v204, v205
	v_fma_f32 v202, v124, v76, v132
	v_fma_f32 v203, v125, v77, v133
	v_fma_f32 v204, v126, v78, v134
	v_fma_f32 v205, v127, v79, v135
	v_fmac_f32_dpp v202, v76, v116 row_shr:1 row_mask:0xf bank_mask:0xf
	v_fmac_f32_dpp v203, v77, v117 row_shr:1 row_mask:0xf bank_mask:0xf
	v_fmac_f32_dpp v204, v78, v118 row_shr:1 row_mask:0xf bank_mask:0xf
	v_fmac_f32_dpp v205, v79, v119 row_shr:1 row_mask:0xf bank_mask:0xf
	v_fmac_f32_dpp v202, v92, v218 row_ror:1 row_mask:0xf bank_mask:0xf
	v_fmac_f32_dpp v203, v93, v219 row_ror:1 row_mask:0xf bank_mask:0xf
	v_fmac_f32_dpp v204, v94, v220 row_ror:1 row_mask:0xf bank_mask:0xf
	v_fmac_f32_dpp v205, v95, v221 row_ror:1 row_mask:0xf bank_mask:0xf
	v_fmac_f32_dpp v202, v76, v128 row_shl:1 row_mask:0xf bank_mask:0xf
	v_fmac_f32_dpp v203, v77, v129 row_shl:1 row_mask:0xf bank_mask:0xf
	v_fmac_f32_dpp v204, v78, v130 row_shl:1 row_mask:0xf bank_mask:0xf
	v_fmac_f32_dpp v205, v79, v131 row_shl:1 row_mask:0xf bank_mask:0xf
	v_fmac_f32_e32 v202, v186, v222
	v_fmac_f32_e32 v203, v187, v223
	v_fmac_f32_e32 v204, v188, v224
	v_fmac_f32_e32 v205, v189, v225
	v_fma_f32 v206, v164, v68, v182
	v_fma_f32 v207, v165, v69, v183
	v_fma_f32 v208, v166, v70, v184
	v_fma_f32 v209, v167, v71, v185
	v_fmac_f32_dpp v206, v68, v160 row_shr:1 row_mask:0xf bank_mask:0xf
	v_fmac_f32_dpp v207, v69, v161 row_shr:1 row_mask:0xf bank_mask:0xf
	v_fmac_f32_dpp v208, v70, v162 row_shr:1 row_mask:0xf bank_mask:0xf
	v_fmac_f32_dpp v209, v71, v163 row_shr:1 row_mask:0xf bank_mask:0xf
	v_fmac_f32_dpp v206, v84, v226 row_ror:1 row_mask:0xf bank_mask:0xf
	v_fmac_f32_dpp v207, v85, v227 row_ror:1 row_mask:0xf bank_mask:0xf
	v_fmac_f32_dpp v208, v86, v228 row_ror:1 row_mask:0xf bank_mask:0xf
	v_fmac_f32_dpp v209, v87, v229 row_ror:1 row_mask:0xf bank_mask:0xf
	v_fmac_f32_dpp v206, v68, v178 row_shl:1 row_mask:0xf bank_mask:0xf
	v_fmac_f32_dpp v207, v69, v179 row_shl:1 row_mask:0xf bank_mask:0xf
	v_fmac_f32_dpp v208, v70, v180 row_shl:1 row_mask:0xf bank_mask:0xf
	v_fmac_f32_dpp v209, v71, v181 row_shl:1 row_mask:0xf bank_mask:0xf
	v_fmac_f32_e32 v206, v190, v232
	v_fmac_f32_e32 v207, v191, v233
	v_fmac_f32_e32 v208, v192, v234
	v_fmac_f32_e32 v209, v193, v235
	v_mul_f32_e32 v210, 0xbfb8aa3b, v202
	v_mul_f32_e32 v211, 0xbfb8aa3b, v203
	v_mul_f32_e32 v212, 0xbfb8aa3b, v204
	v_mul_f32_e32 v213, 0xbfb8aa3b, v205
	v_exp_f32_e32 v210, v210
	v_exp_f32_e32 v211, v211
	v_exp_f32_e32 v212, v212
	v_exp_f32_e32 v213, v213
	v_add_f32_e32 v210, 1.0, v210
	v_add_f32_e32 v211, 1.0, v211
	v_add_f32_e32 v212, 1.0, v212
	v_add_f32_e32 v213, 1.0, v213
	v_rcp_f32_e32 v210, v210
	v_rcp_f32_e32 v211, v211
	v_rcp_f32_e32 v212, v212
	v_rcp_f32_e32 v213, v213
	v_mul_f32_e32 v202, v202, v210
	v_mul_f32_e32 v203, v203, v211
	v_mul_f32_e32 v204, v204, v212
	v_mul_f32_e32 v205, v205, v213
	v_mul_f32_e32 v202, v202, v206
	v_mul_f32_e32 v203, v203, v207
	v_mul_f32_e32 v204, v204, v208
	v_mul_f32_e32 v205, v205, v209
	v_cvt_pk_bf16_f32 v242, v202, v203
	v_cvt_pk_bf16_f32 v243, v204, v205
	v_fma_f32 v202, v124, v60, v132
	v_fma_f32 v203, v125, v61, v133
	v_fma_f32 v204, v126, v62, v134
	v_fma_f32 v205, v127, v63, v135
	v_fmac_f32_dpp v202, v60, v116 row_shr:1 row_mask:0xf bank_mask:0xf
	v_fmac_f32_dpp v203, v61, v117 row_shr:1 row_mask:0xf bank_mask:0xf
	v_fmac_f32_dpp v204, v62, v118 row_shr:1 row_mask:0xf bank_mask:0xf
	v_fmac_f32_dpp v205, v63, v119 row_shr:1 row_mask:0xf bank_mask:0xf
	v_fmac_f32_e32 v202, v194, v218
	v_fmac_f32_e32 v203, v195, v219
	v_fmac_f32_e32 v204, v196, v220
	v_fmac_f32_e32 v205, v197, v221
	v_fmac_f32_dpp v202, v60, v128 row_shl:1 row_mask:0xf bank_mask:0xf
	v_fmac_f32_dpp v203, v61, v129 row_shl:1 row_mask:0xf bank_mask:0xf
	v_fmac_f32_dpp v204, v62, v130 row_shl:1 row_mask:0xf bank_mask:0xf
	v_fmac_f32_dpp v205, v63, v131 row_shl:1 row_mask:0xf bank_mask:0xf
	v_fmac_f32_dpp v202, v44, v222 row_ror:15 row_mask:0xf bank_mask:0xf
	v_fmac_f32_dpp v203, v45, v223 row_ror:15 row_mask:0xf bank_mask:0xf
	v_fmac_f32_dpp v204, v46, v224 row_ror:15 row_mask:0xf bank_mask:0xf
	v_fmac_f32_dpp v205, v47, v225 row_ror:15 row_mask:0xf bank_mask:0xf
	v_fma_f32 v206, v164, v52, v182
	v_fma_f32 v207, v165, v53, v183
	v_fma_f32 v208, v166, v54, v184
	v_fma_f32 v209, v167, v55, v185
	v_fmac_f32_dpp v206, v52, v160 row_shr:1 row_mask:0xf bank_mask:0xf
	v_fmac_f32_dpp v207, v53, v161 row_shr:1 row_mask:0xf bank_mask:0xf
	v_fmac_f32_dpp v208, v54, v162 row_shr:1 row_mask:0xf bank_mask:0xf
	v_fmac_f32_dpp v209, v55, v163 row_shr:1 row_mask:0xf bank_mask:0xf
	v_fmac_f32_e32 v206, v198, v226
	v_fmac_f32_e32 v207, v199, v227
	v_fmac_f32_e32 v208, v200, v228
	v_fmac_f32_e32 v209, v201, v229
	v_fmac_f32_dpp v206, v52, v178 row_shl:1 row_mask:0xf bank_mask:0xf
	v_fmac_f32_dpp v207, v53, v179 row_shl:1 row_mask:0xf bank_mask:0xf
	v_fmac_f32_dpp v208, v54, v180 row_shl:1 row_mask:0xf bank_mask:0xf
	v_fmac_f32_dpp v209, v55, v181 row_shl:1 row_mask:0xf bank_mask:0xf
	v_fmac_f32_dpp v206, v36, v232 row_ror:15 row_mask:0xf bank_mask:0xf
	v_fmac_f32_dpp v207, v37, v233 row_ror:15 row_mask:0xf bank_mask:0xf
	v_fmac_f32_dpp v208, v38, v234 row_ror:15 row_mask:0xf bank_mask:0xf
	v_fmac_f32_dpp v209, v39, v235 row_ror:15 row_mask:0xf bank_mask:0xf
	v_mul_f32_e32 v210, 0xbfb8aa3b, v202
	v_mul_f32_e32 v211, 0xbfb8aa3b, v203
	v_mul_f32_e32 v212, 0xbfb8aa3b, v204
	v_mul_f32_e32 v213, 0xbfb8aa3b, v205
	v_exp_f32_e32 v210, v210
	v_exp_f32_e32 v211, v211
	v_exp_f32_e32 v212, v212
	v_exp_f32_e32 v213, v213
	v_add_f32_e32 v210, 1.0, v210
	v_add_f32_e32 v211, 1.0, v211
	v_add_f32_e32 v212, 1.0, v212
	v_add_f32_e32 v213, 1.0, v213
	v_rcp_f32_e32 v210, v210
	v_rcp_f32_e32 v211, v211
	v_rcp_f32_e32 v212, v212
	v_rcp_f32_e32 v213, v213
	v_mul_f32_e32 v202, v202, v210
	v_mul_f32_e32 v203, v203, v211
	v_mul_f32_e32 v204, v204, v212
	v_mul_f32_e32 v205, v205, v213
	v_mul_f32_e32 v202, v202, v206
	v_mul_f32_e32 v203, v203, v207
	v_mul_f32_e32 v204, v204, v208
	v_mul_f32_e32 v205, v205, v209
	v_cvt_pk_bf16_f32 v244, v202, v203
	v_cvt_pk_bf16_f32 v245, v204, v205
	v_fma_f32 v202, v124, v44, v132
	v_fma_f32 v203, v125, v45, v133
	v_fma_f32 v204, v126, v46, v134
	v_fma_f32 v205, v127, v47, v135
	v_fmac_f32_dpp v202, v44, v116 row_shr:1 row_mask:0xf bank_mask:0xf
	v_fmac_f32_dpp v203, v45, v117 row_shr:1 row_mask:0xf bank_mask:0xf
	v_fmac_f32_dpp v204, v46, v118 row_shr:1 row_mask:0xf bank_mask:0xf
	v_fmac_f32_dpp v205, v47, v119 row_shr:1 row_mask:0xf bank_mask:0xf
	v_fmac_f32_dpp v202, v60, v218 row_ror:1 row_mask:0xf bank_mask:0xf
	v_fmac_f32_dpp v203, v61, v219 row_ror:1 row_mask:0xf bank_mask:0xf
	v_fmac_f32_dpp v204, v62, v220 row_ror:1 row_mask:0xf bank_mask:0xf
	v_fmac_f32_dpp v205, v63, v221 row_ror:1 row_mask:0xf bank_mask:0xf
	v_fmac_f32_dpp v202, v44, v128 row_shl:1 row_mask:0xf bank_mask:0xf
	v_fmac_f32_dpp v203, v45, v129 row_shl:1 row_mask:0xf bank_mask:0xf
	v_fmac_f32_dpp v204, v46, v130 row_shl:1 row_mask:0xf bank_mask:0xf
	v_fmac_f32_dpp v205, v47, v131 row_shl:1 row_mask:0xf bank_mask:0xf
	v_fmac_f32_dpp v202, v28, v222 row_ror:15 row_mask:0xf bank_mask:0xf
	v_fmac_f32_dpp v203, v29, v223 row_ror:15 row_mask:0xf bank_mask:0xf
	v_fmac_f32_dpp v204, v30, v224 row_ror:15 row_mask:0xf bank_mask:0xf
	v_fmac_f32_dpp v205, v31, v225 row_ror:15 row_mask:0xf bank_mask:0xf
	v_fma_f32 v206, v164, v36, v182
	v_fma_f32 v207, v165, v37, v183
	v_fma_f32 v208, v166, v38, v184
	v_fma_f32 v209, v167, v39, v185
	v_fmac_f32_dpp v206, v36, v160 row_shr:1 row_mask:0xf bank_mask:0xf
	v_fmac_f32_dpp v207, v37, v161 row_shr:1 row_mask:0xf bank_mask:0xf
	v_fmac_f32_dpp v208, v38, v162 row_shr:1 row_mask:0xf bank_mask:0xf
	v_fmac_f32_dpp v209, v39, v163 row_shr:1 row_mask:0xf bank_mask:0xf
	v_fmac_f32_dpp v206, v52, v226 row_ror:1 row_mask:0xf bank_mask:0xf
	v_fmac_f32_dpp v207, v53, v227 row_ror:1 row_mask:0xf bank_mask:0xf
	v_fmac_f32_dpp v208, v54, v228 row_ror:1 row_mask:0xf bank_mask:0xf
	v_fmac_f32_dpp v209, v55, v229 row_ror:1 row_mask:0xf bank_mask:0xf
	v_fmac_f32_dpp v206, v36, v178 row_shl:1 row_mask:0xf bank_mask:0xf
	v_fmac_f32_dpp v207, v37, v179 row_shl:1 row_mask:0xf bank_mask:0xf
	v_fmac_f32_dpp v208, v38, v180 row_shl:1 row_mask:0xf bank_mask:0xf
	v_fmac_f32_dpp v209, v39, v181 row_shl:1 row_mask:0xf bank_mask:0xf
	v_fmac_f32_dpp v206, v20, v232 row_ror:15 row_mask:0xf bank_mask:0xf
	v_fmac_f32_dpp v207, v21, v233 row_ror:15 row_mask:0xf bank_mask:0xf
	v_fmac_f32_dpp v208, v22, v234 row_ror:15 row_mask:0xf bank_mask:0xf
	v_fmac_f32_dpp v209, v23, v235 row_ror:15 row_mask:0xf bank_mask:0xf
	v_mul_f32_e32 v210, 0xbfb8aa3b, v202
	v_mul_f32_e32 v211, 0xbfb8aa3b, v203
	v_mul_f32_e32 v212, 0xbfb8aa3b, v204
	v_mul_f32_e32 v213, 0xbfb8aa3b, v205
	v_exp_f32_e32 v210, v210
	v_exp_f32_e32 v211, v211
	v_exp_f32_e32 v212, v212
	v_exp_f32_e32 v213, v213
	v_add_f32_e32 v210, 1.0, v210
	v_add_f32_e32 v211, 1.0, v211
	v_add_f32_e32 v212, 1.0, v212
	v_add_f32_e32 v213, 1.0, v213
	v_rcp_f32_e32 v210, v210
	v_rcp_f32_e32 v211, v211
	v_rcp_f32_e32 v212, v212
	v_rcp_f32_e32 v213, v213
	v_mul_f32_e32 v202, v202, v210
	v_mul_f32_e32 v203, v203, v211
	v_mul_f32_e32 v204, v204, v212
	v_mul_f32_e32 v205, v205, v213
	v_mul_f32_e32 v202, v202, v206
	v_mul_f32_e32 v203, v203, v207
	v_mul_f32_e32 v204, v204, v208
	v_mul_f32_e32 v205, v205, v209
	v_cvt_pk_bf16_f32 v246, v202, v203
	v_cvt_pk_bf16_f32 v247, v204, v205
	v_fma_f32 v202, v124, v28, v132
	v_fma_f32 v203, v125, v29, v133
	v_fma_f32 v204, v126, v30, v134
	v_fma_f32 v205, v127, v31, v135
	v_fmac_f32_dpp v202, v28, v116 row_shr:1 row_mask:0xf bank_mask:0xf
	v_fmac_f32_dpp v203, v29, v117 row_shr:1 row_mask:0xf bank_mask:0xf
	v_fmac_f32_dpp v204, v30, v118 row_shr:1 row_mask:0xf bank_mask:0xf
	v_fmac_f32_dpp v205, v31, v119 row_shr:1 row_mask:0xf bank_mask:0xf
	v_fmac_f32_dpp v202, v44, v218 row_ror:1 row_mask:0xf bank_mask:0xf
	v_fmac_f32_dpp v203, v45, v219 row_ror:1 row_mask:0xf bank_mask:0xf
	v_fmac_f32_dpp v204, v46, v220 row_ror:1 row_mask:0xf bank_mask:0xf
	v_fmac_f32_dpp v205, v47, v221 row_ror:1 row_mask:0xf bank_mask:0xf
	v_fmac_f32_dpp v202, v28, v128 row_shl:1 row_mask:0xf bank_mask:0xf
	v_fmac_f32_dpp v203, v29, v129 row_shl:1 row_mask:0xf bank_mask:0xf
	v_fmac_f32_dpp v204, v30, v130 row_shl:1 row_mask:0xf bank_mask:0xf
	v_fmac_f32_dpp v205, v31, v131 row_shl:1 row_mask:0xf bank_mask:0xf
	v_fmac_f32_dpp v202, v12, v222 row_ror:15 row_mask:0xf bank_mask:0xf
	v_fmac_f32_dpp v203, v13, v223 row_ror:15 row_mask:0xf bank_mask:0xf
	v_fmac_f32_dpp v204, v14, v224 row_ror:15 row_mask:0xf bank_mask:0xf
	v_fmac_f32_dpp v205, v15, v225 row_ror:15 row_mask:0xf bank_mask:0xf
	v_fma_f32 v206, v164, v20, v182
	v_fma_f32 v207, v165, v21, v183
	v_fma_f32 v208, v166, v22, v184
	v_fma_f32 v209, v167, v23, v185
	v_fmac_f32_dpp v206, v20, v160 row_shr:1 row_mask:0xf bank_mask:0xf
	v_fmac_f32_dpp v207, v21, v161 row_shr:1 row_mask:0xf bank_mask:0xf
	v_fmac_f32_dpp v208, v22, v162 row_shr:1 row_mask:0xf bank_mask:0xf
	v_fmac_f32_dpp v209, v23, v163 row_shr:1 row_mask:0xf bank_mask:0xf
	v_fmac_f32_dpp v206, v36, v226 row_ror:1 row_mask:0xf bank_mask:0xf
	v_fmac_f32_dpp v207, v37, v227 row_ror:1 row_mask:0xf bank_mask:0xf
	v_fmac_f32_dpp v208, v38, v228 row_ror:1 row_mask:0xf bank_mask:0xf
	v_fmac_f32_dpp v209, v39, v229 row_ror:1 row_mask:0xf bank_mask:0xf
	v_fmac_f32_dpp v206, v20, v178 row_shl:1 row_mask:0xf bank_mask:0xf
	v_fmac_f32_dpp v207, v21, v179 row_shl:1 row_mask:0xf bank_mask:0xf
	v_fmac_f32_dpp v208, v22, v180 row_shl:1 row_mask:0xf bank_mask:0xf
	v_fmac_f32_dpp v209, v23, v181 row_shl:1 row_mask:0xf bank_mask:0xf
	v_fmac_f32_dpp v206, v4, v232 row_ror:15 row_mask:0xf bank_mask:0xf
	v_fmac_f32_dpp v207, v5, v233 row_ror:15 row_mask:0xf bank_mask:0xf
	v_fmac_f32_dpp v208, v6, v234 row_ror:15 row_mask:0xf bank_mask:0xf
	v_fmac_f32_dpp v209, v7, v235 row_ror:15 row_mask:0xf bank_mask:0xf
	v_mul_f32_e32 v210, 0xbfb8aa3b, v202
	v_mul_f32_e32 v211, 0xbfb8aa3b, v203
	v_mul_f32_e32 v212, 0xbfb8aa3b, v204
	v_mul_f32_e32 v213, 0xbfb8aa3b, v205
	v_exp_f32_e32 v210, v210
	v_exp_f32_e32 v211, v211
	v_exp_f32_e32 v212, v212
	v_exp_f32_e32 v213, v213
	v_add_f32_e32 v210, 1.0, v210
	v_add_f32_e32 v211, 1.0, v211
	v_add_f32_e32 v212, 1.0, v212
	v_add_f32_e32 v213, 1.0, v213
	v_rcp_f32_e32 v210, v210
	v_rcp_f32_e32 v211, v211
	v_rcp_f32_e32 v212, v212
	v_rcp_f32_e32 v213, v213
	v_mul_f32_e32 v202, v202, v210
	v_mul_f32_e32 v203, v203, v211
	v_mul_f32_e32 v204, v204, v212
	v_mul_f32_e32 v205, v205, v213
	v_mul_f32_e32 v202, v202, v206
	v_mul_f32_e32 v203, v203, v207
	v_mul_f32_e32 v204, v204, v208
	v_mul_f32_e32 v205, v205, v209
	v_cvt_pk_bf16_f32 v248, v202, v203
	v_cvt_pk_bf16_f32 v249, v204, v205
	v_fma_f32 v202, v124, v12, v132
	v_fma_f32 v203, v125, v13, v133
	v_fma_f32 v204, v126, v14, v134
	v_fma_f32 v205, v127, v15, v135
	v_fmac_f32_dpp v202, v12, v116 row_shr:1 row_mask:0xf bank_mask:0xf
	v_fmac_f32_dpp v203, v13, v117 row_shr:1 row_mask:0xf bank_mask:0xf
	v_fmac_f32_dpp v204, v14, v118 row_shr:1 row_mask:0xf bank_mask:0xf
	v_fmac_f32_dpp v205, v15, v119 row_shr:1 row_mask:0xf bank_mask:0xf
	v_fmac_f32_dpp v202, v28, v218 row_ror:1 row_mask:0xf bank_mask:0xf
	v_fmac_f32_dpp v203, v29, v219 row_ror:1 row_mask:0xf bank_mask:0xf
	v_fmac_f32_dpp v204, v30, v220 row_ror:1 row_mask:0xf bank_mask:0xf
	v_fmac_f32_dpp v205, v31, v221 row_ror:1 row_mask:0xf bank_mask:0xf
	v_fmac_f32_dpp v202, v12, v128 row_shl:1 row_mask:0xf bank_mask:0xf
	v_fmac_f32_dpp v203, v13, v129 row_shl:1 row_mask:0xf bank_mask:0xf
	v_fmac_f32_dpp v204, v14, v130 row_shl:1 row_mask:0xf bank_mask:0xf
	v_fmac_f32_dpp v205, v15, v131 row_shl:1 row_mask:0xf bank_mask:0xf
	v_fmac_f32_e32 v202, v194, v222
	v_fmac_f32_e32 v203, v195, v223
	v_fmac_f32_e32 v204, v196, v224
	v_fmac_f32_e32 v205, v197, v225
	v_fma_f32 v206, v164, v4, v182
	v_fma_f32 v207, v165, v5, v183
	v_fma_f32 v208, v166, v6, v184
	v_fma_f32 v209, v167, v7, v185
	v_fmac_f32_dpp v206, v4, v160 row_shr:1 row_mask:0xf bank_mask:0xf
	v_fmac_f32_dpp v207, v5, v161 row_shr:1 row_mask:0xf bank_mask:0xf
	v_fmac_f32_dpp v208, v6, v162 row_shr:1 row_mask:0xf bank_mask:0xf
	v_fmac_f32_dpp v209, v7, v163 row_shr:1 row_mask:0xf bank_mask:0xf
	v_fmac_f32_dpp v206, v20, v226 row_ror:1 row_mask:0xf bank_mask:0xf
	v_fmac_f32_dpp v207, v21, v227 row_ror:1 row_mask:0xf bank_mask:0xf
	v_fmac_f32_dpp v208, v22, v228 row_ror:1 row_mask:0xf bank_mask:0xf
	v_fmac_f32_dpp v209, v23, v229 row_ror:1 row_mask:0xf bank_mask:0xf
	v_fmac_f32_dpp v206, v4, v178 row_shl:1 row_mask:0xf bank_mask:0xf
	v_fmac_f32_dpp v207, v5, v179 row_shl:1 row_mask:0xf bank_mask:0xf
	v_fmac_f32_dpp v208, v6, v180 row_shl:1 row_mask:0xf bank_mask:0xf
	v_fmac_f32_dpp v209, v7, v181 row_shl:1 row_mask:0xf bank_mask:0xf
	v_fmac_f32_e32 v206, v198, v232
	v_fmac_f32_e32 v207, v199, v233
	v_fmac_f32_e32 v208, v200, v234
	v_fmac_f32_e32 v209, v201, v235
	v_mul_f32_e32 v210, 0xbfb8aa3b, v202
	v_mul_f32_e32 v211, 0xbfb8aa3b, v203
	v_mul_f32_e32 v212, 0xbfb8aa3b, v204
	v_mul_f32_e32 v213, 0xbfb8aa3b, v205
	v_exp_f32_e32 v210, v210
	v_exp_f32_e32 v211, v211
	v_exp_f32_e32 v212, v212
	v_exp_f32_e32 v213, v213
	v_add_f32_e32 v210, 1.0, v210
	v_add_f32_e32 v211, 1.0, v211
	v_add_f32_e32 v212, 1.0, v212
	v_add_f32_e32 v213, 1.0, v213
	v_rcp_f32_e32 v210, v210
	v_rcp_f32_e32 v211, v211
	v_rcp_f32_e32 v212, v212
	v_rcp_f32_e32 v213, v213
	v_mul_f32_e32 v202, v202, v210
	v_mul_f32_e32 v203, v203, v211
	v_mul_f32_e32 v204, v204, v212
	v_mul_f32_e32 v205, v205, v213
	v_mul_f32_e32 v202, v202, v206
	v_mul_f32_e32 v203, v203, v207
	v_mul_f32_e32 v204, v204, v208
	v_mul_f32_e32 v205, v205, v209
	v_cvt_pk_bf16_f32 v250, v202, v203
	v_cvt_pk_bf16_f32 v251, v204, v205
	global_load_dwordx4 v[116:119], v177, s[2:3] offset:16
	v_add_u32_e32 v213, 0x5800, v177
	global_load_dwordx4 v[124:127], v213, s[2:3] offset:16
	v_add_u32_e32 v212, 0xb000, v177
	global_load_dwordx4 v[128:131], v212, s[2:3] offset:16
	global_load_dwordx4 v[132:135], v177, s[28:29] offset:16
	v_add_u32_e32 v212, 0x2c00, v177
	global_load_dwordx4 v[160:163], v212, s[2:3] offset:16
	v_add_u32_e32 v213, 0x8400, v177
	global_load_dwordx4 v[164:167], v213, s[2:3] offset:16
	v_add_u32_e32 v212, 0xdc00, v177
	global_load_dwordx4 v[178:181], v212, s[2:3] offset:16
	v_add_u32_e32 v213, 0x2c00, v177
	global_load_dwordx4 v[182:185], v213, s[28:29] offset:16
	v_mov_b32_e32 v140, v236
	v_mov_b32_e32 v141, v237
	v_mov_b32_e32 v108, v238
	v_mov_b32_e32 v109, v239
	v_mov_b32_e32 v92, v240
	v_mov_b32_e32 v93, v241
	v_mov_b32_e32 v76, v242
	v_mov_b32_e32 v77, v243
	v_mov_b32_e32 v60, v244
	v_mov_b32_e32 v61, v245
	v_mov_b32_e32 v44, v246
	v_mov_b32_e32 v45, v247
	v_mov_b32_e32 v28, v248
	v_mov_b32_e32 v29, v249
	v_mov_b32_e32 v12, v250
	v_mov_b32_e32 v13, v251
	ds_read_b128 v[186:189], v231 offset:16
	ds_read_b128 v[190:193], v231 offset:528
	ds_read_b128 v[194:197], v231 offset:2064
	ds_read_b128 v[198:201], v231 offset:2576
	s_waitcnt vmcnt(0)
	v_cndmask_b32_e64 v218, 0, v116, s[78:79]
	v_cndmask_b32_e64 v222, 0, v128, s[80:81]
	v_cndmask_b32_e64 v219, 0, v117, s[78:79]
	v_cndmask_b32_e64 v223, 0, v129, s[80:81]
	v_cndmask_b32_e64 v220, 0, v118, s[78:79]
	v_cndmask_b32_e64 v224, 0, v130, s[80:81]
	v_cndmask_b32_e64 v221, 0, v119, s[78:79]
	v_cndmask_b32_e64 v225, 0, v131, s[80:81]
	v_cndmask_b32_e64 v226, 0, v160, s[78:79]
	v_cndmask_b32_e64 v232, 0, v178, s[80:81]
	v_cndmask_b32_e64 v227, 0, v161, s[78:79]
	v_cndmask_b32_e64 v233, 0, v179, s[80:81]
	v_cndmask_b32_e64 v228, 0, v162, s[78:79]
	v_cndmask_b32_e64 v234, 0, v180, s[80:81]
	v_cndmask_b32_e64 v229, 0, v163, s[78:79]
	v_cndmask_b32_e64 v235, 0, v181, s[80:81]
	s_waitcnt lgkmcnt(0)
	s_nop 1
	v_fma_f32 v202, v124, v136, v132
	v_fma_f32 v203, v125, v137, v133
	v_fma_f32 v204, v126, v138, v134
	v_fma_f32 v205, v127, v139, v135
	v_fmac_f32_dpp v202, v136, v116 row_shr:1 row_mask:0xf bank_mask:0xf
	v_fmac_f32_dpp v203, v137, v117 row_shr:1 row_mask:0xf bank_mask:0xf
	v_fmac_f32_dpp v204, v138, v118 row_shr:1 row_mask:0xf bank_mask:0xf
	v_fmac_f32_dpp v205, v139, v119 row_shr:1 row_mask:0xf bank_mask:0xf
	v_fmac_f32_e32 v202, v186, v218
	v_fmac_f32_e32 v203, v187, v219
	v_fmac_f32_e32 v204, v188, v220
	v_fmac_f32_e32 v205, v189, v221
	v_fmac_f32_dpp v202, v136, v128 row_shl:1 row_mask:0xf bank_mask:0xf
	v_fmac_f32_dpp v203, v137, v129 row_shl:1 row_mask:0xf bank_mask:0xf
	v_fmac_f32_dpp v204, v138, v130 row_shl:1 row_mask:0xf bank_mask:0xf
	v_fmac_f32_dpp v205, v139, v131 row_shl:1 row_mask:0xf bank_mask:0xf
	v_fmac_f32_dpp v202, v104, v222 row_ror:15 row_mask:0xf bank_mask:0xf
	v_fmac_f32_dpp v203, v105, v223 row_ror:15 row_mask:0xf bank_mask:0xf
	v_fmac_f32_dpp v204, v106, v224 row_ror:15 row_mask:0xf bank_mask:0xf
	v_fmac_f32_dpp v205, v107, v225 row_ror:15 row_mask:0xf bank_mask:0xf
	v_fma_f32 v206, v164, v112, v182
	v_fma_f32 v207, v165, v113, v183
	v_fma_f32 v208, v166, v114, v184
	v_fma_f32 v209, v167, v115, v185
	v_fmac_f32_dpp v206, v112, v160 row_shr:1 row_mask:0xf bank_mask:0xf
	v_fmac_f32_dpp v207, v113, v161 row_shr:1 row_mask:0xf bank_mask:0xf
	v_fmac_f32_dpp v208, v114, v162 row_shr:1 row_mask:0xf bank_mask:0xf
	v_fmac_f32_dpp v209, v115, v163 row_shr:1 row_mask:0xf bank_mask:0xf
	v_fmac_f32_e32 v206, v190, v226
	v_fmac_f32_e32 v207, v191, v227
	v_fmac_f32_e32 v208, v192, v228
	v_fmac_f32_e32 v209, v193, v229
	v_fmac_f32_dpp v206, v112, v178 row_shl:1 row_mask:0xf bank_mask:0xf
	v_fmac_f32_dpp v207, v113, v179 row_shl:1 row_mask:0xf bank_mask:0xf
	v_fmac_f32_dpp v208, v114, v180 row_shl:1 row_mask:0xf bank_mask:0xf
	v_fmac_f32_dpp v209, v115, v181 row_shl:1 row_mask:0xf bank_mask:0xf
	v_fmac_f32_dpp v206, v96, v232 row_ror:15 row_mask:0xf bank_mask:0xf
	v_fmac_f32_dpp v207, v97, v233 row_ror:15 row_mask:0xf bank_mask:0xf
	v_fmac_f32_dpp v208, v98, v234 row_ror:15 row_mask:0xf bank_mask:0xf
	v_fmac_f32_dpp v209, v99, v235 row_ror:15 row_mask:0xf bank_mask:0xf
	v_mul_f32_e32 v210, 0xbfb8aa3b, v202
	v_mul_f32_e32 v211, 0xbfb8aa3b, v203
	v_mul_f32_e32 v212, 0xbfb8aa3b, v204
	v_mul_f32_e32 v213, 0xbfb8aa3b, v205
	v_exp_f32_e32 v210, v210
	v_exp_f32_e32 v211, v211
	v_exp_f32_e32 v212, v212
	v_exp_f32_e32 v213, v213
	v_add_f32_e32 v210, 1.0, v210
	v_add_f32_e32 v211, 1.0, v211
	v_add_f32_e32 v212, 1.0, v212
	v_add_f32_e32 v213, 1.0, v213
	v_rcp_f32_e32 v210, v210
	v_rcp_f32_e32 v211, v211
	v_rcp_f32_e32 v212, v212
	v_rcp_f32_e32 v213, v213
	v_mul_f32_e32 v202, v202, v210
	v_mul_f32_e32 v203, v203, v211
	v_mul_f32_e32 v204, v204, v212
	v_mul_f32_e32 v205, v205, v213
	v_mul_f32_e32 v202, v202, v206
	v_mul_f32_e32 v203, v203, v207
	v_mul_f32_e32 v204, v204, v208
	v_mul_f32_e32 v205, v205, v209
	v_cvt_pk_bf16_f32 v142, v202, v203
	v_cvt_pk_bf16_f32 v143, v204, v205
	v_fma_f32 v202, v124, v104, v132
	v_fma_f32 v203, v125, v105, v133
	v_fma_f32 v204, v126, v106, v134
	v_fma_f32 v205, v127, v107, v135
	v_fmac_f32_dpp v202, v104, v116 row_shr:1 row_mask:0xf bank_mask:0xf
	v_fmac_f32_dpp v203, v105, v117 row_shr:1 row_mask:0xf bank_mask:0xf
	v_fmac_f32_dpp v204, v106, v118 row_shr:1 row_mask:0xf bank_mask:0xf
	v_fmac_f32_dpp v205, v107, v119 row_shr:1 row_mask:0xf bank_mask:0xf
	v_fmac_f32_dpp v202, v136, v218 row_ror:1 row_mask:0xf bank_mask:0xf
	v_fmac_f32_dpp v203, v137, v219 row_ror:1 row_mask:0xf bank_mask:0xf
	v_fmac_f32_dpp v204, v138, v220 row_ror:1 row_mask:0xf bank_mask:0xf
	v_fmac_f32_dpp v205, v139, v221 row_ror:1 row_mask:0xf bank_mask:0xf
	v_fmac_f32_dpp v202, v104, v128 row_shl:1 row_mask:0xf bank_mask:0xf
	v_fmac_f32_dpp v203, v105, v129 row_shl:1 row_mask:0xf bank_mask:0xf
	v_fmac_f32_dpp v204, v106, v130 row_shl:1 row_mask:0xf bank_mask:0xf
	v_fmac_f32_dpp v205, v107, v131 row_shl:1 row_mask:0xf bank_mask:0xf
	v_fmac_f32_dpp v202, v88, v222 row_ror:15 row_mask:0xf bank_mask:0xf
	v_fmac_f32_dpp v203, v89, v223 row_ror:15 row_mask:0xf bank_mask:0xf
	v_fmac_f32_dpp v204, v90, v224 row_ror:15 row_mask:0xf bank_mask:0xf
	v_fmac_f32_dpp v205, v91, v225 row_ror:15 row_mask:0xf bank_mask:0xf
	v_fma_f32 v206, v164, v96, v182
	v_fma_f32 v207, v165, v97, v183
	v_fma_f32 v208, v166, v98, v184
	v_fma_f32 v209, v167, v99, v185
	v_fmac_f32_dpp v206, v96, v160 row_shr:1 row_mask:0xf bank_mask:0xf
	v_fmac_f32_dpp v207, v97, v161 row_shr:1 row_mask:0xf bank_mask:0xf
	v_fmac_f32_dpp v208, v98, v162 row_shr:1 row_mask:0xf bank_mask:0xf
	v_fmac_f32_dpp v209, v99, v163 row_shr:1 row_mask:0xf bank_mask:0xf
	v_fmac_f32_dpp v206, v112, v226 row_ror:1 row_mask:0xf bank_mask:0xf
	v_fmac_f32_dpp v207, v113, v227 row_ror:1 row_mask:0xf bank_mask:0xf
	v_fmac_f32_dpp v208, v114, v228 row_ror:1 row_mask:0xf bank_mask:0xf
	v_fmac_f32_dpp v209, v115, v229 row_ror:1 row_mask:0xf bank_mask:0xf
	v_fmac_f32_dpp v206, v96, v178 row_shl:1 row_mask:0xf bank_mask:0xf
	v_fmac_f32_dpp v207, v97, v179 row_shl:1 row_mask:0xf bank_mask:0xf
	v_fmac_f32_dpp v208, v98, v180 row_shl:1 row_mask:0xf bank_mask:0xf
	v_fmac_f32_dpp v209, v99, v181 row_shl:1 row_mask:0xf bank_mask:0xf
	v_fmac_f32_dpp v206, v80, v232 row_ror:15 row_mask:0xf bank_mask:0xf
	v_fmac_f32_dpp v207, v81, v233 row_ror:15 row_mask:0xf bank_mask:0xf
	v_fmac_f32_dpp v208, v82, v234 row_ror:15 row_mask:0xf bank_mask:0xf
	v_fmac_f32_dpp v209, v83, v235 row_ror:15 row_mask:0xf bank_mask:0xf
	v_mul_f32_e32 v210, 0xbfb8aa3b, v202
	v_mul_f32_e32 v211, 0xbfb8aa3b, v203
	v_mul_f32_e32 v212, 0xbfb8aa3b, v204
	v_mul_f32_e32 v213, 0xbfb8aa3b, v205
	v_exp_f32_e32 v210, v210
	v_exp_f32_e32 v211, v211
	v_exp_f32_e32 v212, v212
	v_exp_f32_e32 v213, v213
	v_add_f32_e32 v210, 1.0, v210
	v_add_f32_e32 v211, 1.0, v211
	v_add_f32_e32 v212, 1.0, v212
	v_add_f32_e32 v213, 1.0, v213
	v_rcp_f32_e32 v210, v210
	v_rcp_f32_e32 v211, v211
	v_rcp_f32_e32 v212, v212
	v_rcp_f32_e32 v213, v213
	v_mul_f32_e32 v202, v202, v210
	v_mul_f32_e32 v203, v203, v211
	v_mul_f32_e32 v204, v204, v212
	v_mul_f32_e32 v205, v205, v213
	v_mul_f32_e32 v202, v202, v206
	v_mul_f32_e32 v203, v203, v207
	v_mul_f32_e32 v204, v204, v208
	v_mul_f32_e32 v205, v205, v209
	v_cvt_pk_bf16_f32 v110, v202, v203
	v_cvt_pk_bf16_f32 v111, v204, v205
	v_fma_f32 v202, v124, v88, v132
	v_fma_f32 v203, v125, v89, v133
	v_fma_f32 v204, v126, v90, v134
	v_fma_f32 v205, v127, v91, v135
	v_fmac_f32_dpp v202, v88, v116 row_shr:1 row_mask:0xf bank_mask:0xf
	v_fmac_f32_dpp v203, v89, v117 row_shr:1 row_mask:0xf bank_mask:0xf
	v_fmac_f32_dpp v204, v90, v118 row_shr:1 row_mask:0xf bank_mask:0xf
	v_fmac_f32_dpp v205, v91, v119 row_shr:1 row_mask:0xf bank_mask:0xf
	v_fmac_f32_dpp v202, v104, v218 row_ror:1 row_mask:0xf bank_mask:0xf
	v_fmac_f32_dpp v203, v105, v219 row_ror:1 row_mask:0xf bank_mask:0xf
	v_fmac_f32_dpp v204, v106, v220 row_ror:1 row_mask:0xf bank_mask:0xf
	v_fmac_f32_dpp v205, v107, v221 row_ror:1 row_mask:0xf bank_mask:0xf
	v_fmac_f32_dpp v202, v88, v128 row_shl:1 row_mask:0xf bank_mask:0xf
	v_fmac_f32_dpp v203, v89, v129 row_shl:1 row_mask:0xf bank_mask:0xf
	v_fmac_f32_dpp v204, v90, v130 row_shl:1 row_mask:0xf bank_mask:0xf
	v_fmac_f32_dpp v205, v91, v131 row_shl:1 row_mask:0xf bank_mask:0xf
	v_fmac_f32_dpp v202, v72, v222 row_ror:15 row_mask:0xf bank_mask:0xf
	v_fmac_f32_dpp v203, v73, v223 row_ror:15 row_mask:0xf bank_mask:0xf
	v_fmac_f32_dpp v204, v74, v224 row_ror:15 row_mask:0xf bank_mask:0xf
	v_fmac_f32_dpp v205, v75, v225 row_ror:15 row_mask:0xf bank_mask:0xf
	v_fma_f32 v206, v164, v80, v182
	v_fma_f32 v207, v165, v81, v183
	v_fma_f32 v208, v166, v82, v184
	v_fma_f32 v209, v167, v83, v185
	v_fmac_f32_dpp v206, v80, v160 row_shr:1 row_mask:0xf bank_mask:0xf
	v_fmac_f32_dpp v207, v81, v161 row_shr:1 row_mask:0xf bank_mask:0xf
	v_fmac_f32_dpp v208, v82, v162 row_shr:1 row_mask:0xf bank_mask:0xf
	v_fmac_f32_dpp v209, v83, v163 row_shr:1 row_mask:0xf bank_mask:0xf
	v_fmac_f32_dpp v206, v96, v226 row_ror:1 row_mask:0xf bank_mask:0xf
	v_fmac_f32_dpp v207, v97, v227 row_ror:1 row_mask:0xf bank_mask:0xf
	v_fmac_f32_dpp v208, v98, v228 row_ror:1 row_mask:0xf bank_mask:0xf
	v_fmac_f32_dpp v209, v99, v229 row_ror:1 row_mask:0xf bank_mask:0xf
	v_fmac_f32_dpp v206, v80, v178 row_shl:1 row_mask:0xf bank_mask:0xf
	v_fmac_f32_dpp v207, v81, v179 row_shl:1 row_mask:0xf bank_mask:0xf
	v_fmac_f32_dpp v208, v82, v180 row_shl:1 row_mask:0xf bank_mask:0xf
	v_fmac_f32_dpp v209, v83, v181 row_shl:1 row_mask:0xf bank_mask:0xf
	v_fmac_f32_dpp v206, v64, v232 row_ror:15 row_mask:0xf bank_mask:0xf
	v_fmac_f32_dpp v207, v65, v233 row_ror:15 row_mask:0xf bank_mask:0xf
	v_fmac_f32_dpp v208, v66, v234 row_ror:15 row_mask:0xf bank_mask:0xf
	v_fmac_f32_dpp v209, v67, v235 row_ror:15 row_mask:0xf bank_mask:0xf
	v_mul_f32_e32 v210, 0xbfb8aa3b, v202
	v_mul_f32_e32 v211, 0xbfb8aa3b, v203
	v_mul_f32_e32 v212, 0xbfb8aa3b, v204
	v_mul_f32_e32 v213, 0xbfb8aa3b, v205
	v_exp_f32_e32 v210, v210
	v_exp_f32_e32 v211, v211
	v_exp_f32_e32 v212, v212
	v_exp_f32_e32 v213, v213
	v_add_f32_e32 v210, 1.0, v210
	v_add_f32_e32 v211, 1.0, v211
	v_add_f32_e32 v212, 1.0, v212
	v_add_f32_e32 v213, 1.0, v213
	v_rcp_f32_e32 v210, v210
	v_rcp_f32_e32 v211, v211
	v_rcp_f32_e32 v212, v212
	v_rcp_f32_e32 v213, v213
	v_mul_f32_e32 v202, v202, v210
	v_mul_f32_e32 v203, v203, v211
	v_mul_f32_e32 v204, v204, v212
	v_mul_f32_e32 v205, v205, v213
	v_mul_f32_e32 v202, v202, v206
	v_mul_f32_e32 v203, v203, v207
	v_mul_f32_e32 v204, v204, v208
	v_mul_f32_e32 v205, v205, v209
	v_cvt_pk_bf16_f32 v94, v202, v203
	v_cvt_pk_bf16_f32 v95, v204, v205
	v_fma_f32 v202, v124, v72, v132
	v_fma_f32 v203, v125, v73, v133
	v_fma_f32 v204, v126, v74, v134
	v_fma_f32 v205, v127, v75, v135
	v_fmac_f32_dpp v202, v72, v116 row_shr:1 row_mask:0xf bank_mask:0xf
	v_fmac_f32_dpp v203, v73, v117 row_shr:1 row_mask:0xf bank_mask:0xf
	v_fmac_f32_dpp v204, v74, v118 row_shr:1 row_mask:0xf bank_mask:0xf
	v_fmac_f32_dpp v205, v75, v119 row_shr:1 row_mask:0xf bank_mask:0xf
	v_fmac_f32_dpp v202, v88, v218 row_ror:1 row_mask:0xf bank_mask:0xf
	v_fmac_f32_dpp v203, v89, v219 row_ror:1 row_mask:0xf bank_mask:0xf
	v_fmac_f32_dpp v204, v90, v220 row_ror:1 row_mask:0xf bank_mask:0xf
	v_fmac_f32_dpp v205, v91, v221 row_ror:1 row_mask:0xf bank_mask:0xf
	v_fmac_f32_dpp v202, v72, v128 row_shl:1 row_mask:0xf bank_mask:0xf
	v_fmac_f32_dpp v203, v73, v129 row_shl:1 row_mask:0xf bank_mask:0xf
	v_fmac_f32_dpp v204, v74, v130 row_shl:1 row_mask:0xf bank_mask:0xf
	v_fmac_f32_dpp v205, v75, v131 row_shl:1 row_mask:0xf bank_mask:0xf
	v_fmac_f32_e32 v202, v186, v222
	v_fmac_f32_e32 v203, v187, v223
	v_fmac_f32_e32 v204, v188, v224
	v_fmac_f32_e32 v205, v189, v225
	v_fma_f32 v206, v164, v64, v182
	v_fma_f32 v207, v165, v65, v183
	v_fma_f32 v208, v166, v66, v184
	v_fma_f32 v209, v167, v67, v185
	v_fmac_f32_dpp v206, v64, v160 row_shr:1 row_mask:0xf bank_mask:0xf
	v_fmac_f32_dpp v207, v65, v161 row_shr:1 row_mask:0xf bank_mask:0xf
	v_fmac_f32_dpp v208, v66, v162 row_shr:1 row_mask:0xf bank_mask:0xf
	v_fmac_f32_dpp v209, v67, v163 row_shr:1 row_mask:0xf bank_mask:0xf
	v_fmac_f32_dpp v206, v80, v226 row_ror:1 row_mask:0xf bank_mask:0xf
	v_fmac_f32_dpp v207, v81, v227 row_ror:1 row_mask:0xf bank_mask:0xf
	v_fmac_f32_dpp v208, v82, v228 row_ror:1 row_mask:0xf bank_mask:0xf
	v_fmac_f32_dpp v209, v83, v229 row_ror:1 row_mask:0xf bank_mask:0xf
	v_fmac_f32_dpp v206, v64, v178 row_shl:1 row_mask:0xf bank_mask:0xf
	v_fmac_f32_dpp v207, v65, v179 row_shl:1 row_mask:0xf bank_mask:0xf
	v_fmac_f32_dpp v208, v66, v180 row_shl:1 row_mask:0xf bank_mask:0xf
	v_fmac_f32_dpp v209, v67, v181 row_shl:1 row_mask:0xf bank_mask:0xf
	v_fmac_f32_e32 v206, v190, v232
	v_fmac_f32_e32 v207, v191, v233
	v_fmac_f32_e32 v208, v192, v234
	v_fmac_f32_e32 v209, v193, v235
	v_mul_f32_e32 v210, 0xbfb8aa3b, v202
	v_mul_f32_e32 v211, 0xbfb8aa3b, v203
	v_mul_f32_e32 v212, 0xbfb8aa3b, v204
	v_mul_f32_e32 v213, 0xbfb8aa3b, v205
	v_exp_f32_e32 v210, v210
	v_exp_f32_e32 v211, v211
	v_exp_f32_e32 v212, v212
	v_exp_f32_e32 v213, v213
	v_add_f32_e32 v210, 1.0, v210
	v_add_f32_e32 v211, 1.0, v211
	v_add_f32_e32 v212, 1.0, v212
	v_add_f32_e32 v213, 1.0, v213
	v_rcp_f32_e32 v210, v210
	v_rcp_f32_e32 v211, v211
	v_rcp_f32_e32 v212, v212
	v_rcp_f32_e32 v213, v213
	v_mul_f32_e32 v202, v202, v210
	v_mul_f32_e32 v203, v203, v211
	v_mul_f32_e32 v204, v204, v212
	v_mul_f32_e32 v205, v205, v213
	v_mul_f32_e32 v202, v202, v206
	v_mul_f32_e32 v203, v203, v207
	v_mul_f32_e32 v204, v204, v208
	v_mul_f32_e32 v205, v205, v209
	v_cvt_pk_bf16_f32 v78, v202, v203
	v_cvt_pk_bf16_f32 v79, v204, v205
	v_fma_f32 v202, v124, v56, v132
	v_fma_f32 v203, v125, v57, v133
	v_fma_f32 v204, v126, v58, v134
	v_fma_f32 v205, v127, v59, v135
	v_fmac_f32_dpp v202, v56, v116 row_shr:1 row_mask:0xf bank_mask:0xf
	v_fmac_f32_dpp v203, v57, v117 row_shr:1 row_mask:0xf bank_mask:0xf
	v_fmac_f32_dpp v204, v58, v118 row_shr:1 row_mask:0xf bank_mask:0xf
	v_fmac_f32_dpp v205, v59, v119 row_shr:1 row_mask:0xf bank_mask:0xf
	v_fmac_f32_e32 v202, v194, v218
	v_fmac_f32_e32 v203, v195, v219
	v_fmac_f32_e32 v204, v196, v220
	v_fmac_f32_e32 v205, v197, v221
	v_fmac_f32_dpp v202, v56, v128 row_shl:1 row_mask:0xf bank_mask:0xf
	v_fmac_f32_dpp v203, v57, v129 row_shl:1 row_mask:0xf bank_mask:0xf
	v_fmac_f32_dpp v204, v58, v130 row_shl:1 row_mask:0xf bank_mask:0xf
	v_fmac_f32_dpp v205, v59, v131 row_shl:1 row_mask:0xf bank_mask:0xf
	v_fmac_f32_dpp v202, v40, v222 row_ror:15 row_mask:0xf bank_mask:0xf
	v_fmac_f32_dpp v203, v41, v223 row_ror:15 row_mask:0xf bank_mask:0xf
	v_fmac_f32_dpp v204, v42, v224 row_ror:15 row_mask:0xf bank_mask:0xf
	v_fmac_f32_dpp v205, v43, v225 row_ror:15 row_mask:0xf bank_mask:0xf
	v_fma_f32 v206, v164, v48, v182
	v_fma_f32 v207, v165, v49, v183
	v_fma_f32 v208, v166, v50, v184
	v_fma_f32 v209, v167, v51, v185
	v_fmac_f32_dpp v206, v48, v160 row_shr:1 row_mask:0xf bank_mask:0xf
	v_fmac_f32_dpp v207, v49, v161 row_shr:1 row_mask:0xf bank_mask:0xf
	v_fmac_f32_dpp v208, v50, v162 row_shr:1 row_mask:0xf bank_mask:0xf
	v_fmac_f32_dpp v209, v51, v163 row_shr:1 row_mask:0xf bank_mask:0xf
	v_fmac_f32_e32 v206, v198, v226
	v_fmac_f32_e32 v207, v199, v227
	v_fmac_f32_e32 v208, v200, v228
	v_fmac_f32_e32 v209, v201, v229
	v_fmac_f32_dpp v206, v48, v178 row_shl:1 row_mask:0xf bank_mask:0xf
	v_fmac_f32_dpp v207, v49, v179 row_shl:1 row_mask:0xf bank_mask:0xf
	v_fmac_f32_dpp v208, v50, v180 row_shl:1 row_mask:0xf bank_mask:0xf
	v_fmac_f32_dpp v209, v51, v181 row_shl:1 row_mask:0xf bank_mask:0xf
	v_fmac_f32_dpp v206, v32, v232 row_ror:15 row_mask:0xf bank_mask:0xf
	v_fmac_f32_dpp v207, v33, v233 row_ror:15 row_mask:0xf bank_mask:0xf
	v_fmac_f32_dpp v208, v34, v234 row_ror:15 row_mask:0xf bank_mask:0xf
	v_fmac_f32_dpp v209, v35, v235 row_ror:15 row_mask:0xf bank_mask:0xf
	v_mul_f32_e32 v210, 0xbfb8aa3b, v202
	v_mul_f32_e32 v211, 0xbfb8aa3b, v203
	v_mul_f32_e32 v212, 0xbfb8aa3b, v204
	v_mul_f32_e32 v213, 0xbfb8aa3b, v205
	v_exp_f32_e32 v210, v210
	v_exp_f32_e32 v211, v211
	v_exp_f32_e32 v212, v212
	v_exp_f32_e32 v213, v213
	v_add_f32_e32 v210, 1.0, v210
	v_add_f32_e32 v211, 1.0, v211
	v_add_f32_e32 v212, 1.0, v212
	v_add_f32_e32 v213, 1.0, v213
	v_rcp_f32_e32 v210, v210
	v_rcp_f32_e32 v211, v211
	v_rcp_f32_e32 v212, v212
	v_rcp_f32_e32 v213, v213
	v_mul_f32_e32 v202, v202, v210
	v_mul_f32_e32 v203, v203, v211
	v_mul_f32_e32 v204, v204, v212
	v_mul_f32_e32 v205, v205, v213
	v_mul_f32_e32 v202, v202, v206
	v_mul_f32_e32 v203, v203, v207
	v_mul_f32_e32 v204, v204, v208
	v_mul_f32_e32 v205, v205, v209
	v_cvt_pk_bf16_f32 v62, v202, v203
	v_cvt_pk_bf16_f32 v63, v204, v205
	v_fma_f32 v202, v124, v40, v132
	v_fma_f32 v203, v125, v41, v133
	v_fma_f32 v204, v126, v42, v134
	v_fma_f32 v205, v127, v43, v135
	v_fmac_f32_dpp v202, v40, v116 row_shr:1 row_mask:0xf bank_mask:0xf
	v_fmac_f32_dpp v203, v41, v117 row_shr:1 row_mask:0xf bank_mask:0xf
	v_fmac_f32_dpp v204, v42, v118 row_shr:1 row_mask:0xf bank_mask:0xf
	v_fmac_f32_dpp v205, v43, v119 row_shr:1 row_mask:0xf bank_mask:0xf
	v_fmac_f32_dpp v202, v56, v218 row_ror:1 row_mask:0xf bank_mask:0xf
	v_fmac_f32_dpp v203, v57, v219 row_ror:1 row_mask:0xf bank_mask:0xf
	v_fmac_f32_dpp v204, v58, v220 row_ror:1 row_mask:0xf bank_mask:0xf
	v_fmac_f32_dpp v205, v59, v221 row_ror:1 row_mask:0xf bank_mask:0xf
	v_fmac_f32_dpp v202, v40, v128 row_shl:1 row_mask:0xf bank_mask:0xf
	v_fmac_f32_dpp v203, v41, v129 row_shl:1 row_mask:0xf bank_mask:0xf
	v_fmac_f32_dpp v204, v42, v130 row_shl:1 row_mask:0xf bank_mask:0xf
	v_fmac_f32_dpp v205, v43, v131 row_shl:1 row_mask:0xf bank_mask:0xf
	v_fmac_f32_dpp v202, v24, v222 row_ror:15 row_mask:0xf bank_mask:0xf
	v_fmac_f32_dpp v203, v25, v223 row_ror:15 row_mask:0xf bank_mask:0xf
	v_fmac_f32_dpp v204, v26, v224 row_ror:15 row_mask:0xf bank_mask:0xf
	v_fmac_f32_dpp v205, v27, v225 row_ror:15 row_mask:0xf bank_mask:0xf
	v_fma_f32 v206, v164, v32, v182
	v_fma_f32 v207, v165, v33, v183
	v_fma_f32 v208, v166, v34, v184
	v_fma_f32 v209, v167, v35, v185
	v_fmac_f32_dpp v206, v32, v160 row_shr:1 row_mask:0xf bank_mask:0xf
	v_fmac_f32_dpp v207, v33, v161 row_shr:1 row_mask:0xf bank_mask:0xf
	v_fmac_f32_dpp v208, v34, v162 row_shr:1 row_mask:0xf bank_mask:0xf
	v_fmac_f32_dpp v209, v35, v163 row_shr:1 row_mask:0xf bank_mask:0xf
	v_fmac_f32_dpp v206, v48, v226 row_ror:1 row_mask:0xf bank_mask:0xf
	v_fmac_f32_dpp v207, v49, v227 row_ror:1 row_mask:0xf bank_mask:0xf
	v_fmac_f32_dpp v208, v50, v228 row_ror:1 row_mask:0xf bank_mask:0xf
	v_fmac_f32_dpp v209, v51, v229 row_ror:1 row_mask:0xf bank_mask:0xf
	v_fmac_f32_dpp v206, v32, v178 row_shl:1 row_mask:0xf bank_mask:0xf
	v_fmac_f32_dpp v207, v33, v179 row_shl:1 row_mask:0xf bank_mask:0xf
	v_fmac_f32_dpp v208, v34, v180 row_shl:1 row_mask:0xf bank_mask:0xf
	v_fmac_f32_dpp v209, v35, v181 row_shl:1 row_mask:0xf bank_mask:0xf
	v_fmac_f32_dpp v206, v16, v232 row_ror:15 row_mask:0xf bank_mask:0xf
	v_fmac_f32_dpp v207, v17, v233 row_ror:15 row_mask:0xf bank_mask:0xf
	v_fmac_f32_dpp v208, v18, v234 row_ror:15 row_mask:0xf bank_mask:0xf
	v_fmac_f32_dpp v209, v19, v235 row_ror:15 row_mask:0xf bank_mask:0xf
	v_mul_f32_e32 v210, 0xbfb8aa3b, v202
	v_mul_f32_e32 v211, 0xbfb8aa3b, v203
	v_mul_f32_e32 v212, 0xbfb8aa3b, v204
	v_mul_f32_e32 v213, 0xbfb8aa3b, v205
	v_exp_f32_e32 v210, v210
	v_exp_f32_e32 v211, v211
	v_exp_f32_e32 v212, v212
	v_exp_f32_e32 v213, v213
	v_add_f32_e32 v210, 1.0, v210
	v_add_f32_e32 v211, 1.0, v211
	v_add_f32_e32 v212, 1.0, v212
	v_add_f32_e32 v213, 1.0, v213
	v_rcp_f32_e32 v210, v210
	v_rcp_f32_e32 v211, v211
	v_rcp_f32_e32 v212, v212
	v_rcp_f32_e32 v213, v213
	v_mul_f32_e32 v202, v202, v210
	v_mul_f32_e32 v203, v203, v211
	v_mul_f32_e32 v204, v204, v212
	v_mul_f32_e32 v205, v205, v213
	v_mul_f32_e32 v202, v202, v206
	v_mul_f32_e32 v203, v203, v207
	v_mul_f32_e32 v204, v204, v208
	v_mul_f32_e32 v205, v205, v209
	v_cvt_pk_bf16_f32 v46, v202, v203
	v_cvt_pk_bf16_f32 v47, v204, v205
	v_fma_f32 v202, v124, v24, v132
	v_fma_f32 v203, v125, v25, v133
	v_fma_f32 v204, v126, v26, v134
	v_fma_f32 v205, v127, v27, v135
	v_fmac_f32_dpp v202, v24, v116 row_shr:1 row_mask:0xf bank_mask:0xf
	v_fmac_f32_dpp v203, v25, v117 row_shr:1 row_mask:0xf bank_mask:0xf
	v_fmac_f32_dpp v204, v26, v118 row_shr:1 row_mask:0xf bank_mask:0xf
	v_fmac_f32_dpp v205, v27, v119 row_shr:1 row_mask:0xf bank_mask:0xf
	v_fmac_f32_dpp v202, v40, v218 row_ror:1 row_mask:0xf bank_mask:0xf
	v_fmac_f32_dpp v203, v41, v219 row_ror:1 row_mask:0xf bank_mask:0xf
	v_fmac_f32_dpp v204, v42, v220 row_ror:1 row_mask:0xf bank_mask:0xf
	v_fmac_f32_dpp v205, v43, v221 row_ror:1 row_mask:0xf bank_mask:0xf
	v_fmac_f32_dpp v202, v24, v128 row_shl:1 row_mask:0xf bank_mask:0xf
	v_fmac_f32_dpp v203, v25, v129 row_shl:1 row_mask:0xf bank_mask:0xf
	v_fmac_f32_dpp v204, v26, v130 row_shl:1 row_mask:0xf bank_mask:0xf
	v_fmac_f32_dpp v205, v27, v131 row_shl:1 row_mask:0xf bank_mask:0xf
	v_fmac_f32_dpp v202, v8, v222 row_ror:15 row_mask:0xf bank_mask:0xf
	v_fmac_f32_dpp v203, v9, v223 row_ror:15 row_mask:0xf bank_mask:0xf
	v_fmac_f32_dpp v204, v10, v224 row_ror:15 row_mask:0xf bank_mask:0xf
	v_fmac_f32_dpp v205, v11, v225 row_ror:15 row_mask:0xf bank_mask:0xf
	v_fma_f32 v206, v164, v16, v182
	v_fma_f32 v207, v165, v17, v183
	v_fma_f32 v208, v166, v18, v184
	v_fma_f32 v209, v167, v19, v185
	v_fmac_f32_dpp v206, v16, v160 row_shr:1 row_mask:0xf bank_mask:0xf
	v_fmac_f32_dpp v207, v17, v161 row_shr:1 row_mask:0xf bank_mask:0xf
	v_fmac_f32_dpp v208, v18, v162 row_shr:1 row_mask:0xf bank_mask:0xf
	v_fmac_f32_dpp v209, v19, v163 row_shr:1 row_mask:0xf bank_mask:0xf
	v_fmac_f32_dpp v206, v32, v226 row_ror:1 row_mask:0xf bank_mask:0xf
	v_fmac_f32_dpp v207, v33, v227 row_ror:1 row_mask:0xf bank_mask:0xf
	v_fmac_f32_dpp v208, v34, v228 row_ror:1 row_mask:0xf bank_mask:0xf
	v_fmac_f32_dpp v209, v35, v229 row_ror:1 row_mask:0xf bank_mask:0xf
	v_fmac_f32_dpp v206, v16, v178 row_shl:1 row_mask:0xf bank_mask:0xf
	v_fmac_f32_dpp v207, v17, v179 row_shl:1 row_mask:0xf bank_mask:0xf
	v_fmac_f32_dpp v208, v18, v180 row_shl:1 row_mask:0xf bank_mask:0xf
	v_fmac_f32_dpp v209, v19, v181 row_shl:1 row_mask:0xf bank_mask:0xf
	v_fmac_f32_dpp v206, v0, v232 row_ror:15 row_mask:0xf bank_mask:0xf
	v_fmac_f32_dpp v207, v1, v233 row_ror:15 row_mask:0xf bank_mask:0xf
	v_fmac_f32_dpp v208, v2, v234 row_ror:15 row_mask:0xf bank_mask:0xf
	v_fmac_f32_dpp v209, v3, v235 row_ror:15 row_mask:0xf bank_mask:0xf
	v_mul_f32_e32 v210, 0xbfb8aa3b, v202
	v_mul_f32_e32 v211, 0xbfb8aa3b, v203
	v_mul_f32_e32 v212, 0xbfb8aa3b, v204
	v_mul_f32_e32 v213, 0xbfb8aa3b, v205
	v_exp_f32_e32 v210, v210
	v_exp_f32_e32 v211, v211
	v_exp_f32_e32 v212, v212
	v_exp_f32_e32 v213, v213
	v_add_f32_e32 v210, 1.0, v210
	v_add_f32_e32 v211, 1.0, v211
	v_add_f32_e32 v212, 1.0, v212
	v_add_f32_e32 v213, 1.0, v213
	v_rcp_f32_e32 v210, v210
	v_rcp_f32_e32 v211, v211
	v_rcp_f32_e32 v212, v212
	v_rcp_f32_e32 v213, v213
	v_mul_f32_e32 v202, v202, v210
	v_mul_f32_e32 v203, v203, v211
	v_mul_f32_e32 v204, v204, v212
	v_mul_f32_e32 v205, v205, v213
	v_mul_f32_e32 v202, v202, v206
	v_mul_f32_e32 v203, v203, v207
	v_mul_f32_e32 v204, v204, v208
	v_mul_f32_e32 v205, v205, v209
	v_cvt_pk_bf16_f32 v30, v202, v203
	v_cvt_pk_bf16_f32 v31, v204, v205
	v_fma_f32 v202, v124, v8, v132
	v_fma_f32 v203, v125, v9, v133
	v_fma_f32 v204, v126, v10, v134
	v_fma_f32 v205, v127, v11, v135
	v_fmac_f32_dpp v202, v8, v116 row_shr:1 row_mask:0xf bank_mask:0xf
	v_fmac_f32_dpp v203, v9, v117 row_shr:1 row_mask:0xf bank_mask:0xf
	v_fmac_f32_dpp v204, v10, v118 row_shr:1 row_mask:0xf bank_mask:0xf
	v_fmac_f32_dpp v205, v11, v119 row_shr:1 row_mask:0xf bank_mask:0xf
	v_fmac_f32_dpp v202, v24, v218 row_ror:1 row_mask:0xf bank_mask:0xf
	v_fmac_f32_dpp v203, v25, v219 row_ror:1 row_mask:0xf bank_mask:0xf
	v_fmac_f32_dpp v204, v26, v220 row_ror:1 row_mask:0xf bank_mask:0xf
	v_fmac_f32_dpp v205, v27, v221 row_ror:1 row_mask:0xf bank_mask:0xf
	v_fmac_f32_dpp v202, v8, v128 row_shl:1 row_mask:0xf bank_mask:0xf
	v_fmac_f32_dpp v203, v9, v129 row_shl:1 row_mask:0xf bank_mask:0xf
	v_fmac_f32_dpp v204, v10, v130 row_shl:1 row_mask:0xf bank_mask:0xf
	v_fmac_f32_dpp v205, v11, v131 row_shl:1 row_mask:0xf bank_mask:0xf
	v_fmac_f32_e32 v202, v194, v222
	v_fmac_f32_e32 v203, v195, v223
	v_fmac_f32_e32 v204, v196, v224
	v_fmac_f32_e32 v205, v197, v225
	v_fma_f32 v206, v164, v0, v182
	v_fma_f32 v207, v165, v1, v183
	v_fma_f32 v208, v166, v2, v184
	v_fma_f32 v209, v167, v3, v185
	v_fmac_f32_dpp v206, v0, v160 row_shr:1 row_mask:0xf bank_mask:0xf
	v_fmac_f32_dpp v207, v1, v161 row_shr:1 row_mask:0xf bank_mask:0xf
	v_fmac_f32_dpp v208, v2, v162 row_shr:1 row_mask:0xf bank_mask:0xf
	v_fmac_f32_dpp v209, v3, v163 row_shr:1 row_mask:0xf bank_mask:0xf
	v_fmac_f32_dpp v206, v16, v226 row_ror:1 row_mask:0xf bank_mask:0xf
	v_fmac_f32_dpp v207, v17, v227 row_ror:1 row_mask:0xf bank_mask:0xf
	v_fmac_f32_dpp v208, v18, v228 row_ror:1 row_mask:0xf bank_mask:0xf
	v_fmac_f32_dpp v209, v19, v229 row_ror:1 row_mask:0xf bank_mask:0xf
	v_fmac_f32_dpp v206, v0, v178 row_shl:1 row_mask:0xf bank_mask:0xf
	v_fmac_f32_dpp v207, v1, v179 row_shl:1 row_mask:0xf bank_mask:0xf
	v_fmac_f32_dpp v208, v2, v180 row_shl:1 row_mask:0xf bank_mask:0xf
	v_fmac_f32_dpp v209, v3, v181 row_shl:1 row_mask:0xf bank_mask:0xf
	v_fmac_f32_e32 v206, v198, v232
	v_fmac_f32_e32 v207, v199, v233
	v_fmac_f32_e32 v208, v200, v234
	v_fmac_f32_e32 v209, v201, v235
	v_mul_f32_e32 v210, 0xbfb8aa3b, v202
	v_mul_f32_e32 v211, 0xbfb8aa3b, v203
	v_mul_f32_e32 v212, 0xbfb8aa3b, v204
	v_mul_f32_e32 v213, 0xbfb8aa3b, v205
	v_exp_f32_e32 v210, v210
	v_exp_f32_e32 v211, v211
	v_exp_f32_e32 v212, v212
	v_exp_f32_e32 v213, v213
	v_add_f32_e32 v210, 1.0, v210
	v_add_f32_e32 v211, 1.0, v211
	v_add_f32_e32 v212, 1.0, v212
	v_add_f32_e32 v213, 1.0, v213
	v_rcp_f32_e32 v210, v210
	v_rcp_f32_e32 v211, v211
	v_rcp_f32_e32 v212, v212
	v_rcp_f32_e32 v213, v213
	v_mul_f32_e32 v202, v202, v210
	v_mul_f32_e32 v203, v203, v211
	v_mul_f32_e32 v204, v204, v212
	v_mul_f32_e32 v205, v205, v213
	v_mul_f32_e32 v202, v202, v206
	v_mul_f32_e32 v203, v203, v207
	v_mul_f32_e32 v204, v204, v208
	v_mul_f32_e32 v205, v205, v209
	v_cvt_pk_bf16_f32 v14, v202, v203
	v_cvt_pk_bf16_f32 v15, v204, v205
	global_store_dwordx4 v168, v[140:143], s[76:77]
	v_add_u32_e32 v250, 0x16000, v168
	global_store_dwordx4 v250, v[108:111], s[76:77]
	s_nop 0
	v_add_u32_e32 v250, 0x2c000, v168
	global_store_dwordx4 v250, v[92:95], s[76:77]
	s_nop 0
	v_add_u32_e32 v250, 0x42000, v168
	global_store_dwordx4 v250, v[76:79], s[76:77]
	s_nop 0
	v_add_u32_e32 v250, 0xb0000, v168
	global_store_dwordx4 v250, v[60:63], s[76:77]
	s_nop 0
	v_add_u32_e32 v250, 0xc6000, v168
	global_store_dwordx4 v250, v[44:47], s[76:77]
	s_nop 0
	v_add_u32_e32 v250, 0xdc000, v168
	global_store_dwordx4 v250, v[28:31], s[76:77]
	s_nop 0
	v_add_u32_e32 v250, 0xf2000, v168
	global_store_dwordx4 v250, v[12:15], s[76:77]
	s_nop 0
	s_andn2_b64 vcc, exec, s[6:7]
	s_mov_b64 s[4:5], -1
	s_cbranch_vccnz .LBB0_824
	s_andn2_b64 vcc, exec, s[12:13]
	s_cbranch_vccnz .LBB0_823
	s_barrier
	s_branch .LBB0_823

.LBB0_970:
	s_and_b32 s32, s10, 1
	v_readlane_b32 s98, v254, 49
	v_readlane_b32 s99, v254, 50
	s_nop 0
	s_add_i32 s4, s88, 0
	s_ashr_i32 s4, s4, 2
	s_add_i32 s4, s4, 1
	s_cmp_gt_i32 s88, -1
	s_cselect_b32 s4, s4, 0
	s_mul_hi_i32 s5, s4, 0x5800
	s_mulk_i32 s4, 0x5800
	s_add_u32 s4, s98, s4
	s_addc_u32 s5, s99, s5
	v_lshl_add_u32 v236, s88, 8, v170
	v_lshlrev_b32_e32 v236, 2, v236
	v_lshl_or_b32 v177, s66, 7, v172
	v_lshlrev_b32_e32 v177, 2, v177
	global_load_dword v210, v236, s[12:13] offset:0
	global_load_dword v211, v236, s[12:13] offset:64
	global_load_dword v212, v236, s[12:13] offset:128
	global_load_dword v213, v236, s[12:13] offset:192
	global_load_dword v214, v236, s[12:13] offset:512
	global_load_dword v215, v236, s[12:13] offset:576
	global_load_dword v216, v236, s[12:13] offset:640
	global_load_dword v217, v236, s[12:13] offset:704
	global_load_dwordx4 v[202:205], v177, s[4:5]
	global_load_dwordx4 v[206:209], v177, s[4:5] offset:16
	v_add_u32_e32 v226, 0x2c00, v177
	global_load_dwordx4 v[218:221], v226, s[4:5]
	global_load_dwordx4 v[222:225], v226, s[4:5] offset:16
	v_readlane_b32 s2, v254, 5
	v_readlane_b32 s3, v254, 6
	v_readlane_b32 s28, v254, 7
	v_readlane_b32 s29, v254, 8
	s_mul_i32 s76, s88, 0x160000
	s_lshl_b32 s57, s66, 8
	s_add_i32 s76, s76, s57
	s_add_i32 s76, s76, 0xbf00000
	s_add_u32 s76, s76, s70
	s_addc_u32 s77, s71, 0
	v_mul_u32_u24_e32 v168, 0x1600, v170
	v_lshl_add_u32 v168, v172, 1, v168
	s_mov_b32 s55, 0x20800
	v_lshl_add_u32 v169, v172, 2, s55
	v_and_b32_e32 v237, 15, v170
	v_cmp_eq_u32_e64 s[78:79], 0, v237
	v_cmp_eq_u32_e64 s[80:81], 15, v237
	v_and_b32_e32 v231, 8, v237
	v_lshlrev_b32_e32 v231, 9, v231
	s_lshl_b32 s57, s32, 10
	v_add3_u32 v231, v231, v169, s57
	global_load_dwordx4 v[116:119], v177, s[2:3]
	v_add_u32_e32 v229, 0x5800, v177
	global_load_dwordx4 v[124:127], v229, s[2:3]
	v_add_u32_e32 v228, 0xb000, v177
	global_load_dwordx4 v[128:131], v228, s[2:3]
	global_load_dwordx4 v[132:135], v177, s[28:29]
	v_add_u32_e32 v228, 0x2c00, v177
	global_load_dwordx4 v[160:163], v228, s[2:3]
	v_add_u32_e32 v229, 0x8400, v177
	global_load_dwordx4 v[164:167], v229, s[2:3]
	v_add_u32_e32 v228, 0xdc00, v177
	global_load_dwordx4 v[178:181], v228, s[2:3]
	v_add_u32_e32 v229, 0x2c00, v177
	global_load_dwordx4 v[182:185], v229, s[28:29]
	s_waitcnt vmcnt(12)
	v_fmamk_f32 v210, v210, 0x3a800000, v176
	v_fmamk_f32 v211, v211, 0x3a800000, v176
	v_fmamk_f32 v212, v212, 0x3a800000, v176
	v_fmamk_f32 v213, v213, 0x3a800000, v176
	v_fmamk_f32 v214, v214, 0x3a800000, v176
	v_fmamk_f32 v215, v215, 0x3a800000, v176
	v_fmamk_f32 v216, v216, 0x3a800000, v176
	v_fmamk_f32 v217, v217, 0x3a800000, v176
	s_mov_b32 s57, 0x800000
	v_mul_f32_e32 v226, 0x4b800000, v210
	v_mul_f32_e32 v227, 0x4b800000, v211
	v_mul_f32_e32 v228, 0x4b800000, v212
	v_mul_f32_e32 v229, 0x4b800000, v213
	v_mul_f32_e32 v232, 0x4b800000, v214
	v_mul_f32_e32 v233, 0x4b800000, v215
	v_mul_f32_e32 v234, 0x4b800000, v216
	v_mul_f32_e32 v235, 0x4b800000, v217
	v_cmp_gt_f32_e32 vcc, s57, v210
	s_nop 1
	v_cndmask_b32_e32 v210, v210, v226, vcc
	v_rsq_f32_e32 v210, v210
	s_nop 0
	v_mul_f32_e32 v226, 0x45800000, v210
	v_cndmask_b32_e32 v210, v210, v226, vcc
	v_cmp_gt_f32_e32 vcc, s57, v211
	s_nop 1
	v_cndmask_b32_e32 v211, v211, v227, vcc
	v_rsq_f32_e32 v211, v211
	s_nop 0
	v_mul_f32_e32 v227, 0x45800000, v211
	v_cndmask_b32_e32 v211, v211, v227, vcc
	v_cmp_gt_f32_e32 vcc, s57, v212
	s_nop 1
	v_cndmask_b32_e32 v212, v212, v228, vcc
	v_rsq_f32_e32 v212, v212
	s_nop 0
	v_mul_f32_e32 v228, 0x45800000, v212
	v_cndmask_b32_e32 v212, v212, v228, vcc
	v_cmp_gt_f32_e32 vcc, s57, v213
	s_nop 1
	v_cndmask_b32_e32 v213, v213, v229, vcc
	v_rsq_f32_e32 v213, v213
	s_nop 0
	v_mul_f32_e32 v229, 0x45800000, v213
	v_cndmask_b32_e32 v213, v213, v229, vcc
	v_cmp_gt_f32_e32 vcc, s57, v214
	s_nop 1
	v_cndmask_b32_e32 v214, v214, v232, vcc
	v_rsq_f32_e32 v214, v214
	s_nop 0
	v_mul_f32_e32 v232, 0x45800000, v214
	v_cndmask_b32_e32 v214, v214, v232, vcc
	v_cmp_gt_f32_e32 vcc, s57, v215
	s_nop 1
	v_cndmask_b32_e32 v215, v215, v233, vcc
	v_rsq_f32_e32 v215, v215
	s_nop 0
	v_mul_f32_e32 v233, 0x45800000, v215
	v_cndmask_b32_e32 v215, v215, v233, vcc
	v_cmp_gt_f32_e32 vcc, s57, v216
	s_nop 1
	v_cndmask_b32_e32 v216, v216, v234, vcc
	v_rsq_f32_e32 v216, v216
	s_nop 0
	v_mul_f32_e32 v234, 0x45800000, v216
	v_cndmask_b32_e32 v216, v216, v234, vcc
	v_cmp_gt_f32_e32 vcc, s57, v217
	s_nop 1
	v_cndmask_b32_e32 v217, v217, v235, vcc
	v_rsq_f32_e32 v217, v217
	s_nop 0
	v_mul_f32_e32 v235, 0x45800000, v217
	v_cndmask_b32_e32 v217, v217, v235, vcc
	s_waitcnt vmcnt(8)
	v_fma_f32 v140, v140, v210, v202
	v_fma_f32 v141, v141, v210, v203
	v_fma_f32 v142, v142, v210, v204
	v_fma_f32 v143, v143, v210, v205
	v_fma_f32 v136, v136, v210, v206
	v_fma_f32 v137, v137, v210, v207
	v_fma_f32 v138, v138, v210, v208
	v_fma_f32 v139, v139, v210, v209
	v_fma_f32 v120, v120, v210, v218
	v_fma_f32 v121, v121, v210, v219
	v_fma_f32 v122, v122, v210, v220
	v_fma_f32 v123, v123, v210, v221
	v_fma_f32 v112, v112, v210, v222
	v_fma_f32 v113, v113, v210, v223
	v_fma_f32 v114, v114, v210, v224
	v_fma_f32 v115, v115, v210, v225
	v_fma_f32 v108, v108, v211, v202
	v_fma_f32 v109, v109, v211, v203
	v_fma_f32 v110, v110, v211, v204
	v_fma_f32 v111, v111, v211, v205
	v_fma_f32 v104, v104, v211, v206
	v_fma_f32 v105, v105, v211, v207
	v_fma_f32 v106, v106, v211, v208
	v_fma_f32 v107, v107, v211, v209
	v_fma_f32 v100, v100, v211, v218
	v_fma_f32 v101, v101, v211, v219
	v_fma_f32 v102, v102, v211, v220
	v_fma_f32 v103, v103, v211, v221
	v_fma_f32 v96, v96, v211, v222
	v_fma_f32 v97, v97, v211, v223
	v_fma_f32 v98, v98, v211, v224
	v_fma_f32 v99, v99, v211, v225
	v_fma_f32 v92, v92, v212, v202
	v_fma_f32 v93, v93, v212, v203
	v_fma_f32 v94, v94, v212, v204
	v_fma_f32 v95, v95, v212, v205
	v_fma_f32 v88, v88, v212, v206
	v_fma_f32 v89, v89, v212, v207
	v_fma_f32 v90, v90, v212, v208
	v_fma_f32 v91, v91, v212, v209
	v_fma_f32 v84, v84, v212, v218
	v_fma_f32 v85, v85, v212, v219
	v_fma_f32 v86, v86, v212, v220
	v_fma_f32 v87, v87, v212, v221
	v_fma_f32 v80, v80, v212, v222
	v_fma_f32 v81, v81, v212, v223
	v_fma_f32 v82, v82, v212, v224
	v_fma_f32 v83, v83, v212, v225
	v_fma_f32 v76, v76, v213, v202
	v_fma_f32 v77, v77, v213, v203
	v_fma_f32 v78, v78, v213, v204
	v_fma_f32 v79, v79, v213, v205
	v_fma_f32 v72, v72, v213, v206
	v_fma_f32 v73, v73, v213, v207
	v_fma_f32 v74, v74, v213, v208
	v_fma_f32 v75, v75, v213, v209
	v_fma_f32 v68, v68, v213, v218
	v_fma_f32 v69, v69, v213, v219
	v_fma_f32 v70, v70, v213, v220
	v_fma_f32 v71, v71, v213, v221
	v_fma_f32 v64, v64, v213, v222
	v_fma_f32 v65, v65, v213, v223
	v_fma_f32 v66, v66, v213, v224
	v_fma_f32 v67, v67, v213, v225
	v_fma_f32 v60, v60, v214, v202
	v_fma_f32 v61, v61, v214, v203
	v_fma_f32 v62, v62, v214, v204
	v_fma_f32 v63, v63, v214, v205
	v_fma_f32 v56, v56, v214, v206
	v_fma_f32 v57, v57, v214, v207
	v_fma_f32 v58, v58, v214, v208
	v_fma_f32 v59, v59, v214, v209
	v_fma_f32 v52, v52, v214, v218
	v_fma_f32 v53, v53, v214, v219
	v_fma_f32 v54, v54, v214, v220
	v_fma_f32 v55, v55, v214, v221
	v_fma_f32 v48, v48, v214, v222
	v_fma_f32 v49, v49, v214, v223
	v_fma_f32 v50, v50, v214, v224
	v_fma_f32 v51, v51, v214, v225
	v_fma_f32 v44, v44, v215, v202
	v_fma_f32 v45, v45, v215, v203
	v_fma_f32 v46, v46, v215, v204
	v_fma_f32 v47, v47, v215, v205
	v_fma_f32 v40, v40, v215, v206
	v_fma_f32 v41, v41, v215, v207
	v_fma_f32 v42, v42, v215, v208
	v_fma_f32 v43, v43, v215, v209
	v_fma_f32 v36, v36, v215, v218
	v_fma_f32 v37, v37, v215, v219
	v_fma_f32 v38, v38, v215, v220
	v_fma_f32 v39, v39, v215, v221
	v_fma_f32 v32, v32, v215, v222
	v_fma_f32 v33, v33, v215, v223
	v_fma_f32 v34, v34, v215, v224
	v_fma_f32 v35, v35, v215, v225
	v_fma_f32 v28, v28, v216, v202
	v_fma_f32 v29, v29, v216, v203
	v_fma_f32 v30, v30, v216, v204
	v_fma_f32 v31, v31, v216, v205
	v_fma_f32 v24, v24, v216, v206
	v_fma_f32 v25, v25, v216, v207
	v_fma_f32 v26, v26, v216, v208
	v_fma_f32 v27, v27, v216, v209
	v_fma_f32 v20, v20, v216, v218
	v_fma_f32 v21, v21, v216, v219
	v_fma_f32 v22, v22, v216, v220
	v_fma_f32 v23, v23, v216, v221
	v_fma_f32 v16, v16, v216, v222
	v_fma_f32 v17, v17, v216, v223
	v_fma_f32 v18, v18, v216, v224
	v_fma_f32 v19, v19, v216, v225
	v_fma_f32 v12, v12, v217, v202
	v_fma_f32 v13, v13, v217, v203
	v_fma_f32 v14, v14, v217, v204
	v_fma_f32 v15, v15, v217, v205
	v_fma_f32 v8, v8, v217, v206
	v_fma_f32 v9, v9, v217, v207
	v_fma_f32 v10, v10, v217, v208
	v_fma_f32 v11, v11, v217, v209
	v_fma_f32 v4, v4, v217, v218
	v_fma_f32 v5, v5, v217, v219
	v_fma_f32 v6, v6, v217, v220
	v_fma_f32 v7, v7, v217, v221
	v_fma_f32 v0, v0, v217, v222
	v_fma_f32 v1, v1, v217, v223
	v_fma_f32 v2, v2, v217, v224
	v_fma_f32 v3, v3, v217, v225
	v_mov_b32_e32 v214, 0
	v_mov_b32_e32 v215, 0
	v_mov_b32_e32 v216, 0
	v_mov_b32_e32 v217, 0
	s_lshl_b32 s67, s32, 12
	s_sub_i32 s67, 0x2000, s67
	s_mul_i32 s89, s32, 0x1400
	s_add_i32 s89, s89, 0xc00
	s_lshl_b32 s57, s32, 10
	s_add_i32 s100, s57, 5120
	s_add_i32 s101, s57, 1024
	s_mov_b64 s[90:91], exec
	s_mov_b64 exec, s[78:79]
	v_add_u32_e32 v250, s67, v169
	ds_write_b128 v250, v[140:143] offset:0
	ds_write_b128 v250, v[136:139] offset:16
	ds_write_b128 v250, v[120:123] offset:512
	ds_write_b128 v250, v[112:115] offset:528
	v_add_u32_e32 v250, s100, v169
	ds_write_b128 v250, v[60:63] offset:0
	ds_write_b128 v250, v[56:59] offset:16
	ds_write_b128 v250, v[52:55] offset:512
	ds_write_b128 v250, v[48:51] offset:528
	ds_write_b128 v169, v[214:217] offset:0
	ds_write_b128 v169, v[214:217] offset:16
	ds_write_b128 v169, v[214:217] offset:512
	ds_write_b128 v169, v[214:217] offset:528
	s_mov_b64 exec, s[80:81]
	v_add_u32_e32 v251, s101, v169
	ds_write_b128 v251, v[76:79] offset:0
	ds_write_b128 v251, v[72:75] offset:16
	ds_write_b128 v251, v[68:71] offset:512
	ds_write_b128 v251, v[64:67] offset:528
	v_add_u32_e32 v251, s89, v169
	ds_write_b128 v251, v[12:15] offset:0
	ds_write_b128 v251, v[8:11] offset:16
	ds_write_b128 v251, v[4:7] offset:512
	ds_write_b128 v251, v[0:3] offset:528
	ds_write_b128 v169, v[214:217] offset:7168
	ds_write_b128 v169, v[214:217] offset:7184
	ds_write_b128 v169, v[214:217] offset:7680
	ds_write_b128 v169, v[214:217] offset:7696
	s_mov_b64 exec, s[90:91]
	s_cmp_eq_u32 s32, 0
	s_cselect_b64 s[92:93], s[78:79], 0
	s_cselect_b64 s[94:95], 0, s[80:81]
	s_mul_i32 s98, s88, 0x16000
	s_add_u32 s98, s98, 0x5b00000
	s_add_u32 s98, s98, s70
	s_addc_u32 s99, s71, 0
	s_mov_b64 exec, s[92:93]
	global_store_dwordx4 v177, v[140:143], s[98:99]
	global_store_dwordx4 v177, v[136:139], s[98:99] offset:16
	v_add_u32_e32 v250, 0x2c00, v177
	global_store_dwordx4 v250, v[120:123], s[98:99]
	global_store_dwordx4 v250, v[112:115], s[98:99] offset:16
	s_mov_b64 exec, s[94:95]
	v_add_u32_e32 v250, 0xb000, v177
	global_store_dwordx4 v250, v[12:15], s[98:99]
	global_store_dwordx4 v250, v[8:11], s[98:99] offset:16
	v_add_u32_e32 v250, 0xdc00, v177
	global_store_dwordx4 v250, v[4:7], s[98:99]
	global_store_dwordx4 v250, v[0:3], s[98:99] offset:16
	s_mov_b64 exec, s[90:91]
	s_waitcnt lgkmcnt(0)
	s_barrier
	ds_read_b128 v[186:189], v231 offset:0
	ds_read_b128 v[190:193], v231 offset:512
	ds_read_b128 v[194:197], v231 offset:2048
	ds_read_b128 v[198:201], v231 offset:2560
	s_waitcnt vmcnt(0)
	v_cndmask_b32_e64 v218, 0, v116, s[78:79]
	v_cndmask_b32_e64 v222, 0, v128, s[80:81]
	v_cndmask_b32_e64 v219, 0, v117, s[78:79]
	v_cndmask_b32_e64 v223, 0, v129, s[80:81]
	v_cndmask_b32_e64 v220, 0, v118, s[78:79]
	v_cndmask_b32_e64 v224, 0, v130, s[80:81]
	v_cndmask_b32_e64 v221, 0, v119, s[78:79]
	v_cndmask_b32_e64 v225, 0, v131, s[80:81]
	v_cndmask_b32_e64 v226, 0, v160, s[78:79]
	v_cndmask_b32_e64 v232, 0, v178, s[80:81]
	v_cndmask_b32_e64 v227, 0, v161, s[78:79]
	v_cndmask_b32_e64 v233, 0, v179, s[80:81]
	v_cndmask_b32_e64 v228, 0, v162, s[78:79]
	v_cndmask_b32_e64 v234, 0, v180, s[80:81]
	v_cndmask_b32_e64 v229, 0, v163, s[78:79]
	v_cndmask_b32_e64 v235, 0, v181, s[80:81]
	s_waitcnt lgkmcnt(0)
	s_nop 1
	v_fma_f32 v202, v124, v140, v132
	v_fma_f32 v203, v125, v141, v133
	v_fma_f32 v204, v126, v142, v134
	v_fma_f32 v205, v127, v143, v135
	v_fmac_f32_dpp v202, v140, v116 row_shr:1 row_mask:0xf bank_mask:0xf
	v_fmac_f32_dpp v203, v141, v117 row_shr:1 row_mask:0xf bank_mask:0xf
	v_fmac_f32_dpp v204, v142, v118 row_shr:1 row_mask:0xf bank_mask:0xf
	v_fmac_f32_dpp v205, v143, v119 row_shr:1 row_mask:0xf bank_mask:0xf
	v_fmac_f32_e32 v202, v186, v218
	v_fmac_f32_e32 v203, v187, v219
	v_fmac_f32_e32 v204, v188, v220
	v_fmac_f32_e32 v205, v189, v221
	v_fmac_f32_dpp v202, v140, v128 row_shl:1 row_mask:0xf bank_mask:0xf
	v_fmac_f32_dpp v203, v141, v129 row_shl:1 row_mask:0xf bank_mask:0xf
	v_fmac_f32_dpp v204, v142, v130 row_shl:1 row_mask:0xf bank_mask:0xf
	v_fmac_f32_dpp v205, v143, v131 row_shl:1 row_mask:0xf bank_mask:0xf
	v_fmac_f32_dpp v202, v108, v222 row_ror:15 row_mask:0xf bank_mask:0xf
	v_fmac_f32_dpp v203, v109, v223 row_ror:15 row_mask:0xf bank_mask:0xf
	v_fmac_f32_dpp v204, v110, v224 row_ror:15 row_mask:0xf bank_mask:0xf
	v_fmac_f32_dpp v205, v111, v225 row_ror:15 row_mask:0xf bank_mask:0xf
	v_fma_f32 v206, v164, v120, v182
	v_fma_f32 v207, v165, v121, v183
	v_fma_f32 v208, v166, v122, v184
	v_fma_f32 v209, v167, v123, v185
	v_fmac_f32_dpp v206, v120, v160 row_shr:1 row_mask:0xf bank_mask:0xf
	v_fmac_f32_dpp v207, v121, v161 row_shr:1 row_mask:0xf bank_mask:0xf
	v_fmac_f32_dpp v208, v122, v162 row_shr:1 row_mask:0xf bank_mask:0xf
	v_fmac_f32_dpp v209, v123, v163 row_shr:1 row_mask:0xf bank_mask:0xf
	v_fmac_f32_e32 v206, v190, v226
	v_fmac_f32_e32 v207, v191, v227
	v_fmac_f32_e32 v208, v192, v228
	v_fmac_f32_e32 v209, v193, v229
	v_fmac_f32_dpp v206, v120, v178 row_shl:1 row_mask:0xf bank_mask:0xf
	v_fmac_f32_dpp v207, v121, v179 row_shl:1 row_mask:0xf bank_mask:0xf
	v_fmac_f32_dpp v208, v122, v180 row_shl:1 row_mask:0xf bank_mask:0xf
	v_fmac_f32_dpp v209, v123, v181 row_shl:1 row_mask:0xf bank_mask:0xf
	v_fmac_f32_dpp v206, v100, v232 row_ror:15 row_mask:0xf bank_mask:0xf
	v_fmac_f32_dpp v207, v101, v233 row_ror:15 row_mask:0xf bank_mask:0xf
	v_fmac_f32_dpp v208, v102, v234 row_ror:15 row_mask:0xf bank_mask:0xf
	v_fmac_f32_dpp v209, v103, v235 row_ror:15 row_mask:0xf bank_mask:0xf
	s_mov_b64 exec, s[92:93]
	v_add_u32_e32 v250, 0x5800, v177
	global_store_dwordx4 v250, v[202:205], s[98:99]
	v_add_u32_e32 v250, 0x8400, v177
	global_store_dwordx4 v250, v[206:209], s[98:99]
	s_mov_b64 exec, s[90:91]
	s_nop 4
	v_mul_f32_e32 v210, 0xbfb8aa3b, v202
	v_mul_f32_e32 v211, 0xbfb8aa3b, v203
	v_mul_f32_e32 v212, 0xbfb8aa3b, v204
	v_mul_f32_e32 v213, 0xbfb8aa3b, v205
	v_exp_f32_e32 v210, v210
	v_exp_f32_e32 v211, v211
	v_exp_f32_e32 v212, v212
	v_exp_f32_e32 v213, v213
	v_add_f32_e32 v210, 1.0, v210
	v_add_f32_e32 v211, 1.0, v211
	v_add_f32_e32 v212, 1.0, v212
	v_add_f32_e32 v213, 1.0, v213
	v_rcp_f32_e32 v210, v210
	v_rcp_f32_e32 v211, v211
	v_rcp_f32_e32 v212, v212
	v_rcp_f32_e32 v213, v213
	v_mul_f32_e32 v202, v202, v210
	v_mul_f32_e32 v203, v203, v211
	v_mul_f32_e32 v204, v204, v212
	v_mul_f32_e32 v205, v205, v213
	v_mul_f32_e32 v202, v202, v206
	v_mul_f32_e32 v203, v203, v207
	v_mul_f32_e32 v204, v204, v208
	v_mul_f32_e32 v205, v205, v209
	v_cvt_pk_bf16_f32 v236, v202, v203
	v_cvt_pk_bf16_f32 v237, v204, v205
	v_fma_f32 v202, v124, v108, v132
	v_fma_f32 v203, v125, v109, v133
	v_fma_f32 v204, v126, v110, v134
	v_fma_f32 v205, v127, v111, v135
	v_fmac_f32_dpp v202, v108, v116 row_shr:1 row_mask:0xf bank_mask:0xf
	v_fmac_f32_dpp v203, v109, v117 row_shr:1 row_mask:0xf bank_mask:0xf
	v_fmac_f32_dpp v204, v110, v118 row_shr:1 row_mask:0xf bank_mask:0xf
	v_fmac_f32_dpp v205, v111, v119 row_shr:1 row_mask:0xf bank_mask:0xf
	v_fmac_f32_dpp v202, v140, v218 row_ror:1 row_mask:0xf bank_mask:0xf
	v_fmac_f32_dpp v203, v141, v219 row_ror:1 row_mask:0xf bank_mask:0xf
	v_fmac_f32_dpp v204, v142, v220 row_ror:1 row_mask:0xf bank_mask:0xf
	v_fmac_f32_dpp v205, v143, v221 row_ror:1 row_mask:0xf bank_mask:0xf
	v_fmac_f32_dpp v202, v108, v128 row_shl:1 row_mask:0xf bank_mask:0xf
	v_fmac_f32_dpp v203, v109, v129 row_shl:1 row_mask:0xf bank_mask:0xf
	v_fmac_f32_dpp v204, v110, v130 row_shl:1 row_mask:0xf bank_mask:0xf
	v_fmac_f32_dpp v205, v111, v131 row_shl:1 row_mask:0xf bank_mask:0xf
	v_fmac_f32_dpp v202, v92, v222 row_ror:15 row_mask:0xf bank_mask:0xf
	v_fmac_f32_dpp v203, v93, v223 row_ror:15 row_mask:0xf bank_mask:0xf
	v_fmac_f32_dpp v204, v94, v224 row_ror:15 row_mask:0xf bank_mask:0xf
	v_fmac_f32_dpp v205, v95, v225 row_ror:15 row_mask:0xf bank_mask:0xf
	v_fma_f32 v206, v164, v100, v182
	v_fma_f32 v207, v165, v101, v183
	v_fma_f32 v208, v166, v102, v184
	v_fma_f32 v209, v167, v103, v185
	v_fmac_f32_dpp v206, v100, v160 row_shr:1 row_mask:0xf bank_mask:0xf
	v_fmac_f32_dpp v207, v101, v161 row_shr:1 row_mask:0xf bank_mask:0xf
	v_fmac_f32_dpp v208, v102, v162 row_shr:1 row_mask:0xf bank_mask:0xf
	v_fmac_f32_dpp v209, v103, v163 row_shr:1 row_mask:0xf bank_mask:0xf
	v_fmac_f32_dpp v206, v120, v226 row_ror:1 row_mask:0xf bank_mask:0xf
	v_fmac_f32_dpp v207, v121, v227 row_ror:1 row_mask:0xf bank_mask:0xf
	v_fmac_f32_dpp v208, v122, v228 row_ror:1 row_mask:0xf bank_mask:0xf
	v_fmac_f32_dpp v209, v123, v229 row_ror:1 row_mask:0xf bank_mask:0xf
	v_fmac_f32_dpp v206, v100, v178 row_shl:1 row_mask:0xf bank_mask:0xf
	v_fmac_f32_dpp v207, v101, v179 row_shl:1 row_mask:0xf bank_mask:0xf
	v_fmac_f32_dpp v208, v102, v180 row_shl:1 row_mask:0xf bank_mask:0xf
	v_fmac_f32_dpp v209, v103, v181 row_shl:1 row_mask:0xf bank_mask:0xf
	v_fmac_f32_dpp v206, v84, v232 row_ror:15 row_mask:0xf bank_mask:0xf
	v_fmac_f32_dpp v207, v85, v233 row_ror:15 row_mask:0xf bank_mask:0xf
	v_fmac_f32_dpp v208, v86, v234 row_ror:15 row_mask:0xf bank_mask:0xf
	v_fmac_f32_dpp v209, v87, v235 row_ror:15 row_mask:0xf bank_mask:0xf
	v_mul_f32_e32 v210, 0xbfb8aa3b, v202
	v_mul_f32_e32 v211, 0xbfb8aa3b, v203
	v_mul_f32_e32 v212, 0xbfb8aa3b, v204
	v_mul_f32_e32 v213, 0xbfb8aa3b, v205
	v_exp_f32_e32 v210, v210
	v_exp_f32_e32 v211, v211
	v_exp_f32_e32 v212, v212
	v_exp_f32_e32 v213, v213
	v_add_f32_e32 v210, 1.0, v210
	v_add_f32_e32 v211, 1.0, v211
	v_add_f32_e32 v212, 1.0, v212
	v_add_f32_e32 v213, 1.0, v213
	v_rcp_f32_e32 v210, v210
	v_rcp_f32_e32 v211, v211
	v_rcp_f32_e32 v212, v212
	v_rcp_f32_e32 v213, v213
	v_mul_f32_e32 v202, v202, v210
	v_mul_f32_e32 v203, v203, v211
	v_mul_f32_e32 v204, v204, v212
	v_mul_f32_e32 v205, v205, v213
	v_mul_f32_e32 v202, v202, v206
	v_mul_f32_e32 v203, v203, v207
	v_mul_f32_e32 v204, v204, v208
	v_mul_f32_e32 v205, v205, v209
	v_cvt_pk_bf16_f32 v238, v202, v203
	v_cvt_pk_bf16_f32 v239, v204, v205
	v_fma_f32 v202, v124, v92, v132
	v_fma_f32 v203, v125, v93, v133
	v_fma_f32 v204, v126, v94, v134
	v_fma_f32 v205, v127, v95, v135
	v_fmac_f32_dpp v202, v92, v116 row_shr:1 row_mask:0xf bank_mask:0xf
	v_fmac_f32_dpp v203, v93, v117 row_shr:1 row_mask:0xf bank_mask:0xf
	v_fmac_f32_dpp v204, v94, v118 row_shr:1 row_mask:0xf bank_mask:0xf
	v_fmac_f32_dpp v205, v95, v119 row_shr:1 row_mask:0xf bank_mask:0xf
	v_fmac_f32_dpp v202, v108, v218 row_ror:1 row_mask:0xf bank_mask:0xf
	v_fmac_f32_dpp v203, v109, v219 row_ror:1 row_mask:0xf bank_mask:0xf
	v_fmac_f32_dpp v204, v110, v220 row_ror:1 row_mask:0xf bank_mask:0xf
	v_fmac_f32_dpp v205, v111, v221 row_ror:1 row_mask:0xf bank_mask:0xf
	v_fmac_f32_dpp v202, v92, v128 row_shl:1 row_mask:0xf bank_mask:0xf
	v_fmac_f32_dpp v203, v93, v129 row_shl:1 row_mask:0xf bank_mask:0xf
	v_fmac_f32_dpp v204, v94, v130 row_shl:1 row_mask:0xf bank_mask:0xf
	v_fmac_f32_dpp v205, v95, v131 row_shl:1 row_mask:0xf bank_mask:0xf
	v_fmac_f32_dpp v202, v76, v222 row_ror:15 row_mask:0xf bank_mask:0xf
	v_fmac_f32_dpp v203, v77, v223 row_ror:15 row_mask:0xf bank_mask:0xf
	v_fmac_f32_dpp v204, v78, v224 row_ror:15 row_mask:0xf bank_mask:0xf
	v_fmac_f32_dpp v205, v79, v225 row_ror:15 row_mask:0xf bank_mask:0xf
	v_fma_f32 v206, v164, v84, v182
	v_fma_f32 v207, v165, v85, v183
	v_fma_f32 v208, v166, v86, v184
	v_fma_f32 v209, v167, v87, v185
	v_fmac_f32_dpp v206, v84, v160 row_shr:1 row_mask:0xf bank_mask:0xf
	v_fmac_f32_dpp v207, v85, v161 row_shr:1 row_mask:0xf bank_mask:0xf
	v_fmac_f32_dpp v208, v86, v162 row_shr:1 row_mask:0xf bank_mask:0xf
	v_fmac_f32_dpp v209, v87, v163 row_shr:1 row_mask:0xf bank_mask:0xf
	v_fmac_f32_dpp v206, v100, v226 row_ror:1 row_mask:0xf bank_mask:0xf
	v_fmac_f32_dpp v207, v101, v227 row_ror:1 row_mask:0xf bank_mask:0xf
	v_fmac_f32_dpp v208, v102, v228 row_ror:1 row_mask:0xf bank_mask:0xf
	v_fmac_f32_dpp v209, v103, v229 row_ror:1 row_mask:0xf bank_mask:0xf
	v_fmac_f32_dpp v206, v84, v178 row_shl:1 row_mask:0xf bank_mask:0xf
	v_fmac_f32_dpp v207, v85, v179 row_shl:1 row_mask:0xf bank_mask:0xf
	v_fmac_f32_dpp v208, v86, v180 row_shl:1 row_mask:0xf bank_mask:0xf
	v_fmac_f32_dpp v209, v87, v181 row_shl:1 row_mask:0xf bank_mask:0xf
	v_fmac_f32_dpp v206, v68, v232 row_ror:15 row_mask:0xf bank_mask:0xf
	v_fmac_f32_dpp v207, v69, v233 row_ror:15 row_mask:0xf bank_mask:0xf
	v_fmac_f32_dpp v208, v70, v234 row_ror:15 row_mask:0xf bank_mask:0xf
	v_fmac_f32_dpp v209, v71, v235 row_ror:15 row_mask:0xf bank_mask:0xf
	v_mul_f32_e32 v210, 0xbfb8aa3b, v202
	v_mul_f32_e32 v211, 0xbfb8aa3b, v203
	v_mul_f32_e32 v212, 0xbfb8aa3b, v204
	v_mul_f32_e32 v213, 0xbfb8aa3b, v205
	v_exp_f32_e32 v210, v210
	v_exp_f32_e32 v211, v211
	v_exp_f32_e32 v212, v212
	v_exp_f32_e32 v213, v213
	v_add_f32_e32 v210, 1.0, v210
	v_add_f32_e32 v211, 1.0, v211
	v_add_f32_e32 v212, 1.0, v212
	v_add_f32_e32 v213, 1.0, v213
	v_rcp_f32_e32 v210, v210
	v_rcp_f32_e32 v211, v211
	v_rcp_f32_e32 v212, v212
	v_rcp_f32_e32 v213, v213
	v_mul_f32_e32 v202, v202, v210
	v_mul_f32_e32 v203, v203, v211
	v_mul_f32_e32 v204, v204, v212
	v_mul_f32_e32 v205, v205, v213
	v_mul_f32_e32 v202, v202, v206
	v_mul_f32_e32 v203, v203, v207
	v_mul_f32_e32 v204, v204, v208
	v_mul_f32_e32 v205, v205, v209
	v_cvt_pk_bf16_f32 v240, v202, v203
	v_cvt_pk_bf16_f32 v241, v204, v205
	v_fma_f32 v202, v124, v76, v132
	v_fma_f32 v203, v125, v77, v133
	v_fma_f32 v204, v126, v78, v134
	v_fma_f32 v205, v127, v79, v135
	v_fmac_f32_dpp v202, v76, v116 row_shr:1 row_mask:0xf bank_mask:0xf
	v_fmac_f32_dpp v203, v77, v117 row_shr:1 row_mask:0xf bank_mask:0xf
	v_fmac_f32_dpp v204, v78, v118 row_shr:1 row_mask:0xf bank_mask:0xf
	v_fmac_f32_dpp v205, v79, v119 row_shr:1 row_mask:0xf bank_mask:0xf
	v_fmac_f32_dpp v202, v92, v218 row_ror:1 row_mask:0xf bank_mask:0xf
	v_fmac_f32_dpp v203, v93, v219 row_ror:1 row_mask:0xf bank_mask:0xf
	v_fmac_f32_dpp v204, v94, v220 row_ror:1 row_mask:0xf bank_mask:0xf
	v_fmac_f32_dpp v205, v95, v221 row_ror:1 row_mask:0xf bank_mask:0xf
	v_fmac_f32_dpp v202, v76, v128 row_shl:1 row_mask:0xf bank_mask:0xf
	v_fmac_f32_dpp v203, v77, v129 row_shl:1 row_mask:0xf bank_mask:0xf
	v_fmac_f32_dpp v204, v78, v130 row_shl:1 row_mask:0xf bank_mask:0xf
	v_fmac_f32_dpp v205, v79, v131 row_shl:1 row_mask:0xf bank_mask:0xf
	v_fmac_f32_e32 v202, v186, v222
	v_fmac_f32_e32 v203, v187, v223
	v_fmac_f32_e32 v204, v188, v224
	v_fmac_f32_e32 v205, v189, v225
	v_fma_f32 v206, v164, v68, v182
	v_fma_f32 v207, v165, v69, v183
	v_fma_f32 v208, v166, v70, v184
	v_fma_f32 v209, v167, v71, v185
	v_fmac_f32_dpp v206, v68, v160 row_shr:1 row_mask:0xf bank_mask:0xf
	v_fmac_f32_dpp v207, v69, v161 row_shr:1 row_mask:0xf bank_mask:0xf
	v_fmac_f32_dpp v208, v70, v162 row_shr:1 row_mask:0xf bank_mask:0xf
	v_fmac_f32_dpp v209, v71, v163 row_shr:1 row_mask:0xf bank_mask:0xf
	v_fmac_f32_dpp v206, v84, v226 row_ror:1 row_mask:0xf bank_mask:0xf
	v_fmac_f32_dpp v207, v85, v227 row_ror:1 row_mask:0xf bank_mask:0xf
	v_fmac_f32_dpp v208, v86, v228 row_ror:1 row_mask:0xf bank_mask:0xf
	v_fmac_f32_dpp v209, v87, v229 row_ror:1 row_mask:0xf bank_mask:0xf
	v_fmac_f32_dpp v206, v68, v178 row_shl:1 row_mask:0xf bank_mask:0xf
	v_fmac_f32_dpp v207, v69, v179 row_shl:1 row_mask:0xf bank_mask:0xf
	v_fmac_f32_dpp v208, v70, v180 row_shl:1 row_mask:0xf bank_mask:0xf
	v_fmac_f32_dpp v209, v71, v181 row_shl:1 row_mask:0xf bank_mask:0xf
	v_fmac_f32_e32 v206, v190, v232
	v_fmac_f32_e32 v207, v191, v233
	v_fmac_f32_e32 v208, v192, v234
	v_fmac_f32_e32 v209, v193, v235
	v_mul_f32_e32 v210, 0xbfb8aa3b, v202
	v_mul_f32_e32 v211, 0xbfb8aa3b, v203
	v_mul_f32_e32 v212, 0xbfb8aa3b, v204
	v_mul_f32_e32 v213, 0xbfb8aa3b, v205
	v_exp_f32_e32 v210, v210
	v_exp_f32_e32 v211, v211
	v_exp_f32_e32 v212, v212
	v_exp_f32_e32 v213, v213
	v_add_f32_e32 v210, 1.0, v210
	v_add_f32_e32 v211, 1.0, v211
	v_add_f32_e32 v212, 1.0, v212
	v_add_f32_e32 v213, 1.0, v213
	v_rcp_f32_e32 v210, v210
	v_rcp_f32_e32 v211, v211
	v_rcp_f32_e32 v212, v212
	v_rcp_f32_e32 v213, v213
	v_mul_f32_e32 v202, v202, v210
	v_mul_f32_e32 v203, v203, v211
	v_mul_f32_e32 v204, v204, v212
	v_mul_f32_e32 v205, v205, v213
	v_mul_f32_e32 v202, v202, v206
	v_mul_f32_e32 v203, v203, v207
	v_mul_f32_e32 v204, v204, v208
	v_mul_f32_e32 v205, v205, v209
	v_cvt_pk_bf16_f32 v242, v202, v203
	v_cvt_pk_bf16_f32 v243, v204, v205
	v_fma_f32 v202, v124, v60, v132
	v_fma_f32 v203, v125, v61, v133
	v_fma_f32 v204, v126, v62, v134
	v_fma_f32 v205, v127, v63, v135
	v_fmac_f32_dpp v202, v60, v116 row_shr:1 row_mask:0xf bank_mask:0xf
	v_fmac_f32_dpp v203, v61, v117 row_shr:1 row_mask:0xf bank_mask:0xf
	v_fmac_f32_dpp v204, v62, v118 row_shr:1 row_mask:0xf bank_mask:0xf
	v_fmac_f32_dpp v205, v63, v119 row_shr:1 row_mask:0xf bank_mask:0xf
	v_fmac_f32_e32 v202, v194, v218
	v_fmac_f32_e32 v203, v195, v219
	v_fmac_f32_e32 v204, v196, v220
	v_fmac_f32_e32 v205, v197, v221
	v_fmac_f32_dpp v202, v60, v128 row_shl:1 row_mask:0xf bank_mask:0xf
	v_fmac_f32_dpp v203, v61, v129 row_shl:1 row_mask:0xf bank_mask:0xf
	v_fmac_f32_dpp v204, v62, v130 row_shl:1 row_mask:0xf bank_mask:0xf
	v_fmac_f32_dpp v205, v63, v131 row_shl:1 row_mask:0xf bank_mask:0xf
	v_fmac_f32_dpp v202, v44, v222 row_ror:15 row_mask:0xf bank_mask:0xf
	v_fmac_f32_dpp v203, v45, v223 row_ror:15 row_mask:0xf bank_mask:0xf
	v_fmac_f32_dpp v204, v46, v224 row_ror:15 row_mask:0xf bank_mask:0xf
	v_fmac_f32_dpp v205, v47, v225 row_ror:15 row_mask:0xf bank_mask:0xf
	v_fma_f32 v206, v164, v52, v182
	v_fma_f32 v207, v165, v53, v183
	v_fma_f32 v208, v166, v54, v184
	v_fma_f32 v209, v167, v55, v185
	v_fmac_f32_dpp v206, v52, v160 row_shr:1 row_mask:0xf bank_mask:0xf
	v_fmac_f32_dpp v207, v53, v161 row_shr:1 row_mask:0xf bank_mask:0xf
	v_fmac_f32_dpp v208, v54, v162 row_shr:1 row_mask:0xf bank_mask:0xf
	v_fmac_f32_dpp v209, v55, v163 row_shr:1 row_mask:0xf bank_mask:0xf
	v_fmac_f32_e32 v206, v198, v226
	v_fmac_f32_e32 v207, v199, v227
	v_fmac_f32_e32 v208, v200, v228
	v_fmac_f32_e32 v209, v201, v229
	v_fmac_f32_dpp v206, v52, v178 row_shl:1 row_mask:0xf bank_mask:0xf
	v_fmac_f32_dpp v207, v53, v179 row_shl:1 row_mask:0xf bank_mask:0xf
	v_fmac_f32_dpp v208, v54, v180 row_shl:1 row_mask:0xf bank_mask:0xf
	v_fmac_f32_dpp v209, v55, v181 row_shl:1 row_mask:0xf bank_mask:0xf
	v_fmac_f32_dpp v206, v36, v232 row_ror:15 row_mask:0xf bank_mask:0xf
	v_fmac_f32_dpp v207, v37, v233 row_ror:15 row_mask:0xf bank_mask:0xf
	v_fmac_f32_dpp v208, v38, v234 row_ror:15 row_mask:0xf bank_mask:0xf
	v_fmac_f32_dpp v209, v39, v235 row_ror:15 row_mask:0xf bank_mask:0xf
	v_mul_f32_e32 v210, 0xbfb8aa3b, v202
	v_mul_f32_e32 v211, 0xbfb8aa3b, v203
	v_mul_f32_e32 v212, 0xbfb8aa3b, v204
	v_mul_f32_e32 v213, 0xbfb8aa3b, v205
	v_exp_f32_e32 v210, v210
	v_exp_f32_e32 v211, v211
	v_exp_f32_e32 v212, v212
	v_exp_f32_e32 v213, v213
	v_add_f32_e32 v210, 1.0, v210
	v_add_f32_e32 v211, 1.0, v211
	v_add_f32_e32 v212, 1.0, v212
	v_add_f32_e32 v213, 1.0, v213
	v_rcp_f32_e32 v210, v210
	v_rcp_f32_e32 v211, v211
	v_rcp_f32_e32 v212, v212
	v_rcp_f32_e32 v213, v213
	v_mul_f32_e32 v202, v202, v210
	v_mul_f32_e32 v203, v203, v211
	v_mul_f32_e32 v204, v204, v212
	v_mul_f32_e32 v205, v205, v213
	v_mul_f32_e32 v202, v202, v206
	v_mul_f32_e32 v203, v203, v207
	v_mul_f32_e32 v204, v204, v208
	v_mul_f32_e32 v205, v205, v209
	v_cvt_pk_bf16_f32 v244, v202, v203
	v_cvt_pk_bf16_f32 v245, v204, v205
	v_fma_f32 v202, v124, v44, v132
	v_fma_f32 v203, v125, v45, v133
	v_fma_f32 v204, v126, v46, v134
	v_fma_f32 v205, v127, v47, v135
	v_fmac_f32_dpp v202, v44, v116 row_shr:1 row_mask:0xf bank_mask:0xf
	v_fmac_f32_dpp v203, v45, v117 row_shr:1 row_mask:0xf bank_mask:0xf
	v_fmac_f32_dpp v204, v46, v118 row_shr:1 row_mask:0xf bank_mask:0xf
	v_fmac_f32_dpp v205, v47, v119 row_shr:1 row_mask:0xf bank_mask:0xf
	v_fmac_f32_dpp v202, v60, v218 row_ror:1 row_mask:0xf bank_mask:0xf
	v_fmac_f32_dpp v203, v61, v219 row_ror:1 row_mask:0xf bank_mask:0xf
	v_fmac_f32_dpp v204, v62, v220 row_ror:1 row_mask:0xf bank_mask:0xf
	v_fmac_f32_dpp v205, v63, v221 row_ror:1 row_mask:0xf bank_mask:0xf
	v_fmac_f32_dpp v202, v44, v128 row_shl:1 row_mask:0xf bank_mask:0xf
	v_fmac_f32_dpp v203, v45, v129 row_shl:1 row_mask:0xf bank_mask:0xf
	v_fmac_f32_dpp v204, v46, v130 row_shl:1 row_mask:0xf bank_mask:0xf
	v_fmac_f32_dpp v205, v47, v131 row_shl:1 row_mask:0xf bank_mask:0xf
	v_fmac_f32_dpp v202, v28, v222 row_ror:15 row_mask:0xf bank_mask:0xf
	v_fmac_f32_dpp v203, v29, v223 row_ror:15 row_mask:0xf bank_mask:0xf
	v_fmac_f32_dpp v204, v30, v224 row_ror:15 row_mask:0xf bank_mask:0xf
	v_fmac_f32_dpp v205, v31, v225 row_ror:15 row_mask:0xf bank_mask:0xf
	v_fma_f32 v206, v164, v36, v182
	v_fma_f32 v207, v165, v37, v183
	v_fma_f32 v208, v166, v38, v184
	v_fma_f32 v209, v167, v39, v185
	v_fmac_f32_dpp v206, v36, v160 row_shr:1 row_mask:0xf bank_mask:0xf
	v_fmac_f32_dpp v207, v37, v161 row_shr:1 row_mask:0xf bank_mask:0xf
	v_fmac_f32_dpp v208, v38, v162 row_shr:1 row_mask:0xf bank_mask:0xf
	v_fmac_f32_dpp v209, v39, v163 row_shr:1 row_mask:0xf bank_mask:0xf
	v_fmac_f32_dpp v206, v52, v226 row_ror:1 row_mask:0xf bank_mask:0xf
	v_fmac_f32_dpp v207, v53, v227 row_ror:1 row_mask:0xf bank_mask:0xf
	v_fmac_f32_dpp v208, v54, v228 row_ror:1 row_mask:0xf bank_mask:0xf
	v_fmac_f32_dpp v209, v55, v229 row_ror:1 row_mask:0xf bank_mask:0xf
	v_fmac_f32_dpp v206, v36, v178 row_shl:1 row_mask:0xf bank_mask:0xf
	v_fmac_f32_dpp v207, v37, v179 row_shl:1 row_mask:0xf bank_mask:0xf
	v_fmac_f32_dpp v208, v38, v180 row_shl:1 row_mask:0xf bank_mask:0xf
	v_fmac_f32_dpp v209, v39, v181 row_shl:1 row_mask:0xf bank_mask:0xf
	v_fmac_f32_dpp v206, v20, v232 row_ror:15 row_mask:0xf bank_mask:0xf
	v_fmac_f32_dpp v207, v21, v233 row_ror:15 row_mask:0xf bank_mask:0xf
	v_fmac_f32_dpp v208, v22, v234 row_ror:15 row_mask:0xf bank_mask:0xf
	v_fmac_f32_dpp v209, v23, v235 row_ror:15 row_mask:0xf bank_mask:0xf
	v_mul_f32_e32 v210, 0xbfb8aa3b, v202
	v_mul_f32_e32 v211, 0xbfb8aa3b, v203
	v_mul_f32_e32 v212, 0xbfb8aa3b, v204
	v_mul_f32_e32 v213, 0xbfb8aa3b, v205
	v_exp_f32_e32 v210, v210
	v_exp_f32_e32 v211, v211
	v_exp_f32_e32 v212, v212
	v_exp_f32_e32 v213, v213
	v_add_f32_e32 v210, 1.0, v210
	v_add_f32_e32 v211, 1.0, v211
	v_add_f32_e32 v212, 1.0, v212
	v_add_f32_e32 v213, 1.0, v213
	v_rcp_f32_e32 v210, v210
	v_rcp_f32_e32 v211, v211
	v_rcp_f32_e32 v212, v212
	v_rcp_f32_e32 v213, v213
	v_mul_f32_e32 v202, v202, v210
	v_mul_f32_e32 v203, v203, v211
	v_mul_f32_e32 v204, v204, v212
	v_mul_f32_e32 v205, v205, v213
	v_mul_f32_e32 v202, v202, v206
	v_mul_f32_e32 v203, v203, v207
	v_mul_f32_e32 v204, v204, v208
	v_mul_f32_e32 v205, v205, v209
	v_cvt_pk_bf16_f32 v246, v202, v203
	v_cvt_pk_bf16_f32 v247, v204, v205
	v_fma_f32 v202, v124, v28, v132
	v_fma_f32 v203, v125, v29, v133
	v_fma_f32 v204, v126, v30, v134
	v_fma_f32 v205, v127, v31, v135
	v_fmac_f32_dpp v202, v28, v116 row_shr:1 row_mask:0xf bank_mask:0xf
	v_fmac_f32_dpp v203, v29, v117 row_shr:1 row_mask:0xf bank_mask:0xf
	v_fmac_f32_dpp v204, v30, v118 row_shr:1 row_mask:0xf bank_mask:0xf
	v_fmac_f32_dpp v205, v31, v119 row_shr:1 row_mask:0xf bank_mask:0xf
	v_fmac_f32_dpp v202, v44, v218 row_ror:1 row_mask:0xf bank_mask:0xf
	v_fmac_f32_dpp v203, v45, v219 row_ror:1 row_mask:0xf bank_mask:0xf
	v_fmac_f32_dpp v204, v46, v220 row_ror:1 row_mask:0xf bank_mask:0xf
	v_fmac_f32_dpp v205, v47, v221 row_ror:1 row_mask:0xf bank_mask:0xf
	v_fmac_f32_dpp v202, v28, v128 row_shl:1 row_mask:0xf bank_mask:0xf
	v_fmac_f32_dpp v203, v29, v129 row_shl:1 row_mask:0xf bank_mask:0xf
	v_fmac_f32_dpp v204, v30, v130 row_shl:1 row_mask:0xf bank_mask:0xf
	v_fmac_f32_dpp v205, v31, v131 row_shl:1 row_mask:0xf bank_mask:0xf
	v_fmac_f32_dpp v202, v12, v222 row_ror:15 row_mask:0xf bank_mask:0xf
	v_fmac_f32_dpp v203, v13, v223 row_ror:15 row_mask:0xf bank_mask:0xf
	v_fmac_f32_dpp v204, v14, v224 row_ror:15 row_mask:0xf bank_mask:0xf
	v_fmac_f32_dpp v205, v15, v225 row_ror:15 row_mask:0xf bank_mask:0xf
	v_fma_f32 v206, v164, v20, v182
	v_fma_f32 v207, v165, v21, v183
	v_fma_f32 v208, v166, v22, v184
	v_fma_f32 v209, v167, v23, v185
	v_fmac_f32_dpp v206, v20, v160 row_shr:1 row_mask:0xf bank_mask:0xf
	v_fmac_f32_dpp v207, v21, v161 row_shr:1 row_mask:0xf bank_mask:0xf
	v_fmac_f32_dpp v208, v22, v162 row_shr:1 row_mask:0xf bank_mask:0xf
	v_fmac_f32_dpp v209, v23, v163 row_shr:1 row_mask:0xf bank_mask:0xf
	v_fmac_f32_dpp v206, v36, v226 row_ror:1 row_mask:0xf bank_mask:0xf
	v_fmac_f32_dpp v207, v37, v227 row_ror:1 row_mask:0xf bank_mask:0xf
	v_fmac_f32_dpp v208, v38, v228 row_ror:1 row_mask:0xf bank_mask:0xf
	v_fmac_f32_dpp v209, v39, v229 row_ror:1 row_mask:0xf bank_mask:0xf
	v_fmac_f32_dpp v206, v20, v178 row_shl:1 row_mask:0xf bank_mask:0xf
	v_fmac_f32_dpp v207, v21, v179 row_shl:1 row_mask:0xf bank_mask:0xf
	v_fmac_f32_dpp v208, v22, v180 row_shl:1 row_mask:0xf bank_mask:0xf
	v_fmac_f32_dpp v209, v23, v181 row_shl:1 row_mask:0xf bank_mask:0xf
	v_fmac_f32_dpp v206, v4, v232 row_ror:15 row_mask:0xf bank_mask:0xf
	v_fmac_f32_dpp v207, v5, v233 row_ror:15 row_mask:0xf bank_mask:0xf
	v_fmac_f32_dpp v208, v6, v234 row_ror:15 row_mask:0xf bank_mask:0xf
	v_fmac_f32_dpp v209, v7, v235 row_ror:15 row_mask:0xf bank_mask:0xf
	v_mul_f32_e32 v210, 0xbfb8aa3b, v202
	v_mul_f32_e32 v211, 0xbfb8aa3b, v203
	v_mul_f32_e32 v212, 0xbfb8aa3b, v204
	v_mul_f32_e32 v213, 0xbfb8aa3b, v205
	v_exp_f32_e32 v210, v210
	v_exp_f32_e32 v211, v211
	v_exp_f32_e32 v212, v212
	v_exp_f32_e32 v213, v213
	v_add_f32_e32 v210, 1.0, v210
	v_add_f32_e32 v211, 1.0, v211
	v_add_f32_e32 v212, 1.0, v212
	v_add_f32_e32 v213, 1.0, v213
	v_rcp_f32_e32 v210, v210
	v_rcp_f32_e32 v211, v211
	v_rcp_f32_e32 v212, v212
	v_rcp_f32_e32 v213, v213
	v_mul_f32_e32 v202, v202, v210
	v_mul_f32_e32 v203, v203, v211
	v_mul_f32_e32 v204, v204, v212
	v_mul_f32_e32 v205, v205, v213
	v_mul_f32_e32 v202, v202, v206
	v_mul_f32_e32 v203, v203, v207
	v_mul_f32_e32 v204, v204, v208
	v_mul_f32_e32 v205, v205, v209
	v_cvt_pk_bf16_f32 v248, v202, v203
	v_cvt_pk_bf16_f32 v249, v204, v205
	v_fma_f32 v202, v124, v12, v132
	v_fma_f32 v203, v125, v13, v133
	v_fma_f32 v204, v126, v14, v134
	v_fma_f32 v205, v127, v15, v135
	v_fmac_f32_dpp v202, v12, v116 row_shr:1 row_mask:0xf bank_mask:0xf
	v_fmac_f32_dpp v203, v13, v117 row_shr:1 row_mask:0xf bank_mask:0xf
	v_fmac_f32_dpp v204, v14, v118 row_shr:1 row_mask:0xf bank_mask:0xf
	v_fmac_f32_dpp v205, v15, v119 row_shr:1 row_mask:0xf bank_mask:0xf
	v_fmac_f32_dpp v202, v28, v218 row_ror:1 row_mask:0xf bank_mask:0xf
	v_fmac_f32_dpp v203, v29, v219 row_ror:1 row_mask:0xf bank_mask:0xf
	v_fmac_f32_dpp v204, v30, v220 row_ror:1 row_mask:0xf bank_mask:0xf
	v_fmac_f32_dpp v205, v31, v221 row_ror:1 row_mask:0xf bank_mask:0xf
	v_fmac_f32_dpp v202, v12, v128 row_shl:1 row_mask:0xf bank_mask:0xf
	v_fmac_f32_dpp v203, v13, v129 row_shl:1 row_mask:0xf bank_mask:0xf
	v_fmac_f32_dpp v204, v14, v130 row_shl:1 row_mask:0xf bank_mask:0xf
	v_fmac_f32_dpp v205, v15, v131 row_shl:1 row_mask:0xf bank_mask:0xf
	v_fmac_f32_e32 v202, v194, v222
	v_fmac_f32_e32 v203, v195, v223
	v_fmac_f32_e32 v204, v196, v224
	v_fmac_f32_e32 v205, v197, v225
	v_fma_f32 v206, v164, v4, v182
	v_fma_f32 v207, v165, v5, v183
	v_fma_f32 v208, v166, v6, v184
	v_fma_f32 v209, v167, v7, v185
	v_fmac_f32_dpp v206, v4, v160 row_shr:1 row_mask:0xf bank_mask:0xf
	v_fmac_f32_dpp v207, v5, v161 row_shr:1 row_mask:0xf bank_mask:0xf
	v_fmac_f32_dpp v208, v6, v162 row_shr:1 row_mask:0xf bank_mask:0xf
	v_fmac_f32_dpp v209, v7, v163 row_shr:1 row_mask:0xf bank_mask:0xf
	v_fmac_f32_dpp v206, v20, v226 row_ror:1 row_mask:0xf bank_mask:0xf
	v_fmac_f32_dpp v207, v21, v227 row_ror:1 row_mask:0xf bank_mask:0xf
	v_fmac_f32_dpp v208, v22, v228 row_ror:1 row_mask:0xf bank_mask:0xf
	v_fmac_f32_dpp v209, v23, v229 row_ror:1 row_mask:0xf bank_mask:0xf
	v_fmac_f32_dpp v206, v4, v178 row_shl:1 row_mask:0xf bank_mask:0xf
	v_fmac_f32_dpp v207, v5, v179 row_shl:1 row_mask:0xf bank_mask:0xf
	v_fmac_f32_dpp v208, v6, v180 row_shl:1 row_mask:0xf bank_mask:0xf
	v_fmac_f32_dpp v209, v7, v181 row_shl:1 row_mask:0xf bank_mask:0xf
	v_fmac_f32_e32 v206, v198, v232
	v_fmac_f32_e32 v207, v199, v233
	v_fmac_f32_e32 v208, v200, v234
	v_fmac_f32_e32 v209, v201, v235
	s_mov_b64 exec, s[94:95]
	v_add_u32_e32 v250, 0x10800, v177
	global_store_dwordx4 v250, v[202:205], s[98:99]
	v_add_u32_e32 v250, 0x13400, v177
	global_store_dwordx4 v250, v[206:209], s[98:99]
	s_mov_b64 exec, s[90:91]
	s_nop 4
	v_mul_f32_e32 v210, 0xbfb8aa3b, v202
	v_mul_f32_e32 v211, 0xbfb8aa3b, v203
	v_mul_f32_e32 v212, 0xbfb8aa3b, v204
	v_mul_f32_e32 v213, 0xbfb8aa3b, v205
	v_exp_f32_e32 v210, v210
	v_exp_f32_e32 v211, v211
	v_exp_f32_e32 v212, v212
	v_exp_f32_e32 v213, v213
	v_add_f32_e32 v210, 1.0, v210
	v_add_f32_e32 v211, 1.0, v211
	v_add_f32_e32 v212, 1.0, v212
	v_add_f32_e32 v213, 1.0, v213
	v_rcp_f32_e32 v210, v210
	v_rcp_f32_e32 v211, v211
	v_rcp_f32_e32 v212, v212
	v_rcp_f32_e32 v213, v213
	v_mul_f32_e32 v202, v202, v210
	v_mul_f32_e32 v203, v203, v211
	v_mul_f32_e32 v204, v204, v212
	v_mul_f32_e32 v205, v205, v213
	v_mul_f32_e32 v202, v202, v206
	v_mul_f32_e32 v203, v203, v207
	v_mul_f32_e32 v204, v204, v208
	v_mul_f32_e32 v205, v205, v209
	v_cvt_pk_bf16_f32 v250, v202, v203
	v_cvt_pk_bf16_f32 v251, v204, v205
	global_load_dwordx4 v[116:119], v177, s[2:3] offset:16
	v_add_u32_e32 v213, 0x5800, v177
	global_load_dwordx4 v[124:127], v213, s[2:3] offset:16
	v_add_u32_e32 v212, 0xb000, v177
	global_load_dwordx4 v[128:131], v212, s[2:3] offset:16
	global_load_dwordx4 v[132:135], v177, s[28:29] offset:16
	v_add_u32_e32 v212, 0x2c00, v177
	global_load_dwordx4 v[160:163], v212, s[2:3] offset:16
	v_add_u32_e32 v213, 0x8400, v177
	global_load_dwordx4 v[164:167], v213, s[2:3] offset:16
	v_add_u32_e32 v212, 0xdc00, v177
	global_load_dwordx4 v[178:181], v212, s[2:3] offset:16
	v_add_u32_e32 v213, 0x2c00, v177
	global_load_dwordx4 v[182:185], v213, s[28:29] offset:16
	v_mov_b32_e32 v140, v236
	v_mov_b32_e32 v141, v237
	v_mov_b32_e32 v108, v238
	v_mov_b32_e32 v109, v239
	v_mov_b32_e32 v92, v240
	v_mov_b32_e32 v93, v241
	v_mov_b32_e32 v76, v242
	v_mov_b32_e32 v77, v243
	v_mov_b32_e32 v60, v244
	v_mov_b32_e32 v61, v245
	v_mov_b32_e32 v44, v246
	v_mov_b32_e32 v45, v247
	v_mov_b32_e32 v28, v248
	v_mov_b32_e32 v29, v249
	v_mov_b32_e32 v12, v250
	v_mov_b32_e32 v13, v251
	ds_read_b128 v[186:189], v231 offset:16
	ds_read_b128 v[190:193], v231 offset:528
	ds_read_b128 v[194:197], v231 offset:2064
	ds_read_b128 v[198:201], v231 offset:2576
	s_waitcnt vmcnt(0)
	v_cndmask_b32_e64 v218, 0, v116, s[78:79]
	v_cndmask_b32_e64 v222, 0, v128, s[80:81]
	v_cndmask_b32_e64 v219, 0, v117, s[78:79]
	v_cndmask_b32_e64 v223, 0, v129, s[80:81]
	v_cndmask_b32_e64 v220, 0, v118, s[78:79]
	v_cndmask_b32_e64 v224, 0, v130, s[80:81]
	v_cndmask_b32_e64 v221, 0, v119, s[78:79]
	v_cndmask_b32_e64 v225, 0, v131, s[80:81]
	v_cndmask_b32_e64 v226, 0, v160, s[78:79]
	v_cndmask_b32_e64 v232, 0, v178, s[80:81]
	v_cndmask_b32_e64 v227, 0, v161, s[78:79]
	v_cndmask_b32_e64 v233, 0, v179, s[80:81]
	v_cndmask_b32_e64 v228, 0, v162, s[78:79]
	v_cndmask_b32_e64 v234, 0, v180, s[80:81]
	v_cndmask_b32_e64 v229, 0, v163, s[78:79]
	v_cndmask_b32_e64 v235, 0, v181, s[80:81]
	s_waitcnt lgkmcnt(0)
	s_nop 1
	v_fma_f32 v202, v124, v136, v132
	v_fma_f32 v203, v125, v137, v133
	v_fma_f32 v204, v126, v138, v134
	v_fma_f32 v205, v127, v139, v135
	v_fmac_f32_dpp v202, v136, v116 row_shr:1 row_mask:0xf bank_mask:0xf
	v_fmac_f32_dpp v203, v137, v117 row_shr:1 row_mask:0xf bank_mask:0xf
	v_fmac_f32_dpp v204, v138, v118 row_shr:1 row_mask:0xf bank_mask:0xf
	v_fmac_f32_dpp v205, v139, v119 row_shr:1 row_mask:0xf bank_mask:0xf
	v_fmac_f32_e32 v202, v186, v218
	v_fmac_f32_e32 v203, v187, v219
	v_fmac_f32_e32 v204, v188, v220
	v_fmac_f32_e32 v205, v189, v221
	v_fmac_f32_dpp v202, v136, v128 row_shl:1 row_mask:0xf bank_mask:0xf
	v_fmac_f32_dpp v203, v137, v129 row_shl:1 row_mask:0xf bank_mask:0xf
	v_fmac_f32_dpp v204, v138, v130 row_shl:1 row_mask:0xf bank_mask:0xf
	v_fmac_f32_dpp v205, v139, v131 row_shl:1 row_mask:0xf bank_mask:0xf
	v_fmac_f32_dpp v202, v104, v222 row_ror:15 row_mask:0xf bank_mask:0xf
	v_fmac_f32_dpp v203, v105, v223 row_ror:15 row_mask:0xf bank_mask:0xf
	v_fmac_f32_dpp v204, v106, v224 row_ror:15 row_mask:0xf bank_mask:0xf
	v_fmac_f32_dpp v205, v107, v225 row_ror:15 row_mask:0xf bank_mask:0xf
	v_fma_f32 v206, v164, v112, v182
	v_fma_f32 v207, v165, v113, v183
	v_fma_f32 v208, v166, v114, v184
	v_fma_f32 v209, v167, v115, v185
	v_fmac_f32_dpp v206, v112, v160 row_shr:1 row_mask:0xf bank_mask:0xf
	v_fmac_f32_dpp v207, v113, v161 row_shr:1 row_mask:0xf bank_mask:0xf
	v_fmac_f32_dpp v208, v114, v162 row_shr:1 row_mask:0xf bank_mask:0xf
	v_fmac_f32_dpp v209, v115, v163 row_shr:1 row_mask:0xf bank_mask:0xf
	v_fmac_f32_e32 v206, v190, v226
	v_fmac_f32_e32 v207, v191, v227
	v_fmac_f32_e32 v208, v192, v228
	v_fmac_f32_e32 v209, v193, v229
	v_fmac_f32_dpp v206, v112, v178 row_shl:1 row_mask:0xf bank_mask:0xf
	v_fmac_f32_dpp v207, v113, v179 row_shl:1 row_mask:0xf bank_mask:0xf
	v_fmac_f32_dpp v208, v114, v180 row_shl:1 row_mask:0xf bank_mask:0xf
	v_fmac_f32_dpp v209, v115, v181 row_shl:1 row_mask:0xf bank_mask:0xf
	v_fmac_f32_dpp v206, v96, v232 row_ror:15 row_mask:0xf bank_mask:0xf
	v_fmac_f32_dpp v207, v97, v233 row_ror:15 row_mask:0xf bank_mask:0xf
	v_fmac_f32_dpp v208, v98, v234 row_ror:15 row_mask:0xf bank_mask:0xf
	v_fmac_f32_dpp v209, v99, v235 row_ror:15 row_mask:0xf bank_mask:0xf
	s_mov_b64 exec, s[92:93]
	v_add_u32_e32 v250, 0x5800, v177
	global_store_dwordx4 v250, v[202:205], s[98:99] offset:16
	v_add_u32_e32 v250, 0x8400, v177
	global_store_dwordx4 v250, v[206:209], s[98:99] offset:16
	s_mov_b64 exec, s[90:91]
	s_nop 4
	v_mul_f32_e32 v210, 0xbfb8aa3b, v202
	v_mul_f32_e32 v211, 0xbfb8aa3b, v203
	v_mul_f32_e32 v212, 0xbfb8aa3b, v204
	v_mul_f32_e32 v213, 0xbfb8aa3b, v205
	v_exp_f32_e32 v210, v210
	v_exp_f32_e32 v211, v211
	v_exp_f32_e32 v212, v212
	v_exp_f32_e32 v213, v213
	v_add_f32_e32 v210, 1.0, v210
	v_add_f32_e32 v211, 1.0, v211
	v_add_f32_e32 v212, 1.0, v212
	v_add_f32_e32 v213, 1.0, v213
	v_rcp_f32_e32 v210, v210
	v_rcp_f32_e32 v211, v211
	v_rcp_f32_e32 v212, v212
	v_rcp_f32_e32 v213, v213
	v_mul_f32_e32 v202, v202, v210
	v_mul_f32_e32 v203, v203, v211
	v_mul_f32_e32 v204, v204, v212
	v_mul_f32_e32 v205, v205, v213
	v_mul_f32_e32 v202, v202, v206
	v_mul_f32_e32 v203, v203, v207
	v_mul_f32_e32 v204, v204, v208
	v_mul_f32_e32 v205, v205, v209
	v_cvt_pk_bf16_f32 v142, v202, v203
	v_cvt_pk_bf16_f32 v143, v204, v205
	v_fma_f32 v202, v124, v104, v132
	v_fma_f32 v203, v125, v105, v133
	v_fma_f32 v204, v126, v106, v134
	v_fma_f32 v205, v127, v107, v135
	v_fmac_f32_dpp v202, v104, v116 row_shr:1 row_mask:0xf bank_mask:0xf
	v_fmac_f32_dpp v203, v105, v117 row_shr:1 row_mask:0xf bank_mask:0xf
	v_fmac_f32_dpp v204, v106, v118 row_shr:1 row_mask:0xf bank_mask:0xf
	v_fmac_f32_dpp v205, v107, v119 row_shr:1 row_mask:0xf bank_mask:0xf
	v_fmac_f32_dpp v202, v136, v218 row_ror:1 row_mask:0xf bank_mask:0xf
	v_fmac_f32_dpp v203, v137, v219 row_ror:1 row_mask:0xf bank_mask:0xf
	v_fmac_f32_dpp v204, v138, v220 row_ror:1 row_mask:0xf bank_mask:0xf
	v_fmac_f32_dpp v205, v139, v221 row_ror:1 row_mask:0xf bank_mask:0xf
	v_fmac_f32_dpp v202, v104, v128 row_shl:1 row_mask:0xf bank_mask:0xf
	v_fmac_f32_dpp v203, v105, v129 row_shl:1 row_mask:0xf bank_mask:0xf
	v_fmac_f32_dpp v204, v106, v130 row_shl:1 row_mask:0xf bank_mask:0xf
	v_fmac_f32_dpp v205, v107, v131 row_shl:1 row_mask:0xf bank_mask:0xf
	v_fmac_f32_dpp v202, v88, v222 row_ror:15 row_mask:0xf bank_mask:0xf
	v_fmac_f32_dpp v203, v89, v223 row_ror:15 row_mask:0xf bank_mask:0xf
	v_fmac_f32_dpp v204, v90, v224 row_ror:15 row_mask:0xf bank_mask:0xf
	v_fmac_f32_dpp v205, v91, v225 row_ror:15 row_mask:0xf bank_mask:0xf
	v_fma_f32 v206, v164, v96, v182
	v_fma_f32 v207, v165, v97, v183
	v_fma_f32 v208, v166, v98, v184
	v_fma_f32 v209, v167, v99, v185
	v_fmac_f32_dpp v206, v96, v160 row_shr:1 row_mask:0xf bank_mask:0xf
	v_fmac_f32_dpp v207, v97, v161 row_shr:1 row_mask:0xf bank_mask:0xf
	v_fmac_f32_dpp v208, v98, v162 row_shr:1 row_mask:0xf bank_mask:0xf
	v_fmac_f32_dpp v209, v99, v163 row_shr:1 row_mask:0xf bank_mask:0xf
	v_fmac_f32_dpp v206, v112, v226 row_ror:1 row_mask:0xf bank_mask:0xf
	v_fmac_f32_dpp v207, v113, v227 row_ror:1 row_mask:0xf bank_mask:0xf
	v_fmac_f32_dpp v208, v114, v228 row_ror:1 row_mask:0xf bank_mask:0xf
	v_fmac_f32_dpp v209, v115, v229 row_ror:1 row_mask:0xf bank_mask:0xf
	v_fmac_f32_dpp v206, v96, v178 row_shl:1 row_mask:0xf bank_mask:0xf
	v_fmac_f32_dpp v207, v97, v179 row_shl:1 row_mask:0xf bank_mask:0xf
	v_fmac_f32_dpp v208, v98, v180 row_shl:1 row_mask:0xf bank_mask:0xf
	v_fmac_f32_dpp v209, v99, v181 row_shl:1 row_mask:0xf bank_mask:0xf
	v_fmac_f32_dpp v206, v80, v232 row_ror:15 row_mask:0xf bank_mask:0xf
	v_fmac_f32_dpp v207, v81, v233 row_ror:15 row_mask:0xf bank_mask:0xf
	v_fmac_f32_dpp v208, v82, v234 row_ror:15 row_mask:0xf bank_mask:0xf
	v_fmac_f32_dpp v209, v83, v235 row_ror:15 row_mask:0xf bank_mask:0xf
	v_mul_f32_e32 v210, 0xbfb8aa3b, v202
	v_mul_f32_e32 v211, 0xbfb8aa3b, v203
	v_mul_f32_e32 v212, 0xbfb8aa3b, v204
	v_mul_f32_e32 v213, 0xbfb8aa3b, v205
	v_exp_f32_e32 v210, v210
	v_exp_f32_e32 v211, v211
	v_exp_f32_e32 v212, v212
	v_exp_f32_e32 v213, v213
	v_add_f32_e32 v210, 1.0, v210
	v_add_f32_e32 v211, 1.0, v211
	v_add_f32_e32 v212, 1.0, v212
	v_add_f32_e32 v213, 1.0, v213
	v_rcp_f32_e32 v210, v210
	v_rcp_f32_e32 v211, v211
	v_rcp_f32_e32 v212, v212
	v_rcp_f32_e32 v213, v213
	v_mul_f32_e32 v202, v202, v210
	v_mul_f32_e32 v203, v203, v211
	v_mul_f32_e32 v204, v204, v212
	v_mul_f32_e32 v205, v205, v213
	v_mul_f32_e32 v202, v202, v206
	v_mul_f32_e32 v203, v203, v207
	v_mul_f32_e32 v204, v204, v208
	v_mul_f32_e32 v205, v205, v209
	v_cvt_pk_bf16_f32 v110, v202, v203
	v_cvt_pk_bf16_f32 v111, v204, v205
	v_fma_f32 v202, v124, v88, v132
	v_fma_f32 v203, v125, v89, v133
	v_fma_f32 v204, v126, v90, v134
	v_fma_f32 v205, v127, v91, v135
	v_fmac_f32_dpp v202, v88, v116 row_shr:1 row_mask:0xf bank_mask:0xf
	v_fmac_f32_dpp v203, v89, v117 row_shr:1 row_mask:0xf bank_mask:0xf
	v_fmac_f32_dpp v204, v90, v118 row_shr:1 row_mask:0xf bank_mask:0xf
	v_fmac_f32_dpp v205, v91, v119 row_shr:1 row_mask:0xf bank_mask:0xf
	v_fmac_f32_dpp v202, v104, v218 row_ror:1 row_mask:0xf bank_mask:0xf
	v_fmac_f32_dpp v203, v105, v219 row_ror:1 row_mask:0xf bank_mask:0xf
	v_fmac_f32_dpp v204, v106, v220 row_ror:1 row_mask:0xf bank_mask:0xf
	v_fmac_f32_dpp v205, v107, v221 row_ror:1 row_mask:0xf bank_mask:0xf
	v_fmac_f32_dpp v202, v88, v128 row_shl:1 row_mask:0xf bank_mask:0xf
	v_fmac_f32_dpp v203, v89, v129 row_shl:1 row_mask:0xf bank_mask:0xf
	v_fmac_f32_dpp v204, v90, v130 row_shl:1 row_mask:0xf bank_mask:0xf
	v_fmac_f32_dpp v205, v91, v131 row_shl:1 row_mask:0xf bank_mask:0xf
	v_fmac_f32_dpp v202, v72, v222 row_ror:15 row_mask:0xf bank_mask:0xf
	v_fmac_f32_dpp v203, v73, v223 row_ror:15 row_mask:0xf bank_mask:0xf
	v_fmac_f32_dpp v204, v74, v224 row_ror:15 row_mask:0xf bank_mask:0xf
	v_fmac_f32_dpp v205, v75, v225 row_ror:15 row_mask:0xf bank_mask:0xf
	v_fma_f32 v206, v164, v80, v182
	v_fma_f32 v207, v165, v81, v183
	v_fma_f32 v208, v166, v82, v184
	v_fma_f32 v209, v167, v83, v185
	v_fmac_f32_dpp v206, v80, v160 row_shr:1 row_mask:0xf bank_mask:0xf
	v_fmac_f32_dpp v207, v81, v161 row_shr:1 row_mask:0xf bank_mask:0xf
	v_fmac_f32_dpp v208, v82, v162 row_shr:1 row_mask:0xf bank_mask:0xf
	v_fmac_f32_dpp v209, v83, v163 row_shr:1 row_mask:0xf bank_mask:0xf
	v_fmac_f32_dpp v206, v96, v226 row_ror:1 row_mask:0xf bank_mask:0xf
	v_fmac_f32_dpp v207, v97, v227 row_ror:1 row_mask:0xf bank_mask:0xf
	v_fmac_f32_dpp v208, v98, v228 row_ror:1 row_mask:0xf bank_mask:0xf
	v_fmac_f32_dpp v209, v99, v229 row_ror:1 row_mask:0xf bank_mask:0xf
	v_fmac_f32_dpp v206, v80, v178 row_shl:1 row_mask:0xf bank_mask:0xf
	v_fmac_f32_dpp v207, v81, v179 row_shl:1 row_mask:0xf bank_mask:0xf
	v_fmac_f32_dpp v208, v82, v180 row_shl:1 row_mask:0xf bank_mask:0xf
	v_fmac_f32_dpp v209, v83, v181 row_shl:1 row_mask:0xf bank_mask:0xf
	v_fmac_f32_dpp v206, v64, v232 row_ror:15 row_mask:0xf bank_mask:0xf
	v_fmac_f32_dpp v207, v65, v233 row_ror:15 row_mask:0xf bank_mask:0xf
	v_fmac_f32_dpp v208, v66, v234 row_ror:15 row_mask:0xf bank_mask:0xf
	v_fmac_f32_dpp v209, v67, v235 row_ror:15 row_mask:0xf bank_mask:0xf
	v_mul_f32_e32 v210, 0xbfb8aa3b, v202
	v_mul_f32_e32 v211, 0xbfb8aa3b, v203
	v_mul_f32_e32 v212, 0xbfb8aa3b, v204
	v_mul_f32_e32 v213, 0xbfb8aa3b, v205
	v_exp_f32_e32 v210, v210
	v_exp_f32_e32 v211, v211
	v_exp_f32_e32 v212, v212
	v_exp_f32_e32 v213, v213
	v_add_f32_e32 v210, 1.0, v210
	v_add_f32_e32 v211, 1.0, v211
	v_add_f32_e32 v212, 1.0, v212
	v_add_f32_e32 v213, 1.0, v213
	v_rcp_f32_e32 v210, v210
	v_rcp_f32_e32 v211, v211
	v_rcp_f32_e32 v212, v212
	v_rcp_f32_e32 v213, v213
	v_mul_f32_e32 v202, v202, v210
	v_mul_f32_e32 v203, v203, v211
	v_mul_f32_e32 v204, v204, v212
	v_mul_f32_e32 v205, v205, v213
	v_mul_f32_e32 v202, v202, v206
	v_mul_f32_e32 v203, v203, v207
	v_mul_f32_e32 v204, v204, v208
	v_mul_f32_e32 v205, v205, v209
	v_cvt_pk_bf16_f32 v94, v202, v203
	v_cvt_pk_bf16_f32 v95, v204, v205
	v_fma_f32 v202, v124, v72, v132
	v_fma_f32 v203, v125, v73, v133
	v_fma_f32 v204, v126, v74, v134
	v_fma_f32 v205, v127, v75, v135
	v_fmac_f32_dpp v202, v72, v116 row_shr:1 row_mask:0xf bank_mask:0xf
	v_fmac_f32_dpp v203, v73, v117 row_shr:1 row_mask:0xf bank_mask:0xf
	v_fmac_f32_dpp v204, v74, v118 row_shr:1 row_mask:0xf bank_mask:0xf
	v_fmac_f32_dpp v205, v75, v119 row_shr:1 row_mask:0xf bank_mask:0xf
	v_fmac_f32_dpp v202, v88, v218 row_ror:1 row_mask:0xf bank_mask:0xf
	v_fmac_f32_dpp v203, v89, v219 row_ror:1 row_mask:0xf bank_mask:0xf
	v_fmac_f32_dpp v204, v90, v220 row_ror:1 row_mask:0xf bank_mask:0xf
	v_fmac_f32_dpp v205, v91, v221 row_ror:1 row_mask:0xf bank_mask:0xf
	v_fmac_f32_dpp v202, v72, v128 row_shl:1 row_mask:0xf bank_mask:0xf
	v_fmac_f32_dpp v203, v73, v129 row_shl:1 row_mask:0xf bank_mask:0xf
	v_fmac_f32_dpp v204, v74, v130 row_shl:1 row_mask:0xf bank_mask:0xf
	v_fmac_f32_dpp v205, v75, v131 row_shl:1 row_mask:0xf bank_mask:0xf
	v_fmac_f32_e32 v202, v186, v222
	v_fmac_f32_e32 v203, v187, v223
	v_fmac_f32_e32 v204, v188, v224
	v_fmac_f32_e32 v205, v189, v225
	v_fma_f32 v206, v164, v64, v182
	v_fma_f32 v207, v165, v65, v183
	v_fma_f32 v208, v166, v66, v184
	v_fma_f32 v209, v167, v67, v185
	v_fmac_f32_dpp v206, v64, v160 row_shr:1 row_mask:0xf bank_mask:0xf
	v_fmac_f32_dpp v207, v65, v161 row_shr:1 row_mask:0xf bank_mask:0xf
	v_fmac_f32_dpp v208, v66, v162 row_shr:1 row_mask:0xf bank_mask:0xf
	v_fmac_f32_dpp v209, v67, v163 row_shr:1 row_mask:0xf bank_mask:0xf
	v_fmac_f32_dpp v206, v80, v226 row_ror:1 row_mask:0xf bank_mask:0xf
	v_fmac_f32_dpp v207, v81, v227 row_ror:1 row_mask:0xf bank_mask:0xf
	v_fmac_f32_dpp v208, v82, v228 row_ror:1 row_mask:0xf bank_mask:0xf
	v_fmac_f32_dpp v209, v83, v229 row_ror:1 row_mask:0xf bank_mask:0xf
	v_fmac_f32_dpp v206, v64, v178 row_shl:1 row_mask:0xf bank_mask:0xf
	v_fmac_f32_dpp v207, v65, v179 row_shl:1 row_mask:0xf bank_mask:0xf
	v_fmac_f32_dpp v208, v66, v180 row_shl:1 row_mask:0xf bank_mask:0xf
	v_fmac_f32_dpp v209, v67, v181 row_shl:1 row_mask:0xf bank_mask:0xf
	v_fmac_f32_e32 v206, v190, v232
	v_fmac_f32_e32 v207, v191, v233
	v_fmac_f32_e32 v208, v192, v234
	v_fmac_f32_e32 v209, v193, v235
	v_mul_f32_e32 v210, 0xbfb8aa3b, v202
	v_mul_f32_e32 v211, 0xbfb8aa3b, v203
	v_mul_f32_e32 v212, 0xbfb8aa3b, v204
	v_mul_f32_e32 v213, 0xbfb8aa3b, v205
	v_exp_f32_e32 v210, v210
	v_exp_f32_e32 v211, v211
	v_exp_f32_e32 v212, v212
	v_exp_f32_e32 v213, v213
	v_add_f32_e32 v210, 1.0, v210
	v_add_f32_e32 v211, 1.0, v211
	v_add_f32_e32 v212, 1.0, v212
	v_add_f32_e32 v213, 1.0, v213
	v_rcp_f32_e32 v210, v210
	v_rcp_f32_e32 v211, v211
	v_rcp_f32_e32 v212, v212
	v_rcp_f32_e32 v213, v213
	v_mul_f32_e32 v202, v202, v210
	v_mul_f32_e32 v203, v203, v211
	v_mul_f32_e32 v204, v204, v212
	v_mul_f32_e32 v205, v205, v213
	v_mul_f32_e32 v202, v202, v206
	v_mul_f32_e32 v203, v203, v207
	v_mul_f32_e32 v204, v204, v208
	v_mul_f32_e32 v205, v205, v209
	v_cvt_pk_bf16_f32 v78, v202, v203
	v_cvt_pk_bf16_f32 v79, v204, v205
	v_fma_f32 v202, v124, v56, v132
	v_fma_f32 v203, v125, v57, v133
	v_fma_f32 v204, v126, v58, v134
	v_fma_f32 v205, v127, v59, v135
	v_fmac_f32_dpp v202, v56, v116 row_shr:1 row_mask:0xf bank_mask:0xf
	v_fmac_f32_dpp v203, v57, v117 row_shr:1 row_mask:0xf bank_mask:0xf
	v_fmac_f32_dpp v204, v58, v118 row_shr:1 row_mask:0xf bank_mask:0xf
	v_fmac_f32_dpp v205, v59, v119 row_shr:1 row_mask:0xf bank_mask:0xf
	v_fmac_f32_e32 v202, v194, v218
	v_fmac_f32_e32 v203, v195, v219
	v_fmac_f32_e32 v204, v196, v220
	v_fmac_f32_e32 v205, v197, v221
	v_fmac_f32_dpp v202, v56, v128 row_shl:1 row_mask:0xf bank_mask:0xf
	v_fmac_f32_dpp v203, v57, v129 row_shl:1 row_mask:0xf bank_mask:0xf
	v_fmac_f32_dpp v204, v58, v130 row_shl:1 row_mask:0xf bank_mask:0xf
	v_fmac_f32_dpp v205, v59, v131 row_shl:1 row_mask:0xf bank_mask:0xf
	v_fmac_f32_dpp v202, v40, v222 row_ror:15 row_mask:0xf bank_mask:0xf
	v_fmac_f32_dpp v203, v41, v223 row_ror:15 row_mask:0xf bank_mask:0xf
	v_fmac_f32_dpp v204, v42, v224 row_ror:15 row_mask:0xf bank_mask:0xf
	v_fmac_f32_dpp v205, v43, v225 row_ror:15 row_mask:0xf bank_mask:0xf
	v_fma_f32 v206, v164, v48, v182
	v_fma_f32 v207, v165, v49, v183
	v_fma_f32 v208, v166, v50, v184
	v_fma_f32 v209, v167, v51, v185
	v_fmac_f32_dpp v206, v48, v160 row_shr:1 row_mask:0xf bank_mask:0xf
	v_fmac_f32_dpp v207, v49, v161 row_shr:1 row_mask:0xf bank_mask:0xf
	v_fmac_f32_dpp v208, v50, v162 row_shr:1 row_mask:0xf bank_mask:0xf
	v_fmac_f32_dpp v209, v51, v163 row_shr:1 row_mask:0xf bank_mask:0xf
	v_fmac_f32_e32 v206, v198, v226
	v_fmac_f32_e32 v207, v199, v227
	v_fmac_f32_e32 v208, v200, v228
	v_fmac_f32_e32 v209, v201, v229
	v_fmac_f32_dpp v206, v48, v178 row_shl:1 row_mask:0xf bank_mask:0xf
	v_fmac_f32_dpp v207, v49, v179 row_shl:1 row_mask:0xf bank_mask:0xf
	v_fmac_f32_dpp v208, v50, v180 row_shl:1 row_mask:0xf bank_mask:0xf
	v_fmac_f32_dpp v209, v51, v181 row_shl:1 row_mask:0xf bank_mask:0xf
	v_fmac_f32_dpp v206, v32, v232 row_ror:15 row_mask:0xf bank_mask:0xf
	v_fmac_f32_dpp v207, v33, v233 row_ror:15 row_mask:0xf bank_mask:0xf
	v_fmac_f32_dpp v208, v34, v234 row_ror:15 row_mask:0xf bank_mask:0xf
	v_fmac_f32_dpp v209, v35, v235 row_ror:15 row_mask:0xf bank_mask:0xf
	v_mul_f32_e32 v210, 0xbfb8aa3b, v202
	v_mul_f32_e32 v211, 0xbfb8aa3b, v203
	v_mul_f32_e32 v212, 0xbfb8aa3b, v204
	v_mul_f32_e32 v213, 0xbfb8aa3b, v205
	v_exp_f32_e32 v210, v210
	v_exp_f32_e32 v211, v211
	v_exp_f32_e32 v212, v212
	v_exp_f32_e32 v213, v213
	v_add_f32_e32 v210, 1.0, v210
	v_add_f32_e32 v211, 1.0, v211
	v_add_f32_e32 v212, 1.0, v212
	v_add_f32_e32 v213, 1.0, v213
	v_rcp_f32_e32 v210, v210
	v_rcp_f32_e32 v211, v211
	v_rcp_f32_e32 v212, v212
	v_rcp_f32_e32 v213, v213
	v_mul_f32_e32 v202, v202, v210
	v_mul_f32_e32 v203, v203, v211
	v_mul_f32_e32 v204, v204, v212
	v_mul_f32_e32 v205, v205, v213
	v_mul_f32_e32 v202, v202, v206
	v_mul_f32_e32 v203, v203, v207
	v_mul_f32_e32 v204, v204, v208
	v_mul_f32_e32 v205, v205, v209
	v_cvt_pk_bf16_f32 v62, v202, v203
	v_cvt_pk_bf16_f32 v63, v204, v205
	v_fma_f32 v202, v124, v40, v132
	v_fma_f32 v203, v125, v41, v133
	v_fma_f32 v204, v126, v42, v134
	v_fma_f32 v205, v127, v43, v135
	v_fmac_f32_dpp v202, v40, v116 row_shr:1 row_mask:0xf bank_mask:0xf
	v_fmac_f32_dpp v203, v41, v117 row_shr:1 row_mask:0xf bank_mask:0xf
	v_fmac_f32_dpp v204, v42, v118 row_shr:1 row_mask:0xf bank_mask:0xf
	v_fmac_f32_dpp v205, v43, v119 row_shr:1 row_mask:0xf bank_mask:0xf
	v_fmac_f32_dpp v202, v56, v218 row_ror:1 row_mask:0xf bank_mask:0xf
	v_fmac_f32_dpp v203, v57, v219 row_ror:1 row_mask:0xf bank_mask:0xf
	v_fmac_f32_dpp v204, v58, v220 row_ror:1 row_mask:0xf bank_mask:0xf
	v_fmac_f32_dpp v205, v59, v221 row_ror:1 row_mask:0xf bank_mask:0xf
	v_fmac_f32_dpp v202, v40, v128 row_shl:1 row_mask:0xf bank_mask:0xf
	v_fmac_f32_dpp v203, v41, v129 row_shl:1 row_mask:0xf bank_mask:0xf
	v_fmac_f32_dpp v204, v42, v130 row_shl:1 row_mask:0xf bank_mask:0xf
	v_fmac_f32_dpp v205, v43, v131 row_shl:1 row_mask:0xf bank_mask:0xf
	v_fmac_f32_dpp v202, v24, v222 row_ror:15 row_mask:0xf bank_mask:0xf
	v_fmac_f32_dpp v203, v25, v223 row_ror:15 row_mask:0xf bank_mask:0xf
	v_fmac_f32_dpp v204, v26, v224 row_ror:15 row_mask:0xf bank_mask:0xf
	v_fmac_f32_dpp v205, v27, v225 row_ror:15 row_mask:0xf bank_mask:0xf
	v_fma_f32 v206, v164, v32, v182
	v_fma_f32 v207, v165, v33, v183
	v_fma_f32 v208, v166, v34, v184
	v_fma_f32 v209, v167, v35, v185
	v_fmac_f32_dpp v206, v32, v160 row_shr:1 row_mask:0xf bank_mask:0xf
	v_fmac_f32_dpp v207, v33, v161 row_shr:1 row_mask:0xf bank_mask:0xf
	v_fmac_f32_dpp v208, v34, v162 row_shr:1 row_mask:0xf bank_mask:0xf
	v_fmac_f32_dpp v209, v35, v163 row_shr:1 row_mask:0xf bank_mask:0xf
	v_fmac_f32_dpp v206, v48, v226 row_ror:1 row_mask:0xf bank_mask:0xf
	v_fmac_f32_dpp v207, v49, v227 row_ror:1 row_mask:0xf bank_mask:0xf
	v_fmac_f32_dpp v208, v50, v228 row_ror:1 row_mask:0xf bank_mask:0xf
	v_fmac_f32_dpp v209, v51, v229 row_ror:1 row_mask:0xf bank_mask:0xf
	v_fmac_f32_dpp v206, v32, v178 row_shl:1 row_mask:0xf bank_mask:0xf
	v_fmac_f32_dpp v207, v33, v179 row_shl:1 row_mask:0xf bank_mask:0xf
	v_fmac_f32_dpp v208, v34, v180 row_shl:1 row_mask:0xf bank_mask:0xf
	v_fmac_f32_dpp v209, v35, v181 row_shl:1 row_mask:0xf bank_mask:0xf
	v_fmac_f32_dpp v206, v16, v232 row_ror:15 row_mask:0xf bank_mask:0xf
	v_fmac_f32_dpp v207, v17, v233 row_ror:15 row_mask:0xf bank_mask:0xf
	v_fmac_f32_dpp v208, v18, v234 row_ror:15 row_mask:0xf bank_mask:0xf
	v_fmac_f32_dpp v209, v19, v235 row_ror:15 row_mask:0xf bank_mask:0xf
	v_mul_f32_e32 v210, 0xbfb8aa3b, v202
	v_mul_f32_e32 v211, 0xbfb8aa3b, v203
	v_mul_f32_e32 v212, 0xbfb8aa3b, v204
	v_mul_f32_e32 v213, 0xbfb8aa3b, v205
	v_exp_f32_e32 v210, v210
	v_exp_f32_e32 v211, v211
	v_exp_f32_e32 v212, v212
	v_exp_f32_e32 v213, v213
	v_add_f32_e32 v210, 1.0, v210
	v_add_f32_e32 v211, 1.0, v211
	v_add_f32_e32 v212, 1.0, v212
	v_add_f32_e32 v213, 1.0, v213
	v_rcp_f32_e32 v210, v210
	v_rcp_f32_e32 v211, v211
	v_rcp_f32_e32 v212, v212
	v_rcp_f32_e32 v213, v213
	v_mul_f32_e32 v202, v202, v210
	v_mul_f32_e32 v203, v203, v211
	v_mul_f32_e32 v204, v204, v212
	v_mul_f32_e32 v205, v205, v213
	v_mul_f32_e32 v202, v202, v206
	v_mul_f32_e32 v203, v203, v207
	v_mul_f32_e32 v204, v204, v208
	v_mul_f32_e32 v205, v205, v209
	v_cvt_pk_bf16_f32 v46, v202, v203
	v_cvt_pk_bf16_f32 v47, v204, v205
	v_fma_f32 v202, v124, v24, v132
	v_fma_f32 v203, v125, v25, v133
	v_fma_f32 v204, v126, v26, v134
	v_fma_f32 v205, v127, v27, v135
	v_fmac_f32_dpp v202, v24, v116 row_shr:1 row_mask:0xf bank_mask:0xf
	v_fmac_f32_dpp v203, v25, v117 row_shr:1 row_mask:0xf bank_mask:0xf
	v_fmac_f32_dpp v204, v26, v118 row_shr:1 row_mask:0xf bank_mask:0xf
	v_fmac_f32_dpp v205, v27, v119 row_shr:1 row_mask:0xf bank_mask:0xf
	v_fmac_f32_dpp v202, v40, v218 row_ror:1 row_mask:0xf bank_mask:0xf
	v_fmac_f32_dpp v203, v41, v219 row_ror:1 row_mask:0xf bank_mask:0xf
	v_fmac_f32_dpp v204, v42, v220 row_ror:1 row_mask:0xf bank_mask:0xf
	v_fmac_f32_dpp v205, v43, v221 row_ror:1 row_mask:0xf bank_mask:0xf
	v_fmac_f32_dpp v202, v24, v128 row_shl:1 row_mask:0xf bank_mask:0xf
	v_fmac_f32_dpp v203, v25, v129 row_shl:1 row_mask:0xf bank_mask:0xf
	v_fmac_f32_dpp v204, v26, v130 row_shl:1 row_mask:0xf bank_mask:0xf
	v_fmac_f32_dpp v205, v27, v131 row_shl:1 row_mask:0xf bank_mask:0xf
	v_fmac_f32_dpp v202, v8, v222 row_ror:15 row_mask:0xf bank_mask:0xf
	v_fmac_f32_dpp v203, v9, v223 row_ror:15 row_mask:0xf bank_mask:0xf
	v_fmac_f32_dpp v204, v10, v224 row_ror:15 row_mask:0xf bank_mask:0xf
	v_fmac_f32_dpp v205, v11, v225 row_ror:15 row_mask:0xf bank_mask:0xf
	v_fma_f32 v206, v164, v16, v182
	v_fma_f32 v207, v165, v17, v183
	v_fma_f32 v208, v166, v18, v184
	v_fma_f32 v209, v167, v19, v185
	v_fmac_f32_dpp v206, v16, v160 row_shr:1 row_mask:0xf bank_mask:0xf
	v_fmac_f32_dpp v207, v17, v161 row_shr:1 row_mask:0xf bank_mask:0xf
	v_fmac_f32_dpp v208, v18, v162 row_shr:1 row_mask:0xf bank_mask:0xf
	v_fmac_f32_dpp v209, v19, v163 row_shr:1 row_mask:0xf bank_mask:0xf
	v_fmac_f32_dpp v206, v32, v226 row_ror:1 row_mask:0xf bank_mask:0xf
	v_fmac_f32_dpp v207, v33, v227 row_ror:1 row_mask:0xf bank_mask:0xf
	v_fmac_f32_dpp v208, v34, v228 row_ror:1 row_mask:0xf bank_mask:0xf
	v_fmac_f32_dpp v209, v35, v229 row_ror:1 row_mask:0xf bank_mask:0xf
	v_fmac_f32_dpp v206, v16, v178 row_shl:1 row_mask:0xf bank_mask:0xf
	v_fmac_f32_dpp v207, v17, v179 row_shl:1 row_mask:0xf bank_mask:0xf
	v_fmac_f32_dpp v208, v18, v180 row_shl:1 row_mask:0xf bank_mask:0xf
	v_fmac_f32_dpp v209, v19, v181 row_shl:1 row_mask:0xf bank_mask:0xf
	v_fmac_f32_dpp v206, v0, v232 row_ror:15 row_mask:0xf bank_mask:0xf
	v_fmac_f32_dpp v207, v1, v233 row_ror:15 row_mask:0xf bank_mask:0xf
	v_fmac_f32_dpp v208, v2, v234 row_ror:15 row_mask:0xf bank_mask:0xf
	v_fmac_f32_dpp v209, v3, v235 row_ror:15 row_mask:0xf bank_mask:0xf
	v_mul_f32_e32 v210, 0xbfb8aa3b, v202
	v_mul_f32_e32 v211, 0xbfb8aa3b, v203
	v_mul_f32_e32 v212, 0xbfb8aa3b, v204
	v_mul_f32_e32 v213, 0xbfb8aa3b, v205
	v_exp_f32_e32 v210, v210
	v_exp_f32_e32 v211, v211
	v_exp_f32_e32 v212, v212
	v_exp_f32_e32 v213, v213
	v_add_f32_e32 v210, 1.0, v210
	v_add_f32_e32 v211, 1.0, v211
	v_add_f32_e32 v212, 1.0, v212
	v_add_f32_e32 v213, 1.0, v213
	v_rcp_f32_e32 v210, v210
	v_rcp_f32_e32 v211, v211
	v_rcp_f32_e32 v212, v212
	v_rcp_f32_e32 v213, v213
	v_mul_f32_e32 v202, v202, v210
	v_mul_f32_e32 v203, v203, v211
	v_mul_f32_e32 v204, v204, v212
	v_mul_f32_e32 v205, v205, v213
	v_mul_f32_e32 v202, v202, v206
	v_mul_f32_e32 v203, v203, v207
	v_mul_f32_e32 v204, v204, v208
	v_mul_f32_e32 v205, v205, v209
	v_cvt_pk_bf16_f32 v30, v202, v203
	v_cvt_pk_bf16_f32 v31, v204, v205
	v_fma_f32 v202, v124, v8, v132
	v_fma_f32 v203, v125, v9, v133
	v_fma_f32 v204, v126, v10, v134
	v_fma_f32 v205, v127, v11, v135
	v_fmac_f32_dpp v202, v8, v116 row_shr:1 row_mask:0xf bank_mask:0xf
	v_fmac_f32_dpp v203, v9, v117 row_shr:1 row_mask:0xf bank_mask:0xf
	v_fmac_f32_dpp v204, v10, v118 row_shr:1 row_mask:0xf bank_mask:0xf
	v_fmac_f32_dpp v205, v11, v119 row_shr:1 row_mask:0xf bank_mask:0xf
	v_fmac_f32_dpp v202, v24, v218 row_ror:1 row_mask:0xf bank_mask:0xf
	v_fmac_f32_dpp v203, v25, v219 row_ror:1 row_mask:0xf bank_mask:0xf
	v_fmac_f32_dpp v204, v26, v220 row_ror:1 row_mask:0xf bank_mask:0xf
	v_fmac_f32_dpp v205, v27, v221 row_ror:1 row_mask:0xf bank_mask:0xf
	v_fmac_f32_dpp v202, v8, v128 row_shl:1 row_mask:0xf bank_mask:0xf
	v_fmac_f32_dpp v203, v9, v129 row_shl:1 row_mask:0xf bank_mask:0xf
	v_fmac_f32_dpp v204, v10, v130 row_shl:1 row_mask:0xf bank_mask:0xf
	v_fmac_f32_dpp v205, v11, v131 row_shl:1 row_mask:0xf bank_mask:0xf
	v_fmac_f32_e32 v202, v194, v222
	v_fmac_f32_e32 v203, v195, v223
	v_fmac_f32_e32 v204, v196, v224
	v_fmac_f32_e32 v205, v197, v225
	v_fma_f32 v206, v164, v0, v182
	v_fma_f32 v207, v165, v1, v183
	v_fma_f32 v208, v166, v2, v184
	v_fma_f32 v209, v167, v3, v185
	v_fmac_f32_dpp v206, v0, v160 row_shr:1 row_mask:0xf bank_mask:0xf
	v_fmac_f32_dpp v207, v1, v161 row_shr:1 row_mask:0xf bank_mask:0xf
	v_fmac_f32_dpp v208, v2, v162 row_shr:1 row_mask:0xf bank_mask:0xf
	v_fmac_f32_dpp v209, v3, v163 row_shr:1 row_mask:0xf bank_mask:0xf
	v_fmac_f32_dpp v206, v16, v226 row_ror:1 row_mask:0xf bank_mask:0xf
	v_fmac_f32_dpp v207, v17, v227 row_ror:1 row_mask:0xf bank_mask:0xf
	v_fmac_f32_dpp v208, v18, v228 row_ror:1 row_mask:0xf bank_mask:0xf
	v_fmac_f32_dpp v209, v19, v229 row_ror:1 row_mask:0xf bank_mask:0xf
	v_fmac_f32_dpp v206, v0, v178 row_shl:1 row_mask:0xf bank_mask:0xf
	v_fmac_f32_dpp v207, v1, v179 row_shl:1 row_mask:0xf bank_mask:0xf
	v_fmac_f32_dpp v208, v2, v180 row_shl:1 row_mask:0xf bank_mask:0xf
	v_fmac_f32_dpp v209, v3, v181 row_shl:1 row_mask:0xf bank_mask:0xf
	v_fmac_f32_e32 v206, v198, v232
	v_fmac_f32_e32 v207, v199, v233
	v_fmac_f32_e32 v208, v200, v234
	v_fmac_f32_e32 v209, v201, v235
	s_mov_b64 exec, s[94:95]
	v_add_u32_e32 v250, 0x10800, v177
	global_store_dwordx4 v250, v[202:205], s[98:99] offset:16
	v_add_u32_e32 v250, 0x13400, v177
	global_store_dwordx4 v250, v[206:209], s[98:99] offset:16
	s_mov_b64 exec, s[90:91]
	s_nop 4
	v_mul_f32_e32 v210, 0xbfb8aa3b, v202
	v_mul_f32_e32 v211, 0xbfb8aa3b, v203
	v_mul_f32_e32 v212, 0xbfb8aa3b, v204
	v_mul_f32_e32 v213, 0xbfb8aa3b, v205
	v_exp_f32_e32 v210, v210
	v_exp_f32_e32 v211, v211
	v_exp_f32_e32 v212, v212
	v_exp_f32_e32 v213, v213
	v_add_f32_e32 v210, 1.0, v210
	v_add_f32_e32 v211, 1.0, v211
	v_add_f32_e32 v212, 1.0, v212
	v_add_f32_e32 v213, 1.0, v213
	v_rcp_f32_e32 v210, v210
	v_rcp_f32_e32 v211, v211
	v_rcp_f32_e32 v212, v212
	v_rcp_f32_e32 v213, v213
	v_mul_f32_e32 v202, v202, v210
	v_mul_f32_e32 v203, v203, v211
	v_mul_f32_e32 v204, v204, v212
	v_mul_f32_e32 v205, v205, v213
	v_mul_f32_e32 v202, v202, v206
	v_mul_f32_e32 v203, v203, v207
	v_mul_f32_e32 v204, v204, v208
	v_mul_f32_e32 v205, v205, v209
	v_cvt_pk_bf16_f32 v14, v202, v203
	v_cvt_pk_bf16_f32 v15, v204, v205
	global_store_dwordx4 v168, v[140:143], s[76:77]
	v_add_u32_e32 v250, 0x16000, v168
	global_store_dwordx4 v250, v[108:111], s[76:77]
	s_nop 0
	v_add_u32_e32 v250, 0x2c000, v168
	global_store_dwordx4 v250, v[92:95], s[76:77]
	s_nop 0
	v_add_u32_e32 v250, 0x42000, v168
	global_store_dwordx4 v250, v[76:79], s[76:77]
	s_nop 0
	v_add_u32_e32 v250, 0xb0000, v168
	global_store_dwordx4 v250, v[60:63], s[76:77]
	s_nop 0
	v_add_u32_e32 v250, 0xc6000, v168
	global_store_dwordx4 v250, v[44:47], s[76:77]
	s_nop 0
	v_add_u32_e32 v250, 0xdc000, v168
	global_store_dwordx4 v250, v[28:31], s[76:77]
	s_nop 0
	v_add_u32_e32 v250, 0xf2000, v168
	global_store_dwordx4 v250, v[12:15], s[76:77]
	s_nop 0
	s_mov_b64 s[4:5], -1
	s_and_b64 vcc, exec, s[6:7]
	s_cbranch_vccz .LBB0_963
	s_andn2_b64 vcc, exec, s[10:11]
	s_cbranch_vccnz .LBB0_962
	s_barrier
	s_branch .LBB0_962

.LBB0_1516:
	s_barrier
	s_waitcnt vmcnt(3)
	ds_write_b128 v228, v[68:71]
	s_waitcnt vmcnt(2)
	ds_write_b128 v229, v[64:67]
	s_waitcnt vmcnt(1)
	ds_write_b128 v231, v[72:75]
	s_waitcnt vmcnt(0)
	ds_write_b128 v232, v[76:79]
	s_waitcnt lgkmcnt(0)
	s_barrier
	ds_read_b128 v[0:3], v108
	ds_read_b128 v[32:35], v108 offset:32
	s_waitcnt lgkmcnt(1)
	v_mfma_f32_32x32x16_bf16 v[16:31], v[0:3], v[140:143], 0
	ds_read_b128 v[0:3], v108 offset:8704
	ds_read_b128 v[36:39], v108 offset:8736
	v_mov_b32_e32 v114, v107
	v_mov_b32_e32 v178, v109
	s_waitcnt lgkmcnt(1)
	v_mfma_f32_32x32x16_bf16 v[0:15], v[0:3], v[140:143], 0
	v_mfma_f32_32x32x16_bf16 v[16:31], v[32:35], v[136:139], v[16:31]
	s_waitcnt lgkmcnt(0)
	v_mfma_f32_32x32x16_bf16 v[0:15], v[36:39], v[136:139], v[0:15]
	ds_read_b128 v[32:35], v108 offset:64
	ds_read_b128 v[36:39], v108 offset:96
	s_waitcnt lgkmcnt(1)
	v_mfma_f32_32x32x16_bf16 v[16:31], v[32:35], v[132:135], v[16:31]
	ds_read_b128 v[32:35], v108 offset:8768
	ds_read_b128 v[40:43], v108 offset:8800
	s_waitcnt lgkmcnt(1)
	v_mfma_f32_32x32x16_bf16 v[0:15], v[32:35], v[132:135], v[0:15]
	v_lshl_add_u64 v[32:33], v[212:213], 0, s[48:49]
	v_lshl_add_u64 v[34:35], v[210:211], 0, s[48:49]
	global_load_dwordx4 v[68:71], v[32:33], off
	global_load_dwordx4 v[64:67], v[34:35], off
	s_waitcnt lgkmcnt(0)
	v_mfma_f32_32x32x16_bf16 v[0:15], v[40:43], v[128:131], v[0:15]
	v_mfma_f32_32x32x16_bf16 v[16:31], v[36:39], v[128:131], v[16:31]
	s_nop 11
	v_max_f32_e32 v32, v17, v1
	v_max_f32_e32 v33, v18, v2
	v_max3_f32 v32, v16, v0, v32
	v_max_f32_e32 v34, v19, v3
	v_max3_f32 v32, v32, v33, v34
	v_max_f32_e32 v33, v20, v4
	v_max_f32_e32 v34, v21, v5
	v_max3_f32 v32, v32, v33, v34
	v_max_f32_e32 v33, v22, v6
	v_max_f32_e32 v34, v23, v7
	v_max3_f32 v32, v32, v33, v34
	v_max_f32_e32 v33, v24, v8
	v_max_f32_e32 v34, v25, v9
	v_max3_f32 v32, v32, v33, v34
	v_max_f32_e32 v33, v26, v10
	v_max_f32_e32 v34, v27, v11
	v_max3_f32 v32, v32, v33, v34
	v_max_f32_e32 v33, v28, v12
	v_max_f32_e32 v34, v29, v13
	v_max3_f32 v32, v32, v33, v34
	v_max_f32_e32 v33, v30, v14
	v_max_f32_e32 v34, v31, v15
	v_max3_f32 v36, v32, v33, v34
	ds_bpermute_b32 v37, v223, v36
	v_lshl_add_u64 v[32:33], v[208:209], 0, s[48:49]
	v_lshl_add_u64 v[34:35], v[206:207], 0, s[48:49]
	global_load_dwordx4 v[72:75], v[32:33], off
	global_load_dwordx4 v[76:79], v[34:35], off
	ds_read_b128 v[32:35], v108 offset:128
	s_waitcnt lgkmcnt(1)
	v_max3_f32 v107, v114, v36, v37
	v_sub_f32_e32 v0, v0, v107
	v_exp_f32_e32 v117, v0
	v_sub_f32_e32 v0, v17, v107
	v_exp_f32_e32 v119, v0
	v_sub_f32_e32 v0, v1, v107
	v_exp_f32_e32 v121, v0
	v_sub_f32_e32 v0, v18, v107
	v_exp_f32_e32 v123, v0
	v_sub_f32_e32 v0, v2, v107
	v_exp_f32_e32 v125, v0
	v_sub_f32_e32 v0, v19, v107
	v_exp_f32_e32 v127, v0
	v_sub_f32_e32 v0, v3, v107
	v_sub_f32_e32 v16, v16, v107
	v_exp_f32_e32 v161, v0
	v_sub_f32_e32 v0, v20, v107
	v_exp_f32_e32 v115, v16
	v_exp_f32_e32 v163, v0
	ds_read_b128 v[0:3], v108 offset:8832
	ds_read_b128 v[16:19], v108 offset:160
	s_waitcnt lgkmcnt(2)
	v_mfma_f32_32x32x16_bf16 v[32:47], v[32:35], v[156:159], 0
	ds_read_b128 v[110:113], v108 offset:8864
	v_sub_f32_e32 v4, v4, v107
	v_exp_f32_e32 v165, v4
	v_sub_f32_e32 v4, v21, v107
	v_exp_f32_e32 v21, v4
	v_sub_f32_e32 v4, v5, v107
	v_exp_f32_e32 v167, v4
	s_waitcnt lgkmcnt(2)
	v_mfma_f32_32x32x16_bf16 v[48:63], v[0:3], v[156:159], 0
	v_sub_f32_e32 v0, v22, v107
	v_exp_f32_e32 v169, v0
	v_sub_f32_e32 v0, v6, v107
	v_exp_f32_e32 v171, v0
	v_sub_f32_e32 v0, v23, v107
	v_exp_f32_e32 v23, v0
	v_sub_f32_e32 v0, v7, v107
	v_exp_f32_e32 v173, v0
	v_sub_f32_e32 v0, v24, v107
	v_exp_f32_e32 v175, v0
	v_sub_f32_e32 v0, v8, v107
	v_exp_f32_e32 v177, v0
	ds_read_b128 v[0:3], v108 offset:192
	s_waitcnt lgkmcnt(2)
	v_mfma_f32_32x32x16_bf16 v[32:47], v[16:19], v[152:155], v[32:47]
	v_sub_f32_e32 v4, v25, v107
	v_exp_f32_e32 v25, v4
	v_sub_f32_e32 v4, v9, v107
	v_exp_f32_e32 v9, v4
	v_sub_f32_e32 v4, v26, v107
	s_add_u32 s48, s48, 0x8000
	s_addc_u32 s49, s49, 0
	s_waitcnt lgkmcnt(1)
	v_mfma_f32_32x32x16_bf16 v[48:63], v[110:113], v[152:155], v[48:63]
	v_exp_f32_e32 v111, v4
	ds_read_b128 v[4:7], v108 offset:8896
	ds_read_b128 v[16:19], v108 offset:224
	s_cmp_eq_u32 s4, s48
	s_waitcnt lgkmcnt(2)
	v_mfma_f32_32x32x16_bf16 v[32:47], v[0:3], v[148:151], v[32:47]
	v_sub_f32_e32 v0, v10, v107
	v_exp_f32_e32 v113, v0
	v_sub_f32_e32 v0, v27, v107
	v_exp_f32_e32 v27, v0
	v_sub_f32_e32 v0, v11, v107
	v_exp_f32_e32 v11, v0
	ds_read_b128 v[0:3], v108 offset:8928
	s_waitcnt lgkmcnt(2)
	v_mfma_f32_32x32x16_bf16 v[48:63], v[4:7], v[148:151], v[48:63]
	v_sub_f32_e32 v4, v28, v107
	v_exp_f32_e32 v5, v4
	v_sub_f32_e32 v4, v12, v107
	v_exp_f32_e32 v7, v4
	v_sub_f32_e32 v4, v29, v107
	v_exp_f32_e32 v29, v4
	v_sub_f32_e32 v4, v13, v107
	s_waitcnt lgkmcnt(1)
	v_mfma_f32_32x32x16_bf16 v[32:47], v[16:19], v[144:147], v[32:47]
	v_exp_f32_e32 v13, v4
	v_sub_f32_e32 v4, v30, v107
	v_exp_f32_e32 v17, v4
	v_sub_f32_e32 v4, v14, v107
	v_exp_f32_e32 v19, v4
	v_sub_f32_e32 v4, v31, v107
	v_exp_f32_e32 v31, v4
	s_waitcnt lgkmcnt(0)
	v_mfma_f32_32x32x16_bf16 v[48:63], v[0:3], v[144:147], v[48:63]
	s_nop 2
	s_nop 8
	v_max_f32_e32 v0, v33, v49
	v_max_f32_e32 v1, v34, v50
	v_max3_f32 v0, v32, v48, v0
	v_max_f32_e32 v2, v35, v51
	v_max3_f32 v0, v0, v1, v2
	v_max_f32_e32 v1, v36, v52
	v_max_f32_e32 v2, v37, v53
	v_max3_f32 v0, v0, v1, v2
	v_max_f32_e32 v1, v38, v54
	v_max_f32_e32 v2, v39, v55
	v_max3_f32 v0, v0, v1, v2
	v_max_f32_e32 v1, v40, v56
	v_max_f32_e32 v2, v41, v57
	v_max3_f32 v0, v0, v1, v2
	v_max_f32_e32 v1, v42, v58
	v_max_f32_e32 v2, v43, v59
	v_max3_f32 v0, v0, v1, v2
	v_max_f32_e32 v1, v44, v60
	v_max_f32_e32 v2, v45, v61
	v_max3_f32 v0, v0, v1, v2
	v_max_f32_e32 v1, v46, v62
	v_max_f32_e32 v2, v47, v63
	v_max3_f32 v0, v0, v1, v2
	ds_bpermute_b32 v2, v223, v0
	v_sub_f32_e32 v3, v114, v107
	v_sub_f32_e32 v1, v15, v107
	v_exp_f32_e32 v1, v1
	v_exp_f32_e32 v3, v3
	s_waitcnt lgkmcnt(0)
	v_max3_f32 v109, v178, v0, v2
	v_sub_f32_e32 v0, v32, v109
	v_exp_f32_e32 v114, v0
	v_sub_f32_e32 v0, v48, v109
	v_exp_f32_e32 v116, v0
	v_sub_f32_e32 v0, v33, v109
	v_exp_f32_e32 v118, v0
	v_sub_f32_e32 v0, v49, v109
	v_exp_f32_e32 v120, v0
	v_sub_f32_e32 v0, v34, v109
	v_exp_f32_e32 v122, v0
	v_sub_f32_e32 v0, v50, v109
	v_exp_f32_e32 v124, v0
	v_sub_f32_e32 v0, v35, v109
	v_exp_f32_e32 v126, v0
	v_sub_f32_e32 v0, v51, v109
	v_exp_f32_e32 v160, v0
	v_sub_f32_e32 v0, v36, v109
	v_exp_f32_e32 v162, v0
	v_sub_f32_e32 v0, v52, v109
	v_exp_f32_e32 v164, v0
	v_sub_f32_e32 v0, v37, v109
	v_exp_f32_e32 v20, v0
	v_sub_f32_e32 v0, v53, v109
	v_exp_f32_e32 v166, v0
	v_sub_f32_e32 v0, v38, v109
	v_exp_f32_e32 v168, v0
	v_sub_f32_e32 v0, v54, v109
	v_exp_f32_e32 v170, v0
	v_sub_f32_e32 v0, v39, v109
	v_exp_f32_e32 v22, v0
	v_sub_f32_e32 v0, v55, v109
	v_exp_f32_e32 v172, v0
	v_sub_f32_e32 v0, v40, v109
	v_exp_f32_e32 v174, v0
	v_sub_f32_e32 v0, v56, v109
	v_exp_f32_e32 v176, v0
	v_sub_f32_e32 v0, v41, v109
	v_exp_f32_e32 v24, v0
	v_sub_f32_e32 v0, v57, v109
	v_exp_f32_e32 v8, v0
	v_sub_f32_e32 v0, v42, v109
	v_pk_add_f32 v[14:15], v[114:115], v[116:117]
	v_exp_f32_e32 v110, v0
	v_sub_f32_e32 v0, v58, v109
	v_pk_add_f32 v[14:15], v[14:15], 0 op_sel_hi:[1,0]
	v_pk_add_f32 v[32:33], v[118:119], v[120:121]
	v_exp_f32_e32 v112, v0
	v_sub_f32_e32 v0, v43, v109
	v_pk_add_f32 v[14:15], v[32:33], v[14:15]
	v_pk_add_f32 v[32:33], v[122:123], v[124:125]
	v_exp_f32_e32 v26, v0
	v_sub_f32_e32 v0, v59, v109
	v_pk_add_f32 v[14:15], v[32:33], v[14:15]
	v_pk_add_f32 v[32:33], v[126:127], v[160:161]
	v_exp_f32_e32 v10, v0
	v_sub_f32_e32 v0, v44, v109
	v_pk_add_f32 v[14:15], v[32:33], v[14:15]
	v_pk_add_f32 v[32:33], v[162:163], v[164:165]
	v_exp_f32_e32 v4, v0
	v_sub_f32_e32 v0, v60, v109
	v_pk_add_f32 v[14:15], v[32:33], v[14:15]
	v_pk_add_f32 v[20:21], v[20:21], v[166:167]
	v_exp_f32_e32 v6, v0
	v_sub_f32_e32 v0, v45, v109
	v_pk_add_f32 v[14:15], v[20:21], v[14:15]
	v_pk_add_f32 v[20:21], v[168:169], v[170:171]
	v_exp_f32_e32 v28, v0
	v_sub_f32_e32 v0, v61, v109
	v_exp_f32_e32 v12, v0
	v_sub_f32_e32 v0, v46, v109
	v_pk_add_f32 v[14:15], v[20:21], v[14:15]
	v_pk_add_f32 v[20:21], v[22:23], v[172:173]
	v_exp_f32_e32 v16, v0
	v_sub_f32_e32 v0, v62, v109
	v_pk_add_f32 v[14:15], v[20:21], v[14:15]
	v_pk_add_f32 v[20:21], v[174:175], v[176:177]
	v_exp_f32_e32 v18, v0
	v_sub_f32_e32 v0, v47, v109
	v_pk_add_f32 v[14:15], v[20:21], v[14:15]
	v_pk_add_f32 v[8:9], v[24:25], v[8:9]
	v_exp_f32_e32 v30, v0
	v_sub_f32_e32 v0, v63, v109
	v_pk_add_f32 v[8:9], v[8:9], v[14:15]
	v_pk_add_f32 v[14:15], v[110:111], v[112:113]
	v_exp_f32_e32 v0, v0
	v_pk_add_f32 v[8:9], v[14:15], v[8:9]
	v_pk_add_f32 v[10:11], v[26:27], v[10:11]
	v_sub_f32_e32 v2, v178, v109
	v_pk_add_f32 v[8:9], v[10:11], v[8:9]
	v_pk_add_f32 v[4:5], v[4:5], v[6:7]
	v_exp_f32_e32 v2, v2
	v_pk_add_f32 v[4:5], v[4:5], v[8:9]
	v_pk_add_f32 v[6:7], v[28:29], v[12:13]
	v_pk_add_f32 v[0:1], v[30:31], v[0:1]
	v_pk_add_f32 v[4:5], v[6:7], v[4:5]
	v_pk_add_f32 v[6:7], v[16:17], v[18:19]
	s_nop 0
	v_pk_add_f32 v[4:5], v[6:7], v[4:5]
	s_nop 0
	v_pk_add_f32 v[0:1], v[0:1], v[4:5]
	s_nop 0
	v_pk_fma_f32 v[96:97], v[96:97], v[2:3], v[0:1]
	s_cbranch_scc0 .LBB0_1516
	s_barrier
	s_waitcnt vmcnt(3)
	ds_write_b128 v228, v[68:71]
	s_waitcnt vmcnt(2)
	ds_write_b128 v229, v[64:67]
	s_waitcnt vmcnt(1)
	ds_write_b128 v231, v[72:75]
	s_waitcnt vmcnt(0)
	ds_write_b128 v232, v[76:79]
	s_waitcnt lgkmcnt(0)
	s_barrier
	ds_read_b128 v[0:3], v108
	ds_read_b128 v[32:35], v108 offset:32
	s_waitcnt lgkmcnt(1)
	v_mfma_f32_32x32x16_bf16 v[16:31], v[0:3], v[140:143], 0
	ds_read_b128 v[0:3], v108 offset:8704
	ds_read_b128 v[36:39], v108 offset:8736
	v_cmp_ne_u32_e32 vcc, 0, v105
	s_waitcnt lgkmcnt(1)
	v_mfma_f32_32x32x16_bf16 v[0:15], v[0:3], v[140:143], 0
	v_mfma_f32_32x32x16_bf16 v[16:31], v[32:35], v[136:139], v[16:31]
	s_waitcnt lgkmcnt(0)
	v_mfma_f32_32x32x16_bf16 v[0:15], v[36:39], v[136:139], v[0:15]
	ds_read_b128 v[32:35], v108 offset:64
	ds_read_b128 v[36:39], v108 offset:96
	s_waitcnt lgkmcnt(1)
	v_mfma_f32_32x32x16_bf16 v[16:31], v[32:35], v[132:135], v[16:31]
	ds_read_b128 v[32:35], v108 offset:8768
	ds_read_b128 v[40:43], v108 offset:8800
	s_waitcnt lgkmcnt(1)
	v_mfma_f32_32x32x16_bf16 v[0:15], v[32:35], v[132:135], v[0:15]
	s_waitcnt lgkmcnt(0)
	v_mfma_f32_32x32x16_bf16 v[0:15], v[40:43], v[128:131], v[0:15]
	v_mfma_f32_32x32x16_bf16 v[16:31], v[36:39], v[128:131], v[16:31]
	s_nop 11
	v_max_f32_e32 v32, v17, v1
	v_max_f32_e32 v33, v18, v2
	v_max3_f32 v32, v16, v0, v32
	v_max_f32_e32 v34, v19, v3
	v_max3_f32 v32, v32, v33, v34
	v_max_f32_e32 v33, v20, v4
	v_max_f32_e32 v34, v21, v5
	v_max3_f32 v32, v32, v33, v34
	v_max_f32_e32 v33, v22, v6
	v_max_f32_e32 v34, v23, v7
	v_max3_f32 v32, v32, v33, v34
	v_max_f32_e32 v33, v24, v8
	v_max_f32_e32 v34, v25, v9
	v_max3_f32 v32, v32, v33, v34
	v_max_f32_e32 v33, v26, v10
	v_max_f32_e32 v34, v27, v11
	v_max3_f32 v32, v32, v33, v34
	v_max_f32_e32 v33, v28, v12
	v_max_f32_e32 v34, v29, v13
	v_max3_f32 v32, v32, v33, v34
	v_max_f32_e32 v33, v30, v14
	v_max_f32_e32 v34, v31, v15
	v_max3_f32 v32, v32, v33, v34
	ds_bpermute_b32 v33, v223, v32
	s_waitcnt lgkmcnt(0)
	v_max3_f32 v64, v107, v32, v33
	v_sub_f32_e32 v16, v16, v64
	v_sub_f32_e32 v0, v0, v64
	v_exp_f32_e32 v16, v16
	v_exp_f32_e32 v0, v0
	v_sub_f32_e32 v1, v1, v64
	v_exp_f32_e32 v1, v1
	v_sub_f32_e32 v2, v2, v64
	v_add_f32_e32 v0, v16, v0
	v_sub_f32_e32 v16, v17, v64
	v_exp_f32_e32 v16, v16
	v_sub_f32_e32 v17, v18, v64
	v_exp_f32_e32 v17, v17
	v_exp_f32_e32 v2, v2
	v_add_f32_e32 v0, 0, v0
	v_add_f32_e32 v1, v16, v1
	v_add_f32_e32 v0, v1, v0
	v_add_f32_e32 v1, v17, v2
	v_sub_f32_e32 v2, v19, v64
	v_sub_f32_e32 v3, v3, v64
	v_exp_f32_e32 v2, v2
	v_exp_f32_e32 v3, v3
	v_sub_f32_e32 v16, v20, v64
	v_sub_f32_e32 v4, v4, v64
	v_exp_f32_e32 v16, v16
	v_exp_f32_e32 v4, v4
	v_add_f32_e32 v0, v1, v0
	v_add_f32_e32 v1, v2, v3
	v_sub_f32_e32 v2, v21, v64
	v_sub_f32_e32 v3, v5, v64
	v_exp_f32_e32 v2, v2
	v_exp_f32_e32 v3, v3
	v_add_f32_e32 v0, v1, v0
	v_add_f32_e32 v1, v16, v4
	v_sub_f32_e32 v4, v22, v64
	v_sub_f32_e32 v5, v6, v64
	v_add_f32_e32 v0, v1, v0
	v_add_f32_e32 v1, v2, v3
	v_exp_f32_e32 v4, v4
	v_exp_f32_e32 v5, v5
	v_add_f32_e32 v20, v1, v0
	ds_read_b128 v[0:3], v108 offset:128
	s_waitcnt lgkmcnt(0)
	v_mfma_f32_32x32x16_bf16 v[32:47], v[0:3], v[156:159], 0
	v_add_f32_e32 v21, v4, v5
	v_sub_f32_e32 v4, v23, v64
	v_exp_f32_e32 v22, v4
	v_sub_f32_e32 v4, v7, v64
	v_exp_f32_e32 v23, v4
	v_sub_f32_e32 v4, v24, v64
	v_exp_f32_e32 v24, v4
	ds_read_b128 v[4:7], v108 offset:8832
	ds_read_b128 v[16:19], v108 offset:160
	v_sub_f32_e32 v8, v8, v64
	v_exp_f32_e32 v0, v8
	v_add_f32_e32 v1, v21, v20
	v_sub_f32_e32 v21, v25, v64
	s_waitcnt lgkmcnt(1)
	v_mfma_f32_32x32x16_bf16 v[48:63], v[4:7], v[156:159], 0
	v_sub_f32_e32 v5, v9, v64
	v_exp_f32_e32 v4, v21
	v_exp_f32_e32 v5, v5
	v_sub_f32_e32 v6, v26, v64
	v_sub_f32_e32 v7, v10, v64
	v_add_f32_e32 v2, v22, v23
	v_exp_f32_e32 v6, v6
	v_exp_f32_e32 v7, v7
	v_add_f32_e32 v8, v2, v1
	v_add_f32_e32 v20, v24, v0
	ds_read_b128 v[0:3], v108 offset:8864
	v_add_f32_e32 v8, v20, v8
	v_add_f32_e32 v4, v4, v5
	s_waitcnt lgkmcnt(1)
	v_mfma_f32_32x32x16_bf16 v[32:47], v[16:19], v[152:155], v[32:47]
	v_add_f32_e32 v16, v4, v8
	v_sub_f32_e32 v4, v27, v64
	v_add_f32_e32 v17, v6, v7
	v_exp_f32_e32 v18, v4
	ds_read_b128 v[4:7], v108 offset:192
	v_sub_f32_e32 v12, v12, v64
	s_waitcnt lgkmcnt(1)
	v_mfma_f32_32x32x16_bf16 v[48:63], v[0:3], v[152:155], v[48:63]
	v_sub_f32_e32 v0, v11, v64
	v_exp_f32_e32 v19, v0
	v_sub_f32_e32 v0, v28, v64
	v_exp_f32_e32 v20, v0
	ds_read_b128 v[0:3], v108 offset:8896
	ds_read_b128 v[8:11], v108 offset:224
	s_waitcnt lgkmcnt(2)
	v_mfma_f32_32x32x16_bf16 v[32:47], v[4:7], v[148:151], v[32:47]
	v_exp_f32_e32 v4, v12
	v_add_f32_e32 v5, v17, v16
	v_add_f32_e32 v6, v18, v19
	v_add_f32_e32 v12, v6, v5
	v_add_f32_e32 v16, v20, v4
	ds_read_b128 v[4:7], v108 offset:8928
	v_sub_f32_e32 v17, v29, v64
	s_waitcnt lgkmcnt(2)
	v_mfma_f32_32x32x16_bf16 v[48:63], v[0:3], v[148:151], v[48:63]
	v_sub_f32_e32 v1, v13, v64
	v_exp_f32_e32 v0, v17
	v_exp_f32_e32 v1, v1
	v_sub_f32_e32 v2, v30, v64
	v_sub_f32_e32 v3, v14, v64
	v_exp_f32_e32 v2, v2
	v_exp_f32_e32 v3, v3
	s_waitcnt lgkmcnt(1)
	v_mfma_f32_32x32x16_bf16 v[32:47], v[8:11], v[144:147], v[32:47]
	v_add_f32_e32 v8, v16, v12
	v_add_f32_e32 v0, v0, v1
	v_add_f32_e32 v0, v0, v8
	v_add_f32_e32 v1, v2, v3
	v_add_f32_e32 v1, v1, v0
	v_sub_f32_e32 v0, v31, v64
	v_exp_f32_e32 v2, v0
	s_waitcnt lgkmcnt(0)
	v_mfma_f32_32x32x16_bf16 v[48:63], v[4:7], v[144:147], v[48:63]
	s_nop 2
	s_nop 8
	v_max_f32_e32 v0, v33, v49
	v_max_f32_e32 v3, v34, v50
	v_max3_f32 v0, v32, v48, v0
	v_max_f32_e32 v4, v35, v51
	v_max3_f32 v0, v0, v3, v4
	v_max_f32_e32 v3, v36, v52
	v_max_f32_e32 v4, v37, v53
	v_max3_f32 v0, v0, v3, v4
	v_max_f32_e32 v3, v38, v54
	v_max_f32_e32 v4, v39, v55
	v_max3_f32 v0, v0, v3, v4
	v_max_f32_e32 v3, v40, v56
	v_max_f32_e32 v4, v41, v57
	v_max3_f32 v0, v0, v3, v4
	v_max_f32_e32 v3, v42, v58
	v_max_f32_e32 v4, v43, v59
	v_max3_f32 v0, v0, v3, v4
	v_max_f32_e32 v3, v44, v60
	v_max_f32_e32 v4, v45, v61
	v_max3_f32 v0, v0, v3, v4
	v_max_f32_e32 v3, v46, v62
	v_max_f32_e32 v4, v47, v63
	v_max3_f32 v0, v0, v3, v4
	ds_bpermute_b32 v3, v223, v0
	v_sub_f32_e32 v4, v15, v64
	v_exp_f32_e32 v4, v4
	v_sub_f32_e32 v5, v107, v64
	v_exp_f32_e32 v5, v5
	s_waitcnt lgkmcnt(0)
	v_max3_f32 v0, v109, v0, v3
	v_sub_f32_e32 v3, v32, v0
	v_sub_f32_e32 v6, v48, v0
	v_exp_f32_e32 v3, v3
	v_exp_f32_e32 v6, v6
	v_add_f32_e32 v2, v2, v4
	v_add_f32_e32 v1, v2, v1
	v_sub_f32_e32 v4, v49, v0
	v_add_f32_e32 v2, v3, v6
	v_sub_f32_e32 v3, v33, v0
	v_fmac_f32_e32 v1, v97, v5
	v_exp_f32_e32 v3, v3
	v_exp_f32_e32 v4, v4
	v_sub_f32_e32 v5, v34, v0
	v_sub_f32_e32 v6, v50, v0
	v_exp_f32_e32 v5, v5
	v_exp_f32_e32 v6, v6
	v_add_f32_e32 v2, 0, v2
	v_add_f32_e32 v3, v3, v4
	v_add_f32_e32 v2, v3, v2
	v_add_f32_e32 v3, v5, v6
	v_sub_f32_e32 v4, v35, v0
	v_sub_f32_e32 v5, v51, v0
	v_exp_f32_e32 v4, v4
	v_exp_f32_e32 v5, v5
	v_sub_f32_e32 v6, v36, v0
	v_sub_f32_e32 v7, v52, v0
	v_exp_f32_e32 v6, v6
	v_exp_f32_e32 v7, v7
	v_add_f32_e32 v2, v3, v2
	v_add_f32_e32 v3, v4, v5
	v_sub_f32_e32 v4, v37, v0
	v_sub_f32_e32 v5, v53, v0
	v_exp_f32_e32 v4, v4
	v_exp_f32_e32 v5, v5
	v_add_f32_e32 v2, v3, v2
	v_add_f32_e32 v3, v6, v7
	v_sub_f32_e32 v6, v38, v0
	v_sub_f32_e32 v7, v54, v0
	v_exp_f32_e32 v6, v6
	v_exp_f32_e32 v7, v7
	v_add_f32_e32 v2, v3, v2
	v_add_f32_e32 v3, v4, v5
	v_sub_f32_e32 v4, v39, v0
	v_sub_f32_e32 v5, v55, v0
	v_exp_f32_e32 v4, v4
	v_exp_f32_e32 v5, v5
	v_add_f32_e32 v2, v3, v2
	v_add_f32_e32 v3, v6, v7
	v_sub_f32_e32 v6, v40, v0
	v_sub_f32_e32 v7, v56, v0
	v_exp_f32_e32 v6, v6
	v_exp_f32_e32 v7, v7
	v_add_f32_e32 v2, v3, v2
	v_add_f32_e32 v3, v4, v5
	v_sub_f32_e32 v4, v41, v0
	v_sub_f32_e32 v5, v57, v0
	v_exp_f32_e32 v4, v4
	v_exp_f32_e32 v5, v5
	v_add_f32_e32 v2, v3, v2
	v_add_f32_e32 v3, v6, v7
	v_sub_f32_e32 v6, v42, v0
	v_sub_f32_e32 v7, v58, v0
	v_exp_f32_e32 v6, v6
	v_exp_f32_e32 v7, v7
	v_add_f32_e32 v2, v3, v2
	v_add_f32_e32 v3, v4, v5
	v_sub_f32_e32 v4, v43, v0
	v_sub_f32_e32 v5, v59, v0
	v_exp_f32_e32 v4, v4
	v_exp_f32_e32 v5, v5
	v_add_f32_e32 v2, v3, v2
	v_add_f32_e32 v3, v6, v7
	v_sub_f32_e32 v6, v44, v0
	v_sub_f32_e32 v7, v60, v0
	v_exp_f32_e32 v6, v6
	v_exp_f32_e32 v7, v7
	v_add_f32_e32 v2, v3, v2
	v_add_f32_e32 v3, v4, v5
	v_sub_f32_e32 v4, v45, v0
	v_sub_f32_e32 v5, v61, v0
	v_exp_f32_e32 v4, v4
	v_exp_f32_e32 v5, v5
	v_add_f32_e32 v2, v3, v2
	v_add_f32_e32 v3, v6, v7
	v_sub_f32_e32 v6, v46, v0
	v_sub_f32_e32 v7, v62, v0
	v_exp_f32_e32 v6, v6
	v_exp_f32_e32 v7, v7
	v_add_f32_e32 v2, v3, v2
	v_add_f32_e32 v3, v4, v5
	v_sub_f32_e32 v4, v47, v0
	v_sub_f32_e32 v5, v63, v0
	v_exp_f32_e32 v4, v4
	v_exp_f32_e32 v5, v5
	v_add_f32_e32 v2, v3, v2
	v_add_f32_e32 v3, v6, v7
	v_sub_f32_e32 v6, v109, v0
	v_exp_f32_e32 v6, v6
	v_add_f32_e32 v2, v3, v2
	v_add_f32_e32 v3, v4, v5
	v_add_f32_e32 v2, v3, v2
	v_fmac_f32_e32 v2, v96, v6
	ds_bpermute_b32 v4, v223, v1
	ds_bpermute_b32 v7, v223, v2
	v_lshlrev_b32_e32 v3, 1, v104
	v_lshlrev_b32_e32 v6, 3, v227
	v_lshlrev_b32_e32 v5, 3, v98
	s_and_saveexec_b64 s[4:5], vcc
	s_xor_b64 s[4:5], exec, s[4:5]
	v_lshlrev_b32_e32 v3, 1, v104
	v_lshlrev_b32_e32 v6, 3, v227
	v_lshlrev_b32_e32 v5, 3, v98
	s_or_saveexec_b64 s[4:5], s[4:5]
	s_waitcnt lgkmcnt(1)
	v_add_f32_e32 v4, v1, v4
	s_waitcnt lgkmcnt(0)
	v_add_f32_e32 v2, v2, v7
	s_xor_b64 exec, exec, s[4:5]
	s_cbranch_execz .LBB0_1521
	v_or_b32_e32 v1, v3, v6
	v_lshlrev_b32_e32 v1, 8, v1
	v_add3_u32 v7, s53, v5, v1
	v_mov_b32_e32 v65, v4
	v_mov_b32_e32 v1, v2
	ds_write2_b64 v7, v[64:65], v[0:1] offset1:32
.LBB0_1521:
	s_or_b64 exec, exec, s[4:5]
	s_add_u32 s4, s70, s42
	s_addc_u32 s5, s71, s43
	v_bfe_u32 v28, v205, 3, 7
	s_add_u32 s4, s4, s40
	v_and_b32_e32 v1, 56, v106
	v_mul_u32_u24_e32 v7, s44, v28
	v_and_b32_e32 v12, 0xffffffc0, v86
	v_bfe_u32 v29, v103, 3, 7
	s_addc_u32 s5, s5, s41
	v_lshlrev_b32_e32 v10, 1, v7
	v_mov_b32_e32 v11, v201
	v_ashrrev_i32_e32 v13, 31, v12
	v_lshlrev_b32_e32 v16, 1, v1
	v_mul_u32_u24_e32 v1, s44, v29
	v_and_b32_e32 v22, 0xffffffc0, v82
	v_lshl_add_u64 v[8:9], s[4:5], 0, v[10:11]
	v_lshlrev_b64 v[12:13], 1, v[12:13]
	v_lshlrev_b32_e32 v18, 1, v1
	v_mov_b32_e32 v19, v201
	v_ashrrev_i32_e32 v23, 31, v22
	v_lshl_add_u64 v[14:15], v[8:9], 0, v[12:13]
	v_mov_b32_e32 v17, v201
	v_lshl_add_u64 v[20:21], s[4:5], 0, v[18:19]
	v_lshlrev_b64 v[22:23], 1, v[22:23]
	v_lshl_add_u64 v[14:15], v[14:15], 0, v[16:17]
	v_lshl_add_u64 v[20:21], v[20:21], 0, v[22:23]
	global_load_dwordx4 v[168:171], v[88:89], off
	global_load_dwordx4 v[164:167], v[90:91], off
	global_load_dwordx4 v[160:163], v[92:93], off
	global_load_dwordx4 v[172:175], v[94:95], off
	v_lshl_add_u64 v[20:21], v[20:21], 0, v[16:17]
	global_load_dwordx4 v[176:179], v[14:15], off
	global_load_dwordx4 v[180:183], v[20:21], off
	v_and_b32_e32 v14, 0xffffffc0, v84
	v_bfe_u32 v30, v102, 3, 7
	v_ashrrev_i32_e32 v15, 31, v14
	v_mul_u32_u24_e32 v1, s44, v30
	v_and_b32_e32 v26, 0xffffffc0, v80
	v_lshlrev_b64 v[14:15], 1, v[14:15]
	v_lshlrev_b32_e32 v20, 1, v1
	v_mov_b32_e32 v21, v201
	v_ashrrev_i32_e32 v27, 31, v26
	v_lshl_add_u64 v[8:9], v[8:9], 0, v[14:15]
	v_lshl_add_u64 v[24:25], s[4:5], 0, v[20:21]
	v_lshlrev_b64 v[26:27], 1, v[26:27]
	v_lshl_add_u64 v[8:9], v[8:9], 0, v[16:17]
	v_lshl_add_u64 v[24:25], v[24:25], 0, v[26:27]
	v_lshl_add_u64 v[16:17], v[24:25], 0, v[16:17]
	global_load_dwordx4 v[184:187], v[8:9], off
	global_load_dwordx4 v[188:191], v[16:17], off
	v_sub_u32_e32 v1, v3, v6
	v_lshlrev_b32_e32 v1, 8, v1
	v_add3_u32 v1, s53, v5, v1
	v_add_u32_e32 v1, 0x800, v1
	s_waitcnt lgkmcnt(0)
	s_barrier
	ds_read2_b64 v[6:9], v1 offset1:32
	s_lshl_b32 s4, s57, 8
	s_add_u32 s4, s4, 0x100
	s_add_u32 s40, s40, s42
	s_waitcnt lgkmcnt(0)
	v_max_f32_e32 v24, v64, v6
	v_sub_f32_e32 v1, v64, v24
	v_exp_f32_e32 v16, v1
	v_sub_f32_e32 v1, v6, v24
	v_exp_f32_e32 v17, v1
	v_max_f32_e32 v3, v0, v0
	v_max_f32_e32 v6, v3, v8
	v_sub_f32_e32 v0, v0, v6
	v_sub_f32_e32 v1, v8, v6
	v_mov_b32_e32 v5, v7
	v_exp_f32_e32 v0, v0
	v_exp_f32_e32 v1, v1
	v_pk_mul_f32 v[4:5], v[4:5], v[16:17]
	s_addc_u32 s41, s41, s43
	v_add_f32_e32 v3, v4, v5
	v_log_f32_e32 v4, v3
	v_mov_b32_e32 v3, v9
	v_pk_mul_f32 v[0:1], v[2:3], v[0:1]
	v_add_u32_e32 v7, v101, v200
	v_add_f32_e32 v0, v0, v1
	v_log_f32_e32 v0, v0
	v_mul_i32_i24_e32 v1, 0x4800, v227
	v_add_f32_e32 v2, v24, v4
	v_add3_u32 v8, 0, v1, v204
	v_add_f32_e32 v0, v6, v0
	v_sub_f32_e32 v80, v224, v0
	v_mul_i32_i24_e32 v0, 0x4800, v81
	v_mul_u32_u24_e32 v1, 0x90, v28
	v_xor_b32_e32 v64, 0x80000000, v2
	v_add3_u32 v16, 0, v0, v1
	v_mul_i32_i24_e32 v0, 0x4800, v83
	v_mul_u32_u24_e32 v2, 0x90, v29
	v_add3_u32 v17, 0, v0, v2
	v_mul_i32_i24_e32 v0, 0x4800, v85
	v_add3_u32 v24, 0, v0, v1
	v_mul_i32_i24_e32 v0, 0x4800, v87
	v_mul_u32_u24_e32 v1, 0x90, v30
	v_add3_u32 v25, 0, v0, v1
	v_or_b32_e32 v0, 32, v98
	v_mul_u32_u24_e32 v28, 0x90, v0
	v_mul_u32_u24_e32 v29, 0x110, v0
	v_and_b32_e32 v0, 7, v205
	v_lshlrev_b32_e32 v0, 4, v0
	v_mov_b32_e32 v1, v201
	v_lshl_add_u64 v[0:1], s[40:41], 0, v[0:1]
	v_lshl_add_u64 v[2:3], v[0:1], 0, v[10:11]
	v_lshl_add_u64 v[4:5], v[2:3], 0, v[12:13]
	v_lshl_add_u64 v[2:3], v[2:3], 0, v[14:15]
	v_lshl_add_u64 v[216:217], s[22:23], 0, v[2:3]
	v_lshl_add_u64 v[2:3], v[0:1], 0, v[18:19]
	v_lshl_add_u64 v[0:1], v[0:1], 0, v[20:21]
	v_lshl_add_u64 v[0:1], v[0:1], 0, v[26:27]
	v_and_b32_e32 v6, 0x70, v100
	v_mul_u32_u24_e32 v9, 0x90, v98
	v_lshl_add_u64 v[2:3], v[2:3], 0, v[22:23]
	v_lshl_add_u64 v[220:221], s[22:23], 0, v[0:1]
	v_mov_b32_e32 v0, 0
	v_mov_b32_e32 v65, v64
	v_mov_b32_e32 v66, v64
	v_mov_b32_e32 v67, v64
	v_mov_b32_e32 v68, v64
	v_mov_b32_e32 v69, v64
	v_mov_b32_e32 v70, v64
	v_mov_b32_e32 v71, v64
	v_mov_b32_e32 v72, v64
	v_mov_b32_e32 v73, v64
	v_mov_b32_e32 v74, v64
	v_mov_b32_e32 v75, v64
	v_mov_b32_e32 v76, v64
	v_mov_b32_e32 v77, v64
	v_mov_b32_e32 v78, v64
	v_mov_b32_e32 v79, v64
	v_mov_b32_e32 v81, v80
	v_mov_b32_e32 v82, v80
	v_mov_b32_e32 v83, v80
	v_mov_b32_e32 v84, v80
	v_mov_b32_e32 v85, v80
	v_mov_b32_e32 v86, v80
	v_mov_b32_e32 v87, v80
	v_mov_b32_e32 v88, v80
	v_mov_b32_e32 v89, v80
	v_mov_b32_e32 v90, v80
	v_mov_b32_e32 v91, v80
	v_mov_b32_e32 v92, v80
	v_mov_b32_e32 v93, v80
	v_mov_b32_e32 v94, v80
	v_mov_b32_e32 v95, v80
	v_lshl_add_u64 v[214:215], s[22:23], 0, v[4:5]
	v_lshl_add_u64 v[218:219], s[22:23], 0, v[2:3]
	s_mov_b64 s[40:41], 0
	v_add_u32_e32 v235, v16, v6
	v_add_u32_e32 v236, v17, v6
	v_add_u32_e32 v237, v24, v6
	v_add_u32_e32 v238, v25, v6
	v_add_u32_e32 v234, v7, v99
	v_add_u32_e32 v239, v8, v9
	v_add_u32_e32 v240, v8, v28
	v_add_u32_e32 v233, v7, v29
	v_mov_b32_e32 v1, v0
	v_mov_b32_e32 v2, v0
	v_mov_b32_e32 v3, v0
	v_mov_b32_e32 v4, v0
	v_mov_b32_e32 v5, v0
	v_mov_b32_e32 v6, v0
	v_mov_b32_e32 v7, v0
	v_mov_b32_e32 v8, v0
	v_mov_b32_e32 v9, v0
	v_mov_b32_e32 v10, v0
	v_mov_b32_e32 v11, v0
	v_mov_b32_e32 v12, v0
	v_mov_b32_e32 v13, v0
	v_mov_b32_e32 v14, v0
	v_mov_b32_e32 v15, v0
	v_mov_b32_e32 v16, v0
	v_mov_b32_e32 v17, v0
	v_mov_b32_e32 v18, v0
	v_mov_b32_e32 v19, v0
	v_mov_b32_e32 v20, v0
	v_mov_b32_e32 v21, v0
	v_mov_b32_e32 v22, v0
	v_mov_b32_e32 v23, v0
	v_mov_b32_e32 v24, v0
	v_mov_b32_e32 v25, v0
	v_mov_b32_e32 v26, v0
	v_mov_b32_e32 v27, v0
	v_mov_b32_e32 v28, v0
	v_mov_b32_e32 v29, v0
	v_mov_b32_e32 v30, v0
	v_mov_b32_e32 v31, v0
	v_mov_b32_e32 v32, v0
	v_mov_b32_e32 v33, v0
	v_mov_b32_e32 v34, v0
	v_mov_b32_e32 v35, v0
	v_mov_b32_e32 v36, v0
	v_mov_b32_e32 v37, v0
	v_mov_b32_e32 v38, v0
	v_mov_b32_e32 v39, v0
	v_mov_b32_e32 v40, v0
	v_mov_b32_e32 v41, v0
	v_mov_b32_e32 v42, v0
	v_mov_b32_e32 v43, v0
	v_mov_b32_e32 v44, v0
	v_mov_b32_e32 v45, v0
	v_mov_b32_e32 v46, v0
	v_mov_b32_e32 v47, v0
	v_mov_b32_e32 v48, v0
	v_mov_b32_e32 v49, v0
	v_mov_b32_e32 v50, v0
	v_mov_b32_e32 v51, v0
	v_mov_b32_e32 v52, v0
	v_mov_b32_e32 v53, v0
	v_mov_b32_e32 v54, v0
	v_mov_b32_e32 v55, v0
	v_mov_b32_e32 v56, v0
	v_mov_b32_e32 v57, v0
	v_mov_b32_e32 v58, v0
	v_mov_b32_e32 v59, v0
	v_mov_b32_e32 v60, v0
	v_mov_b32_e32 v61, v0
	v_mov_b32_e32 v62, v0
	v_mov_b32_e32 v63, v0

.LBB0_1755:
	s_and_b32 s27, s12, 1
	s_add_i32 s4, s8, -32
	s_ashr_i32 s4, s4, 2
	s_add_i32 s4, s4, 1
	s_cmp_gt_i32 s8, 31
	s_cselect_b32 s4, s4, 0
	s_mul_hi_i32 s5, s4, 0x5800
	s_mulk_i32 s4, 0x5800
	s_add_u32 s4, s33, s4
	s_addc_u32 s5, s50, s5
	v_lshl_add_u32 v236, s8, 8, v164
	v_lshlrev_b32_e32 v236, 2, v236
	v_lshl_or_b32 v229, s9, 7, v166
	v_lshlrev_b32_e32 v229, 2, v229
	global_load_dword v208, v236, s[10:11] offset:0
	global_load_dword v209, v236, s[10:11] offset:64
	global_load_dword v210, v236, s[10:11] offset:128
	global_load_dword v211, v236, s[10:11] offset:192
	global_load_dword v212, v236, s[10:11] offset:512
	global_load_dword v213, v236, s[10:11] offset:576
	global_load_dword v214, v236, s[10:11] offset:640
	global_load_dword v215, v236, s[10:11] offset:704
	global_load_dwordx4 v[200:203], v229, s[4:5]
	global_load_dwordx4 v[204:207], v229, s[4:5] offset:16
	v_add_u32_e32 v224, 0x2c00, v229
	global_load_dwordx4 v[216:219], v224, s[4:5]
	global_load_dwordx4 v[220:223], v224, s[4:5] offset:16
	v_readlane_b32 s36, v254, 5
	v_readlane_b32 s37, v254, 6
	v_readlane_b32 s38, v254, 7
	v_readlane_b32 s39, v254, 8
	s_add_u32 s36, s36, 0x10800
	s_addc_u32 s37, s37, 0
	s_add_u32 s38, s38, 0x5800
	s_addc_u32 s39, s39, 0
	s_mul_i32 s40, s8, 0x160000
	s_lshl_b32 s79, s9, 8
	s_add_i32 s40, s40, s79
	s_add_i32 s40, s40, 0x9300000
	s_add_u32 s40, s40, s70
	s_addc_u32 s41, s71, 0
	v_mul_u32_u24_e32 v171, 0x1600, v164
	v_lshl_add_u32 v171, v166, 1, v171
	s_mov_b32 s32, 0x20800
	v_lshl_add_u32 v228, v166, 2, s32
	v_and_b32_e32 v237, 15, v164
	v_cmp_eq_u32_e64 s[54:55], 0, v237
	v_cmp_eq_u32_e64 s[56:57], 15, v237
	v_and_b32_e32 v231, 8, v237
	v_lshlrev_b32_e32 v231, 9, v231
	s_lshl_b32 s79, s27, 10
	v_add3_u32 v231, v231, v228, s79
	global_load_dwordx4 v[128:131], v229, s[36:37]
	v_add_u32_e32 v227, 0x5800, v229
	global_load_dwordx4 v[132:135], v227, s[36:37]
	v_add_u32_e32 v226, 0xb000, v229
	global_load_dwordx4 v[136:139], v226, s[36:37]
	global_load_dwordx4 v[140:143], v229, s[38:39]
	v_add_u32_e32 v226, 0x2c00, v229
	global_load_dwordx4 v[160:163], v226, s[36:37]
	v_add_u32_e32 v227, 0x8400, v229
	global_load_dwordx4 v[172:175], v227, s[36:37]
	v_add_u32_e32 v226, 0xdc00, v229
	global_load_dwordx4 v[176:179], v226, s[36:37]
	v_add_u32_e32 v227, 0x2c00, v229
	global_load_dwordx4 v[180:183], v227, s[38:39]
	s_waitcnt vmcnt(12)
	v_fmamk_f32 v208, v208, 0x3a800000, v170
	v_fmamk_f32 v209, v209, 0x3a800000, v170
	v_fmamk_f32 v210, v210, 0x3a800000, v170
	v_fmamk_f32 v211, v211, 0x3a800000, v170
	v_fmamk_f32 v212, v212, 0x3a800000, v170
	v_fmamk_f32 v213, v213, 0x3a800000, v170
	v_fmamk_f32 v214, v214, 0x3a800000, v170
	v_fmamk_f32 v215, v215, 0x3a800000, v170
	s_mov_b32 s79, 0x800000
	v_mul_f32_e32 v224, 0x4b800000, v208
	v_mul_f32_e32 v225, 0x4b800000, v209
	v_mul_f32_e32 v226, 0x4b800000, v210
	v_mul_f32_e32 v227, 0x4b800000, v211
	v_mul_f32_e32 v232, 0x4b800000, v212
	v_mul_f32_e32 v233, 0x4b800000, v213
	v_mul_f32_e32 v234, 0x4b800000, v214
	v_mul_f32_e32 v235, 0x4b800000, v215
	v_cmp_gt_f32_e32 vcc, s79, v208
	s_nop 1
	v_cndmask_b32_e32 v208, v208, v224, vcc
	v_rsq_f32_e32 v208, v208
	s_nop 0
	v_mul_f32_e32 v224, 0x45800000, v208
	v_cndmask_b32_e32 v208, v208, v224, vcc
	v_cmp_gt_f32_e32 vcc, s79, v209
	s_nop 1
	v_cndmask_b32_e32 v209, v209, v225, vcc
	v_rsq_f32_e32 v209, v209
	s_nop 0
	v_mul_f32_e32 v225, 0x45800000, v209
	v_cndmask_b32_e32 v209, v209, v225, vcc
	v_cmp_gt_f32_e32 vcc, s79, v210
	s_nop 1
	v_cndmask_b32_e32 v210, v210, v226, vcc
	v_rsq_f32_e32 v210, v210
	s_nop 0
	v_mul_f32_e32 v226, 0x45800000, v210
	v_cndmask_b32_e32 v210, v210, v226, vcc
	v_cmp_gt_f32_e32 vcc, s79, v211
	s_nop 1
	v_cndmask_b32_e32 v211, v211, v227, vcc
	v_rsq_f32_e32 v211, v211
	s_nop 0
	v_mul_f32_e32 v227, 0x45800000, v211
	v_cndmask_b32_e32 v211, v211, v227, vcc
	v_cmp_gt_f32_e32 vcc, s79, v212
	s_nop 1
	v_cndmask_b32_e32 v212, v212, v232, vcc
	v_rsq_f32_e32 v212, v212
	s_nop 0
	v_mul_f32_e32 v232, 0x45800000, v212
	v_cndmask_b32_e32 v212, v212, v232, vcc
	v_cmp_gt_f32_e32 vcc, s79, v213
	s_nop 1
	v_cndmask_b32_e32 v213, v213, v233, vcc
	v_rsq_f32_e32 v213, v213
	s_nop 0
	v_mul_f32_e32 v233, 0x45800000, v213
	v_cndmask_b32_e32 v213, v213, v233, vcc
	v_cmp_gt_f32_e32 vcc, s79, v214
	s_nop 1
	v_cndmask_b32_e32 v214, v214, v234, vcc
	v_rsq_f32_e32 v214, v214
	s_nop 0
	v_mul_f32_e32 v234, 0x45800000, v214
	v_cndmask_b32_e32 v214, v214, v234, vcc
	v_cmp_gt_f32_e32 vcc, s79, v215
	s_nop 1
	v_cndmask_b32_e32 v215, v215, v235, vcc
	v_rsq_f32_e32 v215, v215
	s_nop 0
	v_mul_f32_e32 v235, 0x45800000, v215
	v_cndmask_b32_e32 v215, v215, v235, vcc
	s_waitcnt vmcnt(8)
	v_fma_f32 v124, v124, v208, v200
	v_fma_f32 v125, v125, v208, v201
	v_fma_f32 v126, v126, v208, v202
	v_fma_f32 v127, v127, v208, v203
	v_fma_f32 v120, v120, v208, v204
	v_fma_f32 v121, v121, v208, v205
	v_fma_f32 v122, v122, v208, v206
	v_fma_f32 v123, v123, v208, v207
	v_fma_f32 v108, v108, v208, v216
	v_fma_f32 v109, v109, v208, v217
	v_fma_f32 v110, v110, v208, v218
	v_fma_f32 v111, v111, v208, v219
	v_fma_f32 v104, v104, v208, v220
	v_fma_f32 v105, v105, v208, v221
	v_fma_f32 v106, v106, v208, v222
	v_fma_f32 v107, v107, v208, v223
	v_fma_f32 v116, v116, v209, v200
	v_fma_f32 v117, v117, v209, v201
	v_fma_f32 v118, v118, v209, v202
	v_fma_f32 v119, v119, v209, v203
	v_fma_f32 v112, v112, v209, v204
	v_fma_f32 v113, v113, v209, v205
	v_fma_f32 v114, v114, v209, v206
	v_fma_f32 v115, v115, v209, v207
	v_fma_f32 v100, v100, v209, v216
	v_fma_f32 v101, v101, v209, v217
	v_fma_f32 v102, v102, v209, v218
	v_fma_f32 v103, v103, v209, v219
	v_fma_f32 v92, v92, v209, v220
	v_fma_f32 v93, v93, v209, v221
	v_fma_f32 v94, v94, v209, v222
	v_fma_f32 v95, v95, v209, v223
	v_fma_f32 v96, v96, v210, v200
	v_fma_f32 v97, v97, v210, v201
	v_fma_f32 v98, v98, v210, v202
	v_fma_f32 v99, v99, v210, v203
	v_fma_f32 v88, v88, v210, v204
	v_fma_f32 v89, v89, v210, v205
	v_fma_f32 v90, v90, v210, v206
	v_fma_f32 v91, v91, v210, v207
	v_fma_f32 v84, v84, v210, v216
	v_fma_f32 v85, v85, v210, v217
	v_fma_f32 v86, v86, v210, v218
	v_fma_f32 v87, v87, v210, v219
	v_fma_f32 v76, v76, v210, v220
	v_fma_f32 v77, v77, v210, v221
	v_fma_f32 v78, v78, v210, v222
	v_fma_f32 v79, v79, v210, v223
	v_fma_f32 v80, v80, v211, v200
	v_fma_f32 v81, v81, v211, v201
	v_fma_f32 v82, v82, v211, v202
	v_fma_f32 v83, v83, v211, v203
	v_fma_f32 v72, v72, v211, v204
	v_fma_f32 v73, v73, v211, v205
	v_fma_f32 v74, v74, v211, v206
	v_fma_f32 v75, v75, v211, v207
	v_fma_f32 v68, v68, v211, v216
	v_fma_f32 v69, v69, v211, v217
	v_fma_f32 v70, v70, v211, v218
	v_fma_f32 v71, v71, v211, v219
	v_fma_f32 v64, v64, v211, v220
	v_fma_f32 v65, v65, v211, v221
	v_fma_f32 v66, v66, v211, v222
	v_fma_f32 v67, v67, v211, v223
	v_fma_f32 v60, v60, v212, v200
	v_fma_f32 v61, v61, v212, v201
	v_fma_f32 v62, v62, v212, v202
	v_fma_f32 v63, v63, v212, v203
	v_fma_f32 v56, v56, v212, v204
	v_fma_f32 v57, v57, v212, v205
	v_fma_f32 v58, v58, v212, v206
	v_fma_f32 v59, v59, v212, v207
	v_fma_f32 v52, v52, v212, v216
	v_fma_f32 v53, v53, v212, v217
	v_fma_f32 v54, v54, v212, v218
	v_fma_f32 v55, v55, v212, v219
	v_fma_f32 v44, v44, v212, v220
	v_fma_f32 v45, v45, v212, v221
	v_fma_f32 v46, v46, v212, v222
	v_fma_f32 v47, v47, v212, v223
	v_fma_f32 v48, v48, v213, v200
	v_fma_f32 v49, v49, v213, v201
	v_fma_f32 v50, v50, v213, v202
	v_fma_f32 v51, v51, v213, v203
	v_fma_f32 v40, v40, v213, v204
	v_fma_f32 v41, v41, v213, v205
	v_fma_f32 v42, v42, v213, v206
	v_fma_f32 v43, v43, v213, v207
	v_fma_f32 v36, v36, v213, v216
	v_fma_f32 v37, v37, v213, v217
	v_fma_f32 v38, v38, v213, v218
	v_fma_f32 v39, v39, v213, v219
	v_fma_f32 v28, v28, v213, v220
	v_fma_f32 v29, v29, v213, v221
	v_fma_f32 v30, v30, v213, v222
	v_fma_f32 v31, v31, v213, v223
	v_fma_f32 v32, v32, v214, v200
	v_fma_f32 v33, v33, v214, v201
	v_fma_f32 v34, v34, v214, v202
	v_fma_f32 v35, v35, v214, v203
	v_fma_f32 v24, v24, v214, v204
	v_fma_f32 v25, v25, v214, v205
	v_fma_f32 v26, v26, v214, v206
	v_fma_f32 v27, v27, v214, v207
	v_fma_f32 v20, v20, v214, v216
	v_fma_f32 v21, v21, v214, v217
	v_fma_f32 v22, v22, v214, v218
	v_fma_f32 v23, v23, v214, v219
	v_fma_f32 v12, v12, v214, v220
	v_fma_f32 v13, v13, v214, v221
	v_fma_f32 v14, v14, v214, v222
	v_fma_f32 v15, v15, v214, v223
	v_fma_f32 v16, v16, v215, v200
	v_fma_f32 v17, v17, v215, v201
	v_fma_f32 v18, v18, v215, v202
	v_fma_f32 v19, v19, v215, v203
	v_fma_f32 v8, v8, v215, v204
	v_fma_f32 v9, v9, v215, v205
	v_fma_f32 v10, v10, v215, v206
	v_fma_f32 v11, v11, v215, v207
	v_fma_f32 v4, v4, v215, v216
	v_fma_f32 v5, v5, v215, v217
	v_fma_f32 v6, v6, v215, v218
	v_fma_f32 v7, v7, v215, v219
	v_fma_f32 v0, v0, v215, v220
	v_fma_f32 v1, v1, v215, v221
	v_fma_f32 v2, v2, v215, v222
	v_fma_f32 v3, v3, v215, v223
	v_mov_b32_e32 v212, 0
	v_mov_b32_e32 v213, 0
	v_mov_b32_e32 v214, 0
	v_mov_b32_e32 v215, 0
	s_lshl_b32 s96, s27, 12
	s_sub_i32 s96, 0x2000, s96
	s_mul_i32 s94, s27, 0x1400
	s_add_i32 s94, s94, 0xc00
	s_lshl_b32 s79, s27, 10
	s_add_i32 s95, s79, 5120
	s_add_i32 s92, s79, 1024
	s_mov_b64 s[58:59], exec
	s_mov_b64 exec, s[54:55]
	v_add_u32_e32 v250, s96, v228
	ds_write_b128 v250, v[124:127] offset:0
	ds_write_b128 v250, v[120:123] offset:16
	ds_write_b128 v250, v[108:111] offset:512
	ds_write_b128 v250, v[104:107] offset:528
	v_add_u32_e32 v250, s95, v228
	ds_write_b128 v250, v[60:63] offset:0
	ds_write_b128 v250, v[56:59] offset:16
	ds_write_b128 v250, v[52:55] offset:512
	ds_write_b128 v250, v[44:47] offset:528
	ds_write_b128 v228, v[212:215] offset:0
	ds_write_b128 v228, v[212:215] offset:16
	ds_write_b128 v228, v[212:215] offset:512
	ds_write_b128 v228, v[212:215] offset:528
	s_mov_b64 exec, s[56:57]
	v_add_u32_e32 v251, s92, v228
	ds_write_b128 v251, v[80:83] offset:0
	ds_write_b128 v251, v[72:75] offset:16
	ds_write_b128 v251, v[68:71] offset:512
	ds_write_b128 v251, v[64:67] offset:528
	v_add_u32_e32 v251, s94, v228
	ds_write_b128 v251, v[16:19] offset:0
	ds_write_b128 v251, v[8:11] offset:16
	ds_write_b128 v251, v[4:7] offset:512
	ds_write_b128 v251, v[0:3] offset:528
	ds_write_b128 v228, v[212:215] offset:7168
	ds_write_b128 v228, v[212:215] offset:7184
	ds_write_b128 v228, v[212:215] offset:7680
	ds_write_b128 v228, v[212:215] offset:7696
	s_mov_b64 exec, s[58:59]
	s_waitcnt lgkmcnt(0)
	s_barrier
	ds_read_b128 v[184:187], v231 offset:0
	ds_read_b128 v[188:191], v231 offset:512
	ds_read_b128 v[192:195], v231 offset:2048
	ds_read_b128 v[196:199], v231 offset:2560
	s_waitcnt vmcnt(0)
	v_cndmask_b32_e64 v216, 0, v128, s[54:55]
	v_cndmask_b32_e64 v220, 0, v136, s[56:57]
	v_cndmask_b32_e64 v217, 0, v129, s[54:55]
	v_cndmask_b32_e64 v221, 0, v137, s[56:57]
	v_cndmask_b32_e64 v218, 0, v130, s[54:55]
	v_cndmask_b32_e64 v222, 0, v138, s[56:57]
	v_cndmask_b32_e64 v219, 0, v131, s[54:55]
	v_cndmask_b32_e64 v223, 0, v139, s[56:57]
	v_cndmask_b32_e64 v224, 0, v160, s[54:55]
	v_cndmask_b32_e64 v232, 0, v176, s[56:57]
	v_cndmask_b32_e64 v225, 0, v161, s[54:55]
	v_cndmask_b32_e64 v233, 0, v177, s[56:57]
	v_cndmask_b32_e64 v226, 0, v162, s[54:55]
	v_cndmask_b32_e64 v234, 0, v178, s[56:57]
	v_cndmask_b32_e64 v227, 0, v163, s[54:55]
	v_cndmask_b32_e64 v235, 0, v179, s[56:57]
	s_waitcnt lgkmcnt(0)
	s_nop 1
	v_fma_f32 v200, v132, v124, v140
	v_fma_f32 v201, v133, v125, v141
	v_fma_f32 v202, v134, v126, v142
	v_fma_f32 v203, v135, v127, v143
	v_fmac_f32_dpp v200, v124, v128 row_shr:1 row_mask:0xf bank_mask:0xf
	v_fmac_f32_dpp v201, v125, v129 row_shr:1 row_mask:0xf bank_mask:0xf
	v_fmac_f32_dpp v202, v126, v130 row_shr:1 row_mask:0xf bank_mask:0xf
	v_fmac_f32_dpp v203, v127, v131 row_shr:1 row_mask:0xf bank_mask:0xf
	v_fmac_f32_e32 v200, v184, v216
	v_fmac_f32_e32 v201, v185, v217
	v_fmac_f32_e32 v202, v186, v218
	v_fmac_f32_e32 v203, v187, v219
	v_fmac_f32_dpp v200, v124, v136 row_shl:1 row_mask:0xf bank_mask:0xf
	v_fmac_f32_dpp v201, v125, v137 row_shl:1 row_mask:0xf bank_mask:0xf
	v_fmac_f32_dpp v202, v126, v138 row_shl:1 row_mask:0xf bank_mask:0xf
	v_fmac_f32_dpp v203, v127, v139 row_shl:1 row_mask:0xf bank_mask:0xf
	v_fmac_f32_dpp v200, v116, v220 row_ror:15 row_mask:0xf bank_mask:0xf
	v_fmac_f32_dpp v201, v117, v221 row_ror:15 row_mask:0xf bank_mask:0xf
	v_fmac_f32_dpp v202, v118, v222 row_ror:15 row_mask:0xf bank_mask:0xf
	v_fmac_f32_dpp v203, v119, v223 row_ror:15 row_mask:0xf bank_mask:0xf
	v_fma_f32 v204, v172, v108, v180
	v_fma_f32 v205, v173, v109, v181
	v_fma_f32 v206, v174, v110, v182
	v_fma_f32 v207, v175, v111, v183
	v_fmac_f32_dpp v204, v108, v160 row_shr:1 row_mask:0xf bank_mask:0xf
	v_fmac_f32_dpp v205, v109, v161 row_shr:1 row_mask:0xf bank_mask:0xf
	v_fmac_f32_dpp v206, v110, v162 row_shr:1 row_mask:0xf bank_mask:0xf
	v_fmac_f32_dpp v207, v111, v163 row_shr:1 row_mask:0xf bank_mask:0xf
	v_fmac_f32_e32 v204, v188, v224
	v_fmac_f32_e32 v205, v189, v225
	v_fmac_f32_e32 v206, v190, v226
	v_fmac_f32_e32 v207, v191, v227
	v_fmac_f32_dpp v204, v108, v176 row_shl:1 row_mask:0xf bank_mask:0xf
	v_fmac_f32_dpp v205, v109, v177 row_shl:1 row_mask:0xf bank_mask:0xf
	v_fmac_f32_dpp v206, v110, v178 row_shl:1 row_mask:0xf bank_mask:0xf
	v_fmac_f32_dpp v207, v111, v179 row_shl:1 row_mask:0xf bank_mask:0xf
	v_fmac_f32_dpp v204, v100, v232 row_ror:15 row_mask:0xf bank_mask:0xf
	v_fmac_f32_dpp v205, v101, v233 row_ror:15 row_mask:0xf bank_mask:0xf
	v_fmac_f32_dpp v206, v102, v234 row_ror:15 row_mask:0xf bank_mask:0xf
	v_fmac_f32_dpp v207, v103, v235 row_ror:15 row_mask:0xf bank_mask:0xf
	v_mul_f32_e32 v208, 0xbfb8aa3b, v200
	v_mul_f32_e32 v209, 0xbfb8aa3b, v201
	v_mul_f32_e32 v210, 0xbfb8aa3b, v202
	v_mul_f32_e32 v211, 0xbfb8aa3b, v203
	v_exp_f32_e32 v208, v208
	v_exp_f32_e32 v209, v209
	v_exp_f32_e32 v210, v210
	v_exp_f32_e32 v211, v211
	v_add_f32_e32 v208, 1.0, v208
	v_add_f32_e32 v209, 1.0, v209
	v_add_f32_e32 v210, 1.0, v210
	v_add_f32_e32 v211, 1.0, v211
	v_rcp_f32_e32 v208, v208
	v_rcp_f32_e32 v209, v209
	v_rcp_f32_e32 v210, v210
	v_rcp_f32_e32 v211, v211
	v_mul_f32_e32 v200, v200, v208
	v_mul_f32_e32 v201, v201, v209
	v_mul_f32_e32 v202, v202, v210
	v_mul_f32_e32 v203, v203, v211
	v_mul_f32_e32 v200, v200, v204
	v_mul_f32_e32 v201, v201, v205
	v_mul_f32_e32 v202, v202, v206
	v_mul_f32_e32 v203, v203, v207
	v_cvt_pk_bf16_f32 v236, v200, v201
	v_cvt_pk_bf16_f32 v237, v202, v203
	v_fma_f32 v200, v132, v116, v140
	v_fma_f32 v201, v133, v117, v141
	v_fma_f32 v202, v134, v118, v142
	v_fma_f32 v203, v135, v119, v143
	v_fmac_f32_dpp v200, v116, v128 row_shr:1 row_mask:0xf bank_mask:0xf
	v_fmac_f32_dpp v201, v117, v129 row_shr:1 row_mask:0xf bank_mask:0xf
	v_fmac_f32_dpp v202, v118, v130 row_shr:1 row_mask:0xf bank_mask:0xf
	v_fmac_f32_dpp v203, v119, v131 row_shr:1 row_mask:0xf bank_mask:0xf
	v_fmac_f32_dpp v200, v124, v216 row_ror:1 row_mask:0xf bank_mask:0xf
	v_fmac_f32_dpp v201, v125, v217 row_ror:1 row_mask:0xf bank_mask:0xf
	v_fmac_f32_dpp v202, v126, v218 row_ror:1 row_mask:0xf bank_mask:0xf
	v_fmac_f32_dpp v203, v127, v219 row_ror:1 row_mask:0xf bank_mask:0xf
	v_fmac_f32_dpp v200, v116, v136 row_shl:1 row_mask:0xf bank_mask:0xf
	v_fmac_f32_dpp v201, v117, v137 row_shl:1 row_mask:0xf bank_mask:0xf
	v_fmac_f32_dpp v202, v118, v138 row_shl:1 row_mask:0xf bank_mask:0xf
	v_fmac_f32_dpp v203, v119, v139 row_shl:1 row_mask:0xf bank_mask:0xf
	v_fmac_f32_dpp v200, v96, v220 row_ror:15 row_mask:0xf bank_mask:0xf
	v_fmac_f32_dpp v201, v97, v221 row_ror:15 row_mask:0xf bank_mask:0xf
	v_fmac_f32_dpp v202, v98, v222 row_ror:15 row_mask:0xf bank_mask:0xf
	v_fmac_f32_dpp v203, v99, v223 row_ror:15 row_mask:0xf bank_mask:0xf
	v_fma_f32 v204, v172, v100, v180
	v_fma_f32 v205, v173, v101, v181
	v_fma_f32 v206, v174, v102, v182
	v_fma_f32 v207, v175, v103, v183
	v_fmac_f32_dpp v204, v100, v160 row_shr:1 row_mask:0xf bank_mask:0xf
	v_fmac_f32_dpp v205, v101, v161 row_shr:1 row_mask:0xf bank_mask:0xf
	v_fmac_f32_dpp v206, v102, v162 row_shr:1 row_mask:0xf bank_mask:0xf
	v_fmac_f32_dpp v207, v103, v163 row_shr:1 row_mask:0xf bank_mask:0xf
	v_fmac_f32_dpp v204, v108, v224 row_ror:1 row_mask:0xf bank_mask:0xf
	v_fmac_f32_dpp v205, v109, v225 row_ror:1 row_mask:0xf bank_mask:0xf
	v_fmac_f32_dpp v206, v110, v226 row_ror:1 row_mask:0xf bank_mask:0xf
	v_fmac_f32_dpp v207, v111, v227 row_ror:1 row_mask:0xf bank_mask:0xf
	v_fmac_f32_dpp v204, v100, v176 row_shl:1 row_mask:0xf bank_mask:0xf
	v_fmac_f32_dpp v205, v101, v177 row_shl:1 row_mask:0xf bank_mask:0xf
	v_fmac_f32_dpp v206, v102, v178 row_shl:1 row_mask:0xf bank_mask:0xf
	v_fmac_f32_dpp v207, v103, v179 row_shl:1 row_mask:0xf bank_mask:0xf
	v_fmac_f32_dpp v204, v84, v232 row_ror:15 row_mask:0xf bank_mask:0xf
	v_fmac_f32_dpp v205, v85, v233 row_ror:15 row_mask:0xf bank_mask:0xf
	v_fmac_f32_dpp v206, v86, v234 row_ror:15 row_mask:0xf bank_mask:0xf
	v_fmac_f32_dpp v207, v87, v235 row_ror:15 row_mask:0xf bank_mask:0xf
	v_mul_f32_e32 v208, 0xbfb8aa3b, v200
	v_mul_f32_e32 v209, 0xbfb8aa3b, v201
	v_mul_f32_e32 v210, 0xbfb8aa3b, v202
	v_mul_f32_e32 v211, 0xbfb8aa3b, v203
	v_exp_f32_e32 v208, v208
	v_exp_f32_e32 v209, v209
	v_exp_f32_e32 v210, v210
	v_exp_f32_e32 v211, v211
	v_add_f32_e32 v208, 1.0, v208
	v_add_f32_e32 v209, 1.0, v209
	v_add_f32_e32 v210, 1.0, v210
	v_add_f32_e32 v211, 1.0, v211
	v_rcp_f32_e32 v208, v208
	v_rcp_f32_e32 v209, v209
	v_rcp_f32_e32 v210, v210
	v_rcp_f32_e32 v211, v211
	v_mul_f32_e32 v200, v200, v208
	v_mul_f32_e32 v201, v201, v209
	v_mul_f32_e32 v202, v202, v210
	v_mul_f32_e32 v203, v203, v211
	v_mul_f32_e32 v200, v200, v204
	v_mul_f32_e32 v201, v201, v205
	v_mul_f32_e32 v202, v202, v206
	v_mul_f32_e32 v203, v203, v207
	v_cvt_pk_bf16_f32 v238, v200, v201
	v_cvt_pk_bf16_f32 v239, v202, v203
	v_fma_f32 v200, v132, v96, v140
	v_fma_f32 v201, v133, v97, v141
	v_fma_f32 v202, v134, v98, v142
	v_fma_f32 v203, v135, v99, v143
	v_fmac_f32_dpp v200, v96, v128 row_shr:1 row_mask:0xf bank_mask:0xf
	v_fmac_f32_dpp v201, v97, v129 row_shr:1 row_mask:0xf bank_mask:0xf
	v_fmac_f32_dpp v202, v98, v130 row_shr:1 row_mask:0xf bank_mask:0xf
	v_fmac_f32_dpp v203, v99, v131 row_shr:1 row_mask:0xf bank_mask:0xf
	v_fmac_f32_dpp v200, v116, v216 row_ror:1 row_mask:0xf bank_mask:0xf
	v_fmac_f32_dpp v201, v117, v217 row_ror:1 row_mask:0xf bank_mask:0xf
	v_fmac_f32_dpp v202, v118, v218 row_ror:1 row_mask:0xf bank_mask:0xf
	v_fmac_f32_dpp v203, v119, v219 row_ror:1 row_mask:0xf bank_mask:0xf
	v_fmac_f32_dpp v200, v96, v136 row_shl:1 row_mask:0xf bank_mask:0xf
	v_fmac_f32_dpp v201, v97, v137 row_shl:1 row_mask:0xf bank_mask:0xf
	v_fmac_f32_dpp v202, v98, v138 row_shl:1 row_mask:0xf bank_mask:0xf
	v_fmac_f32_dpp v203, v99, v139 row_shl:1 row_mask:0xf bank_mask:0xf
	v_fmac_f32_dpp v200, v80, v220 row_ror:15 row_mask:0xf bank_mask:0xf
	v_fmac_f32_dpp v201, v81, v221 row_ror:15 row_mask:0xf bank_mask:0xf
	v_fmac_f32_dpp v202, v82, v222 row_ror:15 row_mask:0xf bank_mask:0xf
	v_fmac_f32_dpp v203, v83, v223 row_ror:15 row_mask:0xf bank_mask:0xf
	v_fma_f32 v204, v172, v84, v180
	v_fma_f32 v205, v173, v85, v181
	v_fma_f32 v206, v174, v86, v182
	v_fma_f32 v207, v175, v87, v183
	v_fmac_f32_dpp v204, v84, v160 row_shr:1 row_mask:0xf bank_mask:0xf
	v_fmac_f32_dpp v205, v85, v161 row_shr:1 row_mask:0xf bank_mask:0xf
	v_fmac_f32_dpp v206, v86, v162 row_shr:1 row_mask:0xf bank_mask:0xf
	v_fmac_f32_dpp v207, v87, v163 row_shr:1 row_mask:0xf bank_mask:0xf
	v_fmac_f32_dpp v204, v100, v224 row_ror:1 row_mask:0xf bank_mask:0xf
	v_fmac_f32_dpp v205, v101, v225 row_ror:1 row_mask:0xf bank_mask:0xf
	v_fmac_f32_dpp v206, v102, v226 row_ror:1 row_mask:0xf bank_mask:0xf
	v_fmac_f32_dpp v207, v103, v227 row_ror:1 row_mask:0xf bank_mask:0xf
	v_fmac_f32_dpp v204, v84, v176 row_shl:1 row_mask:0xf bank_mask:0xf
	v_fmac_f32_dpp v205, v85, v177 row_shl:1 row_mask:0xf bank_mask:0xf
	v_fmac_f32_dpp v206, v86, v178 row_shl:1 row_mask:0xf bank_mask:0xf
	v_fmac_f32_dpp v207, v87, v179 row_shl:1 row_mask:0xf bank_mask:0xf
	v_fmac_f32_dpp v204, v68, v232 row_ror:15 row_mask:0xf bank_mask:0xf
	v_fmac_f32_dpp v205, v69, v233 row_ror:15 row_mask:0xf bank_mask:0xf
	v_fmac_f32_dpp v206, v70, v234 row_ror:15 row_mask:0xf bank_mask:0xf
	v_fmac_f32_dpp v207, v71, v235 row_ror:15 row_mask:0xf bank_mask:0xf
	v_mul_f32_e32 v208, 0xbfb8aa3b, v200
	v_mul_f32_e32 v209, 0xbfb8aa3b, v201
	v_mul_f32_e32 v210, 0xbfb8aa3b, v202
	v_mul_f32_e32 v211, 0xbfb8aa3b, v203
	v_exp_f32_e32 v208, v208
	v_exp_f32_e32 v209, v209
	v_exp_f32_e32 v210, v210
	v_exp_f32_e32 v211, v211
	v_add_f32_e32 v208, 1.0, v208
	v_add_f32_e32 v209, 1.0, v209
	v_add_f32_e32 v210, 1.0, v210
	v_add_f32_e32 v211, 1.0, v211
	v_rcp_f32_e32 v208, v208
	v_rcp_f32_e32 v209, v209
	v_rcp_f32_e32 v210, v210
	v_rcp_f32_e32 v211, v211
	v_mul_f32_e32 v200, v200, v208
	v_mul_f32_e32 v201, v201, v209
	v_mul_f32_e32 v202, v202, v210
	v_mul_f32_e32 v203, v203, v211
	v_mul_f32_e32 v200, v200, v204
	v_mul_f32_e32 v201, v201, v205
	v_mul_f32_e32 v202, v202, v206
	v_mul_f32_e32 v203, v203, v207
	v_cvt_pk_bf16_f32 v240, v200, v201
	v_cvt_pk_bf16_f32 v241, v202, v203
	v_fma_f32 v200, v132, v80, v140
	v_fma_f32 v201, v133, v81, v141
	v_fma_f32 v202, v134, v82, v142
	v_fma_f32 v203, v135, v83, v143
	v_fmac_f32_dpp v200, v80, v128 row_shr:1 row_mask:0xf bank_mask:0xf
	v_fmac_f32_dpp v201, v81, v129 row_shr:1 row_mask:0xf bank_mask:0xf
	v_fmac_f32_dpp v202, v82, v130 row_shr:1 row_mask:0xf bank_mask:0xf
	v_fmac_f32_dpp v203, v83, v131 row_shr:1 row_mask:0xf bank_mask:0xf
	v_fmac_f32_dpp v200, v96, v216 row_ror:1 row_mask:0xf bank_mask:0xf
	v_fmac_f32_dpp v201, v97, v217 row_ror:1 row_mask:0xf bank_mask:0xf
	v_fmac_f32_dpp v202, v98, v218 row_ror:1 row_mask:0xf bank_mask:0xf
	v_fmac_f32_dpp v203, v99, v219 row_ror:1 row_mask:0xf bank_mask:0xf
	v_fmac_f32_dpp v200, v80, v136 row_shl:1 row_mask:0xf bank_mask:0xf
	v_fmac_f32_dpp v201, v81, v137 row_shl:1 row_mask:0xf bank_mask:0xf
	v_fmac_f32_dpp v202, v82, v138 row_shl:1 row_mask:0xf bank_mask:0xf
	v_fmac_f32_dpp v203, v83, v139 row_shl:1 row_mask:0xf bank_mask:0xf
	v_fmac_f32_e32 v200, v184, v220
	v_fmac_f32_e32 v201, v185, v221
	v_fmac_f32_e32 v202, v186, v222
	v_fmac_f32_e32 v203, v187, v223
	v_fma_f32 v204, v172, v68, v180
	v_fma_f32 v205, v173, v69, v181
	v_fma_f32 v206, v174, v70, v182
	v_fma_f32 v207, v175, v71, v183
	v_fmac_f32_dpp v204, v68, v160 row_shr:1 row_mask:0xf bank_mask:0xf
	v_fmac_f32_dpp v205, v69, v161 row_shr:1 row_mask:0xf bank_mask:0xf
	v_fmac_f32_dpp v206, v70, v162 row_shr:1 row_mask:0xf bank_mask:0xf
	v_fmac_f32_dpp v207, v71, v163 row_shr:1 row_mask:0xf bank_mask:0xf
	v_fmac_f32_dpp v204, v84, v224 row_ror:1 row_mask:0xf bank_mask:0xf
	v_fmac_f32_dpp v205, v85, v225 row_ror:1 row_mask:0xf bank_mask:0xf
	v_fmac_f32_dpp v206, v86, v226 row_ror:1 row_mask:0xf bank_mask:0xf
	v_fmac_f32_dpp v207, v87, v227 row_ror:1 row_mask:0xf bank_mask:0xf
	v_fmac_f32_dpp v204, v68, v176 row_shl:1 row_mask:0xf bank_mask:0xf
	v_fmac_f32_dpp v205, v69, v177 row_shl:1 row_mask:0xf bank_mask:0xf
	v_fmac_f32_dpp v206, v70, v178 row_shl:1 row_mask:0xf bank_mask:0xf
	v_fmac_f32_dpp v207, v71, v179 row_shl:1 row_mask:0xf bank_mask:0xf
	v_fmac_f32_e32 v204, v188, v232
	v_fmac_f32_e32 v205, v189, v233
	v_fmac_f32_e32 v206, v190, v234
	v_fmac_f32_e32 v207, v191, v235
	v_mul_f32_e32 v208, 0xbfb8aa3b, v200
	v_mul_f32_e32 v209, 0xbfb8aa3b, v201
	v_mul_f32_e32 v210, 0xbfb8aa3b, v202
	v_mul_f32_e32 v211, 0xbfb8aa3b, v203
	v_exp_f32_e32 v208, v208
	v_exp_f32_e32 v209, v209
	v_exp_f32_e32 v210, v210
	v_exp_f32_e32 v211, v211
	v_add_f32_e32 v208, 1.0, v208
	v_add_f32_e32 v209, 1.0, v209
	v_add_f32_e32 v210, 1.0, v210
	v_add_f32_e32 v211, 1.0, v211
	v_rcp_f32_e32 v208, v208
	v_rcp_f32_e32 v209, v209
	v_rcp_f32_e32 v210, v210
	v_rcp_f32_e32 v211, v211
	v_mul_f32_e32 v200, v200, v208
	v_mul_f32_e32 v201, v201, v209
	v_mul_f32_e32 v202, v202, v210
	v_mul_f32_e32 v203, v203, v211
	v_mul_f32_e32 v200, v200, v204
	v_mul_f32_e32 v201, v201, v205
	v_mul_f32_e32 v202, v202, v206
	v_mul_f32_e32 v203, v203, v207
	v_cvt_pk_bf16_f32 v242, v200, v201
	v_cvt_pk_bf16_f32 v243, v202, v203
	v_fma_f32 v200, v132, v60, v140
	v_fma_f32 v201, v133, v61, v141
	v_fma_f32 v202, v134, v62, v142
	v_fma_f32 v203, v135, v63, v143
	v_fmac_f32_dpp v200, v60, v128 row_shr:1 row_mask:0xf bank_mask:0xf
	v_fmac_f32_dpp v201, v61, v129 row_shr:1 row_mask:0xf bank_mask:0xf
	v_fmac_f32_dpp v202, v62, v130 row_shr:1 row_mask:0xf bank_mask:0xf
	v_fmac_f32_dpp v203, v63, v131 row_shr:1 row_mask:0xf bank_mask:0xf
	v_fmac_f32_e32 v200, v192, v216
	v_fmac_f32_e32 v201, v193, v217
	v_fmac_f32_e32 v202, v194, v218
	v_fmac_f32_e32 v203, v195, v219
	v_fmac_f32_dpp v200, v60, v136 row_shl:1 row_mask:0xf bank_mask:0xf
	v_fmac_f32_dpp v201, v61, v137 row_shl:1 row_mask:0xf bank_mask:0xf
	v_fmac_f32_dpp v202, v62, v138 row_shl:1 row_mask:0xf bank_mask:0xf
	v_fmac_f32_dpp v203, v63, v139 row_shl:1 row_mask:0xf bank_mask:0xf
	v_fmac_f32_dpp v200, v48, v220 row_ror:15 row_mask:0xf bank_mask:0xf
	v_fmac_f32_dpp v201, v49, v221 row_ror:15 row_mask:0xf bank_mask:0xf
	v_fmac_f32_dpp v202, v50, v222 row_ror:15 row_mask:0xf bank_mask:0xf
	v_fmac_f32_dpp v203, v51, v223 row_ror:15 row_mask:0xf bank_mask:0xf
	v_fma_f32 v204, v172, v52, v180
	v_fma_f32 v205, v173, v53, v181
	v_fma_f32 v206, v174, v54, v182
	v_fma_f32 v207, v175, v55, v183
	v_fmac_f32_dpp v204, v52, v160 row_shr:1 row_mask:0xf bank_mask:0xf
	v_fmac_f32_dpp v205, v53, v161 row_shr:1 row_mask:0xf bank_mask:0xf
	v_fmac_f32_dpp v206, v54, v162 row_shr:1 row_mask:0xf bank_mask:0xf
	v_fmac_f32_dpp v207, v55, v163 row_shr:1 row_mask:0xf bank_mask:0xf
	v_fmac_f32_e32 v204, v196, v224
	v_fmac_f32_e32 v205, v197, v225
	v_fmac_f32_e32 v206, v198, v226
	v_fmac_f32_e32 v207, v199, v227
	v_fmac_f32_dpp v204, v52, v176 row_shl:1 row_mask:0xf bank_mask:0xf
	v_fmac_f32_dpp v205, v53, v177 row_shl:1 row_mask:0xf bank_mask:0xf
	v_fmac_f32_dpp v206, v54, v178 row_shl:1 row_mask:0xf bank_mask:0xf
	v_fmac_f32_dpp v207, v55, v179 row_shl:1 row_mask:0xf bank_mask:0xf
	v_fmac_f32_dpp v204, v36, v232 row_ror:15 row_mask:0xf bank_mask:0xf
	v_fmac_f32_dpp v205, v37, v233 row_ror:15 row_mask:0xf bank_mask:0xf
	v_fmac_f32_dpp v206, v38, v234 row_ror:15 row_mask:0xf bank_mask:0xf
	v_fmac_f32_dpp v207, v39, v235 row_ror:15 row_mask:0xf bank_mask:0xf
	v_mul_f32_e32 v208, 0xbfb8aa3b, v200
	v_mul_f32_e32 v209, 0xbfb8aa3b, v201
	v_mul_f32_e32 v210, 0xbfb8aa3b, v202
	v_mul_f32_e32 v211, 0xbfb8aa3b, v203
	v_exp_f32_e32 v208, v208
	v_exp_f32_e32 v209, v209
	v_exp_f32_e32 v210, v210
	v_exp_f32_e32 v211, v211
	v_add_f32_e32 v208, 1.0, v208
	v_add_f32_e32 v209, 1.0, v209
	v_add_f32_e32 v210, 1.0, v210
	v_add_f32_e32 v211, 1.0, v211
	v_rcp_f32_e32 v208, v208
	v_rcp_f32_e32 v209, v209
	v_rcp_f32_e32 v210, v210
	v_rcp_f32_e32 v211, v211
	v_mul_f32_e32 v200, v200, v208
	v_mul_f32_e32 v201, v201, v209
	v_mul_f32_e32 v202, v202, v210
	v_mul_f32_e32 v203, v203, v211
	v_mul_f32_e32 v200, v200, v204
	v_mul_f32_e32 v201, v201, v205
	v_mul_f32_e32 v202, v202, v206
	v_mul_f32_e32 v203, v203, v207
	v_cvt_pk_bf16_f32 v244, v200, v201
	v_cvt_pk_bf16_f32 v245, v202, v203
	v_fma_f32 v200, v132, v48, v140
	v_fma_f32 v201, v133, v49, v141
	v_fma_f32 v202, v134, v50, v142
	v_fma_f32 v203, v135, v51, v143
	v_fmac_f32_dpp v200, v48, v128 row_shr:1 row_mask:0xf bank_mask:0xf
	v_fmac_f32_dpp v201, v49, v129 row_shr:1 row_mask:0xf bank_mask:0xf
	v_fmac_f32_dpp v202, v50, v130 row_shr:1 row_mask:0xf bank_mask:0xf
	v_fmac_f32_dpp v203, v51, v131 row_shr:1 row_mask:0xf bank_mask:0xf
	v_fmac_f32_dpp v200, v60, v216 row_ror:1 row_mask:0xf bank_mask:0xf
	v_fmac_f32_dpp v201, v61, v217 row_ror:1 row_mask:0xf bank_mask:0xf
	v_fmac_f32_dpp v202, v62, v218 row_ror:1 row_mask:0xf bank_mask:0xf
	v_fmac_f32_dpp v203, v63, v219 row_ror:1 row_mask:0xf bank_mask:0xf
	v_fmac_f32_dpp v200, v48, v136 row_shl:1 row_mask:0xf bank_mask:0xf
	v_fmac_f32_dpp v201, v49, v137 row_shl:1 row_mask:0xf bank_mask:0xf
	v_fmac_f32_dpp v202, v50, v138 row_shl:1 row_mask:0xf bank_mask:0xf
	v_fmac_f32_dpp v203, v51, v139 row_shl:1 row_mask:0xf bank_mask:0xf
	v_fmac_f32_dpp v200, v32, v220 row_ror:15 row_mask:0xf bank_mask:0xf
	v_fmac_f32_dpp v201, v33, v221 row_ror:15 row_mask:0xf bank_mask:0xf
	v_fmac_f32_dpp v202, v34, v222 row_ror:15 row_mask:0xf bank_mask:0xf
	v_fmac_f32_dpp v203, v35, v223 row_ror:15 row_mask:0xf bank_mask:0xf
	v_fma_f32 v204, v172, v36, v180
	v_fma_f32 v205, v173, v37, v181
	v_fma_f32 v206, v174, v38, v182
	v_fma_f32 v207, v175, v39, v183
	v_fmac_f32_dpp v204, v36, v160 row_shr:1 row_mask:0xf bank_mask:0xf
	v_fmac_f32_dpp v205, v37, v161 row_shr:1 row_mask:0xf bank_mask:0xf
	v_fmac_f32_dpp v206, v38, v162 row_shr:1 row_mask:0xf bank_mask:0xf
	v_fmac_f32_dpp v207, v39, v163 row_shr:1 row_mask:0xf bank_mask:0xf
	v_fmac_f32_dpp v204, v52, v224 row_ror:1 row_mask:0xf bank_mask:0xf
	v_fmac_f32_dpp v205, v53, v225 row_ror:1 row_mask:0xf bank_mask:0xf
	v_fmac_f32_dpp v206, v54, v226 row_ror:1 row_mask:0xf bank_mask:0xf
	v_fmac_f32_dpp v207, v55, v227 row_ror:1 row_mask:0xf bank_mask:0xf
	v_fmac_f32_dpp v204, v36, v176 row_shl:1 row_mask:0xf bank_mask:0xf
	v_fmac_f32_dpp v205, v37, v177 row_shl:1 row_mask:0xf bank_mask:0xf
	v_fmac_f32_dpp v206, v38, v178 row_shl:1 row_mask:0xf bank_mask:0xf
	v_fmac_f32_dpp v207, v39, v179 row_shl:1 row_mask:0xf bank_mask:0xf
	v_fmac_f32_dpp v204, v20, v232 row_ror:15 row_mask:0xf bank_mask:0xf
	v_fmac_f32_dpp v205, v21, v233 row_ror:15 row_mask:0xf bank_mask:0xf
	v_fmac_f32_dpp v206, v22, v234 row_ror:15 row_mask:0xf bank_mask:0xf
	v_fmac_f32_dpp v207, v23, v235 row_ror:15 row_mask:0xf bank_mask:0xf
	v_mul_f32_e32 v208, 0xbfb8aa3b, v200
	v_mul_f32_e32 v209, 0xbfb8aa3b, v201
	v_mul_f32_e32 v210, 0xbfb8aa3b, v202
	v_mul_f32_e32 v211, 0xbfb8aa3b, v203
	v_exp_f32_e32 v208, v208
	v_exp_f32_e32 v209, v209
	v_exp_f32_e32 v210, v210
	v_exp_f32_e32 v211, v211
	v_add_f32_e32 v208, 1.0, v208
	v_add_f32_e32 v209, 1.0, v209
	v_add_f32_e32 v210, 1.0, v210
	v_add_f32_e32 v211, 1.0, v211
	v_rcp_f32_e32 v208, v208
	v_rcp_f32_e32 v209, v209
	v_rcp_f32_e32 v210, v210
	v_rcp_f32_e32 v211, v211
	v_mul_f32_e32 v200, v200, v208
	v_mul_f32_e32 v201, v201, v209
	v_mul_f32_e32 v202, v202, v210
	v_mul_f32_e32 v203, v203, v211
	v_mul_f32_e32 v200, v200, v204
	v_mul_f32_e32 v201, v201, v205
	v_mul_f32_e32 v202, v202, v206
	v_mul_f32_e32 v203, v203, v207
	v_cvt_pk_bf16_f32 v246, v200, v201
	v_cvt_pk_bf16_f32 v247, v202, v203
	v_fma_f32 v200, v132, v32, v140
	v_fma_f32 v201, v133, v33, v141
	v_fma_f32 v202, v134, v34, v142
	v_fma_f32 v203, v135, v35, v143
	v_fmac_f32_dpp v200, v32, v128 row_shr:1 row_mask:0xf bank_mask:0xf
	v_fmac_f32_dpp v201, v33, v129 row_shr:1 row_mask:0xf bank_mask:0xf
	v_fmac_f32_dpp v202, v34, v130 row_shr:1 row_mask:0xf bank_mask:0xf
	v_fmac_f32_dpp v203, v35, v131 row_shr:1 row_mask:0xf bank_mask:0xf
	v_fmac_f32_dpp v200, v48, v216 row_ror:1 row_mask:0xf bank_mask:0xf
	v_fmac_f32_dpp v201, v49, v217 row_ror:1 row_mask:0xf bank_mask:0xf
	v_fmac_f32_dpp v202, v50, v218 row_ror:1 row_mask:0xf bank_mask:0xf
	v_fmac_f32_dpp v203, v51, v219 row_ror:1 row_mask:0xf bank_mask:0xf
	v_fmac_f32_dpp v200, v32, v136 row_shl:1 row_mask:0xf bank_mask:0xf
	v_fmac_f32_dpp v201, v33, v137 row_shl:1 row_mask:0xf bank_mask:0xf
	v_fmac_f32_dpp v202, v34, v138 row_shl:1 row_mask:0xf bank_mask:0xf
	v_fmac_f32_dpp v203, v35, v139 row_shl:1 row_mask:0xf bank_mask:0xf
	v_fmac_f32_dpp v200, v16, v220 row_ror:15 row_mask:0xf bank_mask:0xf
	v_fmac_f32_dpp v201, v17, v221 row_ror:15 row_mask:0xf bank_mask:0xf
	v_fmac_f32_dpp v202, v18, v222 row_ror:15 row_mask:0xf bank_mask:0xf
	v_fmac_f32_dpp v203, v19, v223 row_ror:15 row_mask:0xf bank_mask:0xf
	v_fma_f32 v204, v172, v20, v180
	v_fma_f32 v205, v173, v21, v181
	v_fma_f32 v206, v174, v22, v182
	v_fma_f32 v207, v175, v23, v183
	v_fmac_f32_dpp v204, v20, v160 row_shr:1 row_mask:0xf bank_mask:0xf
	v_fmac_f32_dpp v205, v21, v161 row_shr:1 row_mask:0xf bank_mask:0xf
	v_fmac_f32_dpp v206, v22, v162 row_shr:1 row_mask:0xf bank_mask:0xf
	v_fmac_f32_dpp v207, v23, v163 row_shr:1 row_mask:0xf bank_mask:0xf
	v_fmac_f32_dpp v204, v36, v224 row_ror:1 row_mask:0xf bank_mask:0xf
	v_fmac_f32_dpp v205, v37, v225 row_ror:1 row_mask:0xf bank_mask:0xf
	v_fmac_f32_dpp v206, v38, v226 row_ror:1 row_mask:0xf bank_mask:0xf
	v_fmac_f32_dpp v207, v39, v227 row_ror:1 row_mask:0xf bank_mask:0xf
	v_fmac_f32_dpp v204, v20, v176 row_shl:1 row_mask:0xf bank_mask:0xf
	v_fmac_f32_dpp v205, v21, v177 row_shl:1 row_mask:0xf bank_mask:0xf
	v_fmac_f32_dpp v206, v22, v178 row_shl:1 row_mask:0xf bank_mask:0xf
	v_fmac_f32_dpp v207, v23, v179 row_shl:1 row_mask:0xf bank_mask:0xf
	v_fmac_f32_dpp v204, v4, v232 row_ror:15 row_mask:0xf bank_mask:0xf
	v_fmac_f32_dpp v205, v5, v233 row_ror:15 row_mask:0xf bank_mask:0xf
	v_fmac_f32_dpp v206, v6, v234 row_ror:15 row_mask:0xf bank_mask:0xf
	v_fmac_f32_dpp v207, v7, v235 row_ror:15 row_mask:0xf bank_mask:0xf
	v_mul_f32_e32 v208, 0xbfb8aa3b, v200
	v_mul_f32_e32 v209, 0xbfb8aa3b, v201
	v_mul_f32_e32 v210, 0xbfb8aa3b, v202
	v_mul_f32_e32 v211, 0xbfb8aa3b, v203
	v_exp_f32_e32 v208, v208
	v_exp_f32_e32 v209, v209
	v_exp_f32_e32 v210, v210
	v_exp_f32_e32 v211, v211
	v_add_f32_e32 v208, 1.0, v208
	v_add_f32_e32 v209, 1.0, v209
	v_add_f32_e32 v210, 1.0, v210
	v_add_f32_e32 v211, 1.0, v211
	v_rcp_f32_e32 v208, v208
	v_rcp_f32_e32 v209, v209
	v_rcp_f32_e32 v210, v210
	v_rcp_f32_e32 v211, v211
	v_mul_f32_e32 v200, v200, v208
	v_mul_f32_e32 v201, v201, v209
	v_mul_f32_e32 v202, v202, v210
	v_mul_f32_e32 v203, v203, v211
	v_mul_f32_e32 v200, v200, v204
	v_mul_f32_e32 v201, v201, v205
	v_mul_f32_e32 v202, v202, v206
	v_mul_f32_e32 v203, v203, v207
	v_cvt_pk_bf16_f32 v248, v200, v201
	v_cvt_pk_bf16_f32 v249, v202, v203
	v_fma_f32 v200, v132, v16, v140
	v_fma_f32 v201, v133, v17, v141
	v_fma_f32 v202, v134, v18, v142
	v_fma_f32 v203, v135, v19, v143
	v_fmac_f32_dpp v200, v16, v128 row_shr:1 row_mask:0xf bank_mask:0xf
	v_fmac_f32_dpp v201, v17, v129 row_shr:1 row_mask:0xf bank_mask:0xf
	v_fmac_f32_dpp v202, v18, v130 row_shr:1 row_mask:0xf bank_mask:0xf
	v_fmac_f32_dpp v203, v19, v131 row_shr:1 row_mask:0xf bank_mask:0xf
	v_fmac_f32_dpp v200, v32, v216 row_ror:1 row_mask:0xf bank_mask:0xf
	v_fmac_f32_dpp v201, v33, v217 row_ror:1 row_mask:0xf bank_mask:0xf
	v_fmac_f32_dpp v202, v34, v218 row_ror:1 row_mask:0xf bank_mask:0xf
	v_fmac_f32_dpp v203, v35, v219 row_ror:1 row_mask:0xf bank_mask:0xf
	v_fmac_f32_dpp v200, v16, v136 row_shl:1 row_mask:0xf bank_mask:0xf
	v_fmac_f32_dpp v201, v17, v137 row_shl:1 row_mask:0xf bank_mask:0xf
	v_fmac_f32_dpp v202, v18, v138 row_shl:1 row_mask:0xf bank_mask:0xf
	v_fmac_f32_dpp v203, v19, v139 row_shl:1 row_mask:0xf bank_mask:0xf
	v_fmac_f32_e32 v200, v192, v220
	v_fmac_f32_e32 v201, v193, v221
	v_fmac_f32_e32 v202, v194, v222
	v_fmac_f32_e32 v203, v195, v223
	v_fma_f32 v204, v172, v4, v180
	v_fma_f32 v205, v173, v5, v181
	v_fma_f32 v206, v174, v6, v182
	v_fma_f32 v207, v175, v7, v183
	v_fmac_f32_dpp v204, v4, v160 row_shr:1 row_mask:0xf bank_mask:0xf
	v_fmac_f32_dpp v205, v5, v161 row_shr:1 row_mask:0xf bank_mask:0xf
	v_fmac_f32_dpp v206, v6, v162 row_shr:1 row_mask:0xf bank_mask:0xf
	v_fmac_f32_dpp v207, v7, v163 row_shr:1 row_mask:0xf bank_mask:0xf
	v_fmac_f32_dpp v204, v20, v224 row_ror:1 row_mask:0xf bank_mask:0xf
	v_fmac_f32_dpp v205, v21, v225 row_ror:1 row_mask:0xf bank_mask:0xf
	v_fmac_f32_dpp v206, v22, v226 row_ror:1 row_mask:0xf bank_mask:0xf
	v_fmac_f32_dpp v207, v23, v227 row_ror:1 row_mask:0xf bank_mask:0xf
	v_fmac_f32_dpp v204, v4, v176 row_shl:1 row_mask:0xf bank_mask:0xf
	v_fmac_f32_dpp v205, v5, v177 row_shl:1 row_mask:0xf bank_mask:0xf
	v_fmac_f32_dpp v206, v6, v178 row_shl:1 row_mask:0xf bank_mask:0xf
	v_fmac_f32_dpp v207, v7, v179 row_shl:1 row_mask:0xf bank_mask:0xf
	v_fmac_f32_e32 v204, v196, v232
	v_fmac_f32_e32 v205, v197, v233
	v_fmac_f32_e32 v206, v198, v234
	v_fmac_f32_e32 v207, v199, v235
	v_mul_f32_e32 v208, 0xbfb8aa3b, v200
	v_mul_f32_e32 v209, 0xbfb8aa3b, v201
	v_mul_f32_e32 v210, 0xbfb8aa3b, v202
	v_mul_f32_e32 v211, 0xbfb8aa3b, v203
	v_exp_f32_e32 v208, v208
	v_exp_f32_e32 v209, v209
	v_exp_f32_e32 v210, v210
	v_exp_f32_e32 v211, v211
	v_add_f32_e32 v208, 1.0, v208
	v_add_f32_e32 v209, 1.0, v209
	v_add_f32_e32 v210, 1.0, v210
	v_add_f32_e32 v211, 1.0, v211
	v_rcp_f32_e32 v208, v208
	v_rcp_f32_e32 v209, v209
	v_rcp_f32_e32 v210, v210
	v_rcp_f32_e32 v211, v211
	v_mul_f32_e32 v200, v200, v208
	v_mul_f32_e32 v201, v201, v209
	v_mul_f32_e32 v202, v202, v210
	v_mul_f32_e32 v203, v203, v211
	v_mul_f32_e32 v200, v200, v204
	v_mul_f32_e32 v201, v201, v205
	v_mul_f32_e32 v202, v202, v206
	v_mul_f32_e32 v203, v203, v207
	v_cvt_pk_bf16_f32 v250, v200, v201
	v_cvt_pk_bf16_f32 v251, v202, v203
	global_load_dwordx4 v[128:131], v229, s[36:37] offset:16
	v_add_u32_e32 v211, 0x5800, v229
	global_load_dwordx4 v[132:135], v211, s[36:37] offset:16
	v_add_u32_e32 v210, 0xb000, v229
	global_load_dwordx4 v[136:139], v210, s[36:37] offset:16
	global_load_dwordx4 v[140:143], v229, s[38:39] offset:16
	v_add_u32_e32 v210, 0x2c00, v229
	global_load_dwordx4 v[160:163], v210, s[36:37] offset:16
	v_add_u32_e32 v211, 0x8400, v229
	global_load_dwordx4 v[172:175], v211, s[36:37] offset:16
	v_add_u32_e32 v210, 0xdc00, v229
	global_load_dwordx4 v[176:179], v210, s[36:37] offset:16
	v_add_u32_e32 v211, 0x2c00, v229
	global_load_dwordx4 v[180:183], v211, s[38:39] offset:16
	v_mov_b32_e32 v124, v236
	v_mov_b32_e32 v125, v237
	v_mov_b32_e32 v116, v238
	v_mov_b32_e32 v117, v239
	v_mov_b32_e32 v96, v240
	v_mov_b32_e32 v97, v241
	v_mov_b32_e32 v80, v242
	v_mov_b32_e32 v81, v243
	v_mov_b32_e32 v60, v244
	v_mov_b32_e32 v61, v245
	v_mov_b32_e32 v48, v246
	v_mov_b32_e32 v49, v247
	v_mov_b32_e32 v32, v248
	v_mov_b32_e32 v33, v249
	v_mov_b32_e32 v16, v250
	v_mov_b32_e32 v17, v251
	ds_read_b128 v[184:187], v231 offset:16
	ds_read_b128 v[188:191], v231 offset:528
	ds_read_b128 v[192:195], v231 offset:2064
	ds_read_b128 v[196:199], v231 offset:2576
	s_waitcnt vmcnt(0)
	v_cndmask_b32_e64 v216, 0, v128, s[54:55]
	v_cndmask_b32_e64 v220, 0, v136, s[56:57]
	v_cndmask_b32_e64 v217, 0, v129, s[54:55]
	v_cndmask_b32_e64 v221, 0, v137, s[56:57]
	v_cndmask_b32_e64 v218, 0, v130, s[54:55]
	v_cndmask_b32_e64 v222, 0, v138, s[56:57]
	v_cndmask_b32_e64 v219, 0, v131, s[54:55]
	v_cndmask_b32_e64 v223, 0, v139, s[56:57]
	v_cndmask_b32_e64 v224, 0, v160, s[54:55]
	v_cndmask_b32_e64 v232, 0, v176, s[56:57]
	v_cndmask_b32_e64 v225, 0, v161, s[54:55]
	v_cndmask_b32_e64 v233, 0, v177, s[56:57]
	v_cndmask_b32_e64 v226, 0, v162, s[54:55]
	v_cndmask_b32_e64 v234, 0, v178, s[56:57]
	v_cndmask_b32_e64 v227, 0, v163, s[54:55]
	v_cndmask_b32_e64 v235, 0, v179, s[56:57]
	s_waitcnt lgkmcnt(0)
	s_nop 1
	v_fma_f32 v200, v132, v120, v140
	v_fma_f32 v201, v133, v121, v141
	v_fma_f32 v202, v134, v122, v142
	v_fma_f32 v203, v135, v123, v143
	v_fmac_f32_dpp v200, v120, v128 row_shr:1 row_mask:0xf bank_mask:0xf
	v_fmac_f32_dpp v201, v121, v129 row_shr:1 row_mask:0xf bank_mask:0xf
	v_fmac_f32_dpp v202, v122, v130 row_shr:1 row_mask:0xf bank_mask:0xf
	v_fmac_f32_dpp v203, v123, v131 row_shr:1 row_mask:0xf bank_mask:0xf
	v_fmac_f32_e32 v200, v184, v216
	v_fmac_f32_e32 v201, v185, v217
	v_fmac_f32_e32 v202, v186, v218
	v_fmac_f32_e32 v203, v187, v219
	v_fmac_f32_dpp v200, v120, v136 row_shl:1 row_mask:0xf bank_mask:0xf
	v_fmac_f32_dpp v201, v121, v137 row_shl:1 row_mask:0xf bank_mask:0xf
	v_fmac_f32_dpp v202, v122, v138 row_shl:1 row_mask:0xf bank_mask:0xf
	v_fmac_f32_dpp v203, v123, v139 row_shl:1 row_mask:0xf bank_mask:0xf
	v_fmac_f32_dpp v200, v112, v220 row_ror:15 row_mask:0xf bank_mask:0xf
	v_fmac_f32_dpp v201, v113, v221 row_ror:15 row_mask:0xf bank_mask:0xf
	v_fmac_f32_dpp v202, v114, v222 row_ror:15 row_mask:0xf bank_mask:0xf
	v_fmac_f32_dpp v203, v115, v223 row_ror:15 row_mask:0xf bank_mask:0xf
	v_fma_f32 v204, v172, v104, v180
	v_fma_f32 v205, v173, v105, v181
	v_fma_f32 v206, v174, v106, v182
	v_fma_f32 v207, v175, v107, v183
	v_fmac_f32_dpp v204, v104, v160 row_shr:1 row_mask:0xf bank_mask:0xf
	v_fmac_f32_dpp v205, v105, v161 row_shr:1 row_mask:0xf bank_mask:0xf
	v_fmac_f32_dpp v206, v106, v162 row_shr:1 row_mask:0xf bank_mask:0xf
	v_fmac_f32_dpp v207, v107, v163 row_shr:1 row_mask:0xf bank_mask:0xf
	v_fmac_f32_e32 v204, v188, v224
	v_fmac_f32_e32 v205, v189, v225
	v_fmac_f32_e32 v206, v190, v226
	v_fmac_f32_e32 v207, v191, v227
	v_fmac_f32_dpp v204, v104, v176 row_shl:1 row_mask:0xf bank_mask:0xf
	v_fmac_f32_dpp v205, v105, v177 row_shl:1 row_mask:0xf bank_mask:0xf
	v_fmac_f32_dpp v206, v106, v178 row_shl:1 row_mask:0xf bank_mask:0xf
	v_fmac_f32_dpp v207, v107, v179 row_shl:1 row_mask:0xf bank_mask:0xf
	v_fmac_f32_dpp v204, v92, v232 row_ror:15 row_mask:0xf bank_mask:0xf
	v_fmac_f32_dpp v205, v93, v233 row_ror:15 row_mask:0xf bank_mask:0xf
	v_fmac_f32_dpp v206, v94, v234 row_ror:15 row_mask:0xf bank_mask:0xf
	v_fmac_f32_dpp v207, v95, v235 row_ror:15 row_mask:0xf bank_mask:0xf
	v_mul_f32_e32 v208, 0xbfb8aa3b, v200
	v_mul_f32_e32 v209, 0xbfb8aa3b, v201
	v_mul_f32_e32 v210, 0xbfb8aa3b, v202
	v_mul_f32_e32 v211, 0xbfb8aa3b, v203
	v_exp_f32_e32 v208, v208
	v_exp_f32_e32 v209, v209
	v_exp_f32_e32 v210, v210
	v_exp_f32_e32 v211, v211
	v_add_f32_e32 v208, 1.0, v208
	v_add_f32_e32 v209, 1.0, v209
	v_add_f32_e32 v210, 1.0, v210
	v_add_f32_e32 v211, 1.0, v211
	v_rcp_f32_e32 v208, v208
	v_rcp_f32_e32 v209, v209
	v_rcp_f32_e32 v210, v210
	v_rcp_f32_e32 v211, v211
	v_mul_f32_e32 v200, v200, v208
	v_mul_f32_e32 v201, v201, v209
	v_mul_f32_e32 v202, v202, v210
	v_mul_f32_e32 v203, v203, v211
	v_mul_f32_e32 v200, v200, v204
	v_mul_f32_e32 v201, v201, v205
	v_mul_f32_e32 v202, v202, v206
	v_mul_f32_e32 v203, v203, v207
	v_cvt_pk_bf16_f32 v126, v200, v201
	v_cvt_pk_bf16_f32 v127, v202, v203
	v_fma_f32 v200, v132, v112, v140
	v_fma_f32 v201, v133, v113, v141
	v_fma_f32 v202, v134, v114, v142
	v_fma_f32 v203, v135, v115, v143
	v_fmac_f32_dpp v200, v112, v128 row_shr:1 row_mask:0xf bank_mask:0xf
	v_fmac_f32_dpp v201, v113, v129 row_shr:1 row_mask:0xf bank_mask:0xf
	v_fmac_f32_dpp v202, v114, v130 row_shr:1 row_mask:0xf bank_mask:0xf
	v_fmac_f32_dpp v203, v115, v131 row_shr:1 row_mask:0xf bank_mask:0xf
	v_fmac_f32_dpp v200, v120, v216 row_ror:1 row_mask:0xf bank_mask:0xf
	v_fmac_f32_dpp v201, v121, v217 row_ror:1 row_mask:0xf bank_mask:0xf
	v_fmac_f32_dpp v202, v122, v218 row_ror:1 row_mask:0xf bank_mask:0xf
	v_fmac_f32_dpp v203, v123, v219 row_ror:1 row_mask:0xf bank_mask:0xf
	v_fmac_f32_dpp v200, v112, v136 row_shl:1 row_mask:0xf bank_mask:0xf
	v_fmac_f32_dpp v201, v113, v137 row_shl:1 row_mask:0xf bank_mask:0xf
	v_fmac_f32_dpp v202, v114, v138 row_shl:1 row_mask:0xf bank_mask:0xf
	v_fmac_f32_dpp v203, v115, v139 row_shl:1 row_mask:0xf bank_mask:0xf
	v_fmac_f32_dpp v200, v88, v220 row_ror:15 row_mask:0xf bank_mask:0xf
	v_fmac_f32_dpp v201, v89, v221 row_ror:15 row_mask:0xf bank_mask:0xf
	v_fmac_f32_dpp v202, v90, v222 row_ror:15 row_mask:0xf bank_mask:0xf
	v_fmac_f32_dpp v203, v91, v223 row_ror:15 row_mask:0xf bank_mask:0xf
	v_fma_f32 v204, v172, v92, v180
	v_fma_f32 v205, v173, v93, v181
	v_fma_f32 v206, v174, v94, v182
	v_fma_f32 v207, v175, v95, v183
	v_fmac_f32_dpp v204, v92, v160 row_shr:1 row_mask:0xf bank_mask:0xf
	v_fmac_f32_dpp v205, v93, v161 row_shr:1 row_mask:0xf bank_mask:0xf
	v_fmac_f32_dpp v206, v94, v162 row_shr:1 row_mask:0xf bank_mask:0xf
	v_fmac_f32_dpp v207, v95, v163 row_shr:1 row_mask:0xf bank_mask:0xf
	v_fmac_f32_dpp v204, v104, v224 row_ror:1 row_mask:0xf bank_mask:0xf
	v_fmac_f32_dpp v205, v105, v225 row_ror:1 row_mask:0xf bank_mask:0xf
	v_fmac_f32_dpp v206, v106, v226 row_ror:1 row_mask:0xf bank_mask:0xf
	v_fmac_f32_dpp v207, v107, v227 row_ror:1 row_mask:0xf bank_mask:0xf
	v_fmac_f32_dpp v204, v92, v176 row_shl:1 row_mask:0xf bank_mask:0xf
	v_fmac_f32_dpp v205, v93, v177 row_shl:1 row_mask:0xf bank_mask:0xf
	v_fmac_f32_dpp v206, v94, v178 row_shl:1 row_mask:0xf bank_mask:0xf
	v_fmac_f32_dpp v207, v95, v179 row_shl:1 row_mask:0xf bank_mask:0xf
	v_fmac_f32_dpp v204, v76, v232 row_ror:15 row_mask:0xf bank_mask:0xf
	v_fmac_f32_dpp v205, v77, v233 row_ror:15 row_mask:0xf bank_mask:0xf
	v_fmac_f32_dpp v206, v78, v234 row_ror:15 row_mask:0xf bank_mask:0xf
	v_fmac_f32_dpp v207, v79, v235 row_ror:15 row_mask:0xf bank_mask:0xf
	v_mul_f32_e32 v208, 0xbfb8aa3b, v200
	v_mul_f32_e32 v209, 0xbfb8aa3b, v201
	v_mul_f32_e32 v210, 0xbfb8aa3b, v202
	v_mul_f32_e32 v211, 0xbfb8aa3b, v203
	v_exp_f32_e32 v208, v208
	v_exp_f32_e32 v209, v209
	v_exp_f32_e32 v210, v210
	v_exp_f32_e32 v211, v211
	v_add_f32_e32 v208, 1.0, v208
	v_add_f32_e32 v209, 1.0, v209
	v_add_f32_e32 v210, 1.0, v210
	v_add_f32_e32 v211, 1.0, v211
	v_rcp_f32_e32 v208, v208
	v_rcp_f32_e32 v209, v209
	v_rcp_f32_e32 v210, v210
	v_rcp_f32_e32 v211, v211
	v_mul_f32_e32 v200, v200, v208
	v_mul_f32_e32 v201, v201, v209
	v_mul_f32_e32 v202, v202, v210
	v_mul_f32_e32 v203, v203, v211
	v_mul_f32_e32 v200, v200, v204
	v_mul_f32_e32 v201, v201, v205
	v_mul_f32_e32 v202, v202, v206
	v_mul_f32_e32 v203, v203, v207
	v_cvt_pk_bf16_f32 v118, v200, v201
	v_cvt_pk_bf16_f32 v119, v202, v203
	v_fma_f32 v200, v132, v88, v140
	v_fma_f32 v201, v133, v89, v141
	v_fma_f32 v202, v134, v90, v142
	v_fma_f32 v203, v135, v91, v143
	v_fmac_f32_dpp v200, v88, v128 row_shr:1 row_mask:0xf bank_mask:0xf
	v_fmac_f32_dpp v201, v89, v129 row_shr:1 row_mask:0xf bank_mask:0xf
	v_fmac_f32_dpp v202, v90, v130 row_shr:1 row_mask:0xf bank_mask:0xf
	v_fmac_f32_dpp v203, v91, v131 row_shr:1 row_mask:0xf bank_mask:0xf
	v_fmac_f32_dpp v200, v112, v216 row_ror:1 row_mask:0xf bank_mask:0xf
	v_fmac_f32_dpp v201, v113, v217 row_ror:1 row_mask:0xf bank_mask:0xf
	v_fmac_f32_dpp v202, v114, v218 row_ror:1 row_mask:0xf bank_mask:0xf
	v_fmac_f32_dpp v203, v115, v219 row_ror:1 row_mask:0xf bank_mask:0xf
	v_fmac_f32_dpp v200, v88, v136 row_shl:1 row_mask:0xf bank_mask:0xf
	v_fmac_f32_dpp v201, v89, v137 row_shl:1 row_mask:0xf bank_mask:0xf
	v_fmac_f32_dpp v202, v90, v138 row_shl:1 row_mask:0xf bank_mask:0xf
	v_fmac_f32_dpp v203, v91, v139 row_shl:1 row_mask:0xf bank_mask:0xf
	v_fmac_f32_dpp v200, v72, v220 row_ror:15 row_mask:0xf bank_mask:0xf
	v_fmac_f32_dpp v201, v73, v221 row_ror:15 row_mask:0xf bank_mask:0xf
	v_fmac_f32_dpp v202, v74, v222 row_ror:15 row_mask:0xf bank_mask:0xf
	v_fmac_f32_dpp v203, v75, v223 row_ror:15 row_mask:0xf bank_mask:0xf
	v_fma_f32 v204, v172, v76, v180
	v_fma_f32 v205, v173, v77, v181
	v_fma_f32 v206, v174, v78, v182
	v_fma_f32 v207, v175, v79, v183
	v_fmac_f32_dpp v204, v76, v160 row_shr:1 row_mask:0xf bank_mask:0xf
	v_fmac_f32_dpp v205, v77, v161 row_shr:1 row_mask:0xf bank_mask:0xf
	v_fmac_f32_dpp v206, v78, v162 row_shr:1 row_mask:0xf bank_mask:0xf
	v_fmac_f32_dpp v207, v79, v163 row_shr:1 row_mask:0xf bank_mask:0xf
	v_fmac_f32_dpp v204, v92, v224 row_ror:1 row_mask:0xf bank_mask:0xf
	v_fmac_f32_dpp v205, v93, v225 row_ror:1 row_mask:0xf bank_mask:0xf
	v_fmac_f32_dpp v206, v94, v226 row_ror:1 row_mask:0xf bank_mask:0xf
	v_fmac_f32_dpp v207, v95, v227 row_ror:1 row_mask:0xf bank_mask:0xf
	v_fmac_f32_dpp v204, v76, v176 row_shl:1 row_mask:0xf bank_mask:0xf
	v_fmac_f32_dpp v205, v77, v177 row_shl:1 row_mask:0xf bank_mask:0xf
	v_fmac_f32_dpp v206, v78, v178 row_shl:1 row_mask:0xf bank_mask:0xf
	v_fmac_f32_dpp v207, v79, v179 row_shl:1 row_mask:0xf bank_mask:0xf
	v_fmac_f32_dpp v204, v64, v232 row_ror:15 row_mask:0xf bank_mask:0xf
	v_fmac_f32_dpp v205, v65, v233 row_ror:15 row_mask:0xf bank_mask:0xf
	v_fmac_f32_dpp v206, v66, v234 row_ror:15 row_mask:0xf bank_mask:0xf
	v_fmac_f32_dpp v207, v67, v235 row_ror:15 row_mask:0xf bank_mask:0xf
	v_mul_f32_e32 v208, 0xbfb8aa3b, v200
	v_mul_f32_e32 v209, 0xbfb8aa3b, v201
	v_mul_f32_e32 v210, 0xbfb8aa3b, v202
	v_mul_f32_e32 v211, 0xbfb8aa3b, v203
	v_exp_f32_e32 v208, v208
	v_exp_f32_e32 v209, v209
	v_exp_f32_e32 v210, v210
	v_exp_f32_e32 v211, v211
	v_add_f32_e32 v208, 1.0, v208
	v_add_f32_e32 v209, 1.0, v209
	v_add_f32_e32 v210, 1.0, v210
	v_add_f32_e32 v211, 1.0, v211
	v_rcp_f32_e32 v208, v208
	v_rcp_f32_e32 v209, v209
	v_rcp_f32_e32 v210, v210
	v_rcp_f32_e32 v211, v211
	v_mul_f32_e32 v200, v200, v208
	v_mul_f32_e32 v201, v201, v209
	v_mul_f32_e32 v202, v202, v210
	v_mul_f32_e32 v203, v203, v211
	v_mul_f32_e32 v200, v200, v204
	v_mul_f32_e32 v201, v201, v205
	v_mul_f32_e32 v202, v202, v206
	v_mul_f32_e32 v203, v203, v207
	v_cvt_pk_bf16_f32 v98, v200, v201
	v_cvt_pk_bf16_f32 v99, v202, v203
	v_fma_f32 v200, v132, v72, v140
	v_fma_f32 v201, v133, v73, v141
	v_fma_f32 v202, v134, v74, v142
	v_fma_f32 v203, v135, v75, v143
	v_fmac_f32_dpp v200, v72, v128 row_shr:1 row_mask:0xf bank_mask:0xf
	v_fmac_f32_dpp v201, v73, v129 row_shr:1 row_mask:0xf bank_mask:0xf
	v_fmac_f32_dpp v202, v74, v130 row_shr:1 row_mask:0xf bank_mask:0xf
	v_fmac_f32_dpp v203, v75, v131 row_shr:1 row_mask:0xf bank_mask:0xf
	v_fmac_f32_dpp v200, v88, v216 row_ror:1 row_mask:0xf bank_mask:0xf
	v_fmac_f32_dpp v201, v89, v217 row_ror:1 row_mask:0xf bank_mask:0xf
	v_fmac_f32_dpp v202, v90, v218 row_ror:1 row_mask:0xf bank_mask:0xf
	v_fmac_f32_dpp v203, v91, v219 row_ror:1 row_mask:0xf bank_mask:0xf
	v_fmac_f32_dpp v200, v72, v136 row_shl:1 row_mask:0xf bank_mask:0xf
	v_fmac_f32_dpp v201, v73, v137 row_shl:1 row_mask:0xf bank_mask:0xf
	v_fmac_f32_dpp v202, v74, v138 row_shl:1 row_mask:0xf bank_mask:0xf
	v_fmac_f32_dpp v203, v75, v139 row_shl:1 row_mask:0xf bank_mask:0xf
	v_fmac_f32_e32 v200, v184, v220
	v_fmac_f32_e32 v201, v185, v221
	v_fmac_f32_e32 v202, v186, v222
	v_fmac_f32_e32 v203, v187, v223
	v_fma_f32 v204, v172, v64, v180
	v_fma_f32 v205, v173, v65, v181
	v_fma_f32 v206, v174, v66, v182
	v_fma_f32 v207, v175, v67, v183
	v_fmac_f32_dpp v204, v64, v160 row_shr:1 row_mask:0xf bank_mask:0xf
	v_fmac_f32_dpp v205, v65, v161 row_shr:1 row_mask:0xf bank_mask:0xf
	v_fmac_f32_dpp v206, v66, v162 row_shr:1 row_mask:0xf bank_mask:0xf
	v_fmac_f32_dpp v207, v67, v163 row_shr:1 row_mask:0xf bank_mask:0xf
	v_fmac_f32_dpp v204, v76, v224 row_ror:1 row_mask:0xf bank_mask:0xf
	v_fmac_f32_dpp v205, v77, v225 row_ror:1 row_mask:0xf bank_mask:0xf
	v_fmac_f32_dpp v206, v78, v226 row_ror:1 row_mask:0xf bank_mask:0xf
	v_fmac_f32_dpp v207, v79, v227 row_ror:1 row_mask:0xf bank_mask:0xf
	v_fmac_f32_dpp v204, v64, v176 row_shl:1 row_mask:0xf bank_mask:0xf
	v_fmac_f32_dpp v205, v65, v177 row_shl:1 row_mask:0xf bank_mask:0xf
	v_fmac_f32_dpp v206, v66, v178 row_shl:1 row_mask:0xf bank_mask:0xf
	v_fmac_f32_dpp v207, v67, v179 row_shl:1 row_mask:0xf bank_mask:0xf
	v_fmac_f32_e32 v204, v188, v232
	v_fmac_f32_e32 v205, v189, v233
	v_fmac_f32_e32 v206, v190, v234
	v_fmac_f32_e32 v207, v191, v235
	v_mul_f32_e32 v208, 0xbfb8aa3b, v200
	v_mul_f32_e32 v209, 0xbfb8aa3b, v201
	v_mul_f32_e32 v210, 0xbfb8aa3b, v202
	v_mul_f32_e32 v211, 0xbfb8aa3b, v203
	v_exp_f32_e32 v208, v208
	v_exp_f32_e32 v209, v209
	v_exp_f32_e32 v210, v210
	v_exp_f32_e32 v211, v211
	v_add_f32_e32 v208, 1.0, v208
	v_add_f32_e32 v209, 1.0, v209
	v_add_f32_e32 v210, 1.0, v210
	v_add_f32_e32 v211, 1.0, v211
	v_rcp_f32_e32 v208, v208
	v_rcp_f32_e32 v209, v209
	v_rcp_f32_e32 v210, v210
	v_rcp_f32_e32 v211, v211
	v_mul_f32_e32 v200, v200, v208
	v_mul_f32_e32 v201, v201, v209
	v_mul_f32_e32 v202, v202, v210
	v_mul_f32_e32 v203, v203, v211
	v_mul_f32_e32 v200, v200, v204
	v_mul_f32_e32 v201, v201, v205
	v_mul_f32_e32 v202, v202, v206
	v_mul_f32_e32 v203, v203, v207
	v_cvt_pk_bf16_f32 v82, v200, v201
	v_cvt_pk_bf16_f32 v83, v202, v203
	v_fma_f32 v200, v132, v56, v140
	v_fma_f32 v201, v133, v57, v141
	v_fma_f32 v202, v134, v58, v142
	v_fma_f32 v203, v135, v59, v143
	v_fmac_f32_dpp v200, v56, v128 row_shr:1 row_mask:0xf bank_mask:0xf
	v_fmac_f32_dpp v201, v57, v129 row_shr:1 row_mask:0xf bank_mask:0xf
	v_fmac_f32_dpp v202, v58, v130 row_shr:1 row_mask:0xf bank_mask:0xf
	v_fmac_f32_dpp v203, v59, v131 row_shr:1 row_mask:0xf bank_mask:0xf
	v_fmac_f32_e32 v200, v192, v216
	v_fmac_f32_e32 v201, v193, v217
	v_fmac_f32_e32 v202, v194, v218
	v_fmac_f32_e32 v203, v195, v219
	v_fmac_f32_dpp v200, v56, v136 row_shl:1 row_mask:0xf bank_mask:0xf
	v_fmac_f32_dpp v201, v57, v137 row_shl:1 row_mask:0xf bank_mask:0xf
	v_fmac_f32_dpp v202, v58, v138 row_shl:1 row_mask:0xf bank_mask:0xf
	v_fmac_f32_dpp v203, v59, v139 row_shl:1 row_mask:0xf bank_mask:0xf
	v_fmac_f32_dpp v200, v40, v220 row_ror:15 row_mask:0xf bank_mask:0xf
	v_fmac_f32_dpp v201, v41, v221 row_ror:15 row_mask:0xf bank_mask:0xf
	v_fmac_f32_dpp v202, v42, v222 row_ror:15 row_mask:0xf bank_mask:0xf
	v_fmac_f32_dpp v203, v43, v223 row_ror:15 row_mask:0xf bank_mask:0xf
	v_fma_f32 v204, v172, v44, v180
	v_fma_f32 v205, v173, v45, v181
	v_fma_f32 v206, v174, v46, v182
	v_fma_f32 v207, v175, v47, v183
	v_fmac_f32_dpp v204, v44, v160 row_shr:1 row_mask:0xf bank_mask:0xf
	v_fmac_f32_dpp v205, v45, v161 row_shr:1 row_mask:0xf bank_mask:0xf
	v_fmac_f32_dpp v206, v46, v162 row_shr:1 row_mask:0xf bank_mask:0xf
	v_fmac_f32_dpp v207, v47, v163 row_shr:1 row_mask:0xf bank_mask:0xf
	v_fmac_f32_e32 v204, v196, v224
	v_fmac_f32_e32 v205, v197, v225
	v_fmac_f32_e32 v206, v198, v226
	v_fmac_f32_e32 v207, v199, v227
	v_fmac_f32_dpp v204, v44, v176 row_shl:1 row_mask:0xf bank_mask:0xf
	v_fmac_f32_dpp v205, v45, v177 row_shl:1 row_mask:0xf bank_mask:0xf
	v_fmac_f32_dpp v206, v46, v178 row_shl:1 row_mask:0xf bank_mask:0xf
	v_fmac_f32_dpp v207, v47, v179 row_shl:1 row_mask:0xf bank_mask:0xf
	v_fmac_f32_dpp v204, v28, v232 row_ror:15 row_mask:0xf bank_mask:0xf
	v_fmac_f32_dpp v205, v29, v233 row_ror:15 row_mask:0xf bank_mask:0xf
	v_fmac_f32_dpp v206, v30, v234 row_ror:15 row_mask:0xf bank_mask:0xf
	v_fmac_f32_dpp v207, v31, v235 row_ror:15 row_mask:0xf bank_mask:0xf
	v_mul_f32_e32 v208, 0xbfb8aa3b, v200
	v_mul_f32_e32 v209, 0xbfb8aa3b, v201
	v_mul_f32_e32 v210, 0xbfb8aa3b, v202
	v_mul_f32_e32 v211, 0xbfb8aa3b, v203
	v_exp_f32_e32 v208, v208
	v_exp_f32_e32 v209, v209
	v_exp_f32_e32 v210, v210
	v_exp_f32_e32 v211, v211
	v_add_f32_e32 v208, 1.0, v208
	v_add_f32_e32 v209, 1.0, v209
	v_add_f32_e32 v210, 1.0, v210
	v_add_f32_e32 v211, 1.0, v211
	v_rcp_f32_e32 v208, v208
	v_rcp_f32_e32 v209, v209
	v_rcp_f32_e32 v210, v210
	v_rcp_f32_e32 v211, v211
	v_mul_f32_e32 v200, v200, v208
	v_mul_f32_e32 v201, v201, v209
	v_mul_f32_e32 v202, v202, v210
	v_mul_f32_e32 v203, v203, v211
	v_mul_f32_e32 v200, v200, v204
	v_mul_f32_e32 v201, v201, v205
	v_mul_f32_e32 v202, v202, v206
	v_mul_f32_e32 v203, v203, v207
	v_cvt_pk_bf16_f32 v62, v200, v201
	v_cvt_pk_bf16_f32 v63, v202, v203
	v_fma_f32 v200, v132, v40, v140
	v_fma_f32 v201, v133, v41, v141
	v_fma_f32 v202, v134, v42, v142
	v_fma_f32 v203, v135, v43, v143
	v_fmac_f32_dpp v200, v40, v128 row_shr:1 row_mask:0xf bank_mask:0xf
	v_fmac_f32_dpp v201, v41, v129 row_shr:1 row_mask:0xf bank_mask:0xf
	v_fmac_f32_dpp v202, v42, v130 row_shr:1 row_mask:0xf bank_mask:0xf
	v_fmac_f32_dpp v203, v43, v131 row_shr:1 row_mask:0xf bank_mask:0xf
	v_fmac_f32_dpp v200, v56, v216 row_ror:1 row_mask:0xf bank_mask:0xf
	v_fmac_f32_dpp v201, v57, v217 row_ror:1 row_mask:0xf bank_mask:0xf
	v_fmac_f32_dpp v202, v58, v218 row_ror:1 row_mask:0xf bank_mask:0xf
	v_fmac_f32_dpp v203, v59, v219 row_ror:1 row_mask:0xf bank_mask:0xf
	v_fmac_f32_dpp v200, v40, v136 row_shl:1 row_mask:0xf bank_mask:0xf
	v_fmac_f32_dpp v201, v41, v137 row_shl:1 row_mask:0xf bank_mask:0xf
	v_fmac_f32_dpp v202, v42, v138 row_shl:1 row_mask:0xf bank_mask:0xf
	v_fmac_f32_dpp v203, v43, v139 row_shl:1 row_mask:0xf bank_mask:0xf
	v_fmac_f32_dpp v200, v24, v220 row_ror:15 row_mask:0xf bank_mask:0xf
	v_fmac_f32_dpp v201, v25, v221 row_ror:15 row_mask:0xf bank_mask:0xf
	v_fmac_f32_dpp v202, v26, v222 row_ror:15 row_mask:0xf bank_mask:0xf
	v_fmac_f32_dpp v203, v27, v223 row_ror:15 row_mask:0xf bank_mask:0xf
	v_fma_f32 v204, v172, v28, v180
	v_fma_f32 v205, v173, v29, v181
	v_fma_f32 v206, v174, v30, v182
	v_fma_f32 v207, v175, v31, v183
	v_fmac_f32_dpp v204, v28, v160 row_shr:1 row_mask:0xf bank_mask:0xf
	v_fmac_f32_dpp v205, v29, v161 row_shr:1 row_mask:0xf bank_mask:0xf
	v_fmac_f32_dpp v206, v30, v162 row_shr:1 row_mask:0xf bank_mask:0xf
	v_fmac_f32_dpp v207, v31, v163 row_shr:1 row_mask:0xf bank_mask:0xf
	v_fmac_f32_dpp v204, v44, v224 row_ror:1 row_mask:0xf bank_mask:0xf
	v_fmac_f32_dpp v205, v45, v225 row_ror:1 row_mask:0xf bank_mask:0xf
	v_fmac_f32_dpp v206, v46, v226 row_ror:1 row_mask:0xf bank_mask:0xf
	v_fmac_f32_dpp v207, v47, v227 row_ror:1 row_mask:0xf bank_mask:0xf
	v_fmac_f32_dpp v204, v28, v176 row_shl:1 row_mask:0xf bank_mask:0xf
	v_fmac_f32_dpp v205, v29, v177 row_shl:1 row_mask:0xf bank_mask:0xf
	v_fmac_f32_dpp v206, v30, v178 row_shl:1 row_mask:0xf bank_mask:0xf
	v_fmac_f32_dpp v207, v31, v179 row_shl:1 row_mask:0xf bank_mask:0xf
	v_fmac_f32_dpp v204, v12, v232 row_ror:15 row_mask:0xf bank_mask:0xf
	v_fmac_f32_dpp v205, v13, v233 row_ror:15 row_mask:0xf bank_mask:0xf
	v_fmac_f32_dpp v206, v14, v234 row_ror:15 row_mask:0xf bank_mask:0xf
	v_fmac_f32_dpp v207, v15, v235 row_ror:15 row_mask:0xf bank_mask:0xf
	v_mul_f32_e32 v208, 0xbfb8aa3b, v200
	v_mul_f32_e32 v209, 0xbfb8aa3b, v201
	v_mul_f32_e32 v210, 0xbfb8aa3b, v202
	v_mul_f32_e32 v211, 0xbfb8aa3b, v203
	v_exp_f32_e32 v208, v208
	v_exp_f32_e32 v209, v209
	v_exp_f32_e32 v210, v210
	v_exp_f32_e32 v211, v211
	v_add_f32_e32 v208, 1.0, v208
	v_add_f32_e32 v209, 1.0, v209
	v_add_f32_e32 v210, 1.0, v210
	v_add_f32_e32 v211, 1.0, v211
	v_rcp_f32_e32 v208, v208
	v_rcp_f32_e32 v209, v209
	v_rcp_f32_e32 v210, v210
	v_rcp_f32_e32 v211, v211
	v_mul_f32_e32 v200, v200, v208
	v_mul_f32_e32 v201, v201, v209
	v_mul_f32_e32 v202, v202, v210
	v_mul_f32_e32 v203, v203, v211
	v_mul_f32_e32 v200, v200, v204
	v_mul_f32_e32 v201, v201, v205
	v_mul_f32_e32 v202, v202, v206
	v_mul_f32_e32 v203, v203, v207
	v_cvt_pk_bf16_f32 v50, v200, v201
	v_cvt_pk_bf16_f32 v51, v202, v203
	v_fma_f32 v200, v132, v24, v140
	v_fma_f32 v201, v133, v25, v141
	v_fma_f32 v202, v134, v26, v142
	v_fma_f32 v203, v135, v27, v143
	v_fmac_f32_dpp v200, v24, v128 row_shr:1 row_mask:0xf bank_mask:0xf
	v_fmac_f32_dpp v201, v25, v129 row_shr:1 row_mask:0xf bank_mask:0xf
	v_fmac_f32_dpp v202, v26, v130 row_shr:1 row_mask:0xf bank_mask:0xf
	v_fmac_f32_dpp v203, v27, v131 row_shr:1 row_mask:0xf bank_mask:0xf
	v_fmac_f32_dpp v200, v40, v216 row_ror:1 row_mask:0xf bank_mask:0xf
	v_fmac_f32_dpp v201, v41, v217 row_ror:1 row_mask:0xf bank_mask:0xf
	v_fmac_f32_dpp v202, v42, v218 row_ror:1 row_mask:0xf bank_mask:0xf
	v_fmac_f32_dpp v203, v43, v219 row_ror:1 row_mask:0xf bank_mask:0xf
	v_fmac_f32_dpp v200, v24, v136 row_shl:1 row_mask:0xf bank_mask:0xf
	v_fmac_f32_dpp v201, v25, v137 row_shl:1 row_mask:0xf bank_mask:0xf
	v_fmac_f32_dpp v202, v26, v138 row_shl:1 row_mask:0xf bank_mask:0xf
	v_fmac_f32_dpp v203, v27, v139 row_shl:1 row_mask:0xf bank_mask:0xf
	v_fmac_f32_dpp v200, v8, v220 row_ror:15 row_mask:0xf bank_mask:0xf
	v_fmac_f32_dpp v201, v9, v221 row_ror:15 row_mask:0xf bank_mask:0xf
	v_fmac_f32_dpp v202, v10, v222 row_ror:15 row_mask:0xf bank_mask:0xf
	v_fmac_f32_dpp v203, v11, v223 row_ror:15 row_mask:0xf bank_mask:0xf
	v_fma_f32 v204, v172, v12, v180
	v_fma_f32 v205, v173, v13, v181
	v_fma_f32 v206, v174, v14, v182
	v_fma_f32 v207, v175, v15, v183
	v_fmac_f32_dpp v204, v12, v160 row_shr:1 row_mask:0xf bank_mask:0xf
	v_fmac_f32_dpp v205, v13, v161 row_shr:1 row_mask:0xf bank_mask:0xf
	v_fmac_f32_dpp v206, v14, v162 row_shr:1 row_mask:0xf bank_mask:0xf
	v_fmac_f32_dpp v207, v15, v163 row_shr:1 row_mask:0xf bank_mask:0xf
	v_fmac_f32_dpp v204, v28, v224 row_ror:1 row_mask:0xf bank_mask:0xf
	v_fmac_f32_dpp v205, v29, v225 row_ror:1 row_mask:0xf bank_mask:0xf
	v_fmac_f32_dpp v206, v30, v226 row_ror:1 row_mask:0xf bank_mask:0xf
	v_fmac_f32_dpp v207, v31, v227 row_ror:1 row_mask:0xf bank_mask:0xf
	v_fmac_f32_dpp v204, v12, v176 row_shl:1 row_mask:0xf bank_mask:0xf
	v_fmac_f32_dpp v205, v13, v177 row_shl:1 row_mask:0xf bank_mask:0xf
	v_fmac_f32_dpp v206, v14, v178 row_shl:1 row_mask:0xf bank_mask:0xf
	v_fmac_f32_dpp v207, v15, v179 row_shl:1 row_mask:0xf bank_mask:0xf
	v_fmac_f32_dpp v204, v0, v232 row_ror:15 row_mask:0xf bank_mask:0xf
	v_fmac_f32_dpp v205, v1, v233 row_ror:15 row_mask:0xf bank_mask:0xf
	v_fmac_f32_dpp v206, v2, v234 row_ror:15 row_mask:0xf bank_mask:0xf
	v_fmac_f32_dpp v207, v3, v235 row_ror:15 row_mask:0xf bank_mask:0xf
	v_mul_f32_e32 v208, 0xbfb8aa3b, v200
	v_mul_f32_e32 v209, 0xbfb8aa3b, v201
	v_mul_f32_e32 v210, 0xbfb8aa3b, v202
	v_mul_f32_e32 v211, 0xbfb8aa3b, v203
	v_exp_f32_e32 v208, v208
	v_exp_f32_e32 v209, v209
	v_exp_f32_e32 v210, v210
	v_exp_f32_e32 v211, v211
	v_add_f32_e32 v208, 1.0, v208
	v_add_f32_e32 v209, 1.0, v209
	v_add_f32_e32 v210, 1.0, v210
	v_add_f32_e32 v211, 1.0, v211
	v_rcp_f32_e32 v208, v208
	v_rcp_f32_e32 v209, v209
	v_rcp_f32_e32 v210, v210
	v_rcp_f32_e32 v211, v211
	v_mul_f32_e32 v200, v200, v208
	v_mul_f32_e32 v201, v201, v209
	v_mul_f32_e32 v202, v202, v210
	v_mul_f32_e32 v203, v203, v211
	v_mul_f32_e32 v200, v200, v204
	v_mul_f32_e32 v201, v201, v205
	v_mul_f32_e32 v202, v202, v206
	v_mul_f32_e32 v203, v203, v207
	v_cvt_pk_bf16_f32 v34, v200, v201
	v_cvt_pk_bf16_f32 v35, v202, v203
	v_fma_f32 v200, v132, v8, v140
	v_fma_f32 v201, v133, v9, v141
	v_fma_f32 v202, v134, v10, v142
	v_fma_f32 v203, v135, v11, v143
	v_fmac_f32_dpp v200, v8, v128 row_shr:1 row_mask:0xf bank_mask:0xf
	v_fmac_f32_dpp v201, v9, v129 row_shr:1 row_mask:0xf bank_mask:0xf
	v_fmac_f32_dpp v202, v10, v130 row_shr:1 row_mask:0xf bank_mask:0xf
	v_fmac_f32_dpp v203, v11, v131 row_shr:1 row_mask:0xf bank_mask:0xf
	v_fmac_f32_dpp v200, v24, v216 row_ror:1 row_mask:0xf bank_mask:0xf
	v_fmac_f32_dpp v201, v25, v217 row_ror:1 row_mask:0xf bank_mask:0xf
	v_fmac_f32_dpp v202, v26, v218 row_ror:1 row_mask:0xf bank_mask:0xf
	v_fmac_f32_dpp v203, v27, v219 row_ror:1 row_mask:0xf bank_mask:0xf
	v_fmac_f32_dpp v200, v8, v136 row_shl:1 row_mask:0xf bank_mask:0xf
	v_fmac_f32_dpp v201, v9, v137 row_shl:1 row_mask:0xf bank_mask:0xf
	v_fmac_f32_dpp v202, v10, v138 row_shl:1 row_mask:0xf bank_mask:0xf
	v_fmac_f32_dpp v203, v11, v139 row_shl:1 row_mask:0xf bank_mask:0xf
	v_fmac_f32_e32 v200, v192, v220
	v_fmac_f32_e32 v201, v193, v221
	v_fmac_f32_e32 v202, v194, v222
	v_fmac_f32_e32 v203, v195, v223
	v_fma_f32 v204, v172, v0, v180
	v_fma_f32 v205, v173, v1, v181
	v_fma_f32 v206, v174, v2, v182
	v_fma_f32 v207, v175, v3, v183
	v_fmac_f32_dpp v204, v0, v160 row_shr:1 row_mask:0xf bank_mask:0xf
	v_fmac_f32_dpp v205, v1, v161 row_shr:1 row_mask:0xf bank_mask:0xf
	v_fmac_f32_dpp v206, v2, v162 row_shr:1 row_mask:0xf bank_mask:0xf
	v_fmac_f32_dpp v207, v3, v163 row_shr:1 row_mask:0xf bank_mask:0xf
	v_fmac_f32_dpp v204, v12, v224 row_ror:1 row_mask:0xf bank_mask:0xf
	v_fmac_f32_dpp v205, v13, v225 row_ror:1 row_mask:0xf bank_mask:0xf
	v_fmac_f32_dpp v206, v14, v226 row_ror:1 row_mask:0xf bank_mask:0xf
	v_fmac_f32_dpp v207, v15, v227 row_ror:1 row_mask:0xf bank_mask:0xf
	v_fmac_f32_dpp v204, v0, v176 row_shl:1 row_mask:0xf bank_mask:0xf
	v_fmac_f32_dpp v205, v1, v177 row_shl:1 row_mask:0xf bank_mask:0xf
	v_fmac_f32_dpp v206, v2, v178 row_shl:1 row_mask:0xf bank_mask:0xf
	v_fmac_f32_dpp v207, v3, v179 row_shl:1 row_mask:0xf bank_mask:0xf
	v_fmac_f32_e32 v204, v196, v232
	v_fmac_f32_e32 v205, v197, v233
	v_fmac_f32_e32 v206, v198, v234
	v_fmac_f32_e32 v207, v199, v235
	v_mul_f32_e32 v208, 0xbfb8aa3b, v200
	v_mul_f32_e32 v209, 0xbfb8aa3b, v201
	v_mul_f32_e32 v210, 0xbfb8aa3b, v202
	v_mul_f32_e32 v211, 0xbfb8aa3b, v203
	v_exp_f32_e32 v208, v208
	v_exp_f32_e32 v209, v209
	v_exp_f32_e32 v210, v210
	v_exp_f32_e32 v211, v211
	v_add_f32_e32 v208, 1.0, v208
	v_add_f32_e32 v209, 1.0, v209
	v_add_f32_e32 v210, 1.0, v210
	v_add_f32_e32 v211, 1.0, v211
	v_rcp_f32_e32 v208, v208
	v_rcp_f32_e32 v209, v209
	v_rcp_f32_e32 v210, v210
	v_rcp_f32_e32 v211, v211
	v_mul_f32_e32 v200, v200, v208
	v_mul_f32_e32 v201, v201, v209
	v_mul_f32_e32 v202, v202, v210
	v_mul_f32_e32 v203, v203, v211
	v_mul_f32_e32 v200, v200, v204
	v_mul_f32_e32 v201, v201, v205
	v_mul_f32_e32 v202, v202, v206
	v_mul_f32_e32 v203, v203, v207
	v_cvt_pk_bf16_f32 v18, v200, v201
	v_cvt_pk_bf16_f32 v19, v202, v203
	global_store_dwordx4 v171, v[124:127], s[40:41]
	v_add_u32_e32 v250, 0x16000, v171
	global_store_dwordx4 v250, v[116:119], s[40:41]
	s_nop 0
	v_add_u32_e32 v250, 0x2c000, v171
	global_store_dwordx4 v250, v[96:99], s[40:41]
	s_nop 0
	v_add_u32_e32 v250, 0x42000, v171
	global_store_dwordx4 v250, v[80:83], s[40:41]
	s_nop 0
	v_add_u32_e32 v250, 0xb0000, v171
	global_store_dwordx4 v250, v[60:63], s[40:41]
	s_nop 0
	v_add_u32_e32 v250, 0xc6000, v171
	global_store_dwordx4 v250, v[48:51], s[40:41]
	s_nop 0
	v_add_u32_e32 v250, 0xdc000, v171
	global_store_dwordx4 v250, v[32:35], s[40:41]
	s_nop 0
	v_add_u32_e32 v250, 0xf2000, v171
	global_store_dwordx4 v250, v[16:19], s[40:41]
	s_nop 0
	s_andn2_b64 vcc, exec, s[6:7]
	s_mov_b64 s[4:5], -1
	s_cbranch_vccnz .LBB0_1748
	s_andn2_b64 vcc, exec, s[12:13]
	s_cbranch_vccnz .LBB0_1747
	s_barrier
	s_branch .LBB0_1747

.LBB0_1880:
	s_and_b32 s23, s8, 1
	s_add_i32 s30, s6, 0
	s_ashr_i32 s30, s30, 2
	s_add_i32 s30, s30, 1
	s_cmp_gt_i32 s6, -1
	s_cselect_b32 s30, s30, 0
	s_mul_hi_i32 s31, s30, 0x5800
	s_mulk_i32 s30, 0x5800
	s_add_u32 s30, s33, s30
	s_addc_u32 s31, s50, s31
	v_lshl_add_u32 v236, s6, 8, v164
	v_lshlrev_b32_e32 v236, 2, v236
	v_lshl_or_b32 v229, s7, 7, v166
	v_lshlrev_b32_e32 v229, 2, v229
	global_load_dword v208, v236, s[10:11] offset:0
	global_load_dword v209, v236, s[10:11] offset:64
	global_load_dword v210, v236, s[10:11] offset:128
	global_load_dword v211, v236, s[10:11] offset:192
	global_load_dword v212, v236, s[10:11] offset:512
	global_load_dword v213, v236, s[10:11] offset:576
	global_load_dword v214, v236, s[10:11] offset:640
	global_load_dword v215, v236, s[10:11] offset:704
	global_load_dwordx4 v[200:203], v229, s[30:31]
	global_load_dwordx4 v[204:207], v229, s[30:31] offset:16
	v_add_u32_e32 v224, 0x2c00, v229
	global_load_dwordx4 v[216:219], v224, s[30:31]
	global_load_dwordx4 v[220:223], v224, s[30:31] offset:16
	v_readlane_b32 s34, v254, 5
	v_readlane_b32 s35, v254, 6
	v_readlane_b32 s36, v254, 7
	v_readlane_b32 s37, v254, 8
	s_add_u32 s34, s34, 0x10800
	s_addc_u32 s35, s35, 0
	s_add_u32 s36, s36, 0x5800
	s_addc_u32 s37, s37, 0
	s_mul_i32 s52, s6, 0x160000
	s_lshl_b32 s79, s7, 8
	s_add_i32 s52, s52, s79
	s_add_i32 s52, s52, 0xbf00000
	s_add_u32 s52, s52, s70
	s_addc_u32 s53, s71, 0
	v_mul_u32_u24_e32 v171, 0x1600, v164
	v_lshl_add_u32 v171, v166, 1, v171
	s_mov_b32 s32, 0x20800
	v_lshl_add_u32 v228, v166, 2, s32
	v_and_b32_e32 v237, 15, v164
	v_cmp_eq_u32_e64 s[54:55], 0, v237
	v_cmp_eq_u32_e64 s[56:57], 15, v237
	v_and_b32_e32 v231, 8, v237
	v_lshlrev_b32_e32 v231, 9, v231
	s_lshl_b32 s79, s23, 10
	v_add3_u32 v231, v231, v228, s79
	global_load_dwordx4 v[128:131], v229, s[34:35]
	v_add_u32_e32 v227, 0x5800, v229
	global_load_dwordx4 v[132:135], v227, s[34:35]
	v_add_u32_e32 v226, 0xb000, v229
	global_load_dwordx4 v[136:139], v226, s[34:35]
	global_load_dwordx4 v[140:143], v229, s[36:37]
	v_add_u32_e32 v226, 0x2c00, v229
	global_load_dwordx4 v[160:163], v226, s[34:35]
	v_add_u32_e32 v227, 0x8400, v229
	global_load_dwordx4 v[172:175], v227, s[34:35]
	v_add_u32_e32 v226, 0xdc00, v229
	global_load_dwordx4 v[176:179], v226, s[34:35]
	v_add_u32_e32 v227, 0x2c00, v229
	global_load_dwordx4 v[180:183], v227, s[36:37]
	s_waitcnt vmcnt(12)
	v_fmamk_f32 v208, v208, 0x3a800000, v170
	v_fmamk_f32 v209, v209, 0x3a800000, v170
	v_fmamk_f32 v210, v210, 0x3a800000, v170
	v_fmamk_f32 v211, v211, 0x3a800000, v170
	v_fmamk_f32 v212, v212, 0x3a800000, v170
	v_fmamk_f32 v213, v213, 0x3a800000, v170
	v_fmamk_f32 v214, v214, 0x3a800000, v170
	v_fmamk_f32 v215, v215, 0x3a800000, v170
	s_mov_b32 s79, 0x800000
	v_mul_f32_e32 v224, 0x4b800000, v208
	v_mul_f32_e32 v225, 0x4b800000, v209
	v_mul_f32_e32 v226, 0x4b800000, v210
	v_mul_f32_e32 v227, 0x4b800000, v211
	v_mul_f32_e32 v232, 0x4b800000, v212
	v_mul_f32_e32 v233, 0x4b800000, v213
	v_mul_f32_e32 v234, 0x4b800000, v214
	v_mul_f32_e32 v235, 0x4b800000, v215
	v_cmp_gt_f32_e32 vcc, s79, v208
	s_nop 1
	v_cndmask_b32_e32 v208, v208, v224, vcc
	v_rsq_f32_e32 v208, v208
	s_nop 0
	v_mul_f32_e32 v224, 0x45800000, v208
	v_cndmask_b32_e32 v208, v208, v224, vcc
	v_cmp_gt_f32_e32 vcc, s79, v209
	s_nop 1
	v_cndmask_b32_e32 v209, v209, v225, vcc
	v_rsq_f32_e32 v209, v209
	s_nop 0
	v_mul_f32_e32 v225, 0x45800000, v209
	v_cndmask_b32_e32 v209, v209, v225, vcc
	v_cmp_gt_f32_e32 vcc, s79, v210
	s_nop 1
	v_cndmask_b32_e32 v210, v210, v226, vcc
	v_rsq_f32_e32 v210, v210
	s_nop 0
	v_mul_f32_e32 v226, 0x45800000, v210
	v_cndmask_b32_e32 v210, v210, v226, vcc
	v_cmp_gt_f32_e32 vcc, s79, v211
	s_nop 1
	v_cndmask_b32_e32 v211, v211, v227, vcc
	v_rsq_f32_e32 v211, v211
	s_nop 0
	v_mul_f32_e32 v227, 0x45800000, v211
	v_cndmask_b32_e32 v211, v211, v227, vcc
	v_cmp_gt_f32_e32 vcc, s79, v212
	s_nop 1
	v_cndmask_b32_e32 v212, v212, v232, vcc
	v_rsq_f32_e32 v212, v212
	s_nop 0
	v_mul_f32_e32 v232, 0x45800000, v212
	v_cndmask_b32_e32 v212, v212, v232, vcc
	v_cmp_gt_f32_e32 vcc, s79, v213
	s_nop 1
	v_cndmask_b32_e32 v213, v213, v233, vcc
	v_rsq_f32_e32 v213, v213
	s_nop 0
	v_mul_f32_e32 v233, 0x45800000, v213
	v_cndmask_b32_e32 v213, v213, v233, vcc
	v_cmp_gt_f32_e32 vcc, s79, v214
	s_nop 1
	v_cndmask_b32_e32 v214, v214, v234, vcc
	v_rsq_f32_e32 v214, v214
	s_nop 0
	v_mul_f32_e32 v234, 0x45800000, v214
	v_cndmask_b32_e32 v214, v214, v234, vcc
	v_cmp_gt_f32_e32 vcc, s79, v215
	s_nop 1
	v_cndmask_b32_e32 v215, v215, v235, vcc
	v_rsq_f32_e32 v215, v215
	s_nop 0
	v_mul_f32_e32 v235, 0x45800000, v215
	v_cndmask_b32_e32 v215, v215, v235, vcc
	s_waitcnt vmcnt(8)
	v_fma_f32 v124, v124, v208, v200
	v_fma_f32 v125, v125, v208, v201
	v_fma_f32 v126, v126, v208, v202
	v_fma_f32 v127, v127, v208, v203
	v_fma_f32 v120, v120, v208, v204
	v_fma_f32 v121, v121, v208, v205
	v_fma_f32 v122, v122, v208, v206
	v_fma_f32 v123, v123, v208, v207
	v_fma_f32 v108, v108, v208, v216
	v_fma_f32 v109, v109, v208, v217
	v_fma_f32 v110, v110, v208, v218
	v_fma_f32 v111, v111, v208, v219
	v_fma_f32 v104, v104, v208, v220
	v_fma_f32 v105, v105, v208, v221
	v_fma_f32 v106, v106, v208, v222
	v_fma_f32 v107, v107, v208, v223
	v_fma_f32 v116, v116, v209, v200
	v_fma_f32 v117, v117, v209, v201
	v_fma_f32 v118, v118, v209, v202
	v_fma_f32 v119, v119, v209, v203
	v_fma_f32 v112, v112, v209, v204
	v_fma_f32 v113, v113, v209, v205
	v_fma_f32 v114, v114, v209, v206
	v_fma_f32 v115, v115, v209, v207
	v_fma_f32 v100, v100, v209, v216
	v_fma_f32 v101, v101, v209, v217
	v_fma_f32 v102, v102, v209, v218
	v_fma_f32 v103, v103, v209, v219
	v_fma_f32 v92, v92, v209, v220
	v_fma_f32 v93, v93, v209, v221
	v_fma_f32 v94, v94, v209, v222
	v_fma_f32 v95, v95, v209, v223
	v_fma_f32 v96, v96, v210, v200
	v_fma_f32 v97, v97, v210, v201
	v_fma_f32 v98, v98, v210, v202
	v_fma_f32 v99, v99, v210, v203
	v_fma_f32 v88, v88, v210, v204
	v_fma_f32 v89, v89, v210, v205
	v_fma_f32 v90, v90, v210, v206
	v_fma_f32 v91, v91, v210, v207
	v_fma_f32 v84, v84, v210, v216
	v_fma_f32 v85, v85, v210, v217
	v_fma_f32 v86, v86, v210, v218
	v_fma_f32 v87, v87, v210, v219
	v_fma_f32 v76, v76, v210, v220
	v_fma_f32 v77, v77, v210, v221
	v_fma_f32 v78, v78, v210, v222
	v_fma_f32 v79, v79, v210, v223
	v_fma_f32 v80, v80, v211, v200
	v_fma_f32 v81, v81, v211, v201
	v_fma_f32 v82, v82, v211, v202
	v_fma_f32 v83, v83, v211, v203
	v_fma_f32 v72, v72, v211, v204
	v_fma_f32 v73, v73, v211, v205
	v_fma_f32 v74, v74, v211, v206
	v_fma_f32 v75, v75, v211, v207
	v_fma_f32 v68, v68, v211, v216
	v_fma_f32 v69, v69, v211, v217
	v_fma_f32 v70, v70, v211, v218
	v_fma_f32 v71, v71, v211, v219
	v_fma_f32 v64, v64, v211, v220
	v_fma_f32 v65, v65, v211, v221
	v_fma_f32 v66, v66, v211, v222
	v_fma_f32 v67, v67, v211, v223
	v_fma_f32 v60, v60, v212, v200
	v_fma_f32 v61, v61, v212, v201
	v_fma_f32 v62, v62, v212, v202
	v_fma_f32 v63, v63, v212, v203
	v_fma_f32 v56, v56, v212, v204
	v_fma_f32 v57, v57, v212, v205
	v_fma_f32 v58, v58, v212, v206
	v_fma_f32 v59, v59, v212, v207
	v_fma_f32 v52, v52, v212, v216
	v_fma_f32 v53, v53, v212, v217
	v_fma_f32 v54, v54, v212, v218
	v_fma_f32 v55, v55, v212, v219
	v_fma_f32 v44, v44, v212, v220
	v_fma_f32 v45, v45, v212, v221
	v_fma_f32 v46, v46, v212, v222
	v_fma_f32 v47, v47, v212, v223
	v_fma_f32 v48, v48, v213, v200
	v_fma_f32 v49, v49, v213, v201
	v_fma_f32 v50, v50, v213, v202
	v_fma_f32 v51, v51, v213, v203
	v_fma_f32 v40, v40, v213, v204
	v_fma_f32 v41, v41, v213, v205
	v_fma_f32 v42, v42, v213, v206
	v_fma_f32 v43, v43, v213, v207
	v_fma_f32 v36, v36, v213, v216
	v_fma_f32 v37, v37, v213, v217
	v_fma_f32 v38, v38, v213, v218
	v_fma_f32 v39, v39, v213, v219
	v_fma_f32 v28, v28, v213, v220
	v_fma_f32 v29, v29, v213, v221
	v_fma_f32 v30, v30, v213, v222
	v_fma_f32 v31, v31, v213, v223
	v_fma_f32 v32, v32, v214, v200
	v_fma_f32 v33, v33, v214, v201
	v_fma_f32 v34, v34, v214, v202
	v_fma_f32 v35, v35, v214, v203
	v_fma_f32 v24, v24, v214, v204
	v_fma_f32 v25, v25, v214, v205
	v_fma_f32 v26, v26, v214, v206
	v_fma_f32 v27, v27, v214, v207
	v_fma_f32 v20, v20, v214, v216
	v_fma_f32 v21, v21, v214, v217
	v_fma_f32 v22, v22, v214, v218
	v_fma_f32 v23, v23, v214, v219
	v_fma_f32 v12, v12, v214, v220
	v_fma_f32 v13, v13, v214, v221
	v_fma_f32 v14, v14, v214, v222
	v_fma_f32 v15, v15, v214, v223
	v_fma_f32 v16, v16, v215, v200
	v_fma_f32 v17, v17, v215, v201
	v_fma_f32 v18, v18, v215, v202
	v_fma_f32 v19, v19, v215, v203
	v_fma_f32 v8, v8, v215, v204
	v_fma_f32 v9, v9, v215, v205
	v_fma_f32 v10, v10, v215, v206
	v_fma_f32 v11, v11, v215, v207
	v_fma_f32 v4, v4, v215, v216
	v_fma_f32 v5, v5, v215, v217
	v_fma_f32 v6, v6, v215, v218
	v_fma_f32 v7, v7, v215, v219
	v_fma_f32 v0, v0, v215, v220
	v_fma_f32 v1, v1, v215, v221
	v_fma_f32 v2, v2, v215, v222
	v_fma_f32 v3, v3, v215, v223
	v_mov_b32_e32 v212, 0
	v_mov_b32_e32 v213, 0
	v_mov_b32_e32 v214, 0
	v_mov_b32_e32 v215, 0
	s_lshl_b32 s96, s23, 12
	s_sub_i32 s96, 0x2000, s96
	s_mul_i32 s94, s23, 0x1400
	s_add_i32 s94, s94, 0xc00
	s_lshl_b32 s79, s23, 10
	s_add_i32 s95, s79, 5120
	s_add_i32 s92, s79, 1024
	s_mov_b64 s[58:59], exec
	s_mov_b64 exec, s[54:55]
	v_add_u32_e32 v250, s96, v228
	ds_write_b128 v250, v[124:127] offset:0
	ds_write_b128 v250, v[120:123] offset:16
	ds_write_b128 v250, v[108:111] offset:512
	ds_write_b128 v250, v[104:107] offset:528
	v_add_u32_e32 v250, s95, v228
	ds_write_b128 v250, v[60:63] offset:0
	ds_write_b128 v250, v[56:59] offset:16
	ds_write_b128 v250, v[52:55] offset:512
	ds_write_b128 v250, v[44:47] offset:528
	ds_write_b128 v228, v[212:215] offset:0
	ds_write_b128 v228, v[212:215] offset:16
	ds_write_b128 v228, v[212:215] offset:512
	ds_write_b128 v228, v[212:215] offset:528
	s_mov_b64 exec, s[56:57]
	v_add_u32_e32 v251, s92, v228
	ds_write_b128 v251, v[80:83] offset:0
	ds_write_b128 v251, v[72:75] offset:16
	ds_write_b128 v251, v[68:71] offset:512
	ds_write_b128 v251, v[64:67] offset:528
	v_add_u32_e32 v251, s94, v228
	ds_write_b128 v251, v[16:19] offset:0
	ds_write_b128 v251, v[8:11] offset:16
	ds_write_b128 v251, v[4:7] offset:512
	ds_write_b128 v251, v[0:3] offset:528
	ds_write_b128 v228, v[212:215] offset:7168
	ds_write_b128 v228, v[212:215] offset:7184
	ds_write_b128 v228, v[212:215] offset:7680
	ds_write_b128 v228, v[212:215] offset:7696
	s_mov_b64 exec, s[58:59]
	s_cmp_eq_u32 s23, 0
	s_cselect_b64 s[60:61], s[54:55], 0
	s_cselect_b64 s[62:63], 0, s[56:57]
	s_mul_i32 s64, s6, 0x16000
	s_add_u32 s64, s64, 0x5b00000
	s_add_u32 s64, s64, s70
	s_addc_u32 s65, s71, 0
	s_mov_b64 exec, s[60:61]
	global_store_dwordx4 v229, v[124:127], s[64:65]
	global_store_dwordx4 v229, v[120:123], s[64:65] offset:16
	v_add_u32_e32 v250, 0x2c00, v229
	global_store_dwordx4 v250, v[108:111], s[64:65]
	global_store_dwordx4 v250, v[104:107], s[64:65] offset:16
	s_mov_b64 exec, s[62:63]
	v_add_u32_e32 v250, 0xb000, v229
	global_store_dwordx4 v250, v[16:19], s[64:65]
	global_store_dwordx4 v250, v[8:11], s[64:65] offset:16
	v_add_u32_e32 v250, 0xdc00, v229
	global_store_dwordx4 v250, v[4:7], s[64:65]
	global_store_dwordx4 v250, v[0:3], s[64:65] offset:16
	s_mov_b64 exec, s[58:59]
	s_waitcnt lgkmcnt(0)
	s_barrier
	ds_read_b128 v[184:187], v231 offset:0
	ds_read_b128 v[188:191], v231 offset:512
	ds_read_b128 v[192:195], v231 offset:2048
	ds_read_b128 v[196:199], v231 offset:2560
	s_waitcnt vmcnt(0)
	v_cndmask_b32_e64 v216, 0, v128, s[54:55]
	v_cndmask_b32_e64 v220, 0, v136, s[56:57]
	v_cndmask_b32_e64 v217, 0, v129, s[54:55]
	v_cndmask_b32_e64 v221, 0, v137, s[56:57]
	v_cndmask_b32_e64 v218, 0, v130, s[54:55]
	v_cndmask_b32_e64 v222, 0, v138, s[56:57]
	v_cndmask_b32_e64 v219, 0, v131, s[54:55]
	v_cndmask_b32_e64 v223, 0, v139, s[56:57]
	v_cndmask_b32_e64 v224, 0, v160, s[54:55]
	v_cndmask_b32_e64 v232, 0, v176, s[56:57]
	v_cndmask_b32_e64 v225, 0, v161, s[54:55]
	v_cndmask_b32_e64 v233, 0, v177, s[56:57]
	v_cndmask_b32_e64 v226, 0, v162, s[54:55]
	v_cndmask_b32_e64 v234, 0, v178, s[56:57]
	v_cndmask_b32_e64 v227, 0, v163, s[54:55]
	v_cndmask_b32_e64 v235, 0, v179, s[56:57]
	s_waitcnt lgkmcnt(0)
	s_nop 1
	v_fma_f32 v200, v132, v124, v140
	v_fma_f32 v201, v133, v125, v141
	v_fma_f32 v202, v134, v126, v142
	v_fma_f32 v203, v135, v127, v143
	v_fmac_f32_dpp v200, v124, v128 row_shr:1 row_mask:0xf bank_mask:0xf
	v_fmac_f32_dpp v201, v125, v129 row_shr:1 row_mask:0xf bank_mask:0xf
	v_fmac_f32_dpp v202, v126, v130 row_shr:1 row_mask:0xf bank_mask:0xf
	v_fmac_f32_dpp v203, v127, v131 row_shr:1 row_mask:0xf bank_mask:0xf
	v_fmac_f32_e32 v200, v184, v216
	v_fmac_f32_e32 v201, v185, v217
	v_fmac_f32_e32 v202, v186, v218
	v_fmac_f32_e32 v203, v187, v219
	v_fmac_f32_dpp v200, v124, v136 row_shl:1 row_mask:0xf bank_mask:0xf
	v_fmac_f32_dpp v201, v125, v137 row_shl:1 row_mask:0xf bank_mask:0xf
	v_fmac_f32_dpp v202, v126, v138 row_shl:1 row_mask:0xf bank_mask:0xf
	v_fmac_f32_dpp v203, v127, v139 row_shl:1 row_mask:0xf bank_mask:0xf
	v_fmac_f32_dpp v200, v116, v220 row_ror:15 row_mask:0xf bank_mask:0xf
	v_fmac_f32_dpp v201, v117, v221 row_ror:15 row_mask:0xf bank_mask:0xf
	v_fmac_f32_dpp v202, v118, v222 row_ror:15 row_mask:0xf bank_mask:0xf
	v_fmac_f32_dpp v203, v119, v223 row_ror:15 row_mask:0xf bank_mask:0xf
	v_fma_f32 v204, v172, v108, v180
	v_fma_f32 v205, v173, v109, v181
	v_fma_f32 v206, v174, v110, v182
	v_fma_f32 v207, v175, v111, v183
	v_fmac_f32_dpp v204, v108, v160 row_shr:1 row_mask:0xf bank_mask:0xf
	v_fmac_f32_dpp v205, v109, v161 row_shr:1 row_mask:0xf bank_mask:0xf
	v_fmac_f32_dpp v206, v110, v162 row_shr:1 row_mask:0xf bank_mask:0xf
	v_fmac_f32_dpp v207, v111, v163 row_shr:1 row_mask:0xf bank_mask:0xf
	v_fmac_f32_e32 v204, v188, v224
	v_fmac_f32_e32 v205, v189, v225
	v_fmac_f32_e32 v206, v190, v226
	v_fmac_f32_e32 v207, v191, v227
	v_fmac_f32_dpp v204, v108, v176 row_shl:1 row_mask:0xf bank_mask:0xf
	v_fmac_f32_dpp v205, v109, v177 row_shl:1 row_mask:0xf bank_mask:0xf
	v_fmac_f32_dpp v206, v110, v178 row_shl:1 row_mask:0xf bank_mask:0xf
	v_fmac_f32_dpp v207, v111, v179 row_shl:1 row_mask:0xf bank_mask:0xf
	v_fmac_f32_dpp v204, v100, v232 row_ror:15 row_mask:0xf bank_mask:0xf
	v_fmac_f32_dpp v205, v101, v233 row_ror:15 row_mask:0xf bank_mask:0xf
	v_fmac_f32_dpp v206, v102, v234 row_ror:15 row_mask:0xf bank_mask:0xf
	v_fmac_f32_dpp v207, v103, v235 row_ror:15 row_mask:0xf bank_mask:0xf
	s_mov_b64 exec, s[60:61]
	v_add_u32_e32 v250, 0x5800, v229
	global_store_dwordx4 v250, v[200:203], s[64:65]
	v_add_u32_e32 v250, 0x8400, v229
	global_store_dwordx4 v250, v[204:207], s[64:65]
	s_mov_b64 exec, s[58:59]
	s_nop 4
	v_mul_f32_e32 v208, 0xbfb8aa3b, v200
	v_mul_f32_e32 v209, 0xbfb8aa3b, v201
	v_mul_f32_e32 v210, 0xbfb8aa3b, v202
	v_mul_f32_e32 v211, 0xbfb8aa3b, v203
	v_exp_f32_e32 v208, v208
	v_exp_f32_e32 v209, v209
	v_exp_f32_e32 v210, v210
	v_exp_f32_e32 v211, v211
	v_add_f32_e32 v208, 1.0, v208
	v_add_f32_e32 v209, 1.0, v209
	v_add_f32_e32 v210, 1.0, v210
	v_add_f32_e32 v211, 1.0, v211
	v_rcp_f32_e32 v208, v208
	v_rcp_f32_e32 v209, v209
	v_rcp_f32_e32 v210, v210
	v_rcp_f32_e32 v211, v211
	v_mul_f32_e32 v200, v200, v208
	v_mul_f32_e32 v201, v201, v209
	v_mul_f32_e32 v202, v202, v210
	v_mul_f32_e32 v203, v203, v211
	v_mul_f32_e32 v200, v200, v204
	v_mul_f32_e32 v201, v201, v205
	v_mul_f32_e32 v202, v202, v206
	v_mul_f32_e32 v203, v203, v207
	v_cvt_pk_bf16_f32 v236, v200, v201
	v_cvt_pk_bf16_f32 v237, v202, v203
	v_fma_f32 v200, v132, v116, v140
	v_fma_f32 v201, v133, v117, v141
	v_fma_f32 v202, v134, v118, v142
	v_fma_f32 v203, v135, v119, v143
	v_fmac_f32_dpp v200, v116, v128 row_shr:1 row_mask:0xf bank_mask:0xf
	v_fmac_f32_dpp v201, v117, v129 row_shr:1 row_mask:0xf bank_mask:0xf
	v_fmac_f32_dpp v202, v118, v130 row_shr:1 row_mask:0xf bank_mask:0xf
	v_fmac_f32_dpp v203, v119, v131 row_shr:1 row_mask:0xf bank_mask:0xf
	v_fmac_f32_dpp v200, v124, v216 row_ror:1 row_mask:0xf bank_mask:0xf
	v_fmac_f32_dpp v201, v125, v217 row_ror:1 row_mask:0xf bank_mask:0xf
	v_fmac_f32_dpp v202, v126, v218 row_ror:1 row_mask:0xf bank_mask:0xf
	v_fmac_f32_dpp v203, v127, v219 row_ror:1 row_mask:0xf bank_mask:0xf
	v_fmac_f32_dpp v200, v116, v136 row_shl:1 row_mask:0xf bank_mask:0xf
	v_fmac_f32_dpp v201, v117, v137 row_shl:1 row_mask:0xf bank_mask:0xf
	v_fmac_f32_dpp v202, v118, v138 row_shl:1 row_mask:0xf bank_mask:0xf
	v_fmac_f32_dpp v203, v119, v139 row_shl:1 row_mask:0xf bank_mask:0xf
	v_fmac_f32_dpp v200, v96, v220 row_ror:15 row_mask:0xf bank_mask:0xf
	v_fmac_f32_dpp v201, v97, v221 row_ror:15 row_mask:0xf bank_mask:0xf
	v_fmac_f32_dpp v202, v98, v222 row_ror:15 row_mask:0xf bank_mask:0xf
	v_fmac_f32_dpp v203, v99, v223 row_ror:15 row_mask:0xf bank_mask:0xf
	v_fma_f32 v204, v172, v100, v180
	v_fma_f32 v205, v173, v101, v181
	v_fma_f32 v206, v174, v102, v182
	v_fma_f32 v207, v175, v103, v183
	v_fmac_f32_dpp v204, v100, v160 row_shr:1 row_mask:0xf bank_mask:0xf
	v_fmac_f32_dpp v205, v101, v161 row_shr:1 row_mask:0xf bank_mask:0xf
	v_fmac_f32_dpp v206, v102, v162 row_shr:1 row_mask:0xf bank_mask:0xf
	v_fmac_f32_dpp v207, v103, v163 row_shr:1 row_mask:0xf bank_mask:0xf
	v_fmac_f32_dpp v204, v108, v224 row_ror:1 row_mask:0xf bank_mask:0xf
	v_fmac_f32_dpp v205, v109, v225 row_ror:1 row_mask:0xf bank_mask:0xf
	v_fmac_f32_dpp v206, v110, v226 row_ror:1 row_mask:0xf bank_mask:0xf
	v_fmac_f32_dpp v207, v111, v227 row_ror:1 row_mask:0xf bank_mask:0xf
	v_fmac_f32_dpp v204, v100, v176 row_shl:1 row_mask:0xf bank_mask:0xf
	v_fmac_f32_dpp v205, v101, v177 row_shl:1 row_mask:0xf bank_mask:0xf
	v_fmac_f32_dpp v206, v102, v178 row_shl:1 row_mask:0xf bank_mask:0xf
	v_fmac_f32_dpp v207, v103, v179 row_shl:1 row_mask:0xf bank_mask:0xf
	v_fmac_f32_dpp v204, v84, v232 row_ror:15 row_mask:0xf bank_mask:0xf
	v_fmac_f32_dpp v205, v85, v233 row_ror:15 row_mask:0xf bank_mask:0xf
	v_fmac_f32_dpp v206, v86, v234 row_ror:15 row_mask:0xf bank_mask:0xf
	v_fmac_f32_dpp v207, v87, v235 row_ror:15 row_mask:0xf bank_mask:0xf
	v_mul_f32_e32 v208, 0xbfb8aa3b, v200
	v_mul_f32_e32 v209, 0xbfb8aa3b, v201
	v_mul_f32_e32 v210, 0xbfb8aa3b, v202
	v_mul_f32_e32 v211, 0xbfb8aa3b, v203
	v_exp_f32_e32 v208, v208
	v_exp_f32_e32 v209, v209
	v_exp_f32_e32 v210, v210
	v_exp_f32_e32 v211, v211
	v_add_f32_e32 v208, 1.0, v208
	v_add_f32_e32 v209, 1.0, v209
	v_add_f32_e32 v210, 1.0, v210
	v_add_f32_e32 v211, 1.0, v211
	v_rcp_f32_e32 v208, v208
	v_rcp_f32_e32 v209, v209
	v_rcp_f32_e32 v210, v210
	v_rcp_f32_e32 v211, v211
	v_mul_f32_e32 v200, v200, v208
	v_mul_f32_e32 v201, v201, v209
	v_mul_f32_e32 v202, v202, v210
	v_mul_f32_e32 v203, v203, v211
	v_mul_f32_e32 v200, v200, v204
	v_mul_f32_e32 v201, v201, v205
	v_mul_f32_e32 v202, v202, v206
	v_mul_f32_e32 v203, v203, v207
	v_cvt_pk_bf16_f32 v238, v200, v201
	v_cvt_pk_bf16_f32 v239, v202, v203
	v_fma_f32 v200, v132, v96, v140
	v_fma_f32 v201, v133, v97, v141
	v_fma_f32 v202, v134, v98, v142
	v_fma_f32 v203, v135, v99, v143
	v_fmac_f32_dpp v200, v96, v128 row_shr:1 row_mask:0xf bank_mask:0xf
	v_fmac_f32_dpp v201, v97, v129 row_shr:1 row_mask:0xf bank_mask:0xf
	v_fmac_f32_dpp v202, v98, v130 row_shr:1 row_mask:0xf bank_mask:0xf
	v_fmac_f32_dpp v203, v99, v131 row_shr:1 row_mask:0xf bank_mask:0xf
	v_fmac_f32_dpp v200, v116, v216 row_ror:1 row_mask:0xf bank_mask:0xf
	v_fmac_f32_dpp v201, v117, v217 row_ror:1 row_mask:0xf bank_mask:0xf
	v_fmac_f32_dpp v202, v118, v218 row_ror:1 row_mask:0xf bank_mask:0xf
	v_fmac_f32_dpp v203, v119, v219 row_ror:1 row_mask:0xf bank_mask:0xf
	v_fmac_f32_dpp v200, v96, v136 row_shl:1 row_mask:0xf bank_mask:0xf
	v_fmac_f32_dpp v201, v97, v137 row_shl:1 row_mask:0xf bank_mask:0xf
	v_fmac_f32_dpp v202, v98, v138 row_shl:1 row_mask:0xf bank_mask:0xf
	v_fmac_f32_dpp v203, v99, v139 row_shl:1 row_mask:0xf bank_mask:0xf
	v_fmac_f32_dpp v200, v80, v220 row_ror:15 row_mask:0xf bank_mask:0xf
	v_fmac_f32_dpp v201, v81, v221 row_ror:15 row_mask:0xf bank_mask:0xf
	v_fmac_f32_dpp v202, v82, v222 row_ror:15 row_mask:0xf bank_mask:0xf
	v_fmac_f32_dpp v203, v83, v223 row_ror:15 row_mask:0xf bank_mask:0xf
	v_fma_f32 v204, v172, v84, v180
	v_fma_f32 v205, v173, v85, v181
	v_fma_f32 v206, v174, v86, v182
	v_fma_f32 v207, v175, v87, v183
	v_fmac_f32_dpp v204, v84, v160 row_shr:1 row_mask:0xf bank_mask:0xf
	v_fmac_f32_dpp v205, v85, v161 row_shr:1 row_mask:0xf bank_mask:0xf
	v_fmac_f32_dpp v206, v86, v162 row_shr:1 row_mask:0xf bank_mask:0xf
	v_fmac_f32_dpp v207, v87, v163 row_shr:1 row_mask:0xf bank_mask:0xf
	v_fmac_f32_dpp v204, v100, v224 row_ror:1 row_mask:0xf bank_mask:0xf
	v_fmac_f32_dpp v205, v101, v225 row_ror:1 row_mask:0xf bank_mask:0xf
	v_fmac_f32_dpp v206, v102, v226 row_ror:1 row_mask:0xf bank_mask:0xf
	v_fmac_f32_dpp v207, v103, v227 row_ror:1 row_mask:0xf bank_mask:0xf
	v_fmac_f32_dpp v204, v84, v176 row_shl:1 row_mask:0xf bank_mask:0xf
	v_fmac_f32_dpp v205, v85, v177 row_shl:1 row_mask:0xf bank_mask:0xf
	v_fmac_f32_dpp v206, v86, v178 row_shl:1 row_mask:0xf bank_mask:0xf
	v_fmac_f32_dpp v207, v87, v179 row_shl:1 row_mask:0xf bank_mask:0xf
	v_fmac_f32_dpp v204, v68, v232 row_ror:15 row_mask:0xf bank_mask:0xf
	v_fmac_f32_dpp v205, v69, v233 row_ror:15 row_mask:0xf bank_mask:0xf
	v_fmac_f32_dpp v206, v70, v234 row_ror:15 row_mask:0xf bank_mask:0xf
	v_fmac_f32_dpp v207, v71, v235 row_ror:15 row_mask:0xf bank_mask:0xf
	v_mul_f32_e32 v208, 0xbfb8aa3b, v200
	v_mul_f32_e32 v209, 0xbfb8aa3b, v201
	v_mul_f32_e32 v210, 0xbfb8aa3b, v202
	v_mul_f32_e32 v211, 0xbfb8aa3b, v203
	v_exp_f32_e32 v208, v208
	v_exp_f32_e32 v209, v209
	v_exp_f32_e32 v210, v210
	v_exp_f32_e32 v211, v211
	v_add_f32_e32 v208, 1.0, v208
	v_add_f32_e32 v209, 1.0, v209
	v_add_f32_e32 v210, 1.0, v210
	v_add_f32_e32 v211, 1.0, v211
	v_rcp_f32_e32 v208, v208
	v_rcp_f32_e32 v209, v209
	v_rcp_f32_e32 v210, v210
	v_rcp_f32_e32 v211, v211
	v_mul_f32_e32 v200, v200, v208
	v_mul_f32_e32 v201, v201, v209
	v_mul_f32_e32 v202, v202, v210
	v_mul_f32_e32 v203, v203, v211
	v_mul_f32_e32 v200, v200, v204
	v_mul_f32_e32 v201, v201, v205
	v_mul_f32_e32 v202, v202, v206
	v_mul_f32_e32 v203, v203, v207
	v_cvt_pk_bf16_f32 v240, v200, v201
	v_cvt_pk_bf16_f32 v241, v202, v203
	v_fma_f32 v200, v132, v80, v140
	v_fma_f32 v201, v133, v81, v141
	v_fma_f32 v202, v134, v82, v142
	v_fma_f32 v203, v135, v83, v143
	v_fmac_f32_dpp v200, v80, v128 row_shr:1 row_mask:0xf bank_mask:0xf
	v_fmac_f32_dpp v201, v81, v129 row_shr:1 row_mask:0xf bank_mask:0xf
	v_fmac_f32_dpp v202, v82, v130 row_shr:1 row_mask:0xf bank_mask:0xf
	v_fmac_f32_dpp v203, v83, v131 row_shr:1 row_mask:0xf bank_mask:0xf
	v_fmac_f32_dpp v200, v96, v216 row_ror:1 row_mask:0xf bank_mask:0xf
	v_fmac_f32_dpp v201, v97, v217 row_ror:1 row_mask:0xf bank_mask:0xf
	v_fmac_f32_dpp v202, v98, v218 row_ror:1 row_mask:0xf bank_mask:0xf
	v_fmac_f32_dpp v203, v99, v219 row_ror:1 row_mask:0xf bank_mask:0xf
	v_fmac_f32_dpp v200, v80, v136 row_shl:1 row_mask:0xf bank_mask:0xf
	v_fmac_f32_dpp v201, v81, v137 row_shl:1 row_mask:0xf bank_mask:0xf
	v_fmac_f32_dpp v202, v82, v138 row_shl:1 row_mask:0xf bank_mask:0xf
	v_fmac_f32_dpp v203, v83, v139 row_shl:1 row_mask:0xf bank_mask:0xf
	v_fmac_f32_e32 v200, v184, v220
	v_fmac_f32_e32 v201, v185, v221
	v_fmac_f32_e32 v202, v186, v222
	v_fmac_f32_e32 v203, v187, v223
	v_fma_f32 v204, v172, v68, v180
	v_fma_f32 v205, v173, v69, v181
	v_fma_f32 v206, v174, v70, v182
	v_fma_f32 v207, v175, v71, v183
	v_fmac_f32_dpp v204, v68, v160 row_shr:1 row_mask:0xf bank_mask:0xf
	v_fmac_f32_dpp v205, v69, v161 row_shr:1 row_mask:0xf bank_mask:0xf
	v_fmac_f32_dpp v206, v70, v162 row_shr:1 row_mask:0xf bank_mask:0xf
	v_fmac_f32_dpp v207, v71, v163 row_shr:1 row_mask:0xf bank_mask:0xf
	v_fmac_f32_dpp v204, v84, v224 row_ror:1 row_mask:0xf bank_mask:0xf
	v_fmac_f32_dpp v205, v85, v225 row_ror:1 row_mask:0xf bank_mask:0xf
	v_fmac_f32_dpp v206, v86, v226 row_ror:1 row_mask:0xf bank_mask:0xf
	v_fmac_f32_dpp v207, v87, v227 row_ror:1 row_mask:0xf bank_mask:0xf
	v_fmac_f32_dpp v204, v68, v176 row_shl:1 row_mask:0xf bank_mask:0xf
	v_fmac_f32_dpp v205, v69, v177 row_shl:1 row_mask:0xf bank_mask:0xf
	v_fmac_f32_dpp v206, v70, v178 row_shl:1 row_mask:0xf bank_mask:0xf
	v_fmac_f32_dpp v207, v71, v179 row_shl:1 row_mask:0xf bank_mask:0xf
	v_fmac_f32_e32 v204, v188, v232
	v_fmac_f32_e32 v205, v189, v233
	v_fmac_f32_e32 v206, v190, v234
	v_fmac_f32_e32 v207, v191, v235
	v_mul_f32_e32 v208, 0xbfb8aa3b, v200
	v_mul_f32_e32 v209, 0xbfb8aa3b, v201
	v_mul_f32_e32 v210, 0xbfb8aa3b, v202
	v_mul_f32_e32 v211, 0xbfb8aa3b, v203
	v_exp_f32_e32 v208, v208
	v_exp_f32_e32 v209, v209
	v_exp_f32_e32 v210, v210
	v_exp_f32_e32 v211, v211
	v_add_f32_e32 v208, 1.0, v208
	v_add_f32_e32 v209, 1.0, v209
	v_add_f32_e32 v210, 1.0, v210
	v_add_f32_e32 v211, 1.0, v211
	v_rcp_f32_e32 v208, v208
	v_rcp_f32_e32 v209, v209
	v_rcp_f32_e32 v210, v210
	v_rcp_f32_e32 v211, v211
	v_mul_f32_e32 v200, v200, v208
	v_mul_f32_e32 v201, v201, v209
	v_mul_f32_e32 v202, v202, v210
	v_mul_f32_e32 v203, v203, v211
	v_mul_f32_e32 v200, v200, v204
	v_mul_f32_e32 v201, v201, v205
	v_mul_f32_e32 v202, v202, v206
	v_mul_f32_e32 v203, v203, v207
	v_cvt_pk_bf16_f32 v242, v200, v201
	v_cvt_pk_bf16_f32 v243, v202, v203
	v_fma_f32 v200, v132, v60, v140
	v_fma_f32 v201, v133, v61, v141
	v_fma_f32 v202, v134, v62, v142
	v_fma_f32 v203, v135, v63, v143
	v_fmac_f32_dpp v200, v60, v128 row_shr:1 row_mask:0xf bank_mask:0xf
	v_fmac_f32_dpp v201, v61, v129 row_shr:1 row_mask:0xf bank_mask:0xf
	v_fmac_f32_dpp v202, v62, v130 row_shr:1 row_mask:0xf bank_mask:0xf
	v_fmac_f32_dpp v203, v63, v131 row_shr:1 row_mask:0xf bank_mask:0xf
	v_fmac_f32_e32 v200, v192, v216
	v_fmac_f32_e32 v201, v193, v217
	v_fmac_f32_e32 v202, v194, v218
	v_fmac_f32_e32 v203, v195, v219
	v_fmac_f32_dpp v200, v60, v136 row_shl:1 row_mask:0xf bank_mask:0xf
	v_fmac_f32_dpp v201, v61, v137 row_shl:1 row_mask:0xf bank_mask:0xf
	v_fmac_f32_dpp v202, v62, v138 row_shl:1 row_mask:0xf bank_mask:0xf
	v_fmac_f32_dpp v203, v63, v139 row_shl:1 row_mask:0xf bank_mask:0xf
	v_fmac_f32_dpp v200, v48, v220 row_ror:15 row_mask:0xf bank_mask:0xf
	v_fmac_f32_dpp v201, v49, v221 row_ror:15 row_mask:0xf bank_mask:0xf
	v_fmac_f32_dpp v202, v50, v222 row_ror:15 row_mask:0xf bank_mask:0xf
	v_fmac_f32_dpp v203, v51, v223 row_ror:15 row_mask:0xf bank_mask:0xf
	v_fma_f32 v204, v172, v52, v180
	v_fma_f32 v205, v173, v53, v181
	v_fma_f32 v206, v174, v54, v182
	v_fma_f32 v207, v175, v55, v183
	v_fmac_f32_dpp v204, v52, v160 row_shr:1 row_mask:0xf bank_mask:0xf
	v_fmac_f32_dpp v205, v53, v161 row_shr:1 row_mask:0xf bank_mask:0xf
	v_fmac_f32_dpp v206, v54, v162 row_shr:1 row_mask:0xf bank_mask:0xf
	v_fmac_f32_dpp v207, v55, v163 row_shr:1 row_mask:0xf bank_mask:0xf
	v_fmac_f32_e32 v204, v196, v224
	v_fmac_f32_e32 v205, v197, v225
	v_fmac_f32_e32 v206, v198, v226
	v_fmac_f32_e32 v207, v199, v227
	v_fmac_f32_dpp v204, v52, v176 row_shl:1 row_mask:0xf bank_mask:0xf
	v_fmac_f32_dpp v205, v53, v177 row_shl:1 row_mask:0xf bank_mask:0xf
	v_fmac_f32_dpp v206, v54, v178 row_shl:1 row_mask:0xf bank_mask:0xf
	v_fmac_f32_dpp v207, v55, v179 row_shl:1 row_mask:0xf bank_mask:0xf
	v_fmac_f32_dpp v204, v36, v232 row_ror:15 row_mask:0xf bank_mask:0xf
	v_fmac_f32_dpp v205, v37, v233 row_ror:15 row_mask:0xf bank_mask:0xf
	v_fmac_f32_dpp v206, v38, v234 row_ror:15 row_mask:0xf bank_mask:0xf
	v_fmac_f32_dpp v207, v39, v235 row_ror:15 row_mask:0xf bank_mask:0xf
	v_mul_f32_e32 v208, 0xbfb8aa3b, v200
	v_mul_f32_e32 v209, 0xbfb8aa3b, v201
	v_mul_f32_e32 v210, 0xbfb8aa3b, v202
	v_mul_f32_e32 v211, 0xbfb8aa3b, v203
	v_exp_f32_e32 v208, v208
	v_exp_f32_e32 v209, v209
	v_exp_f32_e32 v210, v210
	v_exp_f32_e32 v211, v211
	v_add_f32_e32 v208, 1.0, v208
	v_add_f32_e32 v209, 1.0, v209
	v_add_f32_e32 v210, 1.0, v210
	v_add_f32_e32 v211, 1.0, v211
	v_rcp_f32_e32 v208, v208
	v_rcp_f32_e32 v209, v209
	v_rcp_f32_e32 v210, v210
	v_rcp_f32_e32 v211, v211
	v_mul_f32_e32 v200, v200, v208
	v_mul_f32_e32 v201, v201, v209
	v_mul_f32_e32 v202, v202, v210
	v_mul_f32_e32 v203, v203, v211
	v_mul_f32_e32 v200, v200, v204
	v_mul_f32_e32 v201, v201, v205
	v_mul_f32_e32 v202, v202, v206
	v_mul_f32_e32 v203, v203, v207
	v_cvt_pk_bf16_f32 v244, v200, v201
	v_cvt_pk_bf16_f32 v245, v202, v203
	v_fma_f32 v200, v132, v48, v140
	v_fma_f32 v201, v133, v49, v141
	v_fma_f32 v202, v134, v50, v142
	v_fma_f32 v203, v135, v51, v143
	v_fmac_f32_dpp v200, v48, v128 row_shr:1 row_mask:0xf bank_mask:0xf
	v_fmac_f32_dpp v201, v49, v129 row_shr:1 row_mask:0xf bank_mask:0xf
	v_fmac_f32_dpp v202, v50, v130 row_shr:1 row_mask:0xf bank_mask:0xf
	v_fmac_f32_dpp v203, v51, v131 row_shr:1 row_mask:0xf bank_mask:0xf
	v_fmac_f32_dpp v200, v60, v216 row_ror:1 row_mask:0xf bank_mask:0xf
	v_fmac_f32_dpp v201, v61, v217 row_ror:1 row_mask:0xf bank_mask:0xf
	v_fmac_f32_dpp v202, v62, v218 row_ror:1 row_mask:0xf bank_mask:0xf
	v_fmac_f32_dpp v203, v63, v219 row_ror:1 row_mask:0xf bank_mask:0xf
	v_fmac_f32_dpp v200, v48, v136 row_shl:1 row_mask:0xf bank_mask:0xf
	v_fmac_f32_dpp v201, v49, v137 row_shl:1 row_mask:0xf bank_mask:0xf
	v_fmac_f32_dpp v202, v50, v138 row_shl:1 row_mask:0xf bank_mask:0xf
	v_fmac_f32_dpp v203, v51, v139 row_shl:1 row_mask:0xf bank_mask:0xf
	v_fmac_f32_dpp v200, v32, v220 row_ror:15 row_mask:0xf bank_mask:0xf
	v_fmac_f32_dpp v201, v33, v221 row_ror:15 row_mask:0xf bank_mask:0xf
	v_fmac_f32_dpp v202, v34, v222 row_ror:15 row_mask:0xf bank_mask:0xf
	v_fmac_f32_dpp v203, v35, v223 row_ror:15 row_mask:0xf bank_mask:0xf
	v_fma_f32 v204, v172, v36, v180
	v_fma_f32 v205, v173, v37, v181
	v_fma_f32 v206, v174, v38, v182
	v_fma_f32 v207, v175, v39, v183
	v_fmac_f32_dpp v204, v36, v160 row_shr:1 row_mask:0xf bank_mask:0xf
	v_fmac_f32_dpp v205, v37, v161 row_shr:1 row_mask:0xf bank_mask:0xf
	v_fmac_f32_dpp v206, v38, v162 row_shr:1 row_mask:0xf bank_mask:0xf
	v_fmac_f32_dpp v207, v39, v163 row_shr:1 row_mask:0xf bank_mask:0xf
	v_fmac_f32_dpp v204, v52, v224 row_ror:1 row_mask:0xf bank_mask:0xf
	v_fmac_f32_dpp v205, v53, v225 row_ror:1 row_mask:0xf bank_mask:0xf
	v_fmac_f32_dpp v206, v54, v226 row_ror:1 row_mask:0xf bank_mask:0xf
	v_fmac_f32_dpp v207, v55, v227 row_ror:1 row_mask:0xf bank_mask:0xf
	v_fmac_f32_dpp v204, v36, v176 row_shl:1 row_mask:0xf bank_mask:0xf
	v_fmac_f32_dpp v205, v37, v177 row_shl:1 row_mask:0xf bank_mask:0xf
	v_fmac_f32_dpp v206, v38, v178 row_shl:1 row_mask:0xf bank_mask:0xf
	v_fmac_f32_dpp v207, v39, v179 row_shl:1 row_mask:0xf bank_mask:0xf
	v_fmac_f32_dpp v204, v20, v232 row_ror:15 row_mask:0xf bank_mask:0xf
	v_fmac_f32_dpp v205, v21, v233 row_ror:15 row_mask:0xf bank_mask:0xf
	v_fmac_f32_dpp v206, v22, v234 row_ror:15 row_mask:0xf bank_mask:0xf
	v_fmac_f32_dpp v207, v23, v235 row_ror:15 row_mask:0xf bank_mask:0xf
	v_mul_f32_e32 v208, 0xbfb8aa3b, v200
	v_mul_f32_e32 v209, 0xbfb8aa3b, v201
	v_mul_f32_e32 v210, 0xbfb8aa3b, v202
	v_mul_f32_e32 v211, 0xbfb8aa3b, v203
	v_exp_f32_e32 v208, v208
	v_exp_f32_e32 v209, v209
	v_exp_f32_e32 v210, v210
	v_exp_f32_e32 v211, v211
	v_add_f32_e32 v208, 1.0, v208
	v_add_f32_e32 v209, 1.0, v209
	v_add_f32_e32 v210, 1.0, v210
	v_add_f32_e32 v211, 1.0, v211
	v_rcp_f32_e32 v208, v208
	v_rcp_f32_e32 v209, v209
	v_rcp_f32_e32 v210, v210
	v_rcp_f32_e32 v211, v211
	v_mul_f32_e32 v200, v200, v208
	v_mul_f32_e32 v201, v201, v209
	v_mul_f32_e32 v202, v202, v210
	v_mul_f32_e32 v203, v203, v211
	v_mul_f32_e32 v200, v200, v204
	v_mul_f32_e32 v201, v201, v205
	v_mul_f32_e32 v202, v202, v206
	v_mul_f32_e32 v203, v203, v207
	v_cvt_pk_bf16_f32 v246, v200, v201
	v_cvt_pk_bf16_f32 v247, v202, v203
	v_fma_f32 v200, v132, v32, v140
	v_fma_f32 v201, v133, v33, v141
	v_fma_f32 v202, v134, v34, v142
	v_fma_f32 v203, v135, v35, v143
	v_fmac_f32_dpp v200, v32, v128 row_shr:1 row_mask:0xf bank_mask:0xf
	v_fmac_f32_dpp v201, v33, v129 row_shr:1 row_mask:0xf bank_mask:0xf
	v_fmac_f32_dpp v202, v34, v130 row_shr:1 row_mask:0xf bank_mask:0xf
	v_fmac_f32_dpp v203, v35, v131 row_shr:1 row_mask:0xf bank_mask:0xf
	v_fmac_f32_dpp v200, v48, v216 row_ror:1 row_mask:0xf bank_mask:0xf
	v_fmac_f32_dpp v201, v49, v217 row_ror:1 row_mask:0xf bank_mask:0xf
	v_fmac_f32_dpp v202, v50, v218 row_ror:1 row_mask:0xf bank_mask:0xf
	v_fmac_f32_dpp v203, v51, v219 row_ror:1 row_mask:0xf bank_mask:0xf
	v_fmac_f32_dpp v200, v32, v136 row_shl:1 row_mask:0xf bank_mask:0xf
	v_fmac_f32_dpp v201, v33, v137 row_shl:1 row_mask:0xf bank_mask:0xf
	v_fmac_f32_dpp v202, v34, v138 row_shl:1 row_mask:0xf bank_mask:0xf
	v_fmac_f32_dpp v203, v35, v139 row_shl:1 row_mask:0xf bank_mask:0xf
	v_fmac_f32_dpp v200, v16, v220 row_ror:15 row_mask:0xf bank_mask:0xf
	v_fmac_f32_dpp v201, v17, v221 row_ror:15 row_mask:0xf bank_mask:0xf
	v_fmac_f32_dpp v202, v18, v222 row_ror:15 row_mask:0xf bank_mask:0xf
	v_fmac_f32_dpp v203, v19, v223 row_ror:15 row_mask:0xf bank_mask:0xf
	v_fma_f32 v204, v172, v20, v180
	v_fma_f32 v205, v173, v21, v181
	v_fma_f32 v206, v174, v22, v182
	v_fma_f32 v207, v175, v23, v183
	v_fmac_f32_dpp v204, v20, v160 row_shr:1 row_mask:0xf bank_mask:0xf
	v_fmac_f32_dpp v205, v21, v161 row_shr:1 row_mask:0xf bank_mask:0xf
	v_fmac_f32_dpp v206, v22, v162 row_shr:1 row_mask:0xf bank_mask:0xf
	v_fmac_f32_dpp v207, v23, v163 row_shr:1 row_mask:0xf bank_mask:0xf
	v_fmac_f32_dpp v204, v36, v224 row_ror:1 row_mask:0xf bank_mask:0xf
	v_fmac_f32_dpp v205, v37, v225 row_ror:1 row_mask:0xf bank_mask:0xf
	v_fmac_f32_dpp v206, v38, v226 row_ror:1 row_mask:0xf bank_mask:0xf
	v_fmac_f32_dpp v207, v39, v227 row_ror:1 row_mask:0xf bank_mask:0xf
	v_fmac_f32_dpp v204, v20, v176 row_shl:1 row_mask:0xf bank_mask:0xf
	v_fmac_f32_dpp v205, v21, v177 row_shl:1 row_mask:0xf bank_mask:0xf
	v_fmac_f32_dpp v206, v22, v178 row_shl:1 row_mask:0xf bank_mask:0xf
	v_fmac_f32_dpp v207, v23, v179 row_shl:1 row_mask:0xf bank_mask:0xf
	v_fmac_f32_dpp v204, v4, v232 row_ror:15 row_mask:0xf bank_mask:0xf
	v_fmac_f32_dpp v205, v5, v233 row_ror:15 row_mask:0xf bank_mask:0xf
	v_fmac_f32_dpp v206, v6, v234 row_ror:15 row_mask:0xf bank_mask:0xf
	v_fmac_f32_dpp v207, v7, v235 row_ror:15 row_mask:0xf bank_mask:0xf
	v_mul_f32_e32 v208, 0xbfb8aa3b, v200
	v_mul_f32_e32 v209, 0xbfb8aa3b, v201
	v_mul_f32_e32 v210, 0xbfb8aa3b, v202
	v_mul_f32_e32 v211, 0xbfb8aa3b, v203
	v_exp_f32_e32 v208, v208
	v_exp_f32_e32 v209, v209
	v_exp_f32_e32 v210, v210
	v_exp_f32_e32 v211, v211
	v_add_f32_e32 v208, 1.0, v208
	v_add_f32_e32 v209, 1.0, v209
	v_add_f32_e32 v210, 1.0, v210
	v_add_f32_e32 v211, 1.0, v211
	v_rcp_f32_e32 v208, v208
	v_rcp_f32_e32 v209, v209
	v_rcp_f32_e32 v210, v210
	v_rcp_f32_e32 v211, v211
	v_mul_f32_e32 v200, v200, v208
	v_mul_f32_e32 v201, v201, v209
	v_mul_f32_e32 v202, v202, v210
	v_mul_f32_e32 v203, v203, v211
	v_mul_f32_e32 v200, v200, v204
	v_mul_f32_e32 v201, v201, v205
	v_mul_f32_e32 v202, v202, v206
	v_mul_f32_e32 v203, v203, v207
	v_cvt_pk_bf16_f32 v248, v200, v201
	v_cvt_pk_bf16_f32 v249, v202, v203
	v_fma_f32 v200, v132, v16, v140
	v_fma_f32 v201, v133, v17, v141
	v_fma_f32 v202, v134, v18, v142
	v_fma_f32 v203, v135, v19, v143
	v_fmac_f32_dpp v200, v16, v128 row_shr:1 row_mask:0xf bank_mask:0xf
	v_fmac_f32_dpp v201, v17, v129 row_shr:1 row_mask:0xf bank_mask:0xf
	v_fmac_f32_dpp v202, v18, v130 row_shr:1 row_mask:0xf bank_mask:0xf
	v_fmac_f32_dpp v203, v19, v131 row_shr:1 row_mask:0xf bank_mask:0xf
	v_fmac_f32_dpp v200, v32, v216 row_ror:1 row_mask:0xf bank_mask:0xf
	v_fmac_f32_dpp v201, v33, v217 row_ror:1 row_mask:0xf bank_mask:0xf
	v_fmac_f32_dpp v202, v34, v218 row_ror:1 row_mask:0xf bank_mask:0xf
	v_fmac_f32_dpp v203, v35, v219 row_ror:1 row_mask:0xf bank_mask:0xf
	v_fmac_f32_dpp v200, v16, v136 row_shl:1 row_mask:0xf bank_mask:0xf
	v_fmac_f32_dpp v201, v17, v137 row_shl:1 row_mask:0xf bank_mask:0xf
	v_fmac_f32_dpp v202, v18, v138 row_shl:1 row_mask:0xf bank_mask:0xf
	v_fmac_f32_dpp v203, v19, v139 row_shl:1 row_mask:0xf bank_mask:0xf
	v_fmac_f32_e32 v200, v192, v220
	v_fmac_f32_e32 v201, v193, v221
	v_fmac_f32_e32 v202, v194, v222
	v_fmac_f32_e32 v203, v195, v223
	v_fma_f32 v204, v172, v4, v180
	v_fma_f32 v205, v173, v5, v181
	v_fma_f32 v206, v174, v6, v182
	v_fma_f32 v207, v175, v7, v183
	v_fmac_f32_dpp v204, v4, v160 row_shr:1 row_mask:0xf bank_mask:0xf
	v_fmac_f32_dpp v205, v5, v161 row_shr:1 row_mask:0xf bank_mask:0xf
	v_fmac_f32_dpp v206, v6, v162 row_shr:1 row_mask:0xf bank_mask:0xf
	v_fmac_f32_dpp v207, v7, v163 row_shr:1 row_mask:0xf bank_mask:0xf
	v_fmac_f32_dpp v204, v20, v224 row_ror:1 row_mask:0xf bank_mask:0xf
	v_fmac_f32_dpp v205, v21, v225 row_ror:1 row_mask:0xf bank_mask:0xf
	v_fmac_f32_dpp v206, v22, v226 row_ror:1 row_mask:0xf bank_mask:0xf
	v_fmac_f32_dpp v207, v23, v227 row_ror:1 row_mask:0xf bank_mask:0xf
	v_fmac_f32_dpp v204, v4, v176 row_shl:1 row_mask:0xf bank_mask:0xf
	v_fmac_f32_dpp v205, v5, v177 row_shl:1 row_mask:0xf bank_mask:0xf
	v_fmac_f32_dpp v206, v6, v178 row_shl:1 row_mask:0xf bank_mask:0xf
	v_fmac_f32_dpp v207, v7, v179 row_shl:1 row_mask:0xf bank_mask:0xf
	v_fmac_f32_e32 v204, v196, v232
	v_fmac_f32_e32 v205, v197, v233
	v_fmac_f32_e32 v206, v198, v234
	v_fmac_f32_e32 v207, v199, v235
	s_mov_b64 exec, s[62:63]
	v_add_u32_e32 v250, 0x10800, v229
	global_store_dwordx4 v250, v[200:203], s[64:65]
	v_add_u32_e32 v250, 0x13400, v229
	global_store_dwordx4 v250, v[204:207], s[64:65]
	s_mov_b64 exec, s[58:59]
	s_nop 4
	v_mul_f32_e32 v208, 0xbfb8aa3b, v200
	v_mul_f32_e32 v209, 0xbfb8aa3b, v201
	v_mul_f32_e32 v210, 0xbfb8aa3b, v202
	v_mul_f32_e32 v211, 0xbfb8aa3b, v203
	v_exp_f32_e32 v208, v208
	v_exp_f32_e32 v209, v209
	v_exp_f32_e32 v210, v210
	v_exp_f32_e32 v211, v211
	v_add_f32_e32 v208, 1.0, v208
	v_add_f32_e32 v209, 1.0, v209
	v_add_f32_e32 v210, 1.0, v210
	v_add_f32_e32 v211, 1.0, v211
	v_rcp_f32_e32 v208, v208
	v_rcp_f32_e32 v209, v209
	v_rcp_f32_e32 v210, v210
	v_rcp_f32_e32 v211, v211
	v_mul_f32_e32 v200, v200, v208
	v_mul_f32_e32 v201, v201, v209
	v_mul_f32_e32 v202, v202, v210
	v_mul_f32_e32 v203, v203, v211
	v_mul_f32_e32 v200, v200, v204
	v_mul_f32_e32 v201, v201, v205
	v_mul_f32_e32 v202, v202, v206
	v_mul_f32_e32 v203, v203, v207
	v_cvt_pk_bf16_f32 v250, v200, v201
	v_cvt_pk_bf16_f32 v251, v202, v203
	global_load_dwordx4 v[128:131], v229, s[34:35] offset:16
	v_add_u32_e32 v211, 0x5800, v229
	global_load_dwordx4 v[132:135], v211, s[34:35] offset:16
	v_add_u32_e32 v210, 0xb000, v229
	global_load_dwordx4 v[136:139], v210, s[34:35] offset:16
	global_load_dwordx4 v[140:143], v229, s[36:37] offset:16
	v_add_u32_e32 v210, 0x2c00, v229
	global_load_dwordx4 v[160:163], v210, s[34:35] offset:16
	v_add_u32_e32 v211, 0x8400, v229
	global_load_dwordx4 v[172:175], v211, s[34:35] offset:16
	v_add_u32_e32 v210, 0xdc00, v229
	global_load_dwordx4 v[176:179], v210, s[34:35] offset:16
	v_add_u32_e32 v211, 0x2c00, v229
	global_load_dwordx4 v[180:183], v211, s[36:37] offset:16
	v_mov_b32_e32 v124, v236
	v_mov_b32_e32 v125, v237
	v_mov_b32_e32 v116, v238
	v_mov_b32_e32 v117, v239
	v_mov_b32_e32 v96, v240
	v_mov_b32_e32 v97, v241
	v_mov_b32_e32 v80, v242
	v_mov_b32_e32 v81, v243
	v_mov_b32_e32 v60, v244
	v_mov_b32_e32 v61, v245
	v_mov_b32_e32 v48, v246
	v_mov_b32_e32 v49, v247
	v_mov_b32_e32 v32, v248
	v_mov_b32_e32 v33, v249
	v_mov_b32_e32 v16, v250
	v_mov_b32_e32 v17, v251
	ds_read_b128 v[184:187], v231 offset:16
	ds_read_b128 v[188:191], v231 offset:528
	ds_read_b128 v[192:195], v231 offset:2064
	ds_read_b128 v[196:199], v231 offset:2576
	s_waitcnt vmcnt(0)
	v_cndmask_b32_e64 v216, 0, v128, s[54:55]
	v_cndmask_b32_e64 v220, 0, v136, s[56:57]
	v_cndmask_b32_e64 v217, 0, v129, s[54:55]
	v_cndmask_b32_e64 v221, 0, v137, s[56:57]
	v_cndmask_b32_e64 v218, 0, v130, s[54:55]
	v_cndmask_b32_e64 v222, 0, v138, s[56:57]
	v_cndmask_b32_e64 v219, 0, v131, s[54:55]
	v_cndmask_b32_e64 v223, 0, v139, s[56:57]
	v_cndmask_b32_e64 v224, 0, v160, s[54:55]
	v_cndmask_b32_e64 v232, 0, v176, s[56:57]
	v_cndmask_b32_e64 v225, 0, v161, s[54:55]
	v_cndmask_b32_e64 v233, 0, v177, s[56:57]
	v_cndmask_b32_e64 v226, 0, v162, s[54:55]
	v_cndmask_b32_e64 v234, 0, v178, s[56:57]
	v_cndmask_b32_e64 v227, 0, v163, s[54:55]
	v_cndmask_b32_e64 v235, 0, v179, s[56:57]
	s_waitcnt lgkmcnt(0)
	s_nop 1
	v_fma_f32 v200, v132, v120, v140
	v_fma_f32 v201, v133, v121, v141
	v_fma_f32 v202, v134, v122, v142
	v_fma_f32 v203, v135, v123, v143
	v_fmac_f32_dpp v200, v120, v128 row_shr:1 row_mask:0xf bank_mask:0xf
	v_fmac_f32_dpp v201, v121, v129 row_shr:1 row_mask:0xf bank_mask:0xf
	v_fmac_f32_dpp v202, v122, v130 row_shr:1 row_mask:0xf bank_mask:0xf
	v_fmac_f32_dpp v203, v123, v131 row_shr:1 row_mask:0xf bank_mask:0xf
	v_fmac_f32_e32 v200, v184, v216
	v_fmac_f32_e32 v201, v185, v217
	v_fmac_f32_e32 v202, v186, v218
	v_fmac_f32_e32 v203, v187, v219
	v_fmac_f32_dpp v200, v120, v136 row_shl:1 row_mask:0xf bank_mask:0xf
	v_fmac_f32_dpp v201, v121, v137 row_shl:1 row_mask:0xf bank_mask:0xf
	v_fmac_f32_dpp v202, v122, v138 row_shl:1 row_mask:0xf bank_mask:0xf
	v_fmac_f32_dpp v203, v123, v139 row_shl:1 row_mask:0xf bank_mask:0xf
	v_fmac_f32_dpp v200, v112, v220 row_ror:15 row_mask:0xf bank_mask:0xf
	v_fmac_f32_dpp v201, v113, v221 row_ror:15 row_mask:0xf bank_mask:0xf
	v_fmac_f32_dpp v202, v114, v222 row_ror:15 row_mask:0xf bank_mask:0xf
	v_fmac_f32_dpp v203, v115, v223 row_ror:15 row_mask:0xf bank_mask:0xf
	v_fma_f32 v204, v172, v104, v180
	v_fma_f32 v205, v173, v105, v181
	v_fma_f32 v206, v174, v106, v182
	v_fma_f32 v207, v175, v107, v183
	v_fmac_f32_dpp v204, v104, v160 row_shr:1 row_mask:0xf bank_mask:0xf
	v_fmac_f32_dpp v205, v105, v161 row_shr:1 row_mask:0xf bank_mask:0xf
	v_fmac_f32_dpp v206, v106, v162 row_shr:1 row_mask:0xf bank_mask:0xf
	v_fmac_f32_dpp v207, v107, v163 row_shr:1 row_mask:0xf bank_mask:0xf
	v_fmac_f32_e32 v204, v188, v224
	v_fmac_f32_e32 v205, v189, v225
	v_fmac_f32_e32 v206, v190, v226
	v_fmac_f32_e32 v207, v191, v227
	v_fmac_f32_dpp v204, v104, v176 row_shl:1 row_mask:0xf bank_mask:0xf
	v_fmac_f32_dpp v205, v105, v177 row_shl:1 row_mask:0xf bank_mask:0xf
	v_fmac_f32_dpp v206, v106, v178 row_shl:1 row_mask:0xf bank_mask:0xf
	v_fmac_f32_dpp v207, v107, v179 row_shl:1 row_mask:0xf bank_mask:0xf
	v_fmac_f32_dpp v204, v92, v232 row_ror:15 row_mask:0xf bank_mask:0xf
	v_fmac_f32_dpp v205, v93, v233 row_ror:15 row_mask:0xf bank_mask:0xf
	v_fmac_f32_dpp v206, v94, v234 row_ror:15 row_mask:0xf bank_mask:0xf
	v_fmac_f32_dpp v207, v95, v235 row_ror:15 row_mask:0xf bank_mask:0xf
	s_mov_b64 exec, s[60:61]
	v_add_u32_e32 v250, 0x5800, v229
	global_store_dwordx4 v250, v[200:203], s[64:65] offset:16
	v_add_u32_e32 v250, 0x8400, v229
	global_store_dwordx4 v250, v[204:207], s[64:65] offset:16
	s_mov_b64 exec, s[58:59]
	s_nop 4
	v_mul_f32_e32 v208, 0xbfb8aa3b, v200
	v_mul_f32_e32 v209, 0xbfb8aa3b, v201
	v_mul_f32_e32 v210, 0xbfb8aa3b, v202
	v_mul_f32_e32 v211, 0xbfb8aa3b, v203
	v_exp_f32_e32 v208, v208
	v_exp_f32_e32 v209, v209
	v_exp_f32_e32 v210, v210
	v_exp_f32_e32 v211, v211
	v_add_f32_e32 v208, 1.0, v208
	v_add_f32_e32 v209, 1.0, v209
	v_add_f32_e32 v210, 1.0, v210
	v_add_f32_e32 v211, 1.0, v211
	v_rcp_f32_e32 v208, v208
	v_rcp_f32_e32 v209, v209
	v_rcp_f32_e32 v210, v210
	v_rcp_f32_e32 v211, v211
	v_mul_f32_e32 v200, v200, v208
	v_mul_f32_e32 v201, v201, v209
	v_mul_f32_e32 v202, v202, v210
	v_mul_f32_e32 v203, v203, v211
	v_mul_f32_e32 v200, v200, v204
	v_mul_f32_e32 v201, v201, v205
	v_mul_f32_e32 v202, v202, v206
	v_mul_f32_e32 v203, v203, v207
	v_cvt_pk_bf16_f32 v126, v200, v201
	v_cvt_pk_bf16_f32 v127, v202, v203
	v_fma_f32 v200, v132, v112, v140
	v_fma_f32 v201, v133, v113, v141
	v_fma_f32 v202, v134, v114, v142
	v_fma_f32 v203, v135, v115, v143
	v_fmac_f32_dpp v200, v112, v128 row_shr:1 row_mask:0xf bank_mask:0xf
	v_fmac_f32_dpp v201, v113, v129 row_shr:1 row_mask:0xf bank_mask:0xf
	v_fmac_f32_dpp v202, v114, v130 row_shr:1 row_mask:0xf bank_mask:0xf
	v_fmac_f32_dpp v203, v115, v131 row_shr:1 row_mask:0xf bank_mask:0xf
	v_fmac_f32_dpp v200, v120, v216 row_ror:1 row_mask:0xf bank_mask:0xf
	v_fmac_f32_dpp v201, v121, v217 row_ror:1 row_mask:0xf bank_mask:0xf
	v_fmac_f32_dpp v202, v122, v218 row_ror:1 row_mask:0xf bank_mask:0xf
	v_fmac_f32_dpp v203, v123, v219 row_ror:1 row_mask:0xf bank_mask:0xf
	v_fmac_f32_dpp v200, v112, v136 row_shl:1 row_mask:0xf bank_mask:0xf
	v_fmac_f32_dpp v201, v113, v137 row_shl:1 row_mask:0xf bank_mask:0xf
	v_fmac_f32_dpp v202, v114, v138 row_shl:1 row_mask:0xf bank_mask:0xf
	v_fmac_f32_dpp v203, v115, v139 row_shl:1 row_mask:0xf bank_mask:0xf
	v_fmac_f32_dpp v200, v88, v220 row_ror:15 row_mask:0xf bank_mask:0xf
	v_fmac_f32_dpp v201, v89, v221 row_ror:15 row_mask:0xf bank_mask:0xf
	v_fmac_f32_dpp v202, v90, v222 row_ror:15 row_mask:0xf bank_mask:0xf
	v_fmac_f32_dpp v203, v91, v223 row_ror:15 row_mask:0xf bank_mask:0xf
	v_fma_f32 v204, v172, v92, v180
	v_fma_f32 v205, v173, v93, v181
	v_fma_f32 v206, v174, v94, v182
	v_fma_f32 v207, v175, v95, v183
	v_fmac_f32_dpp v204, v92, v160 row_shr:1 row_mask:0xf bank_mask:0xf
	v_fmac_f32_dpp v205, v93, v161 row_shr:1 row_mask:0xf bank_mask:0xf
	v_fmac_f32_dpp v206, v94, v162 row_shr:1 row_mask:0xf bank_mask:0xf
	v_fmac_f32_dpp v207, v95, v163 row_shr:1 row_mask:0xf bank_mask:0xf
	v_fmac_f32_dpp v204, v104, v224 row_ror:1 row_mask:0xf bank_mask:0xf
	v_fmac_f32_dpp v205, v105, v225 row_ror:1 row_mask:0xf bank_mask:0xf
	v_fmac_f32_dpp v206, v106, v226 row_ror:1 row_mask:0xf bank_mask:0xf
	v_fmac_f32_dpp v207, v107, v227 row_ror:1 row_mask:0xf bank_mask:0xf
	v_fmac_f32_dpp v204, v92, v176 row_shl:1 row_mask:0xf bank_mask:0xf
	v_fmac_f32_dpp v205, v93, v177 row_shl:1 row_mask:0xf bank_mask:0xf
	v_fmac_f32_dpp v206, v94, v178 row_shl:1 row_mask:0xf bank_mask:0xf
	v_fmac_f32_dpp v207, v95, v179 row_shl:1 row_mask:0xf bank_mask:0xf
	v_fmac_f32_dpp v204, v76, v232 row_ror:15 row_mask:0xf bank_mask:0xf
	v_fmac_f32_dpp v205, v77, v233 row_ror:15 row_mask:0xf bank_mask:0xf
	v_fmac_f32_dpp v206, v78, v234 row_ror:15 row_mask:0xf bank_mask:0xf
	v_fmac_f32_dpp v207, v79, v235 row_ror:15 row_mask:0xf bank_mask:0xf
	v_mul_f32_e32 v208, 0xbfb8aa3b, v200
	v_mul_f32_e32 v209, 0xbfb8aa3b, v201
	v_mul_f32_e32 v210, 0xbfb8aa3b, v202
	v_mul_f32_e32 v211, 0xbfb8aa3b, v203
	v_exp_f32_e32 v208, v208
	v_exp_f32_e32 v209, v209
	v_exp_f32_e32 v210, v210
	v_exp_f32_e32 v211, v211
	v_add_f32_e32 v208, 1.0, v208
	v_add_f32_e32 v209, 1.0, v209
	v_add_f32_e32 v210, 1.0, v210
	v_add_f32_e32 v211, 1.0, v211
	v_rcp_f32_e32 v208, v208
	v_rcp_f32_e32 v209, v209
	v_rcp_f32_e32 v210, v210
	v_rcp_f32_e32 v211, v211
	v_mul_f32_e32 v200, v200, v208
	v_mul_f32_e32 v201, v201, v209
	v_mul_f32_e32 v202, v202, v210
	v_mul_f32_e32 v203, v203, v211
	v_mul_f32_e32 v200, v200, v204
	v_mul_f32_e32 v201, v201, v205
	v_mul_f32_e32 v202, v202, v206
	v_mul_f32_e32 v203, v203, v207
	v_cvt_pk_bf16_f32 v118, v200, v201
	v_cvt_pk_bf16_f32 v119, v202, v203
	v_fma_f32 v200, v132, v88, v140
	v_fma_f32 v201, v133, v89, v141
	v_fma_f32 v202, v134, v90, v142
	v_fma_f32 v203, v135, v91, v143
	v_fmac_f32_dpp v200, v88, v128 row_shr:1 row_mask:0xf bank_mask:0xf
	v_fmac_f32_dpp v201, v89, v129 row_shr:1 row_mask:0xf bank_mask:0xf
	v_fmac_f32_dpp v202, v90, v130 row_shr:1 row_mask:0xf bank_mask:0xf
	v_fmac_f32_dpp v203, v91, v131 row_shr:1 row_mask:0xf bank_mask:0xf
	v_fmac_f32_dpp v200, v112, v216 row_ror:1 row_mask:0xf bank_mask:0xf
	v_fmac_f32_dpp v201, v113, v217 row_ror:1 row_mask:0xf bank_mask:0xf
	v_fmac_f32_dpp v202, v114, v218 row_ror:1 row_mask:0xf bank_mask:0xf
	v_fmac_f32_dpp v203, v115, v219 row_ror:1 row_mask:0xf bank_mask:0xf
	v_fmac_f32_dpp v200, v88, v136 row_shl:1 row_mask:0xf bank_mask:0xf
	v_fmac_f32_dpp v201, v89, v137 row_shl:1 row_mask:0xf bank_mask:0xf
	v_fmac_f32_dpp v202, v90, v138 row_shl:1 row_mask:0xf bank_mask:0xf
	v_fmac_f32_dpp v203, v91, v139 row_shl:1 row_mask:0xf bank_mask:0xf
	v_fmac_f32_dpp v200, v72, v220 row_ror:15 row_mask:0xf bank_mask:0xf
	v_fmac_f32_dpp v201, v73, v221 row_ror:15 row_mask:0xf bank_mask:0xf
	v_fmac_f32_dpp v202, v74, v222 row_ror:15 row_mask:0xf bank_mask:0xf
	v_fmac_f32_dpp v203, v75, v223 row_ror:15 row_mask:0xf bank_mask:0xf
	v_fma_f32 v204, v172, v76, v180
	v_fma_f32 v205, v173, v77, v181
	v_fma_f32 v206, v174, v78, v182
	v_fma_f32 v207, v175, v79, v183
	v_fmac_f32_dpp v204, v76, v160 row_shr:1 row_mask:0xf bank_mask:0xf
	v_fmac_f32_dpp v205, v77, v161 row_shr:1 row_mask:0xf bank_mask:0xf
	v_fmac_f32_dpp v206, v78, v162 row_shr:1 row_mask:0xf bank_mask:0xf
	v_fmac_f32_dpp v207, v79, v163 row_shr:1 row_mask:0xf bank_mask:0xf
	v_fmac_f32_dpp v204, v92, v224 row_ror:1 row_mask:0xf bank_mask:0xf
	v_fmac_f32_dpp v205, v93, v225 row_ror:1 row_mask:0xf bank_mask:0xf
	v_fmac_f32_dpp v206, v94, v226 row_ror:1 row_mask:0xf bank_mask:0xf
	v_fmac_f32_dpp v207, v95, v227 row_ror:1 row_mask:0xf bank_mask:0xf
	v_fmac_f32_dpp v204, v76, v176 row_shl:1 row_mask:0xf bank_mask:0xf
	v_fmac_f32_dpp v205, v77, v177 row_shl:1 row_mask:0xf bank_mask:0xf
	v_fmac_f32_dpp v206, v78, v178 row_shl:1 row_mask:0xf bank_mask:0xf
	v_fmac_f32_dpp v207, v79, v179 row_shl:1 row_mask:0xf bank_mask:0xf
	v_fmac_f32_dpp v204, v64, v232 row_ror:15 row_mask:0xf bank_mask:0xf
	v_fmac_f32_dpp v205, v65, v233 row_ror:15 row_mask:0xf bank_mask:0xf
	v_fmac_f32_dpp v206, v66, v234 row_ror:15 row_mask:0xf bank_mask:0xf
	v_fmac_f32_dpp v207, v67, v235 row_ror:15 row_mask:0xf bank_mask:0xf
	v_mul_f32_e32 v208, 0xbfb8aa3b, v200
	v_mul_f32_e32 v209, 0xbfb8aa3b, v201
	v_mul_f32_e32 v210, 0xbfb8aa3b, v202
	v_mul_f32_e32 v211, 0xbfb8aa3b, v203
	v_exp_f32_e32 v208, v208
	v_exp_f32_e32 v209, v209
	v_exp_f32_e32 v210, v210
	v_exp_f32_e32 v211, v211
	v_add_f32_e32 v208, 1.0, v208
	v_add_f32_e32 v209, 1.0, v209
	v_add_f32_e32 v210, 1.0, v210
	v_add_f32_e32 v211, 1.0, v211
	v_rcp_f32_e32 v208, v208
	v_rcp_f32_e32 v209, v209
	v_rcp_f32_e32 v210, v210
	v_rcp_f32_e32 v211, v211
	v_mul_f32_e32 v200, v200, v208
	v_mul_f32_e32 v201, v201, v209
	v_mul_f32_e32 v202, v202, v210
	v_mul_f32_e32 v203, v203, v211
	v_mul_f32_e32 v200, v200, v204
	v_mul_f32_e32 v201, v201, v205
	v_mul_f32_e32 v202, v202, v206
	v_mul_f32_e32 v203, v203, v207
	v_cvt_pk_bf16_f32 v98, v200, v201
	v_cvt_pk_bf16_f32 v99, v202, v203
	v_fma_f32 v200, v132, v72, v140
	v_fma_f32 v201, v133, v73, v141
	v_fma_f32 v202, v134, v74, v142
	v_fma_f32 v203, v135, v75, v143
	v_fmac_f32_dpp v200, v72, v128 row_shr:1 row_mask:0xf bank_mask:0xf
	v_fmac_f32_dpp v201, v73, v129 row_shr:1 row_mask:0xf bank_mask:0xf
	v_fmac_f32_dpp v202, v74, v130 row_shr:1 row_mask:0xf bank_mask:0xf
	v_fmac_f32_dpp v203, v75, v131 row_shr:1 row_mask:0xf bank_mask:0xf
	v_fmac_f32_dpp v200, v88, v216 row_ror:1 row_mask:0xf bank_mask:0xf
	v_fmac_f32_dpp v201, v89, v217 row_ror:1 row_mask:0xf bank_mask:0xf
	v_fmac_f32_dpp v202, v90, v218 row_ror:1 row_mask:0xf bank_mask:0xf
	v_fmac_f32_dpp v203, v91, v219 row_ror:1 row_mask:0xf bank_mask:0xf
	v_fmac_f32_dpp v200, v72, v136 row_shl:1 row_mask:0xf bank_mask:0xf
	v_fmac_f32_dpp v201, v73, v137 row_shl:1 row_mask:0xf bank_mask:0xf
	v_fmac_f32_dpp v202, v74, v138 row_shl:1 row_mask:0xf bank_mask:0xf
	v_fmac_f32_dpp v203, v75, v139 row_shl:1 row_mask:0xf bank_mask:0xf
	v_fmac_f32_e32 v200, v184, v220
	v_fmac_f32_e32 v201, v185, v221
	v_fmac_f32_e32 v202, v186, v222
	v_fmac_f32_e32 v203, v187, v223
	v_fma_f32 v204, v172, v64, v180
	v_fma_f32 v205, v173, v65, v181
	v_fma_f32 v206, v174, v66, v182
	v_fma_f32 v207, v175, v67, v183
	v_fmac_f32_dpp v204, v64, v160 row_shr:1 row_mask:0xf bank_mask:0xf
	v_fmac_f32_dpp v205, v65, v161 row_shr:1 row_mask:0xf bank_mask:0xf
	v_fmac_f32_dpp v206, v66, v162 row_shr:1 row_mask:0xf bank_mask:0xf
	v_fmac_f32_dpp v207, v67, v163 row_shr:1 row_mask:0xf bank_mask:0xf
	v_fmac_f32_dpp v204, v76, v224 row_ror:1 row_mask:0xf bank_mask:0xf
	v_fmac_f32_dpp v205, v77, v225 row_ror:1 row_mask:0xf bank_mask:0xf
	v_fmac_f32_dpp v206, v78, v226 row_ror:1 row_mask:0xf bank_mask:0xf
	v_fmac_f32_dpp v207, v79, v227 row_ror:1 row_mask:0xf bank_mask:0xf
	v_fmac_f32_dpp v204, v64, v176 row_shl:1 row_mask:0xf bank_mask:0xf
	v_fmac_f32_dpp v205, v65, v177 row_shl:1 row_mask:0xf bank_mask:0xf
	v_fmac_f32_dpp v206, v66, v178 row_shl:1 row_mask:0xf bank_mask:0xf
	v_fmac_f32_dpp v207, v67, v179 row_shl:1 row_mask:0xf bank_mask:0xf
	v_fmac_f32_e32 v204, v188, v232
	v_fmac_f32_e32 v205, v189, v233
	v_fmac_f32_e32 v206, v190, v234
	v_fmac_f32_e32 v207, v191, v235
	v_mul_f32_e32 v208, 0xbfb8aa3b, v200
	v_mul_f32_e32 v209, 0xbfb8aa3b, v201
	v_mul_f32_e32 v210, 0xbfb8aa3b, v202
	v_mul_f32_e32 v211, 0xbfb8aa3b, v203
	v_exp_f32_e32 v208, v208
	v_exp_f32_e32 v209, v209
	v_exp_f32_e32 v210, v210
	v_exp_f32_e32 v211, v211
	v_add_f32_e32 v208, 1.0, v208
	v_add_f32_e32 v209, 1.0, v209
	v_add_f32_e32 v210, 1.0, v210
	v_add_f32_e32 v211, 1.0, v211
	v_rcp_f32_e32 v208, v208
	v_rcp_f32_e32 v209, v209
	v_rcp_f32_e32 v210, v210
	v_rcp_f32_e32 v211, v211
	v_mul_f32_e32 v200, v200, v208
	v_mul_f32_e32 v201, v201, v209
	v_mul_f32_e32 v202, v202, v210
	v_mul_f32_e32 v203, v203, v211
	v_mul_f32_e32 v200, v200, v204
	v_mul_f32_e32 v201, v201, v205
	v_mul_f32_e32 v202, v202, v206
	v_mul_f32_e32 v203, v203, v207
	v_cvt_pk_bf16_f32 v82, v200, v201
	v_cvt_pk_bf16_f32 v83, v202, v203
	v_fma_f32 v200, v132, v56, v140
	v_fma_f32 v201, v133, v57, v141
	v_fma_f32 v202, v134, v58, v142
	v_fma_f32 v203, v135, v59, v143
	v_fmac_f32_dpp v200, v56, v128 row_shr:1 row_mask:0xf bank_mask:0xf
	v_fmac_f32_dpp v201, v57, v129 row_shr:1 row_mask:0xf bank_mask:0xf
	v_fmac_f32_dpp v202, v58, v130 row_shr:1 row_mask:0xf bank_mask:0xf
	v_fmac_f32_dpp v203, v59, v131 row_shr:1 row_mask:0xf bank_mask:0xf
	v_fmac_f32_e32 v200, v192, v216
	v_fmac_f32_e32 v201, v193, v217
	v_fmac_f32_e32 v202, v194, v218
	v_fmac_f32_e32 v203, v195, v219
	v_fmac_f32_dpp v200, v56, v136 row_shl:1 row_mask:0xf bank_mask:0xf
	v_fmac_f32_dpp v201, v57, v137 row_shl:1 row_mask:0xf bank_mask:0xf
	v_fmac_f32_dpp v202, v58, v138 row_shl:1 row_mask:0xf bank_mask:0xf
	v_fmac_f32_dpp v203, v59, v139 row_shl:1 row_mask:0xf bank_mask:0xf
	v_fmac_f32_dpp v200, v40, v220 row_ror:15 row_mask:0xf bank_mask:0xf
	v_fmac_f32_dpp v201, v41, v221 row_ror:15 row_mask:0xf bank_mask:0xf
	v_fmac_f32_dpp v202, v42, v222 row_ror:15 row_mask:0xf bank_mask:0xf
	v_fmac_f32_dpp v203, v43, v223 row_ror:15 row_mask:0xf bank_mask:0xf
	v_fma_f32 v204, v172, v44, v180
	v_fma_f32 v205, v173, v45, v181
	v_fma_f32 v206, v174, v46, v182
	v_fma_f32 v207, v175, v47, v183
	v_fmac_f32_dpp v204, v44, v160 row_shr:1 row_mask:0xf bank_mask:0xf
	v_fmac_f32_dpp v205, v45, v161 row_shr:1 row_mask:0xf bank_mask:0xf
	v_fmac_f32_dpp v206, v46, v162 row_shr:1 row_mask:0xf bank_mask:0xf
	v_fmac_f32_dpp v207, v47, v163 row_shr:1 row_mask:0xf bank_mask:0xf
	v_fmac_f32_e32 v204, v196, v224
	v_fmac_f32_e32 v205, v197, v225
	v_fmac_f32_e32 v206, v198, v226
	v_fmac_f32_e32 v207, v199, v227
	v_fmac_f32_dpp v204, v44, v176 row_shl:1 row_mask:0xf bank_mask:0xf
	v_fmac_f32_dpp v205, v45, v177 row_shl:1 row_mask:0xf bank_mask:0xf
	v_fmac_f32_dpp v206, v46, v178 row_shl:1 row_mask:0xf bank_mask:0xf
	v_fmac_f32_dpp v207, v47, v179 row_shl:1 row_mask:0xf bank_mask:0xf
	v_fmac_f32_dpp v204, v28, v232 row_ror:15 row_mask:0xf bank_mask:0xf
	v_fmac_f32_dpp v205, v29, v233 row_ror:15 row_mask:0xf bank_mask:0xf
	v_fmac_f32_dpp v206, v30, v234 row_ror:15 row_mask:0xf bank_mask:0xf
	v_fmac_f32_dpp v207, v31, v235 row_ror:15 row_mask:0xf bank_mask:0xf
	v_mul_f32_e32 v208, 0xbfb8aa3b, v200
	v_mul_f32_e32 v209, 0xbfb8aa3b, v201
	v_mul_f32_e32 v210, 0xbfb8aa3b, v202
	v_mul_f32_e32 v211, 0xbfb8aa3b, v203
	v_exp_f32_e32 v208, v208
	v_exp_f32_e32 v209, v209
	v_exp_f32_e32 v210, v210
	v_exp_f32_e32 v211, v211
	v_add_f32_e32 v208, 1.0, v208
	v_add_f32_e32 v209, 1.0, v209
	v_add_f32_e32 v210, 1.0, v210
	v_add_f32_e32 v211, 1.0, v211
	v_rcp_f32_e32 v208, v208
	v_rcp_f32_e32 v209, v209
	v_rcp_f32_e32 v210, v210
	v_rcp_f32_e32 v211, v211
	v_mul_f32_e32 v200, v200, v208
	v_mul_f32_e32 v201, v201, v209
	v_mul_f32_e32 v202, v202, v210
	v_mul_f32_e32 v203, v203, v211
	v_mul_f32_e32 v200, v200, v204
	v_mul_f32_e32 v201, v201, v205
	v_mul_f32_e32 v202, v202, v206
	v_mul_f32_e32 v203, v203, v207
	v_cvt_pk_bf16_f32 v62, v200, v201
	v_cvt_pk_bf16_f32 v63, v202, v203
	v_fma_f32 v200, v132, v40, v140
	v_fma_f32 v201, v133, v41, v141
	v_fma_f32 v202, v134, v42, v142
	v_fma_f32 v203, v135, v43, v143
	v_fmac_f32_dpp v200, v40, v128 row_shr:1 row_mask:0xf bank_mask:0xf
	v_fmac_f32_dpp v201, v41, v129 row_shr:1 row_mask:0xf bank_mask:0xf
	v_fmac_f32_dpp v202, v42, v130 row_shr:1 row_mask:0xf bank_mask:0xf
	v_fmac_f32_dpp v203, v43, v131 row_shr:1 row_mask:0xf bank_mask:0xf
	v_fmac_f32_dpp v200, v56, v216 row_ror:1 row_mask:0xf bank_mask:0xf
	v_fmac_f32_dpp v201, v57, v217 row_ror:1 row_mask:0xf bank_mask:0xf
	v_fmac_f32_dpp v202, v58, v218 row_ror:1 row_mask:0xf bank_mask:0xf
	v_fmac_f32_dpp v203, v59, v219 row_ror:1 row_mask:0xf bank_mask:0xf
	v_fmac_f32_dpp v200, v40, v136 row_shl:1 row_mask:0xf bank_mask:0xf
	v_fmac_f32_dpp v201, v41, v137 row_shl:1 row_mask:0xf bank_mask:0xf
	v_fmac_f32_dpp v202, v42, v138 row_shl:1 row_mask:0xf bank_mask:0xf
	v_fmac_f32_dpp v203, v43, v139 row_shl:1 row_mask:0xf bank_mask:0xf
	v_fmac_f32_dpp v200, v24, v220 row_ror:15 row_mask:0xf bank_mask:0xf
	v_fmac_f32_dpp v201, v25, v221 row_ror:15 row_mask:0xf bank_mask:0xf
	v_fmac_f32_dpp v202, v26, v222 row_ror:15 row_mask:0xf bank_mask:0xf
	v_fmac_f32_dpp v203, v27, v223 row_ror:15 row_mask:0xf bank_mask:0xf
	v_fma_f32 v204, v172, v28, v180
	v_fma_f32 v205, v173, v29, v181
	v_fma_f32 v206, v174, v30, v182
	v_fma_f32 v207, v175, v31, v183
	v_fmac_f32_dpp v204, v28, v160 row_shr:1 row_mask:0xf bank_mask:0xf
	v_fmac_f32_dpp v205, v29, v161 row_shr:1 row_mask:0xf bank_mask:0xf
	v_fmac_f32_dpp v206, v30, v162 row_shr:1 row_mask:0xf bank_mask:0xf
	v_fmac_f32_dpp v207, v31, v163 row_shr:1 row_mask:0xf bank_mask:0xf
	v_fmac_f32_dpp v204, v44, v224 row_ror:1 row_mask:0xf bank_mask:0xf
	v_fmac_f32_dpp v205, v45, v225 row_ror:1 row_mask:0xf bank_mask:0xf
	v_fmac_f32_dpp v206, v46, v226 row_ror:1 row_mask:0xf bank_mask:0xf
	v_fmac_f32_dpp v207, v47, v227 row_ror:1 row_mask:0xf bank_mask:0xf
	v_fmac_f32_dpp v204, v28, v176 row_shl:1 row_mask:0xf bank_mask:0xf
	v_fmac_f32_dpp v205, v29, v177 row_shl:1 row_mask:0xf bank_mask:0xf
	v_fmac_f32_dpp v206, v30, v178 row_shl:1 row_mask:0xf bank_mask:0xf
	v_fmac_f32_dpp v207, v31, v179 row_shl:1 row_mask:0xf bank_mask:0xf
	v_fmac_f32_dpp v204, v12, v232 row_ror:15 row_mask:0xf bank_mask:0xf
	v_fmac_f32_dpp v205, v13, v233 row_ror:15 row_mask:0xf bank_mask:0xf
	v_fmac_f32_dpp v206, v14, v234 row_ror:15 row_mask:0xf bank_mask:0xf
	v_fmac_f32_dpp v207, v15, v235 row_ror:15 row_mask:0xf bank_mask:0xf
	v_mul_f32_e32 v208, 0xbfb8aa3b, v200
	v_mul_f32_e32 v209, 0xbfb8aa3b, v201
	v_mul_f32_e32 v210, 0xbfb8aa3b, v202
	v_mul_f32_e32 v211, 0xbfb8aa3b, v203
	v_exp_f32_e32 v208, v208
	v_exp_f32_e32 v209, v209
	v_exp_f32_e32 v210, v210
	v_exp_f32_e32 v211, v211
	v_add_f32_e32 v208, 1.0, v208
	v_add_f32_e32 v209, 1.0, v209
	v_add_f32_e32 v210, 1.0, v210
	v_add_f32_e32 v211, 1.0, v211
	v_rcp_f32_e32 v208, v208
	v_rcp_f32_e32 v209, v209
	v_rcp_f32_e32 v210, v210
	v_rcp_f32_e32 v211, v211
	v_mul_f32_e32 v200, v200, v208
	v_mul_f32_e32 v201, v201, v209
	v_mul_f32_e32 v202, v202, v210
	v_mul_f32_e32 v203, v203, v211
	v_mul_f32_e32 v200, v200, v204
	v_mul_f32_e32 v201, v201, v205
	v_mul_f32_e32 v202, v202, v206
	v_mul_f32_e32 v203, v203, v207
	v_cvt_pk_bf16_f32 v50, v200, v201
	v_cvt_pk_bf16_f32 v51, v202, v203
	v_fma_f32 v200, v132, v24, v140
	v_fma_f32 v201, v133, v25, v141
	v_fma_f32 v202, v134, v26, v142
	v_fma_f32 v203, v135, v27, v143
	v_fmac_f32_dpp v200, v24, v128 row_shr:1 row_mask:0xf bank_mask:0xf
	v_fmac_f32_dpp v201, v25, v129 row_shr:1 row_mask:0xf bank_mask:0xf
	v_fmac_f32_dpp v202, v26, v130 row_shr:1 row_mask:0xf bank_mask:0xf
	v_fmac_f32_dpp v203, v27, v131 row_shr:1 row_mask:0xf bank_mask:0xf
	v_fmac_f32_dpp v200, v40, v216 row_ror:1 row_mask:0xf bank_mask:0xf
	v_fmac_f32_dpp v201, v41, v217 row_ror:1 row_mask:0xf bank_mask:0xf
	v_fmac_f32_dpp v202, v42, v218 row_ror:1 row_mask:0xf bank_mask:0xf
	v_fmac_f32_dpp v203, v43, v219 row_ror:1 row_mask:0xf bank_mask:0xf
	v_fmac_f32_dpp v200, v24, v136 row_shl:1 row_mask:0xf bank_mask:0xf
	v_fmac_f32_dpp v201, v25, v137 row_shl:1 row_mask:0xf bank_mask:0xf
	v_fmac_f32_dpp v202, v26, v138 row_shl:1 row_mask:0xf bank_mask:0xf
	v_fmac_f32_dpp v203, v27, v139 row_shl:1 row_mask:0xf bank_mask:0xf
	v_fmac_f32_dpp v200, v8, v220 row_ror:15 row_mask:0xf bank_mask:0xf
	v_fmac_f32_dpp v201, v9, v221 row_ror:15 row_mask:0xf bank_mask:0xf
	v_fmac_f32_dpp v202, v10, v222 row_ror:15 row_mask:0xf bank_mask:0xf
	v_fmac_f32_dpp v203, v11, v223 row_ror:15 row_mask:0xf bank_mask:0xf
	v_fma_f32 v204, v172, v12, v180
	v_fma_f32 v205, v173, v13, v181
	v_fma_f32 v206, v174, v14, v182
	v_fma_f32 v207, v175, v15, v183
	v_fmac_f32_dpp v204, v12, v160 row_shr:1 row_mask:0xf bank_mask:0xf
	v_fmac_f32_dpp v205, v13, v161 row_shr:1 row_mask:0xf bank_mask:0xf
	v_fmac_f32_dpp v206, v14, v162 row_shr:1 row_mask:0xf bank_mask:0xf
	v_fmac_f32_dpp v207, v15, v163 row_shr:1 row_mask:0xf bank_mask:0xf
	v_fmac_f32_dpp v204, v28, v224 row_ror:1 row_mask:0xf bank_mask:0xf
	v_fmac_f32_dpp v205, v29, v225 row_ror:1 row_mask:0xf bank_mask:0xf
	v_fmac_f32_dpp v206, v30, v226 row_ror:1 row_mask:0xf bank_mask:0xf
	v_fmac_f32_dpp v207, v31, v227 row_ror:1 row_mask:0xf bank_mask:0xf
	v_fmac_f32_dpp v204, v12, v176 row_shl:1 row_mask:0xf bank_mask:0xf
	v_fmac_f32_dpp v205, v13, v177 row_shl:1 row_mask:0xf bank_mask:0xf
	v_fmac_f32_dpp v206, v14, v178 row_shl:1 row_mask:0xf bank_mask:0xf
	v_fmac_f32_dpp v207, v15, v179 row_shl:1 row_mask:0xf bank_mask:0xf
	v_fmac_f32_dpp v204, v0, v232 row_ror:15 row_mask:0xf bank_mask:0xf
	v_fmac_f32_dpp v205, v1, v233 row_ror:15 row_mask:0xf bank_mask:0xf
	v_fmac_f32_dpp v206, v2, v234 row_ror:15 row_mask:0xf bank_mask:0xf
	v_fmac_f32_dpp v207, v3, v235 row_ror:15 row_mask:0xf bank_mask:0xf
	v_mul_f32_e32 v208, 0xbfb8aa3b, v200
	v_mul_f32_e32 v209, 0xbfb8aa3b, v201
	v_mul_f32_e32 v210, 0xbfb8aa3b, v202
	v_mul_f32_e32 v211, 0xbfb8aa3b, v203
	v_exp_f32_e32 v208, v208
	v_exp_f32_e32 v209, v209
	v_exp_f32_e32 v210, v210
	v_exp_f32_e32 v211, v211
	v_add_f32_e32 v208, 1.0, v208
	v_add_f32_e32 v209, 1.0, v209
	v_add_f32_e32 v210, 1.0, v210
	v_add_f32_e32 v211, 1.0, v211
	v_rcp_f32_e32 v208, v208
	v_rcp_f32_e32 v209, v209
	v_rcp_f32_e32 v210, v210
	v_rcp_f32_e32 v211, v211
	v_mul_f32_e32 v200, v200, v208
	v_mul_f32_e32 v201, v201, v209
	v_mul_f32_e32 v202, v202, v210
	v_mul_f32_e32 v203, v203, v211
	v_mul_f32_e32 v200, v200, v204
	v_mul_f32_e32 v201, v201, v205
	v_mul_f32_e32 v202, v202, v206
	v_mul_f32_e32 v203, v203, v207
	v_cvt_pk_bf16_f32 v34, v200, v201
	v_cvt_pk_bf16_f32 v35, v202, v203
	v_fma_f32 v200, v132, v8, v140
	v_fma_f32 v201, v133, v9, v141
	v_fma_f32 v202, v134, v10, v142
	v_fma_f32 v203, v135, v11, v143
	v_fmac_f32_dpp v200, v8, v128 row_shr:1 row_mask:0xf bank_mask:0xf
	v_fmac_f32_dpp v201, v9, v129 row_shr:1 row_mask:0xf bank_mask:0xf
	v_fmac_f32_dpp v202, v10, v130 row_shr:1 row_mask:0xf bank_mask:0xf
	v_fmac_f32_dpp v203, v11, v131 row_shr:1 row_mask:0xf bank_mask:0xf
	v_fmac_f32_dpp v200, v24, v216 row_ror:1 row_mask:0xf bank_mask:0xf
	v_fmac_f32_dpp v201, v25, v217 row_ror:1 row_mask:0xf bank_mask:0xf
	v_fmac_f32_dpp v202, v26, v218 row_ror:1 row_mask:0xf bank_mask:0xf
	v_fmac_f32_dpp v203, v27, v219 row_ror:1 row_mask:0xf bank_mask:0xf
	v_fmac_f32_dpp v200, v8, v136 row_shl:1 row_mask:0xf bank_mask:0xf
	v_fmac_f32_dpp v201, v9, v137 row_shl:1 row_mask:0xf bank_mask:0xf
	v_fmac_f32_dpp v202, v10, v138 row_shl:1 row_mask:0xf bank_mask:0xf
	v_fmac_f32_dpp v203, v11, v139 row_shl:1 row_mask:0xf bank_mask:0xf
	v_fmac_f32_e32 v200, v192, v220
	v_fmac_f32_e32 v201, v193, v221
	v_fmac_f32_e32 v202, v194, v222
	v_fmac_f32_e32 v203, v195, v223
	v_fma_f32 v204, v172, v0, v180
	v_fma_f32 v205, v173, v1, v181
	v_fma_f32 v206, v174, v2, v182
	v_fma_f32 v207, v175, v3, v183
	v_fmac_f32_dpp v204, v0, v160 row_shr:1 row_mask:0xf bank_mask:0xf
	v_fmac_f32_dpp v205, v1, v161 row_shr:1 row_mask:0xf bank_mask:0xf
	v_fmac_f32_dpp v206, v2, v162 row_shr:1 row_mask:0xf bank_mask:0xf
	v_fmac_f32_dpp v207, v3, v163 row_shr:1 row_mask:0xf bank_mask:0xf
	v_fmac_f32_dpp v204, v12, v224 row_ror:1 row_mask:0xf bank_mask:0xf
	v_fmac_f32_dpp v205, v13, v225 row_ror:1 row_mask:0xf bank_mask:0xf
	v_fmac_f32_dpp v206, v14, v226 row_ror:1 row_mask:0xf bank_mask:0xf
	v_fmac_f32_dpp v207, v15, v227 row_ror:1 row_mask:0xf bank_mask:0xf
	v_fmac_f32_dpp v204, v0, v176 row_shl:1 row_mask:0xf bank_mask:0xf
	v_fmac_f32_dpp v205, v1, v177 row_shl:1 row_mask:0xf bank_mask:0xf
	v_fmac_f32_dpp v206, v2, v178 row_shl:1 row_mask:0xf bank_mask:0xf
	v_fmac_f32_dpp v207, v3, v179 row_shl:1 row_mask:0xf bank_mask:0xf
	v_fmac_f32_e32 v204, v196, v232
	v_fmac_f32_e32 v205, v197, v233
	v_fmac_f32_e32 v206, v198, v234
	v_fmac_f32_e32 v207, v199, v235
	s_mov_b64 exec, s[62:63]
	v_add_u32_e32 v250, 0x10800, v229
	global_store_dwordx4 v250, v[200:203], s[64:65] offset:16
	v_add_u32_e32 v250, 0x13400, v229
	global_store_dwordx4 v250, v[204:207], s[64:65] offset:16
	s_mov_b64 exec, s[58:59]
	s_nop 4
	v_mul_f32_e32 v208, 0xbfb8aa3b, v200
	v_mul_f32_e32 v209, 0xbfb8aa3b, v201
	v_mul_f32_e32 v210, 0xbfb8aa3b, v202
	v_mul_f32_e32 v211, 0xbfb8aa3b, v203
	v_exp_f32_e32 v208, v208
	v_exp_f32_e32 v209, v209
	v_exp_f32_e32 v210, v210
	v_exp_f32_e32 v211, v211
	v_add_f32_e32 v208, 1.0, v208
	v_add_f32_e32 v209, 1.0, v209
	v_add_f32_e32 v210, 1.0, v210
	v_add_f32_e32 v211, 1.0, v211
	v_rcp_f32_e32 v208, v208
	v_rcp_f32_e32 v209, v209
	v_rcp_f32_e32 v210, v210
	v_rcp_f32_e32 v211, v211
	v_mul_f32_e32 v200, v200, v208
	v_mul_f32_e32 v201, v201, v209
	v_mul_f32_e32 v202, v202, v210
	v_mul_f32_e32 v203, v203, v211
	v_mul_f32_e32 v200, v200, v204
	v_mul_f32_e32 v201, v201, v205
	v_mul_f32_e32 v202, v202, v206
	v_mul_f32_e32 v203, v203, v207
	v_cvt_pk_bf16_f32 v18, v200, v201
	v_cvt_pk_bf16_f32 v19, v202, v203
	global_store_dwordx4 v171, v[124:127], s[52:53]
	v_add_u32_e32 v250, 0x16000, v171
	global_store_dwordx4 v250, v[116:119], s[52:53]
	s_nop 0
	v_add_u32_e32 v250, 0x2c000, v171
	global_store_dwordx4 v250, v[96:99], s[52:53]
	s_nop 0
	v_add_u32_e32 v250, 0x42000, v171
	global_store_dwordx4 v250, v[80:83], s[52:53]
	s_nop 0
	v_add_u32_e32 v250, 0xb0000, v171
	global_store_dwordx4 v250, v[60:63], s[52:53]
	s_nop 0
	v_add_u32_e32 v250, 0xc6000, v171
	global_store_dwordx4 v250, v[48:51], s[52:53]
	s_nop 0
	v_add_u32_e32 v250, 0xdc000, v171
	global_store_dwordx4 v250, v[32:35], s[52:53]
	s_nop 0
	v_add_u32_e32 v250, 0xf2000, v171
	global_store_dwordx4 v250, v[16:19], s[52:53]
	s_nop 0
	s_mov_b64 s[6:7], -1
	s_and_b64 vcc, exec, s[4:5]
	s_cbranch_vccz .LBB0_1873
	s_andn2_b64 vcc, exec, s[8:9]
	s_cbranch_vccnz .LBB0_1872
	s_barrier
	s_branch .LBB0_1872
